# gather_v rewritten by hand on a sliced fp6 V table (column sub-phases, pk_fma accumulate, permlane/DPP reduce-scatter, float4 RMW, per-wave rmsnorm pass); gather_u inner loop trimmed
# speedup vs baseline: 1.1145x; 1.0382x over previous
.LBB0_40:
	s_or_b64 exec, exec, s[14:15]
	v_mov_b32_e32 v2, v205
	v_mov_b32_e32 v1, v205
	s_add_u32 s54, s26, 0x1410000
	v_ashrrev_i32_e32 v1, 6, v1
	v_add_u32_e32 v1, s21, v1
	s_movk_i32 s0, 0x2000
	s_addc_u32 s55, s27, 0
	v_cmp_gt_i32_e32 vcc, s0, v1
	s_and_saveexec_b64 s[14:15], vcc
	s_cbranch_execz .LBB0_45
	v_and_b32_e32 v5, 31, v2
	v_bfe_u32 v4, v2, 5, 1
	v_lshlrev_b32_e32 v2, 7, v5
	v_mov_b32_e32 v3, 0
	v_mbcnt_hi_u32_b32 v6, -1, v207
	v_lshl_add_u64 v[26:27], s[10:11], 0, v[2:3]
	v_and_b32_e32 v2, 64, v6
	v_add_u32_e32 v7, 64, v2
	v_and_b32_e32 v2, 7, v5
	v_mul_u32_u24_e32 v2, 24, v2
	v_lshrrev_b32_e32 v3, 3, v5
	v_mul_u32_u24_e32 v3, 0x300000, v3
	v_add_u32_e32 v2, v2, v3
	v_mov_b32_e32 v3, 0
	v_lshl_add_u64 v[2:3], s[26:27], 0, v[2:3]
	s_mov_b64 s[0:1], 0x3800000
	v_lshl_add_u64 v[28:29], v[2:3], 0, s[0:1]
	v_xor_b32_e32 v2, 16, v6
	v_cmp_lt_i32_e32 vcc, v2, v7
	v_cmp_eq_u32_e64 s[0:1], 0, v5
	s_lshl_b32 s28, s19, 2
	v_cndmask_b32_e32 v2, v6, v2, vcc
	v_lshlrev_b32_e32 v38, 2, v2
	v_xor_b32_e32 v2, 8, v6
	v_cmp_lt_i32_e32 vcc, v2, v7
	v_lshl_or_b32 v30, v1, 1, v4
	s_lshl_b32 s29, s3, 4
	v_cndmask_b32_e32 v2, v6, v2, vcc
	v_lshlrev_b32_e32 v39, 2, v2
	v_xor_b32_e32 v2, 4, v6
	v_cmp_lt_i32_e32 vcc, v2, v7
	s_mov_b64 s[16:17], 0
	s_movk_i32 s30, 0xc0
	v_cndmask_b32_e32 v2, v6, v2, vcc
	v_lshlrev_b32_e32 v40, 2, v2
	v_xor_b32_e32 v2, 2, v6
	v_cmp_lt_i32_e32 vcc, v2, v7
	s_mov_b32 s31, 0x40f00000
	s_mov_b32 s18, 0x41000000
	v_cndmask_b32_e32 v2, v6, v2, vcc
	v_lshlrev_b32_e32 v41, 2, v2
	v_xor_b32_e32 v2, 1, v6
	v_cmp_lt_i32_e32 vcc, v2, v7
	s_mov_b32 s20, 0x41800000
	s_movk_i32 s34, 0x1fff
	v_cndmask_b32_e32 v2, v6, v2, vcc
	v_lshlrev_b32_e32 v42, 2, v2
	s_branch .LBB0_43

.LBB0_50:
	s_or_b64 exec, exec, s[14:15]
	v_mov_b32_e32 v2, v205
	v_mov_b32_e32 v1, v205
	s_add_u32 s30, s26, 0x1430000
	v_ashrrev_i32_e32 v1, 6, v1
	v_add_u32_e32 v1, s21, v1
	s_movk_i32 s0, 0x2000
	s_addc_u32 s31, s27, 0
	v_cmp_gt_i32_e32 vcc, s0, v1
	s_and_saveexec_b64 s[8:9], vcc
	s_cbranch_execz .LBB0_55
	v_and_b32_e32 v7, 31, v2
	v_bfe_u32 v6, v2, 5, 1
	v_lshlrev_b32_e32 v2, 7, v7
	v_mov_b32_e32 v3, 0
	v_lshl_add_u64 v[4:5], s[10:11], 0, v[2:3]
	s_mov_b64 s[0:1], 0x4000000
	v_lshl_add_u64 v[26:27], v[4:5], 0, s[0:1]
	v_mbcnt_hi_u32_b32 v4, -1, v207
	v_and_b32_e32 v2, 64, v4
	v_add_u32_e32 v5, 64, v2
	v_and_b32_e32 v2, 7, v7
	v_mul_u32_u24_e32 v2, 24, v2
	v_lshrrev_b32_e32 v3, 3, v7
	v_mul_u32_u24_e32 v3, 0x300000, v3
	v_add_u32_e32 v2, v2, v3
	v_mov_b32_e32 v3, 0
	v_lshl_add_u64 v[2:3], s[26:27], 0, v[2:3]
	s_mov_b64 s[0:1], 0x4800000
	v_lshl_add_u64 v[28:29], v[2:3], 0, s[0:1]
	v_xor_b32_e32 v2, 16, v4
	v_cmp_lt_i32_e32 vcc, v2, v5
	v_cmp_eq_u32_e64 s[0:1], 0, v7
	s_lshl_b32 s15, s19, 2
	v_cndmask_b32_e32 v2, v4, v2, vcc
	v_lshlrev_b32_e32 v38, 2, v2
	v_xor_b32_e32 v2, 8, v4
	v_cmp_lt_i32_e32 vcc, v2, v5
	v_lshl_or_b32 v30, v1, 1, v6
	s_lshl_b32 s3, s3, 4
	v_cndmask_b32_e32 v2, v4, v2, vcc
	v_lshlrev_b32_e32 v39, 2, v2
	v_xor_b32_e32 v2, 4, v4
	v_cmp_lt_i32_e32 vcc, v2, v5
	s_mov_b64 s[10:11], 0
	s_movk_i32 s17, 0xc0
	v_cndmask_b32_e32 v2, v4, v2, vcc
	v_lshlrev_b32_e32 v40, 2, v2
	v_xor_b32_e32 v2, 2, v4
	v_cmp_lt_i32_e32 vcc, v2, v5
	s_mov_b32 s18, 0x40f00000
	s_mov_b32 s14, 0x41000000
	v_cndmask_b32_e32 v2, v4, v2, vcc
	v_lshlrev_b32_e32 v41, 2, v2
	v_xor_b32_e32 v2, 1, v4
	v_cmp_lt_i32_e32 vcc, v2, v5
	s_mov_b32 s16, 0x41800000
	s_movk_i32 s19, 0x1fff
	v_cndmask_b32_e32 v2, v4, v2, vcc
	v_lshlrev_b32_e32 v42, 2, v2
	s_branch .LBB0_53

.Lgu0_start:
	s_mov_b64 exec, -1
	v_and_b32_e32 v171, 63, v205
	v_lshrrev_b32_e32 v172, 6, v205
	v_lshlrev_b32_e32 v160, 2, v171
	v_readfirstlane_b32 s68, v172
	v_and_b32_e32 v172, 7, v171
	v_lshlrev_b32_e32 v163, 6, v172
	v_mul_u32_u24_e32 v164, 24, v172
	s_nop 3
	s_lshl_b32 s17, s68, 14
	s_add_i32 s69, s93, s68
	v_lshrrev_b32_e32 v172, 3, v171
	v_lshl_add_u32 v162, v172, 2, s17
	v_add_u32_e32 v161, 0x2000, v162
	v_and_b32_e32 v172, 7, v171
	v_lshl_add_u32 v162, v172, 5, v162
	v_lshl_add_u32 v173, v171, 4, s17
	v_add_u32_e32 v175, s17, v160
	v_add_u32_e32 v174, 0x2000, v175
.Lgu0_chunk:
	s_movk_i32 s64, 0xc0
	s_lshl_b32 s65, s92, 13
	s_mov_b32 s14, 0xaaaaaaaa
	s_mov_b32 s15, 0xaaaaaaaa
	s_mov_b32 s100, 0xcccccccc
	s_mov_b32 s101, 0xcccccccc
	s_add_u32 s10, s26, 0xd800000
	s_addc_u32 s11, s27, 0
	s_lshl_b32 s17, s69, 9
	s_add_u32 s10, s10, s17
	s_addc_u32 s11, s11, 0
	s_lshl_b32 s18, s92, 11
	global_load_dword v16, v160, s[10:11]
	global_load_dword v17, v160, s[10:11] offset:256
	s_add_u32 s10, s10, s18
	s_addc_u32 s11, s11, 0
	global_load_dword v18, v160, s[10:11]
	global_load_dword v19, v160, s[10:11] offset:256
	s_add_u32 s10, s10, s18
	s_addc_u32 s11, s11, 0
	global_load_dword v20, v160, s[10:11]
	global_load_dword v21, v160, s[10:11] offset:256
	s_add_u32 s10, s10, s18
	s_addc_u32 s11, s11, 0
	global_load_dword v22, v160, s[10:11]
	global_load_dword v23, v160, s[10:11] offset:256
	s_add_u32 s10, s10, s18
	s_addc_u32 s11, s11, 0
	global_load_dword v24, v160, s[10:11]
	global_load_dword v25, v160, s[10:11] offset:256
	s_add_u32 s10, s10, s18
	s_addc_u32 s11, s11, 0
	global_load_dword v26, v160, s[10:11]
	global_load_dword v27, v160, s[10:11] offset:256
	s_add_u32 s10, s10, s18
	s_addc_u32 s11, s11, 0
	global_load_dword v28, v160, s[10:11]
	global_load_dword v29, v160, s[10:11] offset:256
	s_add_u32 s10, s10, s18
	s_addc_u32 s11, s11, 0
	global_load_dword v30, v160, s[10:11]
	global_load_dword v31, v160, s[10:11] offset:256
	s_add_u32 s10, s10, s18
	s_addc_u32 s11, s11, 0
	global_load_dword v32, v160, s[10:11]
	global_load_dword v33, v160, s[10:11] offset:256
	s_add_u32 s10, s10, s18
	s_addc_u32 s11, s11, 0
	global_load_dword v34, v160, s[10:11]
	global_load_dword v35, v160, s[10:11] offset:256
	s_add_u32 s10, s10, s18
	s_addc_u32 s11, s11, 0
	global_load_dword v36, v160, s[10:11]
	global_load_dword v37, v160, s[10:11] offset:256
	s_add_u32 s10, s10, s18
	s_addc_u32 s11, s11, 0
	global_load_dword v38, v160, s[10:11]
	global_load_dword v39, v160, s[10:11] offset:256
	s_add_u32 s10, s10, s18
	s_addc_u32 s11, s11, 0
	global_load_dword v40, v160, s[10:11]
	global_load_dword v41, v160, s[10:11] offset:256
	s_add_u32 s10, s10, s18
	s_addc_u32 s11, s11, 0
	global_load_dword v42, v160, s[10:11]
	global_load_dword v43, v160, s[10:11] offset:256
	s_add_u32 s10, s10, s18
	s_addc_u32 s11, s11, 0
	global_load_dword v44, v160, s[10:11]
	global_load_dword v45, v160, s[10:11] offset:256
	s_add_u32 s10, s10, s18
	s_addc_u32 s11, s11, 0
	global_load_dword v46, v160, s[10:11]
	global_load_dword v47, v160, s[10:11] offset:256
	s_add_u32 s10, s10, s18
	s_addc_u32 s11, s11, 0
	v_mov_b32_e32 v0, 0
	v_mov_b32_e32 v1, 0
	v_mov_b32_e32 v2, 0
	v_mov_b32_e32 v3, 0
	ds_write_b128 v173, v[0:3] offset:0
	ds_write_b128 v173, v[0:3] offset:1024
	ds_write_b128 v173, v[0:3] offset:2048
	ds_write_b128 v173, v[0:3] offset:3072
	ds_write_b128 v173, v[0:3] offset:4096
	ds_write_b128 v173, v[0:3] offset:5120
	ds_write_b128 v173, v[0:3] offset:6144
	ds_write_b128 v173, v[0:3] offset:7168
	s_waitcnt vmcnt(0)
	ds_write2st64_b32 v174, v16, v17 offset0:0 offset1:1
	ds_write2st64_b32 v174, v18, v19 offset0:2 offset1:3
	ds_write2st64_b32 v174, v20, v21 offset0:4 offset1:5
	ds_write2st64_b32 v174, v22, v23 offset0:6 offset1:7
	ds_write2st64_b32 v174, v24, v25 offset0:8 offset1:9
	ds_write2st64_b32 v174, v26, v27 offset0:10 offset1:11
	ds_write2st64_b32 v174, v28, v29 offset0:12 offset1:13
	ds_write2st64_b32 v174, v30, v31 offset0:14 offset1:15
	ds_write2st64_b32 v174, v32, v33 offset0:16 offset1:17
	ds_write2st64_b32 v174, v34, v35 offset0:18 offset1:19
	ds_write2st64_b32 v174, v36, v37 offset0:20 offset1:21
	ds_write2st64_b32 v174, v38, v39 offset0:22 offset1:23
	ds_write2st64_b32 v174, v40, v41 offset0:24 offset1:25
	ds_write2st64_b32 v174, v42, v43 offset0:26 offset1:27
	ds_write2st64_b32 v174, v44, v45 offset0:28 offset1:29
	ds_write2st64_b32 v174, v46, v47 offset0:30 offset1:31
	s_waitcnt lgkmcnt(0)
	s_add_u32 s4, s26, 0x1800000
	s_addc_u32 s5, s27, 0
	s_add_u32 s8, s26, 0x5800000
	s_addc_u32 s9, s27, 0
	s_lshl_b32 s17, s69, 11
	s_add_u32 s8, s8, s17
	s_addc_u32 s9, s9, 0
	s_mov_b32 s16, 0
	s_and_b32 s19, s16, 15
	s_lshr_b32 s50, s16, 4
	s_lshl_b32 s51, s19, 9
	s_mul_i32 s17, s19, s65
	s_lshl_b32 s18, s50, 9
	s_add_u32 s17, s17, s18
	s_add_u32 s10, s8, s17
	s_addc_u32 s11, s9, 0
	s_mul_i32 s17, s50, 0x300000
	s_add_u32 s4, s26, 0x1800000
	s_addc_u32 s5, s27, 0
	s_add_u32 s4, s4, s17
	s_addc_u32 s5, s5, 0
	v_mov_b32_e32 v165, v164
	v_add_u32_e32 v167, s51, v161
	v_add_u32_e32 v169, s51, v162
	ds_read2_b32 v[144:145], v167 offset0:0 offset1:8
	ds_read2_b32 v[146:147], v167 offset0:16 offset1:24
	ds_read2_b32 v[148:149], v167 offset0:32 offset1:40
	ds_read2_b32 v[150:151], v167 offset0:48 offset1:56
	global_load_dwordx4 v[112:115], v163, s[10:11]
	global_load_dwordx4 v[116:119], v163, s[10:11] offset:16
	global_load_dwordx4 v[120:123], v163, s[10:11] offset:32
	global_load_dwordx4 v[124:127], v163, s[10:11] offset:48
	s_waitcnt lgkmcnt(0)
	v_mad_u32_u24 v144, v144, s64, v165
	v_mad_u32_u24 v145, v145, s64, v165
	v_mad_u32_u24 v146, v146, s64, v165
	v_mad_u32_u24 v147, v147, s64, v165
	v_mad_u32_u24 v148, v148, s64, v165
	v_mad_u32_u24 v149, v149, s64, v165
	v_mad_u32_u24 v150, v150, s64, v165
	v_mad_u32_u24 v151, v151, s64, v165
	global_load_dwordx4 v[16:19], v144, s[4:5]
	global_load_dwordx2 v[20:21], v144, s[4:5] offset:16
	global_load_dwordx4 v[22:25], v145, s[4:5]
	global_load_dwordx2 v[26:27], v145, s[4:5] offset:16
	global_load_dwordx4 v[28:31], v146, s[4:5]
	global_load_dwordx2 v[32:33], v146, s[4:5] offset:16
	global_load_dwordx4 v[34:37], v147, s[4:5]
	global_load_dwordx2 v[38:39], v147, s[4:5] offset:16
	global_load_dwordx4 v[40:43], v148, s[4:5]
	global_load_dwordx2 v[44:45], v148, s[4:5] offset:16
	global_load_dwordx4 v[46:49], v149, s[4:5]
	global_load_dwordx2 v[50:51], v149, s[4:5] offset:16
	global_load_dwordx4 v[52:55], v150, s[4:5]
	global_load_dwordx2 v[56:57], v150, s[4:5] offset:16
	global_load_dwordx4 v[58:61], v151, s[4:5]
	global_load_dwordx2 v[62:63], v151, s[4:5] offset:16
	ds_read2_b32 v[176:177], v167 offset0:64 offset1:72
	ds_read2_b32 v[178:179], v167 offset0:80 offset1:88
	ds_read2_b32 v[180:181], v167 offset0:96 offset1:104
	ds_read2_b32 v[182:183], v167 offset0:112 offset1:120
.Lgu0_loop:
	s_waitcnt lgkmcnt(0)
	v_mad_u32_u24 v176, v176, s64, v165
	v_mad_u32_u24 v177, v177, s64, v165
	v_mad_u32_u24 v178, v178, s64, v165
	v_mad_u32_u24 v179, v179, s64, v165
	v_mad_u32_u24 v180, v180, s64, v165
	v_mad_u32_u24 v181, v181, s64, v165
	v_mad_u32_u24 v182, v182, s64, v165
	v_mad_u32_u24 v183, v183, s64, v165
	global_load_dwordx4 v[64:67], v176, s[4:5]
	global_load_dwordx2 v[68:69], v176, s[4:5] offset:16
	global_load_dwordx4 v[70:73], v177, s[4:5]
	global_load_dwordx2 v[74:75], v177, s[4:5] offset:16
	global_load_dwordx4 v[76:79], v178, s[4:5]
	global_load_dwordx2 v[80:81], v178, s[4:5] offset:16
	global_load_dwordx4 v[82:85], v179, s[4:5]
	global_load_dwordx2 v[86:87], v179, s[4:5] offset:16
	global_load_dwordx4 v[88:91], v180, s[4:5]
	global_load_dwordx2 v[92:93], v180, s[4:5] offset:16
	global_load_dwordx4 v[94:97], v181, s[4:5]
	global_load_dwordx2 v[98:99], v181, s[4:5] offset:16
	global_load_dwordx4 v[100:103], v182, s[4:5]
	global_load_dwordx2 v[104:105], v182, s[4:5] offset:16
	global_load_dwordx4 v[106:109], v183, s[4:5]
	global_load_dwordx2 v[110:111], v183, s[4:5] offset:16
	s_add_u32 s16, s16, 1
	s_and_b32 s19, s16, 15
	s_lshr_b32 s50, s16, 4
	s_lshl_b32 s51, s19, 9
	s_mul_i32 s17, s19, s65
	s_lshl_b32 s18, s50, 9
	s_add_u32 s17, s17, s18
	s_add_u32 s12, s8, s17
	s_addc_u32 s13, s9, 0
	s_mul_i32 s17, s50, 0x300000
	s_add_u32 s4, s26, 0x1800000
	s_addc_u32 s5, s27, 0
	s_add_u32 s4, s4, s17
	s_addc_u32 s5, s5, 0
	v_mov_b32_e32 v166, v164
	v_add_u32_e32 v168, s51, v161
	v_add_u32_e32 v170, s51, v162
	ds_read2_b32 v[144:145], v168 offset0:0 offset1:8
	ds_read2_b32 v[146:147], v168 offset0:16 offset1:24
	ds_read2_b32 v[148:149], v168 offset0:32 offset1:40
	ds_read2_b32 v[150:151], v168 offset0:48 offset1:56
	s_waitcnt vmcnt(30)
	v_cvt_scalef32_pk32_bf16_fp6 v[0:15], v[16:21], 1.0
	v_dot2_f32_bf16 v152, v0, v112, 0
	v_dot2_f32_bf16 v153, v1, v113, 0
	v_dot2_f32_bf16 v154, v2, v114, 0
	v_dot2_f32_bf16 v155, v3, v115, 0
	v_dot2c_f32_bf16_e32 v152, v4, v116
	v_dot2c_f32_bf16_e32 v153, v5, v117
	v_dot2c_f32_bf16_e32 v154, v6, v118
	v_dot2c_f32_bf16_e32 v155, v7, v119
	v_dot2c_f32_bf16_e32 v152, v8, v120
	v_dot2c_f32_bf16_e32 v153, v9, v121
	v_dot2c_f32_bf16_e32 v154, v10, v122
	v_dot2c_f32_bf16_e32 v155, v11, v123
	v_dot2c_f32_bf16_e32 v152, v12, v124
	v_dot2c_f32_bf16_e32 v153, v13, v125
	v_dot2c_f32_bf16_e32 v154, v14, v126
	v_dot2c_f32_bf16_e32 v155, v15, v127
	s_waitcnt vmcnt(28)
	v_cvt_scalef32_pk32_bf16_fp6 v[0:15], v[22:27], 1.0
	v_dot2_f32_bf16 v192, v0, v112, 0
	v_dot2_f32_bf16 v193, v1, v113, 0
	v_dot2_f32_bf16 v194, v2, v114, 0
	v_dot2_f32_bf16 v195, v3, v115, 0
	v_dot2c_f32_bf16_e32 v192, v4, v116
	v_dot2c_f32_bf16_e32 v193, v5, v117
	v_add_f32_e32 v156, v152, v153
	v_dot2c_f32_bf16_e32 v194, v6, v118
	v_dot2c_f32_bf16_e32 v195, v7, v119
	v_dot2c_f32_bf16_e32 v192, v8, v120
	v_add_f32_e32 v157, v154, v155
	v_dot2c_f32_bf16_e32 v193, v9, v121
	v_dot2c_f32_bf16_e32 v194, v10, v122
	v_dot2c_f32_bf16_e32 v195, v11, v123
	v_add_f32_e32 v184, v156, v157
	v_dot2c_f32_bf16_e32 v192, v12, v124
	v_dot2c_f32_bf16_e32 v193, v13, v125
	v_dot2c_f32_bf16_e32 v194, v14, v126
	v_dot2c_f32_bf16_e32 v195, v15, v127
	s_waitcnt vmcnt(26)
	v_cvt_scalef32_pk32_bf16_fp6 v[0:15], v[28:33], 1.0
	v_dot2_f32_bf16 v152, v0, v112, 0
	v_dot2_f32_bf16 v153, v1, v113, 0
	v_dot2_f32_bf16 v154, v2, v114, 0
	v_dot2_f32_bf16 v155, v3, v115, 0
	v_dot2c_f32_bf16_e32 v152, v4, v116
	v_dot2c_f32_bf16_e32 v153, v5, v117
	v_add_f32_e32 v156, v192, v193
	v_dot2c_f32_bf16_e32 v154, v6, v118
	v_dot2c_f32_bf16_e32 v155, v7, v119
	v_dot2c_f32_bf16_e32 v152, v8, v120
	v_add_f32_e32 v157, v194, v195
	v_dot2c_f32_bf16_e32 v153, v9, v121
	v_dot2c_f32_bf16_e32 v154, v10, v122
	v_dot2c_f32_bf16_e32 v155, v11, v123
	v_add_f32_e32 v185, v156, v157
	v_dot2c_f32_bf16_e32 v152, v12, v124
	v_dot2c_f32_bf16_e32 v153, v13, v125
	v_dot2c_f32_bf16_e32 v154, v14, v126
	v_dot2c_f32_bf16_e32 v155, v15, v127
	s_waitcnt vmcnt(24)
	v_cvt_scalef32_pk32_bf16_fp6 v[0:15], v[34:39], 1.0
	v_dot2_f32_bf16 v192, v0, v112, 0
	v_dot2_f32_bf16 v193, v1, v113, 0
	v_dot2_f32_bf16 v194, v2, v114, 0
	v_dot2_f32_bf16 v195, v3, v115, 0
	v_dot2c_f32_bf16_e32 v192, v4, v116
	v_dot2c_f32_bf16_e32 v193, v5, v117
	v_add_f32_e32 v156, v152, v153
	v_dot2c_f32_bf16_e32 v194, v6, v118
	v_dot2c_f32_bf16_e32 v195, v7, v119
	v_dot2c_f32_bf16_e32 v192, v8, v120
	v_add_f32_e32 v157, v154, v155
	v_dot2c_f32_bf16_e32 v193, v9, v121
	v_dot2c_f32_bf16_e32 v194, v10, v122
	v_dot2c_f32_bf16_e32 v195, v11, v123
	v_add_f32_e32 v186, v156, v157
	v_dot2c_f32_bf16_e32 v192, v12, v124
	v_dot2c_f32_bf16_e32 v193, v13, v125
	v_dot2c_f32_bf16_e32 v194, v14, v126
	v_dot2c_f32_bf16_e32 v195, v15, v127
	s_waitcnt vmcnt(22)
	v_cvt_scalef32_pk32_bf16_fp6 v[0:15], v[40:45], 1.0
	v_dot2_f32_bf16 v152, v0, v112, 0
	v_dot2_f32_bf16 v153, v1, v113, 0
	v_dot2_f32_bf16 v154, v2, v114, 0
	v_dot2_f32_bf16 v155, v3, v115, 0
	v_dot2c_f32_bf16_e32 v152, v4, v116
	v_dot2c_f32_bf16_e32 v153, v5, v117
	v_add_f32_e32 v156, v192, v193
	v_dot2c_f32_bf16_e32 v154, v6, v118
	v_dot2c_f32_bf16_e32 v155, v7, v119
	v_dot2c_f32_bf16_e32 v152, v8, v120
	v_add_f32_e32 v157, v194, v195
	v_dot2c_f32_bf16_e32 v153, v9, v121
	v_dot2c_f32_bf16_e32 v154, v10, v122
	v_dot2c_f32_bf16_e32 v155, v11, v123
	v_add_f32_e32 v187, v156, v157
	v_dot2c_f32_bf16_e32 v152, v12, v124
	v_dot2c_f32_bf16_e32 v153, v13, v125
	v_dot2c_f32_bf16_e32 v154, v14, v126
	v_dot2c_f32_bf16_e32 v155, v15, v127
	s_waitcnt vmcnt(20)
	v_cvt_scalef32_pk32_bf16_fp6 v[0:15], v[46:51], 1.0
	v_dot2_f32_bf16 v192, v0, v112, 0
	v_dot2_f32_bf16 v193, v1, v113, 0
	v_dot2_f32_bf16 v194, v2, v114, 0
	v_dot2_f32_bf16 v195, v3, v115, 0
	v_dot2c_f32_bf16_e32 v192, v4, v116
	v_dot2c_f32_bf16_e32 v193, v5, v117
	v_add_f32_e32 v156, v152, v153
	v_dot2c_f32_bf16_e32 v194, v6, v118
	v_dot2c_f32_bf16_e32 v195, v7, v119
	v_dot2c_f32_bf16_e32 v192, v8, v120
	v_add_f32_e32 v157, v154, v155
	v_dot2c_f32_bf16_e32 v193, v9, v121
	v_dot2c_f32_bf16_e32 v194, v10, v122
	v_dot2c_f32_bf16_e32 v195, v11, v123
	v_add_f32_e32 v188, v156, v157
	v_dot2c_f32_bf16_e32 v192, v12, v124
	v_dot2c_f32_bf16_e32 v193, v13, v125
	v_dot2c_f32_bf16_e32 v194, v14, v126
	v_dot2c_f32_bf16_e32 v195, v15, v127
	s_waitcnt vmcnt(18)
	v_cvt_scalef32_pk32_bf16_fp6 v[0:15], v[52:57], 1.0
	v_dot2_f32_bf16 v152, v0, v112, 0
	v_dot2_f32_bf16 v153, v1, v113, 0
	v_dot2_f32_bf16 v154, v2, v114, 0
	v_dot2_f32_bf16 v155, v3, v115, 0
	v_dot2c_f32_bf16_e32 v152, v4, v116
	v_dot2c_f32_bf16_e32 v153, v5, v117
	v_add_f32_e32 v156, v192, v193
	v_dot2c_f32_bf16_e32 v154, v6, v118
	v_dot2c_f32_bf16_e32 v155, v7, v119
	v_dot2c_f32_bf16_e32 v152, v8, v120
	v_add_f32_e32 v157, v194, v195
	v_dot2c_f32_bf16_e32 v153, v9, v121
	v_dot2c_f32_bf16_e32 v154, v10, v122
	v_dot2c_f32_bf16_e32 v155, v11, v123
	v_add_f32_e32 v189, v156, v157
	v_dot2c_f32_bf16_e32 v152, v12, v124
	v_dot2c_f32_bf16_e32 v153, v13, v125
	v_dot2c_f32_bf16_e32 v154, v14, v126
	v_dot2c_f32_bf16_e32 v155, v15, v127
	s_waitcnt vmcnt(16)
	v_cvt_scalef32_pk32_bf16_fp6 v[0:15], v[58:63], 1.0
	v_dot2_f32_bf16 v192, v0, v112, 0
	v_dot2_f32_bf16 v193, v1, v113, 0
	v_dot2_f32_bf16 v194, v2, v114, 0
	v_dot2_f32_bf16 v195, v3, v115, 0
	v_dot2c_f32_bf16_e32 v192, v4, v116
	v_dot2c_f32_bf16_e32 v193, v5, v117
	v_add_f32_e32 v156, v152, v153
	v_dot2c_f32_bf16_e32 v194, v6, v118
	v_dot2c_f32_bf16_e32 v195, v7, v119
	v_dot2c_f32_bf16_e32 v192, v8, v120
	v_add_f32_e32 v157, v154, v155
	v_dot2c_f32_bf16_e32 v193, v9, v121
	v_dot2c_f32_bf16_e32 v194, v10, v122
	v_dot2c_f32_bf16_e32 v195, v11, v123
	v_add_f32_e32 v190, v156, v157
	v_dot2c_f32_bf16_e32 v192, v12, v124
	v_dot2c_f32_bf16_e32 v193, v13, v125
	v_dot2c_f32_bf16_e32 v194, v14, v126
	v_dot2c_f32_bf16_e32 v195, v15, v127
	s_nop 1
	v_add_f32_e32 v156, v192, v193
	v_add_f32_e32 v157, v194, v195
	v_add_f32_e32 v191, v156, v157
	v_add_f32_dpp v184, v184, v184 row_half_mirror row_mask:0xf bank_mask:0x5
	v_add_f32_dpp v185, v185, v185 row_half_mirror row_mask:0xf bank_mask:0x5
	v_add_f32_dpp v186, v186, v186 row_half_mirror row_mask:0xf bank_mask:0x5
	v_add_f32_dpp v187, v187, v187 row_half_mirror row_mask:0xf bank_mask:0x5
	v_add_f32_dpp v184, v188, v188 row_half_mirror row_mask:0xf bank_mask:0xa
	v_add_f32_dpp v185, v189, v189 row_half_mirror row_mask:0xf bank_mask:0xa
	v_add_f32_dpp v186, v190, v190 row_half_mirror row_mask:0xf bank_mask:0xa
	v_add_f32_dpp v187, v191, v191 row_half_mirror row_mask:0xf bank_mask:0xa
	v_add_f32_dpp v184, v184, v184 quad_perm:[1,0,3,2] row_mask:0xf bank_mask:0xf
	v_add_f32_dpp v185, v185, v185 quad_perm:[1,0,3,2] row_mask:0xf bank_mask:0xf
	v_add_f32_dpp v186, v186, v186 quad_perm:[1,0,3,2] row_mask:0xf bank_mask:0xf
	v_add_f32_dpp v187, v187, v187 quad_perm:[1,0,3,2] row_mask:0xf bank_mask:0xf
	v_add_f32_dpp v184, v184, v184 quad_perm:[2,3,0,1] row_mask:0xf bank_mask:0xf
	v_add_f32_dpp v185, v185, v185 quad_perm:[2,3,0,1] row_mask:0xf bank_mask:0xf
	v_add_f32_dpp v186, v186, v186 quad_perm:[2,3,0,1] row_mask:0xf bank_mask:0xf
	v_add_f32_dpp v187, v187, v187 quad_perm:[2,3,0,1] row_mask:0xf bank_mask:0xf
	v_cndmask_b32_e64 v156, v184, v185, s[14:15]
	v_cndmask_b32_e64 v157, v186, v187, s[14:15]
	v_cndmask_b32_e64 v156, v156, v157, s[100:101]
	ds_add_f32 v169, v156 offset:0
	global_load_dwordx4 v[128:131], v163, s[12:13]
	global_load_dwordx4 v[132:135], v163, s[12:13] offset:16
	global_load_dwordx4 v[136:139], v163, s[12:13] offset:32
	global_load_dwordx4 v[140:143], v163, s[12:13] offset:48
	s_waitcnt lgkmcnt(0)
	v_mad_u32_u24 v144, v144, s64, v166
	v_mad_u32_u24 v145, v145, s64, v166
	v_mad_u32_u24 v146, v146, s64, v166
	v_mad_u32_u24 v147, v147, s64, v166
	v_mad_u32_u24 v148, v148, s64, v166
	v_mad_u32_u24 v149, v149, s64, v166
	v_mad_u32_u24 v150, v150, s64, v166
	v_mad_u32_u24 v151, v151, s64, v166
	global_load_dwordx4 v[16:19], v144, s[4:5]
	global_load_dwordx2 v[20:21], v144, s[4:5] offset:16
	global_load_dwordx4 v[22:25], v145, s[4:5]
	global_load_dwordx2 v[26:27], v145, s[4:5] offset:16
	global_load_dwordx4 v[28:31], v146, s[4:5]
	global_load_dwordx2 v[32:33], v146, s[4:5] offset:16
	global_load_dwordx4 v[34:37], v147, s[4:5]
	global_load_dwordx2 v[38:39], v147, s[4:5] offset:16
	global_load_dwordx4 v[40:43], v148, s[4:5]
	global_load_dwordx2 v[44:45], v148, s[4:5] offset:16
	global_load_dwordx4 v[46:49], v149, s[4:5]
	global_load_dwordx2 v[50:51], v149, s[4:5] offset:16
	global_load_dwordx4 v[52:55], v150, s[4:5]
	global_load_dwordx2 v[56:57], v150, s[4:5] offset:16
	global_load_dwordx4 v[58:61], v151, s[4:5]
	global_load_dwordx2 v[62:63], v151, s[4:5] offset:16
	ds_read2_b32 v[176:177], v168 offset0:64 offset1:72
	ds_read2_b32 v[178:179], v168 offset0:80 offset1:88
	ds_read2_b32 v[180:181], v168 offset0:96 offset1:104
	ds_read2_b32 v[182:183], v168 offset0:112 offset1:120
	s_waitcnt vmcnt(34)
	v_cvt_scalef32_pk32_bf16_fp6 v[0:15], v[64:69], 1.0
	v_dot2_f32_bf16 v152, v0, v112, 0
	v_dot2_f32_bf16 v153, v1, v113, 0
	v_dot2_f32_bf16 v154, v2, v114, 0
	v_dot2_f32_bf16 v155, v3, v115, 0
	v_dot2c_f32_bf16_e32 v152, v4, v116
	v_dot2c_f32_bf16_e32 v153, v5, v117
	v_dot2c_f32_bf16_e32 v154, v6, v118
	v_dot2c_f32_bf16_e32 v155, v7, v119
	v_dot2c_f32_bf16_e32 v152, v8, v120
	v_dot2c_f32_bf16_e32 v153, v9, v121
	v_dot2c_f32_bf16_e32 v154, v10, v122
	v_dot2c_f32_bf16_e32 v155, v11, v123
	v_dot2c_f32_bf16_e32 v152, v12, v124
	v_dot2c_f32_bf16_e32 v153, v13, v125
	v_dot2c_f32_bf16_e32 v154, v14, v126
	v_dot2c_f32_bf16_e32 v155, v15, v127
	s_waitcnt vmcnt(32)
	v_cvt_scalef32_pk32_bf16_fp6 v[0:15], v[70:75], 1.0
	v_dot2_f32_bf16 v192, v0, v112, 0
	v_dot2_f32_bf16 v193, v1, v113, 0
	v_dot2_f32_bf16 v194, v2, v114, 0
	v_dot2_f32_bf16 v195, v3, v115, 0
	v_dot2c_f32_bf16_e32 v192, v4, v116
	v_dot2c_f32_bf16_e32 v193, v5, v117
	v_add_f32_e32 v156, v152, v153
	v_dot2c_f32_bf16_e32 v194, v6, v118
	v_dot2c_f32_bf16_e32 v195, v7, v119
	v_dot2c_f32_bf16_e32 v192, v8, v120
	v_add_f32_e32 v157, v154, v155
	v_dot2c_f32_bf16_e32 v193, v9, v121
	v_dot2c_f32_bf16_e32 v194, v10, v122
	v_dot2c_f32_bf16_e32 v195, v11, v123
	v_add_f32_e32 v184, v156, v157
	v_dot2c_f32_bf16_e32 v192, v12, v124
	v_dot2c_f32_bf16_e32 v193, v13, v125
	v_dot2c_f32_bf16_e32 v194, v14, v126
	v_dot2c_f32_bf16_e32 v195, v15, v127
	s_waitcnt vmcnt(30)
	v_cvt_scalef32_pk32_bf16_fp6 v[0:15], v[76:81], 1.0
	v_dot2_f32_bf16 v152, v0, v112, 0
	v_dot2_f32_bf16 v153, v1, v113, 0
	v_dot2_f32_bf16 v154, v2, v114, 0
	v_dot2_f32_bf16 v155, v3, v115, 0
	v_dot2c_f32_bf16_e32 v152, v4, v116
	v_dot2c_f32_bf16_e32 v153, v5, v117
	v_add_f32_e32 v156, v192, v193
	v_dot2c_f32_bf16_e32 v154, v6, v118
	v_dot2c_f32_bf16_e32 v155, v7, v119
	v_dot2c_f32_bf16_e32 v152, v8, v120
	v_add_f32_e32 v157, v194, v195
	v_dot2c_f32_bf16_e32 v153, v9, v121
	v_dot2c_f32_bf16_e32 v154, v10, v122
	v_dot2c_f32_bf16_e32 v155, v11, v123
	v_add_f32_e32 v185, v156, v157
	v_dot2c_f32_bf16_e32 v152, v12, v124
	v_dot2c_f32_bf16_e32 v153, v13, v125
	v_dot2c_f32_bf16_e32 v154, v14, v126
	v_dot2c_f32_bf16_e32 v155, v15, v127
	s_waitcnt vmcnt(28)
	v_cvt_scalef32_pk32_bf16_fp6 v[0:15], v[82:87], 1.0
	v_dot2_f32_bf16 v192, v0, v112, 0
	v_dot2_f32_bf16 v193, v1, v113, 0
	v_dot2_f32_bf16 v194, v2, v114, 0
	v_dot2_f32_bf16 v195, v3, v115, 0
	v_dot2c_f32_bf16_e32 v192, v4, v116
	v_dot2c_f32_bf16_e32 v193, v5, v117
	v_add_f32_e32 v156, v152, v153
	v_dot2c_f32_bf16_e32 v194, v6, v118
	v_dot2c_f32_bf16_e32 v195, v7, v119
	v_dot2c_f32_bf16_e32 v192, v8, v120
	v_add_f32_e32 v157, v154, v155
	v_dot2c_f32_bf16_e32 v193, v9, v121
	v_dot2c_f32_bf16_e32 v194, v10, v122
	v_dot2c_f32_bf16_e32 v195, v11, v123
	v_add_f32_e32 v186, v156, v157
	v_dot2c_f32_bf16_e32 v192, v12, v124
	v_dot2c_f32_bf16_e32 v193, v13, v125
	v_dot2c_f32_bf16_e32 v194, v14, v126
	v_dot2c_f32_bf16_e32 v195, v15, v127
	s_waitcnt vmcnt(26)
	v_cvt_scalef32_pk32_bf16_fp6 v[0:15], v[88:93], 1.0
	v_dot2_f32_bf16 v152, v0, v112, 0
	v_dot2_f32_bf16 v153, v1, v113, 0
	v_dot2_f32_bf16 v154, v2, v114, 0
	v_dot2_f32_bf16 v155, v3, v115, 0
	v_dot2c_f32_bf16_e32 v152, v4, v116
	v_dot2c_f32_bf16_e32 v153, v5, v117
	v_add_f32_e32 v156, v192, v193
	v_dot2c_f32_bf16_e32 v154, v6, v118
	v_dot2c_f32_bf16_e32 v155, v7, v119
	v_dot2c_f32_bf16_e32 v152, v8, v120
	v_add_f32_e32 v157, v194, v195
	v_dot2c_f32_bf16_e32 v153, v9, v121
	v_dot2c_f32_bf16_e32 v154, v10, v122
	v_dot2c_f32_bf16_e32 v155, v11, v123
	v_add_f32_e32 v187, v156, v157
	v_dot2c_f32_bf16_e32 v152, v12, v124
	v_dot2c_f32_bf16_e32 v153, v13, v125
	v_dot2c_f32_bf16_e32 v154, v14, v126
	v_dot2c_f32_bf16_e32 v155, v15, v127
	s_waitcnt vmcnt(24)
	v_cvt_scalef32_pk32_bf16_fp6 v[0:15], v[94:99], 1.0
	v_dot2_f32_bf16 v192, v0, v112, 0
	v_dot2_f32_bf16 v193, v1, v113, 0
	v_dot2_f32_bf16 v194, v2, v114, 0
	v_dot2_f32_bf16 v195, v3, v115, 0
	v_dot2c_f32_bf16_e32 v192, v4, v116
	v_dot2c_f32_bf16_e32 v193, v5, v117
	v_add_f32_e32 v156, v152, v153
	v_dot2c_f32_bf16_e32 v194, v6, v118
	v_dot2c_f32_bf16_e32 v195, v7, v119
	v_dot2c_f32_bf16_e32 v192, v8, v120
	v_add_f32_e32 v157, v154, v155
	v_dot2c_f32_bf16_e32 v193, v9, v121
	v_dot2c_f32_bf16_e32 v194, v10, v122
	v_dot2c_f32_bf16_e32 v195, v11, v123
	v_add_f32_e32 v188, v156, v157
	v_dot2c_f32_bf16_e32 v192, v12, v124
	v_dot2c_f32_bf16_e32 v193, v13, v125
	v_dot2c_f32_bf16_e32 v194, v14, v126
	v_dot2c_f32_bf16_e32 v195, v15, v127
	s_waitcnt vmcnt(22)
	v_cvt_scalef32_pk32_bf16_fp6 v[0:15], v[100:105], 1.0
	v_dot2_f32_bf16 v152, v0, v112, 0
	v_dot2_f32_bf16 v153, v1, v113, 0
	v_dot2_f32_bf16 v154, v2, v114, 0
	v_dot2_f32_bf16 v155, v3, v115, 0
	v_dot2c_f32_bf16_e32 v152, v4, v116
	v_dot2c_f32_bf16_e32 v153, v5, v117
	v_add_f32_e32 v156, v192, v193
	v_dot2c_f32_bf16_e32 v154, v6, v118
	v_dot2c_f32_bf16_e32 v155, v7, v119
	v_dot2c_f32_bf16_e32 v152, v8, v120
	v_add_f32_e32 v157, v194, v195
	v_dot2c_f32_bf16_e32 v153, v9, v121
	v_dot2c_f32_bf16_e32 v154, v10, v122
	v_dot2c_f32_bf16_e32 v155, v11, v123
	v_add_f32_e32 v189, v156, v157
	v_dot2c_f32_bf16_e32 v152, v12, v124
	v_dot2c_f32_bf16_e32 v153, v13, v125
	v_dot2c_f32_bf16_e32 v154, v14, v126
	v_dot2c_f32_bf16_e32 v155, v15, v127
	s_waitcnt vmcnt(20)
	v_cvt_scalef32_pk32_bf16_fp6 v[0:15], v[106:111], 1.0
	v_dot2_f32_bf16 v192, v0, v112, 0
	v_dot2_f32_bf16 v193, v1, v113, 0
	v_dot2_f32_bf16 v194, v2, v114, 0
	v_dot2_f32_bf16 v195, v3, v115, 0
	v_dot2c_f32_bf16_e32 v192, v4, v116
	v_dot2c_f32_bf16_e32 v193, v5, v117
	v_add_f32_e32 v156, v152, v153
	v_dot2c_f32_bf16_e32 v194, v6, v118
	v_dot2c_f32_bf16_e32 v195, v7, v119
	v_dot2c_f32_bf16_e32 v192, v8, v120
	v_add_f32_e32 v157, v154, v155
	v_dot2c_f32_bf16_e32 v193, v9, v121
	v_dot2c_f32_bf16_e32 v194, v10, v122
	v_dot2c_f32_bf16_e32 v195, v11, v123
	v_add_f32_e32 v190, v156, v157
	v_dot2c_f32_bf16_e32 v192, v12, v124
	v_dot2c_f32_bf16_e32 v193, v13, v125
	v_dot2c_f32_bf16_e32 v194, v14, v126
	v_dot2c_f32_bf16_e32 v195, v15, v127
	s_nop 1
	v_add_f32_e32 v156, v192, v193
	v_add_f32_e32 v157, v194, v195
	v_add_f32_e32 v191, v156, v157
	v_add_f32_dpp v184, v184, v184 row_half_mirror row_mask:0xf bank_mask:0x5
	v_add_f32_dpp v185, v185, v185 row_half_mirror row_mask:0xf bank_mask:0x5
	v_add_f32_dpp v186, v186, v186 row_half_mirror row_mask:0xf bank_mask:0x5
	v_add_f32_dpp v187, v187, v187 row_half_mirror row_mask:0xf bank_mask:0x5
	v_add_f32_dpp v184, v188, v188 row_half_mirror row_mask:0xf bank_mask:0xa
	v_add_f32_dpp v185, v189, v189 row_half_mirror row_mask:0xf bank_mask:0xa
	v_add_f32_dpp v186, v190, v190 row_half_mirror row_mask:0xf bank_mask:0xa
	v_add_f32_dpp v187, v191, v191 row_half_mirror row_mask:0xf bank_mask:0xa
	v_add_f32_dpp v184, v184, v184 quad_perm:[1,0,3,2] row_mask:0xf bank_mask:0xf
	v_add_f32_dpp v185, v185, v185 quad_perm:[1,0,3,2] row_mask:0xf bank_mask:0xf
	v_add_f32_dpp v186, v186, v186 quad_perm:[1,0,3,2] row_mask:0xf bank_mask:0xf
	v_add_f32_dpp v187, v187, v187 quad_perm:[1,0,3,2] row_mask:0xf bank_mask:0xf
	v_add_f32_dpp v184, v184, v184 quad_perm:[2,3,0,1] row_mask:0xf bank_mask:0xf
	v_add_f32_dpp v185, v185, v185 quad_perm:[2,3,0,1] row_mask:0xf bank_mask:0xf
	v_add_f32_dpp v186, v186, v186 quad_perm:[2,3,0,1] row_mask:0xf bank_mask:0xf
	v_add_f32_dpp v187, v187, v187 quad_perm:[2,3,0,1] row_mask:0xf bank_mask:0xf
	v_cndmask_b32_e64 v156, v184, v185, s[14:15]
	v_cndmask_b32_e64 v157, v186, v187, s[14:15]
	v_cndmask_b32_e64 v156, v156, v157, s[100:101]
	ds_add_f32 v169, v156 offset:256
	s_waitcnt lgkmcnt(0)
	v_mad_u32_u24 v176, v176, s64, v166
	v_mad_u32_u24 v177, v177, s64, v166
	v_mad_u32_u24 v178, v178, s64, v166
	v_mad_u32_u24 v179, v179, s64, v166
	v_mad_u32_u24 v180, v180, s64, v166
	v_mad_u32_u24 v181, v181, s64, v166
	v_mad_u32_u24 v182, v182, s64, v166
	v_mad_u32_u24 v183, v183, s64, v166
	global_load_dwordx4 v[64:67], v176, s[4:5]
	global_load_dwordx2 v[68:69], v176, s[4:5] offset:16
	global_load_dwordx4 v[70:73], v177, s[4:5]
	global_load_dwordx2 v[74:75], v177, s[4:5] offset:16
	global_load_dwordx4 v[76:79], v178, s[4:5]
	global_load_dwordx2 v[80:81], v178, s[4:5] offset:16
	global_load_dwordx4 v[82:85], v179, s[4:5]
	global_load_dwordx2 v[86:87], v179, s[4:5] offset:16
	global_load_dwordx4 v[88:91], v180, s[4:5]
	global_load_dwordx2 v[92:93], v180, s[4:5] offset:16
	global_load_dwordx4 v[94:97], v181, s[4:5]
	global_load_dwordx2 v[98:99], v181, s[4:5] offset:16
	global_load_dwordx4 v[100:103], v182, s[4:5]
	global_load_dwordx2 v[104:105], v182, s[4:5] offset:16
	global_load_dwordx4 v[106:109], v183, s[4:5]
	global_load_dwordx2 v[110:111], v183, s[4:5] offset:16
	s_add_u32 s16, s16, 1
	s_and_b32 s16, s16, 63
	s_and_b32 s19, s16, 15
	s_lshr_b32 s50, s16, 4
	s_lshl_b32 s51, s19, 9
	s_mul_i32 s17, s19, s65
	s_lshl_b32 s18, s50, 9
	s_add_u32 s17, s17, s18
	s_add_u32 s10, s8, s17
	s_addc_u32 s11, s9, 0
	s_mul_i32 s17, s50, 0x300000
	s_add_u32 s4, s26, 0x1800000
	s_addc_u32 s5, s27, 0
	s_add_u32 s4, s4, s17
	s_addc_u32 s5, s5, 0
	v_mov_b32_e32 v165, v164
	v_add_u32_e32 v167, s51, v161
	v_add_u32_e32 v169, s51, v162
	ds_read2_b32 v[144:145], v167 offset0:0 offset1:8
	ds_read2_b32 v[146:147], v167 offset0:16 offset1:24
	ds_read2_b32 v[148:149], v167 offset0:32 offset1:40
	ds_read2_b32 v[150:151], v167 offset0:48 offset1:56
	s_waitcnt vmcnt(30)
	v_cvt_scalef32_pk32_bf16_fp6 v[0:15], v[16:21], 1.0
	v_dot2_f32_bf16 v152, v0, v128, 0
	v_dot2_f32_bf16 v153, v1, v129, 0
	v_dot2_f32_bf16 v154, v2, v130, 0
	v_dot2_f32_bf16 v155, v3, v131, 0
	v_dot2c_f32_bf16_e32 v152, v4, v132
	v_dot2c_f32_bf16_e32 v153, v5, v133
	v_dot2c_f32_bf16_e32 v154, v6, v134
	v_dot2c_f32_bf16_e32 v155, v7, v135
	v_dot2c_f32_bf16_e32 v152, v8, v136
	v_dot2c_f32_bf16_e32 v153, v9, v137
	v_dot2c_f32_bf16_e32 v154, v10, v138
	v_dot2c_f32_bf16_e32 v155, v11, v139
	v_dot2c_f32_bf16_e32 v152, v12, v140
	v_dot2c_f32_bf16_e32 v153, v13, v141
	v_dot2c_f32_bf16_e32 v154, v14, v142
	v_dot2c_f32_bf16_e32 v155, v15, v143
	s_waitcnt vmcnt(28)
	v_cvt_scalef32_pk32_bf16_fp6 v[0:15], v[22:27], 1.0
	v_dot2_f32_bf16 v192, v0, v128, 0
	v_dot2_f32_bf16 v193, v1, v129, 0
	v_dot2_f32_bf16 v194, v2, v130, 0
	v_dot2_f32_bf16 v195, v3, v131, 0
	v_dot2c_f32_bf16_e32 v192, v4, v132
	v_dot2c_f32_bf16_e32 v193, v5, v133
	v_add_f32_e32 v156, v152, v153
	v_dot2c_f32_bf16_e32 v194, v6, v134
	v_dot2c_f32_bf16_e32 v195, v7, v135
	v_dot2c_f32_bf16_e32 v192, v8, v136
	v_add_f32_e32 v157, v154, v155
	v_dot2c_f32_bf16_e32 v193, v9, v137
	v_dot2c_f32_bf16_e32 v194, v10, v138
	v_dot2c_f32_bf16_e32 v195, v11, v139
	v_add_f32_e32 v184, v156, v157
	v_dot2c_f32_bf16_e32 v192, v12, v140
	v_dot2c_f32_bf16_e32 v193, v13, v141
	v_dot2c_f32_bf16_e32 v194, v14, v142
	v_dot2c_f32_bf16_e32 v195, v15, v143
	s_waitcnt vmcnt(26)
	v_cvt_scalef32_pk32_bf16_fp6 v[0:15], v[28:33], 1.0
	v_dot2_f32_bf16 v152, v0, v128, 0
	v_dot2_f32_bf16 v153, v1, v129, 0
	v_dot2_f32_bf16 v154, v2, v130, 0
	v_dot2_f32_bf16 v155, v3, v131, 0
	v_dot2c_f32_bf16_e32 v152, v4, v132
	v_dot2c_f32_bf16_e32 v153, v5, v133
	v_add_f32_e32 v156, v192, v193
	v_dot2c_f32_bf16_e32 v154, v6, v134
	v_dot2c_f32_bf16_e32 v155, v7, v135
	v_dot2c_f32_bf16_e32 v152, v8, v136
	v_add_f32_e32 v157, v194, v195
	v_dot2c_f32_bf16_e32 v153, v9, v137
	v_dot2c_f32_bf16_e32 v154, v10, v138
	v_dot2c_f32_bf16_e32 v155, v11, v139
	v_add_f32_e32 v185, v156, v157
	v_dot2c_f32_bf16_e32 v152, v12, v140
	v_dot2c_f32_bf16_e32 v153, v13, v141
	v_dot2c_f32_bf16_e32 v154, v14, v142
	v_dot2c_f32_bf16_e32 v155, v15, v143
	s_waitcnt vmcnt(24)
	v_cvt_scalef32_pk32_bf16_fp6 v[0:15], v[34:39], 1.0
	v_dot2_f32_bf16 v192, v0, v128, 0
	v_dot2_f32_bf16 v193, v1, v129, 0
	v_dot2_f32_bf16 v194, v2, v130, 0
	v_dot2_f32_bf16 v195, v3, v131, 0
	v_dot2c_f32_bf16_e32 v192, v4, v132
	v_dot2c_f32_bf16_e32 v193, v5, v133
	v_add_f32_e32 v156, v152, v153
	v_dot2c_f32_bf16_e32 v194, v6, v134
	v_dot2c_f32_bf16_e32 v195, v7, v135
	v_dot2c_f32_bf16_e32 v192, v8, v136
	v_add_f32_e32 v157, v154, v155
	v_dot2c_f32_bf16_e32 v193, v9, v137
	v_dot2c_f32_bf16_e32 v194, v10, v138
	v_dot2c_f32_bf16_e32 v195, v11, v139
	v_add_f32_e32 v186, v156, v157
	v_dot2c_f32_bf16_e32 v192, v12, v140
	v_dot2c_f32_bf16_e32 v193, v13, v141
	v_dot2c_f32_bf16_e32 v194, v14, v142
	v_dot2c_f32_bf16_e32 v195, v15, v143
	s_waitcnt vmcnt(22)
	v_cvt_scalef32_pk32_bf16_fp6 v[0:15], v[40:45], 1.0
	v_dot2_f32_bf16 v152, v0, v128, 0
	v_dot2_f32_bf16 v153, v1, v129, 0
	v_dot2_f32_bf16 v154, v2, v130, 0
	v_dot2_f32_bf16 v155, v3, v131, 0
	v_dot2c_f32_bf16_e32 v152, v4, v132
	v_dot2c_f32_bf16_e32 v153, v5, v133
	v_add_f32_e32 v156, v192, v193
	v_dot2c_f32_bf16_e32 v154, v6, v134
	v_dot2c_f32_bf16_e32 v155, v7, v135
	v_dot2c_f32_bf16_e32 v152, v8, v136
	v_add_f32_e32 v157, v194, v195
	v_dot2c_f32_bf16_e32 v153, v9, v137
	v_dot2c_f32_bf16_e32 v154, v10, v138
	v_dot2c_f32_bf16_e32 v155, v11, v139
	v_add_f32_e32 v187, v156, v157
	v_dot2c_f32_bf16_e32 v152, v12, v140
	v_dot2c_f32_bf16_e32 v153, v13, v141
	v_dot2c_f32_bf16_e32 v154, v14, v142
	v_dot2c_f32_bf16_e32 v155, v15, v143
	s_waitcnt vmcnt(20)
	v_cvt_scalef32_pk32_bf16_fp6 v[0:15], v[46:51], 1.0
	v_dot2_f32_bf16 v192, v0, v128, 0
	v_dot2_f32_bf16 v193, v1, v129, 0
	v_dot2_f32_bf16 v194, v2, v130, 0
	v_dot2_f32_bf16 v195, v3, v131, 0
	v_dot2c_f32_bf16_e32 v192, v4, v132
	v_dot2c_f32_bf16_e32 v193, v5, v133
	v_add_f32_e32 v156, v152, v153
	v_dot2c_f32_bf16_e32 v194, v6, v134
	v_dot2c_f32_bf16_e32 v195, v7, v135
	v_dot2c_f32_bf16_e32 v192, v8, v136
	v_add_f32_e32 v157, v154, v155
	v_dot2c_f32_bf16_e32 v193, v9, v137
	v_dot2c_f32_bf16_e32 v194, v10, v138
	v_dot2c_f32_bf16_e32 v195, v11, v139
	v_add_f32_e32 v188, v156, v157
	v_dot2c_f32_bf16_e32 v192, v12, v140
	v_dot2c_f32_bf16_e32 v193, v13, v141
	v_dot2c_f32_bf16_e32 v194, v14, v142
	v_dot2c_f32_bf16_e32 v195, v15, v143
	s_waitcnt vmcnt(18)
	v_cvt_scalef32_pk32_bf16_fp6 v[0:15], v[52:57], 1.0
	v_dot2_f32_bf16 v152, v0, v128, 0
	v_dot2_f32_bf16 v153, v1, v129, 0
	v_dot2_f32_bf16 v154, v2, v130, 0
	v_dot2_f32_bf16 v155, v3, v131, 0
	v_dot2c_f32_bf16_e32 v152, v4, v132
	v_dot2c_f32_bf16_e32 v153, v5, v133
	v_add_f32_e32 v156, v192, v193
	v_dot2c_f32_bf16_e32 v154, v6, v134
	v_dot2c_f32_bf16_e32 v155, v7, v135
	v_dot2c_f32_bf16_e32 v152, v8, v136
	v_add_f32_e32 v157, v194, v195
	v_dot2c_f32_bf16_e32 v153, v9, v137
	v_dot2c_f32_bf16_e32 v154, v10, v138
	v_dot2c_f32_bf16_e32 v155, v11, v139
	v_add_f32_e32 v189, v156, v157
	v_dot2c_f32_bf16_e32 v152, v12, v140
	v_dot2c_f32_bf16_e32 v153, v13, v141
	v_dot2c_f32_bf16_e32 v154, v14, v142
	v_dot2c_f32_bf16_e32 v155, v15, v143
	s_waitcnt vmcnt(16)
	v_cvt_scalef32_pk32_bf16_fp6 v[0:15], v[58:63], 1.0
	v_dot2_f32_bf16 v192, v0, v128, 0
	v_dot2_f32_bf16 v193, v1, v129, 0
	v_dot2_f32_bf16 v194, v2, v130, 0
	v_dot2_f32_bf16 v195, v3, v131, 0
	v_dot2c_f32_bf16_e32 v192, v4, v132
	v_dot2c_f32_bf16_e32 v193, v5, v133
	v_add_f32_e32 v156, v152, v153
	v_dot2c_f32_bf16_e32 v194, v6, v134
	v_dot2c_f32_bf16_e32 v195, v7, v135
	v_dot2c_f32_bf16_e32 v192, v8, v136
	v_add_f32_e32 v157, v154, v155
	v_dot2c_f32_bf16_e32 v193, v9, v137
	v_dot2c_f32_bf16_e32 v194, v10, v138
	v_dot2c_f32_bf16_e32 v195, v11, v139
	v_add_f32_e32 v190, v156, v157
	v_dot2c_f32_bf16_e32 v192, v12, v140
	v_dot2c_f32_bf16_e32 v193, v13, v141
	v_dot2c_f32_bf16_e32 v194, v14, v142
	v_dot2c_f32_bf16_e32 v195, v15, v143
	s_nop 1
	v_add_f32_e32 v156, v192, v193
	v_add_f32_e32 v157, v194, v195
	v_add_f32_e32 v191, v156, v157
	v_add_f32_dpp v184, v184, v184 row_half_mirror row_mask:0xf bank_mask:0x5
	v_add_f32_dpp v185, v185, v185 row_half_mirror row_mask:0xf bank_mask:0x5
	v_add_f32_dpp v186, v186, v186 row_half_mirror row_mask:0xf bank_mask:0x5
	v_add_f32_dpp v187, v187, v187 row_half_mirror row_mask:0xf bank_mask:0x5
	v_add_f32_dpp v184, v188, v188 row_half_mirror row_mask:0xf bank_mask:0xa
	v_add_f32_dpp v185, v189, v189 row_half_mirror row_mask:0xf bank_mask:0xa
	v_add_f32_dpp v186, v190, v190 row_half_mirror row_mask:0xf bank_mask:0xa
	v_add_f32_dpp v187, v191, v191 row_half_mirror row_mask:0xf bank_mask:0xa
	v_add_f32_dpp v184, v184, v184 quad_perm:[1,0,3,2] row_mask:0xf bank_mask:0xf
	v_add_f32_dpp v185, v185, v185 quad_perm:[1,0,3,2] row_mask:0xf bank_mask:0xf
	v_add_f32_dpp v186, v186, v186 quad_perm:[1,0,3,2] row_mask:0xf bank_mask:0xf
	v_add_f32_dpp v187, v187, v187 quad_perm:[1,0,3,2] row_mask:0xf bank_mask:0xf
	v_add_f32_dpp v184, v184, v184 quad_perm:[2,3,0,1] row_mask:0xf bank_mask:0xf
	v_add_f32_dpp v185, v185, v185 quad_perm:[2,3,0,1] row_mask:0xf bank_mask:0xf
	v_add_f32_dpp v186, v186, v186 quad_perm:[2,3,0,1] row_mask:0xf bank_mask:0xf
	v_add_f32_dpp v187, v187, v187 quad_perm:[2,3,0,1] row_mask:0xf bank_mask:0xf
	v_cndmask_b32_e64 v156, v184, v185, s[14:15]
	v_cndmask_b32_e64 v157, v186, v187, s[14:15]
	v_cndmask_b32_e64 v156, v156, v157, s[100:101]
	ds_add_f32 v170, v156 offset:0
	global_load_dwordx4 v[112:115], v163, s[10:11]
	global_load_dwordx4 v[116:119], v163, s[10:11] offset:16
	global_load_dwordx4 v[120:123], v163, s[10:11] offset:32
	global_load_dwordx4 v[124:127], v163, s[10:11] offset:48
	s_waitcnt lgkmcnt(0)
	v_mad_u32_u24 v144, v144, s64, v165
	v_mad_u32_u24 v145, v145, s64, v165
	v_mad_u32_u24 v146, v146, s64, v165
	v_mad_u32_u24 v147, v147, s64, v165
	v_mad_u32_u24 v148, v148, s64, v165
	v_mad_u32_u24 v149, v149, s64, v165
	v_mad_u32_u24 v150, v150, s64, v165
	v_mad_u32_u24 v151, v151, s64, v165
	global_load_dwordx4 v[16:19], v144, s[4:5]
	global_load_dwordx2 v[20:21], v144, s[4:5] offset:16
	global_load_dwordx4 v[22:25], v145, s[4:5]
	global_load_dwordx2 v[26:27], v145, s[4:5] offset:16
	global_load_dwordx4 v[28:31], v146, s[4:5]
	global_load_dwordx2 v[32:33], v146, s[4:5] offset:16
	global_load_dwordx4 v[34:37], v147, s[4:5]
	global_load_dwordx2 v[38:39], v147, s[4:5] offset:16
	global_load_dwordx4 v[40:43], v148, s[4:5]
	global_load_dwordx2 v[44:45], v148, s[4:5] offset:16
	global_load_dwordx4 v[46:49], v149, s[4:5]
	global_load_dwordx2 v[50:51], v149, s[4:5] offset:16
	global_load_dwordx4 v[52:55], v150, s[4:5]
	global_load_dwordx2 v[56:57], v150, s[4:5] offset:16
	global_load_dwordx4 v[58:61], v151, s[4:5]
	global_load_dwordx2 v[62:63], v151, s[4:5] offset:16
	ds_read2_b32 v[176:177], v167 offset0:64 offset1:72
	ds_read2_b32 v[178:179], v167 offset0:80 offset1:88
	ds_read2_b32 v[180:181], v167 offset0:96 offset1:104
	ds_read2_b32 v[182:183], v167 offset0:112 offset1:120
	s_waitcnt vmcnt(34)
	v_cvt_scalef32_pk32_bf16_fp6 v[0:15], v[64:69], 1.0
	v_dot2_f32_bf16 v152, v0, v128, 0
	v_dot2_f32_bf16 v153, v1, v129, 0
	v_dot2_f32_bf16 v154, v2, v130, 0
	v_dot2_f32_bf16 v155, v3, v131, 0
	v_dot2c_f32_bf16_e32 v152, v4, v132
	v_dot2c_f32_bf16_e32 v153, v5, v133
	v_dot2c_f32_bf16_e32 v154, v6, v134
	v_dot2c_f32_bf16_e32 v155, v7, v135
	v_dot2c_f32_bf16_e32 v152, v8, v136
	v_dot2c_f32_bf16_e32 v153, v9, v137
	v_dot2c_f32_bf16_e32 v154, v10, v138
	v_dot2c_f32_bf16_e32 v155, v11, v139
	v_dot2c_f32_bf16_e32 v152, v12, v140
	v_dot2c_f32_bf16_e32 v153, v13, v141
	v_dot2c_f32_bf16_e32 v154, v14, v142
	v_dot2c_f32_bf16_e32 v155, v15, v143
	s_waitcnt vmcnt(32)
	v_cvt_scalef32_pk32_bf16_fp6 v[0:15], v[70:75], 1.0
	v_dot2_f32_bf16 v192, v0, v128, 0
	v_dot2_f32_bf16 v193, v1, v129, 0
	v_dot2_f32_bf16 v194, v2, v130, 0
	v_dot2_f32_bf16 v195, v3, v131, 0
	v_dot2c_f32_bf16_e32 v192, v4, v132
	v_dot2c_f32_bf16_e32 v193, v5, v133
	v_add_f32_e32 v156, v152, v153
	v_dot2c_f32_bf16_e32 v194, v6, v134
	v_dot2c_f32_bf16_e32 v195, v7, v135
	v_dot2c_f32_bf16_e32 v192, v8, v136
	v_add_f32_e32 v157, v154, v155
	v_dot2c_f32_bf16_e32 v193, v9, v137
	v_dot2c_f32_bf16_e32 v194, v10, v138
	v_dot2c_f32_bf16_e32 v195, v11, v139
	v_add_f32_e32 v184, v156, v157
	v_dot2c_f32_bf16_e32 v192, v12, v140
	v_dot2c_f32_bf16_e32 v193, v13, v141
	v_dot2c_f32_bf16_e32 v194, v14, v142
	v_dot2c_f32_bf16_e32 v195, v15, v143
	s_waitcnt vmcnt(30)
	v_cvt_scalef32_pk32_bf16_fp6 v[0:15], v[76:81], 1.0
	v_dot2_f32_bf16 v152, v0, v128, 0
	v_dot2_f32_bf16 v153, v1, v129, 0
	v_dot2_f32_bf16 v154, v2, v130, 0
	v_dot2_f32_bf16 v155, v3, v131, 0
	v_dot2c_f32_bf16_e32 v152, v4, v132
	v_dot2c_f32_bf16_e32 v153, v5, v133
	v_add_f32_e32 v156, v192, v193
	v_dot2c_f32_bf16_e32 v154, v6, v134
	v_dot2c_f32_bf16_e32 v155, v7, v135
	v_dot2c_f32_bf16_e32 v152, v8, v136
	v_add_f32_e32 v157, v194, v195
	v_dot2c_f32_bf16_e32 v153, v9, v137
	v_dot2c_f32_bf16_e32 v154, v10, v138
	v_dot2c_f32_bf16_e32 v155, v11, v139
	v_add_f32_e32 v185, v156, v157
	v_dot2c_f32_bf16_e32 v152, v12, v140
	v_dot2c_f32_bf16_e32 v153, v13, v141
	v_dot2c_f32_bf16_e32 v154, v14, v142
	v_dot2c_f32_bf16_e32 v155, v15, v143
	s_waitcnt vmcnt(28)
	v_cvt_scalef32_pk32_bf16_fp6 v[0:15], v[82:87], 1.0
	v_dot2_f32_bf16 v192, v0, v128, 0
	v_dot2_f32_bf16 v193, v1, v129, 0
	v_dot2_f32_bf16 v194, v2, v130, 0
	v_dot2_f32_bf16 v195, v3, v131, 0
	v_dot2c_f32_bf16_e32 v192, v4, v132
	v_dot2c_f32_bf16_e32 v193, v5, v133
	v_add_f32_e32 v156, v152, v153
	v_dot2c_f32_bf16_e32 v194, v6, v134
	v_dot2c_f32_bf16_e32 v195, v7, v135
	v_dot2c_f32_bf16_e32 v192, v8, v136
	v_add_f32_e32 v157, v154, v155
	v_dot2c_f32_bf16_e32 v193, v9, v137
	v_dot2c_f32_bf16_e32 v194, v10, v138
	v_dot2c_f32_bf16_e32 v195, v11, v139
	v_add_f32_e32 v186, v156, v157
	v_dot2c_f32_bf16_e32 v192, v12, v140
	v_dot2c_f32_bf16_e32 v193, v13, v141
	v_dot2c_f32_bf16_e32 v194, v14, v142
	v_dot2c_f32_bf16_e32 v195, v15, v143
	s_waitcnt vmcnt(26)
	v_cvt_scalef32_pk32_bf16_fp6 v[0:15], v[88:93], 1.0
	v_dot2_f32_bf16 v152, v0, v128, 0
	v_dot2_f32_bf16 v153, v1, v129, 0
	v_dot2_f32_bf16 v154, v2, v130, 0
	v_dot2_f32_bf16 v155, v3, v131, 0
	v_dot2c_f32_bf16_e32 v152, v4, v132
	v_dot2c_f32_bf16_e32 v153, v5, v133
	v_add_f32_e32 v156, v192, v193
	v_dot2c_f32_bf16_e32 v154, v6, v134
	v_dot2c_f32_bf16_e32 v155, v7, v135
	v_dot2c_f32_bf16_e32 v152, v8, v136
	v_add_f32_e32 v157, v194, v195
	v_dot2c_f32_bf16_e32 v153, v9, v137
	v_dot2c_f32_bf16_e32 v154, v10, v138
	v_dot2c_f32_bf16_e32 v155, v11, v139
	v_add_f32_e32 v187, v156, v157
	v_dot2c_f32_bf16_e32 v152, v12, v140
	v_dot2c_f32_bf16_e32 v153, v13, v141
	v_dot2c_f32_bf16_e32 v154, v14, v142
	v_dot2c_f32_bf16_e32 v155, v15, v143
	s_waitcnt vmcnt(24)
	v_cvt_scalef32_pk32_bf16_fp6 v[0:15], v[94:99], 1.0
	v_dot2_f32_bf16 v192, v0, v128, 0
	v_dot2_f32_bf16 v193, v1, v129, 0
	v_dot2_f32_bf16 v194, v2, v130, 0
	v_dot2_f32_bf16 v195, v3, v131, 0
	v_dot2c_f32_bf16_e32 v192, v4, v132
	v_dot2c_f32_bf16_e32 v193, v5, v133
	v_add_f32_e32 v156, v152, v153
	v_dot2c_f32_bf16_e32 v194, v6, v134
	v_dot2c_f32_bf16_e32 v195, v7, v135
	v_dot2c_f32_bf16_e32 v192, v8, v136
	v_add_f32_e32 v157, v154, v155
	v_dot2c_f32_bf16_e32 v193, v9, v137
	v_dot2c_f32_bf16_e32 v194, v10, v138
	v_dot2c_f32_bf16_e32 v195, v11, v139
	v_add_f32_e32 v188, v156, v157
	v_dot2c_f32_bf16_e32 v192, v12, v140
	v_dot2c_f32_bf16_e32 v193, v13, v141
	v_dot2c_f32_bf16_e32 v194, v14, v142
	v_dot2c_f32_bf16_e32 v195, v15, v143
	s_waitcnt vmcnt(22)
	v_cvt_scalef32_pk32_bf16_fp6 v[0:15], v[100:105], 1.0
	v_dot2_f32_bf16 v152, v0, v128, 0
	v_dot2_f32_bf16 v153, v1, v129, 0
	v_dot2_f32_bf16 v154, v2, v130, 0
	v_dot2_f32_bf16 v155, v3, v131, 0
	v_dot2c_f32_bf16_e32 v152, v4, v132
	v_dot2c_f32_bf16_e32 v153, v5, v133
	v_add_f32_e32 v156, v192, v193
	v_dot2c_f32_bf16_e32 v154, v6, v134
	v_dot2c_f32_bf16_e32 v155, v7, v135
	v_dot2c_f32_bf16_e32 v152, v8, v136
	v_add_f32_e32 v157, v194, v195
	v_dot2c_f32_bf16_e32 v153, v9, v137
	v_dot2c_f32_bf16_e32 v154, v10, v138
	v_dot2c_f32_bf16_e32 v155, v11, v139
	v_add_f32_e32 v189, v156, v157
	v_dot2c_f32_bf16_e32 v152, v12, v140
	v_dot2c_f32_bf16_e32 v153, v13, v141
	v_dot2c_f32_bf16_e32 v154, v14, v142
	v_dot2c_f32_bf16_e32 v155, v15, v143
	s_waitcnt vmcnt(20)
	v_cvt_scalef32_pk32_bf16_fp6 v[0:15], v[106:111], 1.0
	v_dot2_f32_bf16 v192, v0, v128, 0
	v_dot2_f32_bf16 v193, v1, v129, 0
	v_dot2_f32_bf16 v194, v2, v130, 0
	v_dot2_f32_bf16 v195, v3, v131, 0
	v_dot2c_f32_bf16_e32 v192, v4, v132
	v_dot2c_f32_bf16_e32 v193, v5, v133
	v_add_f32_e32 v156, v152, v153
	v_dot2c_f32_bf16_e32 v194, v6, v134
	v_dot2c_f32_bf16_e32 v195, v7, v135
	v_dot2c_f32_bf16_e32 v192, v8, v136
	v_add_f32_e32 v157, v154, v155
	v_dot2c_f32_bf16_e32 v193, v9, v137
	v_dot2c_f32_bf16_e32 v194, v10, v138
	v_dot2c_f32_bf16_e32 v195, v11, v139
	v_add_f32_e32 v190, v156, v157
	v_dot2c_f32_bf16_e32 v192, v12, v140
	v_dot2c_f32_bf16_e32 v193, v13, v141
	v_dot2c_f32_bf16_e32 v194, v14, v142
	v_dot2c_f32_bf16_e32 v195, v15, v143
	s_nop 1
	v_add_f32_e32 v156, v192, v193
	v_add_f32_e32 v157, v194, v195
	v_add_f32_e32 v191, v156, v157
	v_add_f32_dpp v184, v184, v184 row_half_mirror row_mask:0xf bank_mask:0x5
	v_add_f32_dpp v185, v185, v185 row_half_mirror row_mask:0xf bank_mask:0x5
	v_add_f32_dpp v186, v186, v186 row_half_mirror row_mask:0xf bank_mask:0x5
	v_add_f32_dpp v187, v187, v187 row_half_mirror row_mask:0xf bank_mask:0x5
	v_add_f32_dpp v184, v188, v188 row_half_mirror row_mask:0xf bank_mask:0xa
	v_add_f32_dpp v185, v189, v189 row_half_mirror row_mask:0xf bank_mask:0xa
	v_add_f32_dpp v186, v190, v190 row_half_mirror row_mask:0xf bank_mask:0xa
	v_add_f32_dpp v187, v191, v191 row_half_mirror row_mask:0xf bank_mask:0xa
	v_add_f32_dpp v184, v184, v184 quad_perm:[1,0,3,2] row_mask:0xf bank_mask:0xf
	v_add_f32_dpp v185, v185, v185 quad_perm:[1,0,3,2] row_mask:0xf bank_mask:0xf
	v_add_f32_dpp v186, v186, v186 quad_perm:[1,0,3,2] row_mask:0xf bank_mask:0xf
	v_add_f32_dpp v187, v187, v187 quad_perm:[1,0,3,2] row_mask:0xf bank_mask:0xf
	v_add_f32_dpp v184, v184, v184 quad_perm:[2,3,0,1] row_mask:0xf bank_mask:0xf
	v_add_f32_dpp v185, v185, v185 quad_perm:[2,3,0,1] row_mask:0xf bank_mask:0xf
	v_add_f32_dpp v186, v186, v186 quad_perm:[2,3,0,1] row_mask:0xf bank_mask:0xf
	v_add_f32_dpp v187, v187, v187 quad_perm:[2,3,0,1] row_mask:0xf bank_mask:0xf
	v_cndmask_b32_e64 v156, v184, v185, s[14:15]
	v_cndmask_b32_e64 v157, v186, v187, s[14:15]
	v_cndmask_b32_e64 v156, v156, v157, s[100:101]
	ds_add_f32 v170, v156 offset:256
	s_cmp_lg_u32 s16, 0
	s_cbranch_scc1 .Lgu0_loop
	s_waitcnt vmcnt(0) lgkmcnt(0)
	s_add_u32 s4, s26, 0x1400000
	s_addc_u32 s5, s27, 0
	s_add_u32 s8, s26, 0x1410000
	s_addc_u32 s9, s27, 0
	s_lshl_b32 s17, s69, 9
	s_add_u32 s10, s26, 0xe800000
	s_addc_u32 s11, s27, 0
	s_add_u32 s10, s10, s17
	s_addc_u32 s11, s11, 0
	s_add_u32 s12, s26, 0xf800000
	s_addc_u32 s13, s27, 0
	s_add_u32 s12, s12, s17
	s_addc_u32 s13, s13, 0
	s_lshl_b32 s18, s92, 11
	s_mov_b32 s16, 0x378e98ab
	s_mov_b32 s19, 0x3b7cd369
	s_mov_b32 s50, 0xbcc618b2
	s_mov_b32 s51, 0x3dda74e4
	s_mov_b32 s64, 0x3f228afd
	s_mov_b32 s65, 0x3e03c728
	s_mov_b32 s98, 0xbfb8aa3b
	s_mov_b32 s70, 0x42ce8ed0
	s_mov_b32 s71, 0xc2b17218
	s_mov_b32 s14, 0x7fffffff
	v_mov_b32_e32 v176, 0x3ba10414
	v_mov_b32_e32 v177, 0xb9c68948
	v_mov_b32_e32 v178, 0x7f800000
	ds_read2st64_b32 v[16:17], v174 offset0:0 offset1:1
	ds_read2st64_b32 v[80:81], v175 offset0:0 offset1:1
	ds_read2st64_b32 v[18:19], v174 offset0:2 offset1:3
	ds_read2st64_b32 v[82:83], v175 offset0:2 offset1:3
	ds_read2st64_b32 v[20:21], v174 offset0:4 offset1:5
	ds_read2st64_b32 v[84:85], v175 offset0:4 offset1:5
	ds_read2st64_b32 v[22:23], v174 offset0:6 offset1:7
	ds_read2st64_b32 v[86:87], v175 offset0:6 offset1:7
	ds_read2st64_b32 v[24:25], v174 offset0:8 offset1:9
	ds_read2st64_b32 v[88:89], v175 offset0:8 offset1:9
	ds_read2st64_b32 v[26:27], v174 offset0:10 offset1:11
	ds_read2st64_b32 v[90:91], v175 offset0:10 offset1:11
	ds_read2st64_b32 v[28:29], v174 offset0:12 offset1:13
	ds_read2st64_b32 v[92:93], v175 offset0:12 offset1:13
	ds_read2st64_b32 v[30:31], v174 offset0:14 offset1:15
	ds_read2st64_b32 v[94:95], v175 offset0:14 offset1:15
	s_waitcnt lgkmcnt(0)
	v_lshlrev_b32_e32 v16, 2, v16
	v_lshlrev_b32_e32 v17, 2, v17
	v_lshlrev_b32_e32 v18, 2, v18
	v_lshlrev_b32_e32 v19, 2, v19
	v_lshlrev_b32_e32 v20, 2, v20
	v_lshlrev_b32_e32 v21, 2, v21
	v_lshlrev_b32_e32 v22, 2, v22
	v_lshlrev_b32_e32 v23, 2, v23
	v_lshlrev_b32_e32 v24, 2, v24
	v_lshlrev_b32_e32 v25, 2, v25
	v_lshlrev_b32_e32 v26, 2, v26
	v_lshlrev_b32_e32 v27, 2, v27
	v_lshlrev_b32_e32 v28, 2, v28
	v_lshlrev_b32_e32 v29, 2, v29
	v_lshlrev_b32_e32 v30, 2, v30
	v_lshlrev_b32_e32 v31, 2, v31
	global_load_dword v32, v160, s[10:11]
	global_load_dword v33, v160, s[10:11] offset:256
	global_load_dword v34, v16, s[4:5]
	global_load_dword v35, v17, s[4:5]
	global_load_dword v36, v16, s[8:9]
	global_load_dword v37, v17, s[8:9]
	s_add_u32 s10, s10, s18
	s_addc_u32 s11, s11, 0
	global_load_dword v38, v160, s[10:11]
	global_load_dword v39, v160, s[10:11] offset:256
	global_load_dword v40, v18, s[4:5]
	global_load_dword v41, v19, s[4:5]
	global_load_dword v42, v18, s[8:9]
	global_load_dword v43, v19, s[8:9]
	s_add_u32 s10, s10, s18
	s_addc_u32 s11, s11, 0
	global_load_dword v44, v160, s[10:11]
	global_load_dword v45, v160, s[10:11] offset:256
	global_load_dword v46, v20, s[4:5]
	global_load_dword v47, v21, s[4:5]
	global_load_dword v48, v20, s[8:9]
	global_load_dword v49, v21, s[8:9]
	s_add_u32 s10, s10, s18
	s_addc_u32 s11, s11, 0
	global_load_dword v50, v160, s[10:11]
	global_load_dword v51, v160, s[10:11] offset:256
	global_load_dword v52, v22, s[4:5]
	global_load_dword v53, v23, s[4:5]
	global_load_dword v54, v22, s[8:9]
	global_load_dword v55, v23, s[8:9]
	s_add_u32 s10, s10, s18
	s_addc_u32 s11, s11, 0
	global_load_dword v56, v160, s[10:11]
	global_load_dword v57, v160, s[10:11] offset:256
	global_load_dword v58, v24, s[4:5]
	global_load_dword v59, v25, s[4:5]
	global_load_dword v60, v24, s[8:9]
	global_load_dword v61, v25, s[8:9]
	s_add_u32 s10, s10, s18
	s_addc_u32 s11, s11, 0
	global_load_dword v62, v160, s[10:11]
	global_load_dword v63, v160, s[10:11] offset:256
	global_load_dword v64, v26, s[4:5]
	global_load_dword v65, v27, s[4:5]
	global_load_dword v66, v26, s[8:9]
	global_load_dword v67, v27, s[8:9]
	s_add_u32 s10, s10, s18
	s_addc_u32 s11, s11, 0
	global_load_dword v68, v160, s[10:11]
	global_load_dword v69, v160, s[10:11] offset:256
	global_load_dword v70, v28, s[4:5]
	global_load_dword v71, v29, s[4:5]
	global_load_dword v72, v28, s[8:9]
	global_load_dword v73, v29, s[8:9]
	s_add_u32 s10, s10, s18
	s_addc_u32 s11, s11, 0
	global_load_dword v74, v160, s[10:11]
	global_load_dword v75, v160, s[10:11] offset:256
	global_load_dword v76, v30, s[4:5]
	global_load_dword v77, v31, s[4:5]
	global_load_dword v78, v30, s[8:9]
	global_load_dword v79, v31, s[8:9]
	s_add_u32 s10, s10, s18
	s_addc_u32 s11, s11, 0
	s_waitcnt vmcnt(0)
	v_mul_f32_e32 v80, v34, v80
	v_mul_f32_e32 v180, 0x3f3504f3, v80
	v_fma_f32 v182, |v180|, s16, v177
	v_fma_f32 v182, |v180|, v182, s19
	v_fma_f32 v182, |v180|, v182, s50
	v_fma_f32 v182, |v180|, v182, s51
	v_fma_f32 v182, |v180|, v182, s64
	v_fma_f32 v182, |v180|, v182, s65
	v_fma_f32 v182, |v180|, v182, |v180|
	v_mul_f32_e32 v184, 0xbfb8aa3b, v182
	v_fma_f32 v185, v182, s98, -v184
	v_rndne_f32_e32 v186, v184
	v_fmac_f32_e32 v185, 0xb2a5705f, v182
	v_sub_f32_e32 v184, v184, v186
	v_add_f32_e32 v184, v184, v185
	v_cvt_i32_f32_e32 v185, v186
	v_exp_f32_e32 v184, v184
	v_cmp_nlt_f32_e32 vcc, s70, v182
	v_ldexp_f32 v184, v184, v185
	s_nop 0
	v_cndmask_b32_e32 v184, 0, v184, vcc
	v_cmp_ngt_f32_e32 vcc, s71, v182
	s_nop 1
	v_cndmask_b32_e32 v184, v178, v184, vcc
	v_sub_f32_e32 v184, 1.0, v184
	v_mul_f32_e32 v183, v180, v180
	v_fmamk_f32 v185, v183, 0xba1345e1, v176
	v_fmaak_f32 v185, v183, v185, 0xbcdac9b8
	v_fmaak_f32 v185, v183, v185, 0x3de703be
	v_fmaak_f32 v185, v183, v185, 0xbec09330
	v_fmaak_f32 v183, v183, v185, 0x3e0375d0
	v_fma_f32 v183, |v180|, v183, |v180|
	v_cmp_nlt_f32_e64 vcc, |v180|, 1.0
	s_nop 1
	v_cndmask_b32_e32 v184, v183, v184, vcc
	v_bfi_b32 v184, s14, v184, v180
	v_add_f32_e32 v184, 1.0, v184
	v_mul_f32_e32 v80, 0.5, v80
	v_mul_f32_e32 v32, v32, v36
	v_mul_f32_e32 v80, v80, v184
	v_mul_f32_e32 v80, v32, v80
	v_mul_f32_e32 v81, v35, v81
	v_mul_f32_e32 v180, 0x3f3504f3, v81
	v_fma_f32 v182, |v180|, s16, v177
	v_fma_f32 v182, |v180|, v182, s19
	v_fma_f32 v182, |v180|, v182, s50
	v_fma_f32 v182, |v180|, v182, s51
	v_fma_f32 v182, |v180|, v182, s64
	v_fma_f32 v182, |v180|, v182, s65
	v_fma_f32 v182, |v180|, v182, |v180|
	v_mul_f32_e32 v184, 0xbfb8aa3b, v182
	v_fma_f32 v185, v182, s98, -v184
	v_rndne_f32_e32 v186, v184
	v_fmac_f32_e32 v185, 0xb2a5705f, v182
	v_sub_f32_e32 v184, v184, v186
	v_add_f32_e32 v184, v184, v185
	v_cvt_i32_f32_e32 v185, v186
	v_exp_f32_e32 v184, v184
	v_cmp_nlt_f32_e32 vcc, s70, v182
	v_ldexp_f32 v184, v184, v185
	s_nop 0
	v_cndmask_b32_e32 v184, 0, v184, vcc
	v_cmp_ngt_f32_e32 vcc, s71, v182
	s_nop 1
	v_cndmask_b32_e32 v184, v178, v184, vcc
	v_sub_f32_e32 v184, 1.0, v184
	v_mul_f32_e32 v183, v180, v180
	v_fmamk_f32 v185, v183, 0xba1345e1, v176
	v_fmaak_f32 v185, v183, v185, 0xbcdac9b8
	v_fmaak_f32 v185, v183, v185, 0x3de703be
	v_fmaak_f32 v185, v183, v185, 0xbec09330
	v_fmaak_f32 v183, v183, v185, 0x3e0375d0
	v_fma_f32 v183, |v180|, v183, |v180|
	v_cmp_nlt_f32_e64 vcc, |v180|, 1.0
	s_nop 1
	v_cndmask_b32_e32 v184, v183, v184, vcc
	v_bfi_b32 v184, s14, v184, v180
	v_add_f32_e32 v184, 1.0, v184
	v_mul_f32_e32 v81, 0.5, v81
	v_mul_f32_e32 v33, v33, v37
	v_mul_f32_e32 v81, v81, v184
	v_mul_f32_e32 v81, v33, v81
	global_store_dword v160, v80, s[12:13]
	global_store_dword v160, v81, s[12:13] offset:256
	s_add_u32 s12, s12, s18
	s_addc_u32 s13, s13, 0
	v_mul_f32_e32 v82, v40, v82
	v_mul_f32_e32 v180, 0x3f3504f3, v82
	v_fma_f32 v182, |v180|, s16, v177
	v_fma_f32 v182, |v180|, v182, s19
	v_fma_f32 v182, |v180|, v182, s50
	v_fma_f32 v182, |v180|, v182, s51
	v_fma_f32 v182, |v180|, v182, s64
	v_fma_f32 v182, |v180|, v182, s65
	v_fma_f32 v182, |v180|, v182, |v180|
	v_mul_f32_e32 v184, 0xbfb8aa3b, v182
	v_fma_f32 v185, v182, s98, -v184
	v_rndne_f32_e32 v186, v184
	v_fmac_f32_e32 v185, 0xb2a5705f, v182
	v_sub_f32_e32 v184, v184, v186
	v_add_f32_e32 v184, v184, v185
	v_cvt_i32_f32_e32 v185, v186
	v_exp_f32_e32 v184, v184
	v_cmp_nlt_f32_e32 vcc, s70, v182
	v_ldexp_f32 v184, v184, v185
	s_nop 0
	v_cndmask_b32_e32 v184, 0, v184, vcc
	v_cmp_ngt_f32_e32 vcc, s71, v182
	s_nop 1
	v_cndmask_b32_e32 v184, v178, v184, vcc
	v_sub_f32_e32 v184, 1.0, v184
	v_mul_f32_e32 v183, v180, v180
	v_fmamk_f32 v185, v183, 0xba1345e1, v176
	v_fmaak_f32 v185, v183, v185, 0xbcdac9b8
	v_fmaak_f32 v185, v183, v185, 0x3de703be
	v_fmaak_f32 v185, v183, v185, 0xbec09330
	v_fmaak_f32 v183, v183, v185, 0x3e0375d0
	v_fma_f32 v183, |v180|, v183, |v180|
	v_cmp_nlt_f32_e64 vcc, |v180|, 1.0
	s_nop 1
	v_cndmask_b32_e32 v184, v183, v184, vcc
	v_bfi_b32 v184, s14, v184, v180
	v_add_f32_e32 v184, 1.0, v184
	v_mul_f32_e32 v82, 0.5, v82
	v_mul_f32_e32 v38, v38, v42
	v_mul_f32_e32 v82, v82, v184
	v_mul_f32_e32 v82, v38, v82
	v_mul_f32_e32 v83, v41, v83
	v_mul_f32_e32 v180, 0x3f3504f3, v83
	v_fma_f32 v182, |v180|, s16, v177
	v_fma_f32 v182, |v180|, v182, s19
	v_fma_f32 v182, |v180|, v182, s50
	v_fma_f32 v182, |v180|, v182, s51
	v_fma_f32 v182, |v180|, v182, s64
	v_fma_f32 v182, |v180|, v182, s65
	v_fma_f32 v182, |v180|, v182, |v180|
	v_mul_f32_e32 v184, 0xbfb8aa3b, v182
	v_fma_f32 v185, v182, s98, -v184
	v_rndne_f32_e32 v186, v184
	v_fmac_f32_e32 v185, 0xb2a5705f, v182
	v_sub_f32_e32 v184, v184, v186
	v_add_f32_e32 v184, v184, v185
	v_cvt_i32_f32_e32 v185, v186
	v_exp_f32_e32 v184, v184
	v_cmp_nlt_f32_e32 vcc, s70, v182
	v_ldexp_f32 v184, v184, v185
	s_nop 0
	v_cndmask_b32_e32 v184, 0, v184, vcc
	v_cmp_ngt_f32_e32 vcc, s71, v182
	s_nop 1
	v_cndmask_b32_e32 v184, v178, v184, vcc
	v_sub_f32_e32 v184, 1.0, v184
	v_mul_f32_e32 v183, v180, v180
	v_fmamk_f32 v185, v183, 0xba1345e1, v176
	v_fmaak_f32 v185, v183, v185, 0xbcdac9b8
	v_fmaak_f32 v185, v183, v185, 0x3de703be
	v_fmaak_f32 v185, v183, v185, 0xbec09330
	v_fmaak_f32 v183, v183, v185, 0x3e0375d0
	v_fma_f32 v183, |v180|, v183, |v180|
	v_cmp_nlt_f32_e64 vcc, |v180|, 1.0
	s_nop 1
	v_cndmask_b32_e32 v184, v183, v184, vcc
	v_bfi_b32 v184, s14, v184, v180
	v_add_f32_e32 v184, 1.0, v184
	v_mul_f32_e32 v83, 0.5, v83
	v_mul_f32_e32 v39, v39, v43
	v_mul_f32_e32 v83, v83, v184
	v_mul_f32_e32 v83, v39, v83
	global_store_dword v160, v82, s[12:13]
	global_store_dword v160, v83, s[12:13] offset:256
	s_add_u32 s12, s12, s18
	s_addc_u32 s13, s13, 0
	v_mul_f32_e32 v84, v46, v84
	v_mul_f32_e32 v180, 0x3f3504f3, v84
	v_fma_f32 v182, |v180|, s16, v177
	v_fma_f32 v182, |v180|, v182, s19
	v_fma_f32 v182, |v180|, v182, s50
	v_fma_f32 v182, |v180|, v182, s51
	v_fma_f32 v182, |v180|, v182, s64
	v_fma_f32 v182, |v180|, v182, s65
	v_fma_f32 v182, |v180|, v182, |v180|
	v_mul_f32_e32 v184, 0xbfb8aa3b, v182
	v_fma_f32 v185, v182, s98, -v184
	v_rndne_f32_e32 v186, v184
	v_fmac_f32_e32 v185, 0xb2a5705f, v182
	v_sub_f32_e32 v184, v184, v186
	v_add_f32_e32 v184, v184, v185
	v_cvt_i32_f32_e32 v185, v186
	v_exp_f32_e32 v184, v184
	v_cmp_nlt_f32_e32 vcc, s70, v182
	v_ldexp_f32 v184, v184, v185
	s_nop 0
	v_cndmask_b32_e32 v184, 0, v184, vcc
	v_cmp_ngt_f32_e32 vcc, s71, v182
	s_nop 1
	v_cndmask_b32_e32 v184, v178, v184, vcc
	v_sub_f32_e32 v184, 1.0, v184
	v_mul_f32_e32 v183, v180, v180
	v_fmamk_f32 v185, v183, 0xba1345e1, v176
	v_fmaak_f32 v185, v183, v185, 0xbcdac9b8
	v_fmaak_f32 v185, v183, v185, 0x3de703be
	v_fmaak_f32 v185, v183, v185, 0xbec09330
	v_fmaak_f32 v183, v183, v185, 0x3e0375d0
	v_fma_f32 v183, |v180|, v183, |v180|
	v_cmp_nlt_f32_e64 vcc, |v180|, 1.0
	s_nop 1
	v_cndmask_b32_e32 v184, v183, v184, vcc
	v_bfi_b32 v184, s14, v184, v180
	v_add_f32_e32 v184, 1.0, v184
	v_mul_f32_e32 v84, 0.5, v84
	v_mul_f32_e32 v44, v44, v48
	v_mul_f32_e32 v84, v84, v184
	v_mul_f32_e32 v84, v44, v84
	v_mul_f32_e32 v85, v47, v85
	v_mul_f32_e32 v180, 0x3f3504f3, v85
	v_fma_f32 v182, |v180|, s16, v177
	v_fma_f32 v182, |v180|, v182, s19
	v_fma_f32 v182, |v180|, v182, s50
	v_fma_f32 v182, |v180|, v182, s51
	v_fma_f32 v182, |v180|, v182, s64
	v_fma_f32 v182, |v180|, v182, s65
	v_fma_f32 v182, |v180|, v182, |v180|
	v_mul_f32_e32 v184, 0xbfb8aa3b, v182
	v_fma_f32 v185, v182, s98, -v184
	v_rndne_f32_e32 v186, v184
	v_fmac_f32_e32 v185, 0xb2a5705f, v182
	v_sub_f32_e32 v184, v184, v186
	v_add_f32_e32 v184, v184, v185
	v_cvt_i32_f32_e32 v185, v186
	v_exp_f32_e32 v184, v184
	v_cmp_nlt_f32_e32 vcc, s70, v182
	v_ldexp_f32 v184, v184, v185
	s_nop 0
	v_cndmask_b32_e32 v184, 0, v184, vcc
	v_cmp_ngt_f32_e32 vcc, s71, v182
	s_nop 1
	v_cndmask_b32_e32 v184, v178, v184, vcc
	v_sub_f32_e32 v184, 1.0, v184
	v_mul_f32_e32 v183, v180, v180
	v_fmamk_f32 v185, v183, 0xba1345e1, v176
	v_fmaak_f32 v185, v183, v185, 0xbcdac9b8
	v_fmaak_f32 v185, v183, v185, 0x3de703be
	v_fmaak_f32 v185, v183, v185, 0xbec09330
	v_fmaak_f32 v183, v183, v185, 0x3e0375d0
	v_fma_f32 v183, |v180|, v183, |v180|
	v_cmp_nlt_f32_e64 vcc, |v180|, 1.0
	s_nop 1
	v_cndmask_b32_e32 v184, v183, v184, vcc
	v_bfi_b32 v184, s14, v184, v180
	v_add_f32_e32 v184, 1.0, v184
	v_mul_f32_e32 v85, 0.5, v85
	v_mul_f32_e32 v45, v45, v49
	v_mul_f32_e32 v85, v85, v184
	v_mul_f32_e32 v85, v45, v85
	global_store_dword v160, v84, s[12:13]
	global_store_dword v160, v85, s[12:13] offset:256
	s_add_u32 s12, s12, s18
	s_addc_u32 s13, s13, 0
	v_mul_f32_e32 v86, v52, v86
	v_mul_f32_e32 v180, 0x3f3504f3, v86
	v_fma_f32 v182, |v180|, s16, v177
	v_fma_f32 v182, |v180|, v182, s19
	v_fma_f32 v182, |v180|, v182, s50
	v_fma_f32 v182, |v180|, v182, s51
	v_fma_f32 v182, |v180|, v182, s64
	v_fma_f32 v182, |v180|, v182, s65
	v_fma_f32 v182, |v180|, v182, |v180|
	v_mul_f32_e32 v184, 0xbfb8aa3b, v182
	v_fma_f32 v185, v182, s98, -v184
	v_rndne_f32_e32 v186, v184
	v_fmac_f32_e32 v185, 0xb2a5705f, v182
	v_sub_f32_e32 v184, v184, v186
	v_add_f32_e32 v184, v184, v185
	v_cvt_i32_f32_e32 v185, v186
	v_exp_f32_e32 v184, v184
	v_cmp_nlt_f32_e32 vcc, s70, v182
	v_ldexp_f32 v184, v184, v185
	s_nop 0
	v_cndmask_b32_e32 v184, 0, v184, vcc
	v_cmp_ngt_f32_e32 vcc, s71, v182
	s_nop 1
	v_cndmask_b32_e32 v184, v178, v184, vcc
	v_sub_f32_e32 v184, 1.0, v184
	v_mul_f32_e32 v183, v180, v180
	v_fmamk_f32 v185, v183, 0xba1345e1, v176
	v_fmaak_f32 v185, v183, v185, 0xbcdac9b8
	v_fmaak_f32 v185, v183, v185, 0x3de703be
	v_fmaak_f32 v185, v183, v185, 0xbec09330
	v_fmaak_f32 v183, v183, v185, 0x3e0375d0
	v_fma_f32 v183, |v180|, v183, |v180|
	v_cmp_nlt_f32_e64 vcc, |v180|, 1.0
	s_nop 1
	v_cndmask_b32_e32 v184, v183, v184, vcc
	v_bfi_b32 v184, s14, v184, v180
	v_add_f32_e32 v184, 1.0, v184
	v_mul_f32_e32 v86, 0.5, v86
	v_mul_f32_e32 v50, v50, v54
	v_mul_f32_e32 v86, v86, v184
	v_mul_f32_e32 v86, v50, v86
	v_mul_f32_e32 v87, v53, v87
	v_mul_f32_e32 v180, 0x3f3504f3, v87
	v_fma_f32 v182, |v180|, s16, v177
	v_fma_f32 v182, |v180|, v182, s19
	v_fma_f32 v182, |v180|, v182, s50
	v_fma_f32 v182, |v180|, v182, s51
	v_fma_f32 v182, |v180|, v182, s64
	v_fma_f32 v182, |v180|, v182, s65
	v_fma_f32 v182, |v180|, v182, |v180|
	v_mul_f32_e32 v184, 0xbfb8aa3b, v182
	v_fma_f32 v185, v182, s98, -v184
	v_rndne_f32_e32 v186, v184
	v_fmac_f32_e32 v185, 0xb2a5705f, v182
	v_sub_f32_e32 v184, v184, v186
	v_add_f32_e32 v184, v184, v185
	v_cvt_i32_f32_e32 v185, v186
	v_exp_f32_e32 v184, v184
	v_cmp_nlt_f32_e32 vcc, s70, v182
	v_ldexp_f32 v184, v184, v185
	s_nop 0
	v_cndmask_b32_e32 v184, 0, v184, vcc
	v_cmp_ngt_f32_e32 vcc, s71, v182
	s_nop 1
	v_cndmask_b32_e32 v184, v178, v184, vcc
	v_sub_f32_e32 v184, 1.0, v184
	v_mul_f32_e32 v183, v180, v180
	v_fmamk_f32 v185, v183, 0xba1345e1, v176
	v_fmaak_f32 v185, v183, v185, 0xbcdac9b8
	v_fmaak_f32 v185, v183, v185, 0x3de703be
	v_fmaak_f32 v185, v183, v185, 0xbec09330
	v_fmaak_f32 v183, v183, v185, 0x3e0375d0
	v_fma_f32 v183, |v180|, v183, |v180|
	v_cmp_nlt_f32_e64 vcc, |v180|, 1.0
	s_nop 1
	v_cndmask_b32_e32 v184, v183, v184, vcc
	v_bfi_b32 v184, s14, v184, v180
	v_add_f32_e32 v184, 1.0, v184
	v_mul_f32_e32 v87, 0.5, v87
	v_mul_f32_e32 v51, v51, v55
	v_mul_f32_e32 v87, v87, v184
	v_mul_f32_e32 v87, v51, v87
	global_store_dword v160, v86, s[12:13]
	global_store_dword v160, v87, s[12:13] offset:256
	s_add_u32 s12, s12, s18
	s_addc_u32 s13, s13, 0
	v_mul_f32_e32 v88, v58, v88
	v_mul_f32_e32 v180, 0x3f3504f3, v88
	v_fma_f32 v182, |v180|, s16, v177
	v_fma_f32 v182, |v180|, v182, s19
	v_fma_f32 v182, |v180|, v182, s50
	v_fma_f32 v182, |v180|, v182, s51
	v_fma_f32 v182, |v180|, v182, s64
	v_fma_f32 v182, |v180|, v182, s65
	v_fma_f32 v182, |v180|, v182, |v180|
	v_mul_f32_e32 v184, 0xbfb8aa3b, v182
	v_fma_f32 v185, v182, s98, -v184
	v_rndne_f32_e32 v186, v184
	v_fmac_f32_e32 v185, 0xb2a5705f, v182
	v_sub_f32_e32 v184, v184, v186
	v_add_f32_e32 v184, v184, v185
	v_cvt_i32_f32_e32 v185, v186
	v_exp_f32_e32 v184, v184
	v_cmp_nlt_f32_e32 vcc, s70, v182
	v_ldexp_f32 v184, v184, v185
	s_nop 0
	v_cndmask_b32_e32 v184, 0, v184, vcc
	v_cmp_ngt_f32_e32 vcc, s71, v182
	s_nop 1
	v_cndmask_b32_e32 v184, v178, v184, vcc
	v_sub_f32_e32 v184, 1.0, v184
	v_mul_f32_e32 v183, v180, v180
	v_fmamk_f32 v185, v183, 0xba1345e1, v176
	v_fmaak_f32 v185, v183, v185, 0xbcdac9b8
	v_fmaak_f32 v185, v183, v185, 0x3de703be
	v_fmaak_f32 v185, v183, v185, 0xbec09330
	v_fmaak_f32 v183, v183, v185, 0x3e0375d0
	v_fma_f32 v183, |v180|, v183, |v180|
	v_cmp_nlt_f32_e64 vcc, |v180|, 1.0
	s_nop 1
	v_cndmask_b32_e32 v184, v183, v184, vcc
	v_bfi_b32 v184, s14, v184, v180
	v_add_f32_e32 v184, 1.0, v184
	v_mul_f32_e32 v88, 0.5, v88
	v_mul_f32_e32 v56, v56, v60
	v_mul_f32_e32 v88, v88, v184
	v_mul_f32_e32 v88, v56, v88
	v_mul_f32_e32 v89, v59, v89
	v_mul_f32_e32 v180, 0x3f3504f3, v89
	v_fma_f32 v182, |v180|, s16, v177
	v_fma_f32 v182, |v180|, v182, s19
	v_fma_f32 v182, |v180|, v182, s50
	v_fma_f32 v182, |v180|, v182, s51
	v_fma_f32 v182, |v180|, v182, s64
	v_fma_f32 v182, |v180|, v182, s65
	v_fma_f32 v182, |v180|, v182, |v180|
	v_mul_f32_e32 v184, 0xbfb8aa3b, v182
	v_fma_f32 v185, v182, s98, -v184
	v_rndne_f32_e32 v186, v184
	v_fmac_f32_e32 v185, 0xb2a5705f, v182
	v_sub_f32_e32 v184, v184, v186
	v_add_f32_e32 v184, v184, v185
	v_cvt_i32_f32_e32 v185, v186
	v_exp_f32_e32 v184, v184
	v_cmp_nlt_f32_e32 vcc, s70, v182
	v_ldexp_f32 v184, v184, v185
	s_nop 0
	v_cndmask_b32_e32 v184, 0, v184, vcc
	v_cmp_ngt_f32_e32 vcc, s71, v182
	s_nop 1
	v_cndmask_b32_e32 v184, v178, v184, vcc
	v_sub_f32_e32 v184, 1.0, v184
	v_mul_f32_e32 v183, v180, v180
	v_fmamk_f32 v185, v183, 0xba1345e1, v176
	v_fmaak_f32 v185, v183, v185, 0xbcdac9b8
	v_fmaak_f32 v185, v183, v185, 0x3de703be
	v_fmaak_f32 v185, v183, v185, 0xbec09330
	v_fmaak_f32 v183, v183, v185, 0x3e0375d0
	v_fma_f32 v183, |v180|, v183, |v180|
	v_cmp_nlt_f32_e64 vcc, |v180|, 1.0
	s_nop 1
	v_cndmask_b32_e32 v184, v183, v184, vcc
	v_bfi_b32 v184, s14, v184, v180
	v_add_f32_e32 v184, 1.0, v184
	v_mul_f32_e32 v89, 0.5, v89
	v_mul_f32_e32 v57, v57, v61
	v_mul_f32_e32 v89, v89, v184
	v_mul_f32_e32 v89, v57, v89
	global_store_dword v160, v88, s[12:13]
	global_store_dword v160, v89, s[12:13] offset:256
	s_add_u32 s12, s12, s18
	s_addc_u32 s13, s13, 0
	v_mul_f32_e32 v90, v64, v90
	v_mul_f32_e32 v180, 0x3f3504f3, v90
	v_fma_f32 v182, |v180|, s16, v177
	v_fma_f32 v182, |v180|, v182, s19
	v_fma_f32 v182, |v180|, v182, s50
	v_fma_f32 v182, |v180|, v182, s51
	v_fma_f32 v182, |v180|, v182, s64
	v_fma_f32 v182, |v180|, v182, s65
	v_fma_f32 v182, |v180|, v182, |v180|
	v_mul_f32_e32 v184, 0xbfb8aa3b, v182
	v_fma_f32 v185, v182, s98, -v184
	v_rndne_f32_e32 v186, v184
	v_fmac_f32_e32 v185, 0xb2a5705f, v182
	v_sub_f32_e32 v184, v184, v186
	v_add_f32_e32 v184, v184, v185
	v_cvt_i32_f32_e32 v185, v186
	v_exp_f32_e32 v184, v184
	v_cmp_nlt_f32_e32 vcc, s70, v182
	v_ldexp_f32 v184, v184, v185
	s_nop 0
	v_cndmask_b32_e32 v184, 0, v184, vcc
	v_cmp_ngt_f32_e32 vcc, s71, v182
	s_nop 1
	v_cndmask_b32_e32 v184, v178, v184, vcc
	v_sub_f32_e32 v184, 1.0, v184
	v_mul_f32_e32 v183, v180, v180
	v_fmamk_f32 v185, v183, 0xba1345e1, v176
	v_fmaak_f32 v185, v183, v185, 0xbcdac9b8
	v_fmaak_f32 v185, v183, v185, 0x3de703be
	v_fmaak_f32 v185, v183, v185, 0xbec09330
	v_fmaak_f32 v183, v183, v185, 0x3e0375d0
	v_fma_f32 v183, |v180|, v183, |v180|
	v_cmp_nlt_f32_e64 vcc, |v180|, 1.0
	s_nop 1
	v_cndmask_b32_e32 v184, v183, v184, vcc
	v_bfi_b32 v184, s14, v184, v180
	v_add_f32_e32 v184, 1.0, v184
	v_mul_f32_e32 v90, 0.5, v90
	v_mul_f32_e32 v62, v62, v66
	v_mul_f32_e32 v90, v90, v184
	v_mul_f32_e32 v90, v62, v90
	v_mul_f32_e32 v91, v65, v91
	v_mul_f32_e32 v180, 0x3f3504f3, v91
	v_fma_f32 v182, |v180|, s16, v177
	v_fma_f32 v182, |v180|, v182, s19
	v_fma_f32 v182, |v180|, v182, s50
	v_fma_f32 v182, |v180|, v182, s51
	v_fma_f32 v182, |v180|, v182, s64
	v_fma_f32 v182, |v180|, v182, s65
	v_fma_f32 v182, |v180|, v182, |v180|
	v_mul_f32_e32 v184, 0xbfb8aa3b, v182
	v_fma_f32 v185, v182, s98, -v184
	v_rndne_f32_e32 v186, v184
	v_fmac_f32_e32 v185, 0xb2a5705f, v182
	v_sub_f32_e32 v184, v184, v186
	v_add_f32_e32 v184, v184, v185
	v_cvt_i32_f32_e32 v185, v186
	v_exp_f32_e32 v184, v184
	v_cmp_nlt_f32_e32 vcc, s70, v182
	v_ldexp_f32 v184, v184, v185
	s_nop 0
	v_cndmask_b32_e32 v184, 0, v184, vcc
	v_cmp_ngt_f32_e32 vcc, s71, v182
	s_nop 1
	v_cndmask_b32_e32 v184, v178, v184, vcc
	v_sub_f32_e32 v184, 1.0, v184
	v_mul_f32_e32 v183, v180, v180
	v_fmamk_f32 v185, v183, 0xba1345e1, v176
	v_fmaak_f32 v185, v183, v185, 0xbcdac9b8
	v_fmaak_f32 v185, v183, v185, 0x3de703be
	v_fmaak_f32 v185, v183, v185, 0xbec09330
	v_fmaak_f32 v183, v183, v185, 0x3e0375d0
	v_fma_f32 v183, |v180|, v183, |v180|
	v_cmp_nlt_f32_e64 vcc, |v180|, 1.0
	s_nop 1
	v_cndmask_b32_e32 v184, v183, v184, vcc
	v_bfi_b32 v184, s14, v184, v180
	v_add_f32_e32 v184, 1.0, v184
	v_mul_f32_e32 v91, 0.5, v91
	v_mul_f32_e32 v63, v63, v67
	v_mul_f32_e32 v91, v91, v184
	v_mul_f32_e32 v91, v63, v91
	global_store_dword v160, v90, s[12:13]
	global_store_dword v160, v91, s[12:13] offset:256
	s_add_u32 s12, s12, s18
	s_addc_u32 s13, s13, 0
	v_mul_f32_e32 v92, v70, v92
	v_mul_f32_e32 v180, 0x3f3504f3, v92
	v_fma_f32 v182, |v180|, s16, v177
	v_fma_f32 v182, |v180|, v182, s19
	v_fma_f32 v182, |v180|, v182, s50
	v_fma_f32 v182, |v180|, v182, s51
	v_fma_f32 v182, |v180|, v182, s64
	v_fma_f32 v182, |v180|, v182, s65
	v_fma_f32 v182, |v180|, v182, |v180|
	v_mul_f32_e32 v184, 0xbfb8aa3b, v182
	v_fma_f32 v185, v182, s98, -v184
	v_rndne_f32_e32 v186, v184
	v_fmac_f32_e32 v185, 0xb2a5705f, v182
	v_sub_f32_e32 v184, v184, v186
	v_add_f32_e32 v184, v184, v185
	v_cvt_i32_f32_e32 v185, v186
	v_exp_f32_e32 v184, v184
	v_cmp_nlt_f32_e32 vcc, s70, v182
	v_ldexp_f32 v184, v184, v185
	s_nop 0
	v_cndmask_b32_e32 v184, 0, v184, vcc
	v_cmp_ngt_f32_e32 vcc, s71, v182
	s_nop 1
	v_cndmask_b32_e32 v184, v178, v184, vcc
	v_sub_f32_e32 v184, 1.0, v184
	v_mul_f32_e32 v183, v180, v180
	v_fmamk_f32 v185, v183, 0xba1345e1, v176
	v_fmaak_f32 v185, v183, v185, 0xbcdac9b8
	v_fmaak_f32 v185, v183, v185, 0x3de703be
	v_fmaak_f32 v185, v183, v185, 0xbec09330
	v_fmaak_f32 v183, v183, v185, 0x3e0375d0
	v_fma_f32 v183, |v180|, v183, |v180|
	v_cmp_nlt_f32_e64 vcc, |v180|, 1.0
	s_nop 1
	v_cndmask_b32_e32 v184, v183, v184, vcc
	v_bfi_b32 v184, s14, v184, v180
	v_add_f32_e32 v184, 1.0, v184
	v_mul_f32_e32 v92, 0.5, v92
	v_mul_f32_e32 v68, v68, v72
	v_mul_f32_e32 v92, v92, v184
	v_mul_f32_e32 v92, v68, v92
	v_mul_f32_e32 v93, v71, v93
	v_mul_f32_e32 v180, 0x3f3504f3, v93
	v_fma_f32 v182, |v180|, s16, v177
	v_fma_f32 v182, |v180|, v182, s19
	v_fma_f32 v182, |v180|, v182, s50
	v_fma_f32 v182, |v180|, v182, s51
	v_fma_f32 v182, |v180|, v182, s64
	v_fma_f32 v182, |v180|, v182, s65
	v_fma_f32 v182, |v180|, v182, |v180|
	v_mul_f32_e32 v184, 0xbfb8aa3b, v182
	v_fma_f32 v185, v182, s98, -v184
	v_rndne_f32_e32 v186, v184
	v_fmac_f32_e32 v185, 0xb2a5705f, v182
	v_sub_f32_e32 v184, v184, v186
	v_add_f32_e32 v184, v184, v185
	v_cvt_i32_f32_e32 v185, v186
	v_exp_f32_e32 v184, v184
	v_cmp_nlt_f32_e32 vcc, s70, v182
	v_ldexp_f32 v184, v184, v185
	s_nop 0
	v_cndmask_b32_e32 v184, 0, v184, vcc
	v_cmp_ngt_f32_e32 vcc, s71, v182
	s_nop 1
	v_cndmask_b32_e32 v184, v178, v184, vcc
	v_sub_f32_e32 v184, 1.0, v184
	v_mul_f32_e32 v183, v180, v180
	v_fmamk_f32 v185, v183, 0xba1345e1, v176
	v_fmaak_f32 v185, v183, v185, 0xbcdac9b8
	v_fmaak_f32 v185, v183, v185, 0x3de703be
	v_fmaak_f32 v185, v183, v185, 0xbec09330
	v_fmaak_f32 v183, v183, v185, 0x3e0375d0
	v_fma_f32 v183, |v180|, v183, |v180|
	v_cmp_nlt_f32_e64 vcc, |v180|, 1.0
	s_nop 1
	v_cndmask_b32_e32 v184, v183, v184, vcc
	v_bfi_b32 v184, s14, v184, v180
	v_add_f32_e32 v184, 1.0, v184
	v_mul_f32_e32 v93, 0.5, v93
	v_mul_f32_e32 v69, v69, v73
	v_mul_f32_e32 v93, v93, v184
	v_mul_f32_e32 v93, v69, v93
	global_store_dword v160, v92, s[12:13]
	global_store_dword v160, v93, s[12:13] offset:256
	s_add_u32 s12, s12, s18
	s_addc_u32 s13, s13, 0
	v_mul_f32_e32 v94, v76, v94
	v_mul_f32_e32 v180, 0x3f3504f3, v94
	v_fma_f32 v182, |v180|, s16, v177
	v_fma_f32 v182, |v180|, v182, s19
	v_fma_f32 v182, |v180|, v182, s50
	v_fma_f32 v182, |v180|, v182, s51
	v_fma_f32 v182, |v180|, v182, s64
	v_fma_f32 v182, |v180|, v182, s65
	v_fma_f32 v182, |v180|, v182, |v180|
	v_mul_f32_e32 v184, 0xbfb8aa3b, v182
	v_fma_f32 v185, v182, s98, -v184
	v_rndne_f32_e32 v186, v184
	v_fmac_f32_e32 v185, 0xb2a5705f, v182
	v_sub_f32_e32 v184, v184, v186
	v_add_f32_e32 v184, v184, v185
	v_cvt_i32_f32_e32 v185, v186
	v_exp_f32_e32 v184, v184
	v_cmp_nlt_f32_e32 vcc, s70, v182
	v_ldexp_f32 v184, v184, v185
	s_nop 0
	v_cndmask_b32_e32 v184, 0, v184, vcc
	v_cmp_ngt_f32_e32 vcc, s71, v182
	s_nop 1
	v_cndmask_b32_e32 v184, v178, v184, vcc
	v_sub_f32_e32 v184, 1.0, v184
	v_mul_f32_e32 v183, v180, v180
	v_fmamk_f32 v185, v183, 0xba1345e1, v176
	v_fmaak_f32 v185, v183, v185, 0xbcdac9b8
	v_fmaak_f32 v185, v183, v185, 0x3de703be
	v_fmaak_f32 v185, v183, v185, 0xbec09330
	v_fmaak_f32 v183, v183, v185, 0x3e0375d0
	v_fma_f32 v183, |v180|, v183, |v180|
	v_cmp_nlt_f32_e64 vcc, |v180|, 1.0
	s_nop 1
	v_cndmask_b32_e32 v184, v183, v184, vcc
	v_bfi_b32 v184, s14, v184, v180
	v_add_f32_e32 v184, 1.0, v184
	v_mul_f32_e32 v94, 0.5, v94
	v_mul_f32_e32 v74, v74, v78
	v_mul_f32_e32 v94, v94, v184
	v_mul_f32_e32 v94, v74, v94
	v_mul_f32_e32 v95, v77, v95
	v_mul_f32_e32 v180, 0x3f3504f3, v95
	v_fma_f32 v182, |v180|, s16, v177
	v_fma_f32 v182, |v180|, v182, s19
	v_fma_f32 v182, |v180|, v182, s50
	v_fma_f32 v182, |v180|, v182, s51
	v_fma_f32 v182, |v180|, v182, s64
	v_fma_f32 v182, |v180|, v182, s65
	v_fma_f32 v182, |v180|, v182, |v180|
	v_mul_f32_e32 v184, 0xbfb8aa3b, v182
	v_fma_f32 v185, v182, s98, -v184
	v_rndne_f32_e32 v186, v184
	v_fmac_f32_e32 v185, 0xb2a5705f, v182
	v_sub_f32_e32 v184, v184, v186
	v_add_f32_e32 v184, v184, v185
	v_cvt_i32_f32_e32 v185, v186
	v_exp_f32_e32 v184, v184
	v_cmp_nlt_f32_e32 vcc, s70, v182
	v_ldexp_f32 v184, v184, v185
	s_nop 0
	v_cndmask_b32_e32 v184, 0, v184, vcc
	v_cmp_ngt_f32_e32 vcc, s71, v182
	s_nop 1
	v_cndmask_b32_e32 v184, v178, v184, vcc
	v_sub_f32_e32 v184, 1.0, v184
	v_mul_f32_e32 v183, v180, v180
	v_fmamk_f32 v185, v183, 0xba1345e1, v176
	v_fmaak_f32 v185, v183, v185, 0xbcdac9b8
	v_fmaak_f32 v185, v183, v185, 0x3de703be
	v_fmaak_f32 v185, v183, v185, 0xbec09330
	v_fmaak_f32 v183, v183, v185, 0x3e0375d0
	v_fma_f32 v183, |v180|, v183, |v180|
	v_cmp_nlt_f32_e64 vcc, |v180|, 1.0
	s_nop 1
	v_cndmask_b32_e32 v184, v183, v184, vcc
	v_bfi_b32 v184, s14, v184, v180
	v_add_f32_e32 v184, 1.0, v184
	v_mul_f32_e32 v95, 0.5, v95
	v_mul_f32_e32 v75, v75, v79
	v_mul_f32_e32 v95, v95, v184
	v_mul_f32_e32 v95, v75, v95
	global_store_dword v160, v94, s[12:13]
	global_store_dword v160, v95, s[12:13] offset:256
	s_add_u32 s12, s12, s18
	s_addc_u32 s13, s13, 0
	ds_read2st64_b32 v[16:17], v174 offset0:16 offset1:17
	ds_read2st64_b32 v[80:81], v175 offset0:16 offset1:17
	ds_read2st64_b32 v[18:19], v174 offset0:18 offset1:19
	ds_read2st64_b32 v[82:83], v175 offset0:18 offset1:19
	ds_read2st64_b32 v[20:21], v174 offset0:20 offset1:21
	ds_read2st64_b32 v[84:85], v175 offset0:20 offset1:21
	ds_read2st64_b32 v[22:23], v174 offset0:22 offset1:23
	ds_read2st64_b32 v[86:87], v175 offset0:22 offset1:23
	ds_read2st64_b32 v[24:25], v174 offset0:24 offset1:25
	ds_read2st64_b32 v[88:89], v175 offset0:24 offset1:25
	ds_read2st64_b32 v[26:27], v174 offset0:26 offset1:27
	ds_read2st64_b32 v[90:91], v175 offset0:26 offset1:27
	ds_read2st64_b32 v[28:29], v174 offset0:28 offset1:29
	ds_read2st64_b32 v[92:93], v175 offset0:28 offset1:29
	ds_read2st64_b32 v[30:31], v174 offset0:30 offset1:31
	ds_read2st64_b32 v[94:95], v175 offset0:30 offset1:31
	s_waitcnt lgkmcnt(0)
	v_lshlrev_b32_e32 v16, 2, v16
	v_lshlrev_b32_e32 v17, 2, v17
	v_lshlrev_b32_e32 v18, 2, v18
	v_lshlrev_b32_e32 v19, 2, v19
	v_lshlrev_b32_e32 v20, 2, v20
	v_lshlrev_b32_e32 v21, 2, v21
	v_lshlrev_b32_e32 v22, 2, v22
	v_lshlrev_b32_e32 v23, 2, v23
	v_lshlrev_b32_e32 v24, 2, v24
	v_lshlrev_b32_e32 v25, 2, v25
	v_lshlrev_b32_e32 v26, 2, v26
	v_lshlrev_b32_e32 v27, 2, v27
	v_lshlrev_b32_e32 v28, 2, v28
	v_lshlrev_b32_e32 v29, 2, v29
	v_lshlrev_b32_e32 v30, 2, v30
	v_lshlrev_b32_e32 v31, 2, v31
	global_load_dword v32, v160, s[10:11]
	global_load_dword v33, v160, s[10:11] offset:256
	global_load_dword v34, v16, s[4:5]
	global_load_dword v35, v17, s[4:5]
	global_load_dword v36, v16, s[8:9]
	global_load_dword v37, v17, s[8:9]
	s_add_u32 s10, s10, s18
	s_addc_u32 s11, s11, 0
	global_load_dword v38, v160, s[10:11]
	global_load_dword v39, v160, s[10:11] offset:256
	global_load_dword v40, v18, s[4:5]
	global_load_dword v41, v19, s[4:5]
	global_load_dword v42, v18, s[8:9]
	global_load_dword v43, v19, s[8:9]
	s_add_u32 s10, s10, s18
	s_addc_u32 s11, s11, 0
	global_load_dword v44, v160, s[10:11]
	global_load_dword v45, v160, s[10:11] offset:256
	global_load_dword v46, v20, s[4:5]
	global_load_dword v47, v21, s[4:5]
	global_load_dword v48, v20, s[8:9]
	global_load_dword v49, v21, s[8:9]
	s_add_u32 s10, s10, s18
	s_addc_u32 s11, s11, 0
	global_load_dword v50, v160, s[10:11]
	global_load_dword v51, v160, s[10:11] offset:256
	global_load_dword v52, v22, s[4:5]
	global_load_dword v53, v23, s[4:5]
	global_load_dword v54, v22, s[8:9]
	global_load_dword v55, v23, s[8:9]
	s_add_u32 s10, s10, s18
	s_addc_u32 s11, s11, 0
	global_load_dword v56, v160, s[10:11]
	global_load_dword v57, v160, s[10:11] offset:256
	global_load_dword v58, v24, s[4:5]
	global_load_dword v59, v25, s[4:5]
	global_load_dword v60, v24, s[8:9]
	global_load_dword v61, v25, s[8:9]
	s_add_u32 s10, s10, s18
	s_addc_u32 s11, s11, 0
	global_load_dword v62, v160, s[10:11]
	global_load_dword v63, v160, s[10:11] offset:256
	global_load_dword v64, v26, s[4:5]
	global_load_dword v65, v27, s[4:5]
	global_load_dword v66, v26, s[8:9]
	global_load_dword v67, v27, s[8:9]
	s_add_u32 s10, s10, s18
	s_addc_u32 s11, s11, 0
	global_load_dword v68, v160, s[10:11]
	global_load_dword v69, v160, s[10:11] offset:256
	global_load_dword v70, v28, s[4:5]
	global_load_dword v71, v29, s[4:5]
	global_load_dword v72, v28, s[8:9]
	global_load_dword v73, v29, s[8:9]
	s_add_u32 s10, s10, s18
	s_addc_u32 s11, s11, 0
	global_load_dword v74, v160, s[10:11]
	global_load_dword v75, v160, s[10:11] offset:256
	global_load_dword v76, v30, s[4:5]
	global_load_dword v77, v31, s[4:5]
	global_load_dword v78, v30, s[8:9]
	global_load_dword v79, v31, s[8:9]
	s_add_u32 s10, s10, s18
	s_addc_u32 s11, s11, 0
	s_waitcnt vmcnt(0)
	v_mul_f32_e32 v80, v34, v80
	v_mul_f32_e32 v180, 0x3f3504f3, v80
	v_fma_f32 v182, |v180|, s16, v177
	v_fma_f32 v182, |v180|, v182, s19
	v_fma_f32 v182, |v180|, v182, s50
	v_fma_f32 v182, |v180|, v182, s51
	v_fma_f32 v182, |v180|, v182, s64
	v_fma_f32 v182, |v180|, v182, s65
	v_fma_f32 v182, |v180|, v182, |v180|
	v_mul_f32_e32 v184, 0xbfb8aa3b, v182
	v_fma_f32 v185, v182, s98, -v184
	v_rndne_f32_e32 v186, v184
	v_fmac_f32_e32 v185, 0xb2a5705f, v182
	v_sub_f32_e32 v184, v184, v186
	v_add_f32_e32 v184, v184, v185
	v_cvt_i32_f32_e32 v185, v186
	v_exp_f32_e32 v184, v184
	v_cmp_nlt_f32_e32 vcc, s70, v182
	v_ldexp_f32 v184, v184, v185
	s_nop 0
	v_cndmask_b32_e32 v184, 0, v184, vcc
	v_cmp_ngt_f32_e32 vcc, s71, v182
	s_nop 1
	v_cndmask_b32_e32 v184, v178, v184, vcc
	v_sub_f32_e32 v184, 1.0, v184
	v_mul_f32_e32 v183, v180, v180
	v_fmamk_f32 v185, v183, 0xba1345e1, v176
	v_fmaak_f32 v185, v183, v185, 0xbcdac9b8
	v_fmaak_f32 v185, v183, v185, 0x3de703be
	v_fmaak_f32 v185, v183, v185, 0xbec09330
	v_fmaak_f32 v183, v183, v185, 0x3e0375d0
	v_fma_f32 v183, |v180|, v183, |v180|
	v_cmp_nlt_f32_e64 vcc, |v180|, 1.0
	s_nop 1
	v_cndmask_b32_e32 v184, v183, v184, vcc
	v_bfi_b32 v184, s14, v184, v180
	v_add_f32_e32 v184, 1.0, v184
	v_mul_f32_e32 v80, 0.5, v80
	v_mul_f32_e32 v32, v32, v36
	v_mul_f32_e32 v80, v80, v184
	v_mul_f32_e32 v80, v32, v80
	v_mul_f32_e32 v81, v35, v81
	v_mul_f32_e32 v180, 0x3f3504f3, v81
	v_fma_f32 v182, |v180|, s16, v177
	v_fma_f32 v182, |v180|, v182, s19
	v_fma_f32 v182, |v180|, v182, s50
	v_fma_f32 v182, |v180|, v182, s51
	v_fma_f32 v182, |v180|, v182, s64
	v_fma_f32 v182, |v180|, v182, s65
	v_fma_f32 v182, |v180|, v182, |v180|
	v_mul_f32_e32 v184, 0xbfb8aa3b, v182
	v_fma_f32 v185, v182, s98, -v184
	v_rndne_f32_e32 v186, v184
	v_fmac_f32_e32 v185, 0xb2a5705f, v182
	v_sub_f32_e32 v184, v184, v186
	v_add_f32_e32 v184, v184, v185
	v_cvt_i32_f32_e32 v185, v186
	v_exp_f32_e32 v184, v184
	v_cmp_nlt_f32_e32 vcc, s70, v182
	v_ldexp_f32 v184, v184, v185
	s_nop 0
	v_cndmask_b32_e32 v184, 0, v184, vcc
	v_cmp_ngt_f32_e32 vcc, s71, v182
	s_nop 1
	v_cndmask_b32_e32 v184, v178, v184, vcc
	v_sub_f32_e32 v184, 1.0, v184
	v_mul_f32_e32 v183, v180, v180
	v_fmamk_f32 v185, v183, 0xba1345e1, v176
	v_fmaak_f32 v185, v183, v185, 0xbcdac9b8
	v_fmaak_f32 v185, v183, v185, 0x3de703be
	v_fmaak_f32 v185, v183, v185, 0xbec09330
	v_fmaak_f32 v183, v183, v185, 0x3e0375d0
	v_fma_f32 v183, |v180|, v183, |v180|
	v_cmp_nlt_f32_e64 vcc, |v180|, 1.0
	s_nop 1
	v_cndmask_b32_e32 v184, v183, v184, vcc
	v_bfi_b32 v184, s14, v184, v180
	v_add_f32_e32 v184, 1.0, v184
	v_mul_f32_e32 v81, 0.5, v81
	v_mul_f32_e32 v33, v33, v37
	v_mul_f32_e32 v81, v81, v184
	v_mul_f32_e32 v81, v33, v81
	global_store_dword v160, v80, s[12:13]
	global_store_dword v160, v81, s[12:13] offset:256
	s_add_u32 s12, s12, s18
	s_addc_u32 s13, s13, 0
	v_mul_f32_e32 v82, v40, v82
	v_mul_f32_e32 v180, 0x3f3504f3, v82
	v_fma_f32 v182, |v180|, s16, v177
	v_fma_f32 v182, |v180|, v182, s19
	v_fma_f32 v182, |v180|, v182, s50
	v_fma_f32 v182, |v180|, v182, s51
	v_fma_f32 v182, |v180|, v182, s64
	v_fma_f32 v182, |v180|, v182, s65
	v_fma_f32 v182, |v180|, v182, |v180|
	v_mul_f32_e32 v184, 0xbfb8aa3b, v182
	v_fma_f32 v185, v182, s98, -v184
	v_rndne_f32_e32 v186, v184
	v_fmac_f32_e32 v185, 0xb2a5705f, v182
	v_sub_f32_e32 v184, v184, v186
	v_add_f32_e32 v184, v184, v185
	v_cvt_i32_f32_e32 v185, v186
	v_exp_f32_e32 v184, v184
	v_cmp_nlt_f32_e32 vcc, s70, v182
	v_ldexp_f32 v184, v184, v185
	s_nop 0
	v_cndmask_b32_e32 v184, 0, v184, vcc
	v_cmp_ngt_f32_e32 vcc, s71, v182
	s_nop 1
	v_cndmask_b32_e32 v184, v178, v184, vcc
	v_sub_f32_e32 v184, 1.0, v184
	v_mul_f32_e32 v183, v180, v180
	v_fmamk_f32 v185, v183, 0xba1345e1, v176
	v_fmaak_f32 v185, v183, v185, 0xbcdac9b8
	v_fmaak_f32 v185, v183, v185, 0x3de703be
	v_fmaak_f32 v185, v183, v185, 0xbec09330
	v_fmaak_f32 v183, v183, v185, 0x3e0375d0
	v_fma_f32 v183, |v180|, v183, |v180|
	v_cmp_nlt_f32_e64 vcc, |v180|, 1.0
	s_nop 1
	v_cndmask_b32_e32 v184, v183, v184, vcc
	v_bfi_b32 v184, s14, v184, v180
	v_add_f32_e32 v184, 1.0, v184
	v_mul_f32_e32 v82, 0.5, v82
	v_mul_f32_e32 v38, v38, v42
	v_mul_f32_e32 v82, v82, v184
	v_mul_f32_e32 v82, v38, v82
	v_mul_f32_e32 v83, v41, v83
	v_mul_f32_e32 v180, 0x3f3504f3, v83
	v_fma_f32 v182, |v180|, s16, v177
	v_fma_f32 v182, |v180|, v182, s19
	v_fma_f32 v182, |v180|, v182, s50
	v_fma_f32 v182, |v180|, v182, s51
	v_fma_f32 v182, |v180|, v182, s64
	v_fma_f32 v182, |v180|, v182, s65
	v_fma_f32 v182, |v180|, v182, |v180|
	v_mul_f32_e32 v184, 0xbfb8aa3b, v182
	v_fma_f32 v185, v182, s98, -v184
	v_rndne_f32_e32 v186, v184
	v_fmac_f32_e32 v185, 0xb2a5705f, v182
	v_sub_f32_e32 v184, v184, v186
	v_add_f32_e32 v184, v184, v185
	v_cvt_i32_f32_e32 v185, v186
	v_exp_f32_e32 v184, v184
	v_cmp_nlt_f32_e32 vcc, s70, v182
	v_ldexp_f32 v184, v184, v185
	s_nop 0
	v_cndmask_b32_e32 v184, 0, v184, vcc
	v_cmp_ngt_f32_e32 vcc, s71, v182
	s_nop 1
	v_cndmask_b32_e32 v184, v178, v184, vcc
	v_sub_f32_e32 v184, 1.0, v184
	v_mul_f32_e32 v183, v180, v180
	v_fmamk_f32 v185, v183, 0xba1345e1, v176
	v_fmaak_f32 v185, v183, v185, 0xbcdac9b8
	v_fmaak_f32 v185, v183, v185, 0x3de703be
	v_fmaak_f32 v185, v183, v185, 0xbec09330
	v_fmaak_f32 v183, v183, v185, 0x3e0375d0
	v_fma_f32 v183, |v180|, v183, |v180|
	v_cmp_nlt_f32_e64 vcc, |v180|, 1.0
	s_nop 1
	v_cndmask_b32_e32 v184, v183, v184, vcc
	v_bfi_b32 v184, s14, v184, v180
	v_add_f32_e32 v184, 1.0, v184
	v_mul_f32_e32 v83, 0.5, v83
	v_mul_f32_e32 v39, v39, v43
	v_mul_f32_e32 v83, v83, v184
	v_mul_f32_e32 v83, v39, v83
	global_store_dword v160, v82, s[12:13]
	global_store_dword v160, v83, s[12:13] offset:256
	s_add_u32 s12, s12, s18
	s_addc_u32 s13, s13, 0
	v_mul_f32_e32 v84, v46, v84
	v_mul_f32_e32 v180, 0x3f3504f3, v84
	v_fma_f32 v182, |v180|, s16, v177
	v_fma_f32 v182, |v180|, v182, s19
	v_fma_f32 v182, |v180|, v182, s50
	v_fma_f32 v182, |v180|, v182, s51
	v_fma_f32 v182, |v180|, v182, s64
	v_fma_f32 v182, |v180|, v182, s65
	v_fma_f32 v182, |v180|, v182, |v180|
	v_mul_f32_e32 v184, 0xbfb8aa3b, v182
	v_fma_f32 v185, v182, s98, -v184
	v_rndne_f32_e32 v186, v184
	v_fmac_f32_e32 v185, 0xb2a5705f, v182
	v_sub_f32_e32 v184, v184, v186
	v_add_f32_e32 v184, v184, v185
	v_cvt_i32_f32_e32 v185, v186
	v_exp_f32_e32 v184, v184
	v_cmp_nlt_f32_e32 vcc, s70, v182
	v_ldexp_f32 v184, v184, v185
	s_nop 0
	v_cndmask_b32_e32 v184, 0, v184, vcc
	v_cmp_ngt_f32_e32 vcc, s71, v182
	s_nop 1
	v_cndmask_b32_e32 v184, v178, v184, vcc
	v_sub_f32_e32 v184, 1.0, v184
	v_mul_f32_e32 v183, v180, v180
	v_fmamk_f32 v185, v183, 0xba1345e1, v176
	v_fmaak_f32 v185, v183, v185, 0xbcdac9b8
	v_fmaak_f32 v185, v183, v185, 0x3de703be
	v_fmaak_f32 v185, v183, v185, 0xbec09330
	v_fmaak_f32 v183, v183, v185, 0x3e0375d0
	v_fma_f32 v183, |v180|, v183, |v180|
	v_cmp_nlt_f32_e64 vcc, |v180|, 1.0
	s_nop 1
	v_cndmask_b32_e32 v184, v183, v184, vcc
	v_bfi_b32 v184, s14, v184, v180
	v_add_f32_e32 v184, 1.0, v184
	v_mul_f32_e32 v84, 0.5, v84
	v_mul_f32_e32 v44, v44, v48
	v_mul_f32_e32 v84, v84, v184
	v_mul_f32_e32 v84, v44, v84
	v_mul_f32_e32 v85, v47, v85
	v_mul_f32_e32 v180, 0x3f3504f3, v85
	v_fma_f32 v182, |v180|, s16, v177
	v_fma_f32 v182, |v180|, v182, s19
	v_fma_f32 v182, |v180|, v182, s50
	v_fma_f32 v182, |v180|, v182, s51
	v_fma_f32 v182, |v180|, v182, s64
	v_fma_f32 v182, |v180|, v182, s65
	v_fma_f32 v182, |v180|, v182, |v180|
	v_mul_f32_e32 v184, 0xbfb8aa3b, v182
	v_fma_f32 v185, v182, s98, -v184
	v_rndne_f32_e32 v186, v184
	v_fmac_f32_e32 v185, 0xb2a5705f, v182
	v_sub_f32_e32 v184, v184, v186
	v_add_f32_e32 v184, v184, v185
	v_cvt_i32_f32_e32 v185, v186
	v_exp_f32_e32 v184, v184
	v_cmp_nlt_f32_e32 vcc, s70, v182
	v_ldexp_f32 v184, v184, v185
	s_nop 0
	v_cndmask_b32_e32 v184, 0, v184, vcc
	v_cmp_ngt_f32_e32 vcc, s71, v182
	s_nop 1
	v_cndmask_b32_e32 v184, v178, v184, vcc
	v_sub_f32_e32 v184, 1.0, v184
	v_mul_f32_e32 v183, v180, v180
	v_fmamk_f32 v185, v183, 0xba1345e1, v176
	v_fmaak_f32 v185, v183, v185, 0xbcdac9b8
	v_fmaak_f32 v185, v183, v185, 0x3de703be
	v_fmaak_f32 v185, v183, v185, 0xbec09330
	v_fmaak_f32 v183, v183, v185, 0x3e0375d0
	v_fma_f32 v183, |v180|, v183, |v180|
	v_cmp_nlt_f32_e64 vcc, |v180|, 1.0
	s_nop 1
	v_cndmask_b32_e32 v184, v183, v184, vcc
	v_bfi_b32 v184, s14, v184, v180
	v_add_f32_e32 v184, 1.0, v184
	v_mul_f32_e32 v85, 0.5, v85
	v_mul_f32_e32 v45, v45, v49
	v_mul_f32_e32 v85, v85, v184
	v_mul_f32_e32 v85, v45, v85
	global_store_dword v160, v84, s[12:13]
	global_store_dword v160, v85, s[12:13] offset:256
	s_add_u32 s12, s12, s18
	s_addc_u32 s13, s13, 0
	v_mul_f32_e32 v86, v52, v86
	v_mul_f32_e32 v180, 0x3f3504f3, v86
	v_fma_f32 v182, |v180|, s16, v177
	v_fma_f32 v182, |v180|, v182, s19
	v_fma_f32 v182, |v180|, v182, s50
	v_fma_f32 v182, |v180|, v182, s51
	v_fma_f32 v182, |v180|, v182, s64
	v_fma_f32 v182, |v180|, v182, s65
	v_fma_f32 v182, |v180|, v182, |v180|
	v_mul_f32_e32 v184, 0xbfb8aa3b, v182
	v_fma_f32 v185, v182, s98, -v184
	v_rndne_f32_e32 v186, v184
	v_fmac_f32_e32 v185, 0xb2a5705f, v182
	v_sub_f32_e32 v184, v184, v186
	v_add_f32_e32 v184, v184, v185
	v_cvt_i32_f32_e32 v185, v186
	v_exp_f32_e32 v184, v184
	v_cmp_nlt_f32_e32 vcc, s70, v182
	v_ldexp_f32 v184, v184, v185
	s_nop 0
	v_cndmask_b32_e32 v184, 0, v184, vcc
	v_cmp_ngt_f32_e32 vcc, s71, v182
	s_nop 1
	v_cndmask_b32_e32 v184, v178, v184, vcc
	v_sub_f32_e32 v184, 1.0, v184
	v_mul_f32_e32 v183, v180, v180
	v_fmamk_f32 v185, v183, 0xba1345e1, v176
	v_fmaak_f32 v185, v183, v185, 0xbcdac9b8
	v_fmaak_f32 v185, v183, v185, 0x3de703be
	v_fmaak_f32 v185, v183, v185, 0xbec09330
	v_fmaak_f32 v183, v183, v185, 0x3e0375d0
	v_fma_f32 v183, |v180|, v183, |v180|
	v_cmp_nlt_f32_e64 vcc, |v180|, 1.0
	s_nop 1
	v_cndmask_b32_e32 v184, v183, v184, vcc
	v_bfi_b32 v184, s14, v184, v180
	v_add_f32_e32 v184, 1.0, v184
	v_mul_f32_e32 v86, 0.5, v86
	v_mul_f32_e32 v50, v50, v54
	v_mul_f32_e32 v86, v86, v184
	v_mul_f32_e32 v86, v50, v86
	v_mul_f32_e32 v87, v53, v87
	v_mul_f32_e32 v180, 0x3f3504f3, v87
	v_fma_f32 v182, |v180|, s16, v177
	v_fma_f32 v182, |v180|, v182, s19
	v_fma_f32 v182, |v180|, v182, s50
	v_fma_f32 v182, |v180|, v182, s51
	v_fma_f32 v182, |v180|, v182, s64
	v_fma_f32 v182, |v180|, v182, s65
	v_fma_f32 v182, |v180|, v182, |v180|
	v_mul_f32_e32 v184, 0xbfb8aa3b, v182
	v_fma_f32 v185, v182, s98, -v184
	v_rndne_f32_e32 v186, v184
	v_fmac_f32_e32 v185, 0xb2a5705f, v182
	v_sub_f32_e32 v184, v184, v186
	v_add_f32_e32 v184, v184, v185
	v_cvt_i32_f32_e32 v185, v186
	v_exp_f32_e32 v184, v184
	v_cmp_nlt_f32_e32 vcc, s70, v182
	v_ldexp_f32 v184, v184, v185
	s_nop 0
	v_cndmask_b32_e32 v184, 0, v184, vcc
	v_cmp_ngt_f32_e32 vcc, s71, v182
	s_nop 1
	v_cndmask_b32_e32 v184, v178, v184, vcc
	v_sub_f32_e32 v184, 1.0, v184
	v_mul_f32_e32 v183, v180, v180
	v_fmamk_f32 v185, v183, 0xba1345e1, v176
	v_fmaak_f32 v185, v183, v185, 0xbcdac9b8
	v_fmaak_f32 v185, v183, v185, 0x3de703be
	v_fmaak_f32 v185, v183, v185, 0xbec09330
	v_fmaak_f32 v183, v183, v185, 0x3e0375d0
	v_fma_f32 v183, |v180|, v183, |v180|
	v_cmp_nlt_f32_e64 vcc, |v180|, 1.0
	s_nop 1
	v_cndmask_b32_e32 v184, v183, v184, vcc
	v_bfi_b32 v184, s14, v184, v180
	v_add_f32_e32 v184, 1.0, v184
	v_mul_f32_e32 v87, 0.5, v87
	v_mul_f32_e32 v51, v51, v55
	v_mul_f32_e32 v87, v87, v184
	v_mul_f32_e32 v87, v51, v87
	global_store_dword v160, v86, s[12:13]
	global_store_dword v160, v87, s[12:13] offset:256
	s_add_u32 s12, s12, s18
	s_addc_u32 s13, s13, 0
	v_mul_f32_e32 v88, v58, v88
	v_mul_f32_e32 v180, 0x3f3504f3, v88
	v_fma_f32 v182, |v180|, s16, v177
	v_fma_f32 v182, |v180|, v182, s19
	v_fma_f32 v182, |v180|, v182, s50
	v_fma_f32 v182, |v180|, v182, s51
	v_fma_f32 v182, |v180|, v182, s64
	v_fma_f32 v182, |v180|, v182, s65
	v_fma_f32 v182, |v180|, v182, |v180|
	v_mul_f32_e32 v184, 0xbfb8aa3b, v182
	v_fma_f32 v185, v182, s98, -v184
	v_rndne_f32_e32 v186, v184
	v_fmac_f32_e32 v185, 0xb2a5705f, v182
	v_sub_f32_e32 v184, v184, v186
	v_add_f32_e32 v184, v184, v185
	v_cvt_i32_f32_e32 v185, v186
	v_exp_f32_e32 v184, v184
	v_cmp_nlt_f32_e32 vcc, s70, v182
	v_ldexp_f32 v184, v184, v185
	s_nop 0
	v_cndmask_b32_e32 v184, 0, v184, vcc
	v_cmp_ngt_f32_e32 vcc, s71, v182
	s_nop 1
	v_cndmask_b32_e32 v184, v178, v184, vcc
	v_sub_f32_e32 v184, 1.0, v184
	v_mul_f32_e32 v183, v180, v180
	v_fmamk_f32 v185, v183, 0xba1345e1, v176
	v_fmaak_f32 v185, v183, v185, 0xbcdac9b8
	v_fmaak_f32 v185, v183, v185, 0x3de703be
	v_fmaak_f32 v185, v183, v185, 0xbec09330
	v_fmaak_f32 v183, v183, v185, 0x3e0375d0
	v_fma_f32 v183, |v180|, v183, |v180|
	v_cmp_nlt_f32_e64 vcc, |v180|, 1.0
	s_nop 1
	v_cndmask_b32_e32 v184, v183, v184, vcc
	v_bfi_b32 v184, s14, v184, v180
	v_add_f32_e32 v184, 1.0, v184
	v_mul_f32_e32 v88, 0.5, v88
	v_mul_f32_e32 v56, v56, v60
	v_mul_f32_e32 v88, v88, v184
	v_mul_f32_e32 v88, v56, v88
	v_mul_f32_e32 v89, v59, v89
	v_mul_f32_e32 v180, 0x3f3504f3, v89
	v_fma_f32 v182, |v180|, s16, v177
	v_fma_f32 v182, |v180|, v182, s19
	v_fma_f32 v182, |v180|, v182, s50
	v_fma_f32 v182, |v180|, v182, s51
	v_fma_f32 v182, |v180|, v182, s64
	v_fma_f32 v182, |v180|, v182, s65
	v_fma_f32 v182, |v180|, v182, |v180|
	v_mul_f32_e32 v184, 0xbfb8aa3b, v182
	v_fma_f32 v185, v182, s98, -v184
	v_rndne_f32_e32 v186, v184
	v_fmac_f32_e32 v185, 0xb2a5705f, v182
	v_sub_f32_e32 v184, v184, v186
	v_add_f32_e32 v184, v184, v185
	v_cvt_i32_f32_e32 v185, v186
	v_exp_f32_e32 v184, v184
	v_cmp_nlt_f32_e32 vcc, s70, v182
	v_ldexp_f32 v184, v184, v185
	s_nop 0
	v_cndmask_b32_e32 v184, 0, v184, vcc
	v_cmp_ngt_f32_e32 vcc, s71, v182
	s_nop 1
	v_cndmask_b32_e32 v184, v178, v184, vcc
	v_sub_f32_e32 v184, 1.0, v184
	v_mul_f32_e32 v183, v180, v180
	v_fmamk_f32 v185, v183, 0xba1345e1, v176
	v_fmaak_f32 v185, v183, v185, 0xbcdac9b8
	v_fmaak_f32 v185, v183, v185, 0x3de703be
	v_fmaak_f32 v185, v183, v185, 0xbec09330
	v_fmaak_f32 v183, v183, v185, 0x3e0375d0
	v_fma_f32 v183, |v180|, v183, |v180|
	v_cmp_nlt_f32_e64 vcc, |v180|, 1.0
	s_nop 1
	v_cndmask_b32_e32 v184, v183, v184, vcc
	v_bfi_b32 v184, s14, v184, v180
	v_add_f32_e32 v184, 1.0, v184
	v_mul_f32_e32 v89, 0.5, v89
	v_mul_f32_e32 v57, v57, v61
	v_mul_f32_e32 v89, v89, v184
	v_mul_f32_e32 v89, v57, v89
	global_store_dword v160, v88, s[12:13]
	global_store_dword v160, v89, s[12:13] offset:256
	s_add_u32 s12, s12, s18
	s_addc_u32 s13, s13, 0
	v_mul_f32_e32 v90, v64, v90
	v_mul_f32_e32 v180, 0x3f3504f3, v90
	v_fma_f32 v182, |v180|, s16, v177
	v_fma_f32 v182, |v180|, v182, s19
	v_fma_f32 v182, |v180|, v182, s50
	v_fma_f32 v182, |v180|, v182, s51
	v_fma_f32 v182, |v180|, v182, s64
	v_fma_f32 v182, |v180|, v182, s65
	v_fma_f32 v182, |v180|, v182, |v180|
	v_mul_f32_e32 v184, 0xbfb8aa3b, v182
	v_fma_f32 v185, v182, s98, -v184
	v_rndne_f32_e32 v186, v184
	v_fmac_f32_e32 v185, 0xb2a5705f, v182
	v_sub_f32_e32 v184, v184, v186
	v_add_f32_e32 v184, v184, v185
	v_cvt_i32_f32_e32 v185, v186
	v_exp_f32_e32 v184, v184
	v_cmp_nlt_f32_e32 vcc, s70, v182
	v_ldexp_f32 v184, v184, v185
	s_nop 0
	v_cndmask_b32_e32 v184, 0, v184, vcc
	v_cmp_ngt_f32_e32 vcc, s71, v182
	s_nop 1
	v_cndmask_b32_e32 v184, v178, v184, vcc
	v_sub_f32_e32 v184, 1.0, v184
	v_mul_f32_e32 v183, v180, v180
	v_fmamk_f32 v185, v183, 0xba1345e1, v176
	v_fmaak_f32 v185, v183, v185, 0xbcdac9b8
	v_fmaak_f32 v185, v183, v185, 0x3de703be
	v_fmaak_f32 v185, v183, v185, 0xbec09330
	v_fmaak_f32 v183, v183, v185, 0x3e0375d0
	v_fma_f32 v183, |v180|, v183, |v180|
	v_cmp_nlt_f32_e64 vcc, |v180|, 1.0
	s_nop 1
	v_cndmask_b32_e32 v184, v183, v184, vcc
	v_bfi_b32 v184, s14, v184, v180
	v_add_f32_e32 v184, 1.0, v184
	v_mul_f32_e32 v90, 0.5, v90
	v_mul_f32_e32 v62, v62, v66
	v_mul_f32_e32 v90, v90, v184
	v_mul_f32_e32 v90, v62, v90
	v_mul_f32_e32 v91, v65, v91
	v_mul_f32_e32 v180, 0x3f3504f3, v91
	v_fma_f32 v182, |v180|, s16, v177
	v_fma_f32 v182, |v180|, v182, s19
	v_fma_f32 v182, |v180|, v182, s50
	v_fma_f32 v182, |v180|, v182, s51
	v_fma_f32 v182, |v180|, v182, s64
	v_fma_f32 v182, |v180|, v182, s65
	v_fma_f32 v182, |v180|, v182, |v180|
	v_mul_f32_e32 v184, 0xbfb8aa3b, v182
	v_fma_f32 v185, v182, s98, -v184
	v_rndne_f32_e32 v186, v184
	v_fmac_f32_e32 v185, 0xb2a5705f, v182
	v_sub_f32_e32 v184, v184, v186
	v_add_f32_e32 v184, v184, v185
	v_cvt_i32_f32_e32 v185, v186
	v_exp_f32_e32 v184, v184
	v_cmp_nlt_f32_e32 vcc, s70, v182
	v_ldexp_f32 v184, v184, v185
	s_nop 0
	v_cndmask_b32_e32 v184, 0, v184, vcc
	v_cmp_ngt_f32_e32 vcc, s71, v182
	s_nop 1
	v_cndmask_b32_e32 v184, v178, v184, vcc
	v_sub_f32_e32 v184, 1.0, v184
	v_mul_f32_e32 v183, v180, v180
	v_fmamk_f32 v185, v183, 0xba1345e1, v176
	v_fmaak_f32 v185, v183, v185, 0xbcdac9b8
	v_fmaak_f32 v185, v183, v185, 0x3de703be
	v_fmaak_f32 v185, v183, v185, 0xbec09330
	v_fmaak_f32 v183, v183, v185, 0x3e0375d0
	v_fma_f32 v183, |v180|, v183, |v180|
	v_cmp_nlt_f32_e64 vcc, |v180|, 1.0
	s_nop 1
	v_cndmask_b32_e32 v184, v183, v184, vcc
	v_bfi_b32 v184, s14, v184, v180
	v_add_f32_e32 v184, 1.0, v184
	v_mul_f32_e32 v91, 0.5, v91
	v_mul_f32_e32 v63, v63, v67
	v_mul_f32_e32 v91, v91, v184
	v_mul_f32_e32 v91, v63, v91
	global_store_dword v160, v90, s[12:13]
	global_store_dword v160, v91, s[12:13] offset:256
	s_add_u32 s12, s12, s18
	s_addc_u32 s13, s13, 0
	v_mul_f32_e32 v92, v70, v92
	v_mul_f32_e32 v180, 0x3f3504f3, v92
	v_fma_f32 v182, |v180|, s16, v177
	v_fma_f32 v182, |v180|, v182, s19
	v_fma_f32 v182, |v180|, v182, s50
	v_fma_f32 v182, |v180|, v182, s51
	v_fma_f32 v182, |v180|, v182, s64
	v_fma_f32 v182, |v180|, v182, s65
	v_fma_f32 v182, |v180|, v182, |v180|
	v_mul_f32_e32 v184, 0xbfb8aa3b, v182
	v_fma_f32 v185, v182, s98, -v184
	v_rndne_f32_e32 v186, v184
	v_fmac_f32_e32 v185, 0xb2a5705f, v182
	v_sub_f32_e32 v184, v184, v186
	v_add_f32_e32 v184, v184, v185
	v_cvt_i32_f32_e32 v185, v186
	v_exp_f32_e32 v184, v184
	v_cmp_nlt_f32_e32 vcc, s70, v182
	v_ldexp_f32 v184, v184, v185
	s_nop 0
	v_cndmask_b32_e32 v184, 0, v184, vcc
	v_cmp_ngt_f32_e32 vcc, s71, v182
	s_nop 1
	v_cndmask_b32_e32 v184, v178, v184, vcc
	v_sub_f32_e32 v184, 1.0, v184
	v_mul_f32_e32 v183, v180, v180
	v_fmamk_f32 v185, v183, 0xba1345e1, v176
	v_fmaak_f32 v185, v183, v185, 0xbcdac9b8
	v_fmaak_f32 v185, v183, v185, 0x3de703be
	v_fmaak_f32 v185, v183, v185, 0xbec09330
	v_fmaak_f32 v183, v183, v185, 0x3e0375d0
	v_fma_f32 v183, |v180|, v183, |v180|
	v_cmp_nlt_f32_e64 vcc, |v180|, 1.0
	s_nop 1
	v_cndmask_b32_e32 v184, v183, v184, vcc
	v_bfi_b32 v184, s14, v184, v180
	v_add_f32_e32 v184, 1.0, v184
	v_mul_f32_e32 v92, 0.5, v92
	v_mul_f32_e32 v68, v68, v72
	v_mul_f32_e32 v92, v92, v184
	v_mul_f32_e32 v92, v68, v92
	v_mul_f32_e32 v93, v71, v93
	v_mul_f32_e32 v180, 0x3f3504f3, v93
	v_fma_f32 v182, |v180|, s16, v177
	v_fma_f32 v182, |v180|, v182, s19
	v_fma_f32 v182, |v180|, v182, s50
	v_fma_f32 v182, |v180|, v182, s51
	v_fma_f32 v182, |v180|, v182, s64
	v_fma_f32 v182, |v180|, v182, s65
	v_fma_f32 v182, |v180|, v182, |v180|
	v_mul_f32_e32 v184, 0xbfb8aa3b, v182
	v_fma_f32 v185, v182, s98, -v184
	v_rndne_f32_e32 v186, v184
	v_fmac_f32_e32 v185, 0xb2a5705f, v182
	v_sub_f32_e32 v184, v184, v186
	v_add_f32_e32 v184, v184, v185
	v_cvt_i32_f32_e32 v185, v186
	v_exp_f32_e32 v184, v184
	v_cmp_nlt_f32_e32 vcc, s70, v182
	v_ldexp_f32 v184, v184, v185
	s_nop 0
	v_cndmask_b32_e32 v184, 0, v184, vcc
	v_cmp_ngt_f32_e32 vcc, s71, v182
	s_nop 1
	v_cndmask_b32_e32 v184, v178, v184, vcc
	v_sub_f32_e32 v184, 1.0, v184
	v_mul_f32_e32 v183, v180, v180
	v_fmamk_f32 v185, v183, 0xba1345e1, v176
	v_fmaak_f32 v185, v183, v185, 0xbcdac9b8
	v_fmaak_f32 v185, v183, v185, 0x3de703be
	v_fmaak_f32 v185, v183, v185, 0xbec09330
	v_fmaak_f32 v183, v183, v185, 0x3e0375d0
	v_fma_f32 v183, |v180|, v183, |v180|
	v_cmp_nlt_f32_e64 vcc, |v180|, 1.0
	s_nop 1
	v_cndmask_b32_e32 v184, v183, v184, vcc
	v_bfi_b32 v184, s14, v184, v180
	v_add_f32_e32 v184, 1.0, v184
	v_mul_f32_e32 v93, 0.5, v93
	v_mul_f32_e32 v69, v69, v73
	v_mul_f32_e32 v93, v93, v184
	v_mul_f32_e32 v93, v69, v93
	global_store_dword v160, v92, s[12:13]
	global_store_dword v160, v93, s[12:13] offset:256
	s_add_u32 s12, s12, s18
	s_addc_u32 s13, s13, 0
	v_mul_f32_e32 v94, v76, v94
	v_mul_f32_e32 v180, 0x3f3504f3, v94
	v_fma_f32 v182, |v180|, s16, v177
	v_fma_f32 v182, |v180|, v182, s19
	v_fma_f32 v182, |v180|, v182, s50
	v_fma_f32 v182, |v180|, v182, s51
	v_fma_f32 v182, |v180|, v182, s64
	v_fma_f32 v182, |v180|, v182, s65
	v_fma_f32 v182, |v180|, v182, |v180|
	v_mul_f32_e32 v184, 0xbfb8aa3b, v182
	v_fma_f32 v185, v182, s98, -v184
	v_rndne_f32_e32 v186, v184
	v_fmac_f32_e32 v185, 0xb2a5705f, v182
	v_sub_f32_e32 v184, v184, v186
	v_add_f32_e32 v184, v184, v185
	v_cvt_i32_f32_e32 v185, v186
	v_exp_f32_e32 v184, v184
	v_cmp_nlt_f32_e32 vcc, s70, v182
	v_ldexp_f32 v184, v184, v185
	s_nop 0
	v_cndmask_b32_e32 v184, 0, v184, vcc
	v_cmp_ngt_f32_e32 vcc, s71, v182
	s_nop 1
	v_cndmask_b32_e32 v184, v178, v184, vcc
	v_sub_f32_e32 v184, 1.0, v184
	v_mul_f32_e32 v183, v180, v180
	v_fmamk_f32 v185, v183, 0xba1345e1, v176
	v_fmaak_f32 v185, v183, v185, 0xbcdac9b8
	v_fmaak_f32 v185, v183, v185, 0x3de703be
	v_fmaak_f32 v185, v183, v185, 0xbec09330
	v_fmaak_f32 v183, v183, v185, 0x3e0375d0
	v_fma_f32 v183, |v180|, v183, |v180|
	v_cmp_nlt_f32_e64 vcc, |v180|, 1.0
	s_nop 1
	v_cndmask_b32_e32 v184, v183, v184, vcc
	v_bfi_b32 v184, s14, v184, v180
	v_add_f32_e32 v184, 1.0, v184
	v_mul_f32_e32 v94, 0.5, v94
	v_mul_f32_e32 v74, v74, v78
	v_mul_f32_e32 v94, v94, v184
	v_mul_f32_e32 v94, v74, v94
	v_mul_f32_e32 v95, v77, v95
	v_mul_f32_e32 v180, 0x3f3504f3, v95
	v_fma_f32 v182, |v180|, s16, v177
	v_fma_f32 v182, |v180|, v182, s19
	v_fma_f32 v182, |v180|, v182, s50
	v_fma_f32 v182, |v180|, v182, s51
	v_fma_f32 v182, |v180|, v182, s64
	v_fma_f32 v182, |v180|, v182, s65
	v_fma_f32 v182, |v180|, v182, |v180|
	v_mul_f32_e32 v184, 0xbfb8aa3b, v182
	v_fma_f32 v185, v182, s98, -v184
	v_rndne_f32_e32 v186, v184
	v_fmac_f32_e32 v185, 0xb2a5705f, v182
	v_sub_f32_e32 v184, v184, v186
	v_add_f32_e32 v184, v184, v185
	v_cvt_i32_f32_e32 v185, v186
	v_exp_f32_e32 v184, v184
	v_cmp_nlt_f32_e32 vcc, s70, v182
	v_ldexp_f32 v184, v184, v185
	s_nop 0
	v_cndmask_b32_e32 v184, 0, v184, vcc
	v_cmp_ngt_f32_e32 vcc, s71, v182
	s_nop 1
	v_cndmask_b32_e32 v184, v178, v184, vcc
	v_sub_f32_e32 v184, 1.0, v184
	v_mul_f32_e32 v183, v180, v180
	v_fmamk_f32 v185, v183, 0xba1345e1, v176
	v_fmaak_f32 v185, v183, v185, 0xbcdac9b8
	v_fmaak_f32 v185, v183, v185, 0x3de703be
	v_fmaak_f32 v185, v183, v185, 0xbec09330
	v_fmaak_f32 v183, v183, v185, 0x3e0375d0
	v_fma_f32 v183, |v180|, v183, |v180|
	v_cmp_nlt_f32_e64 vcc, |v180|, 1.0
	s_nop 1
	v_cndmask_b32_e32 v184, v183, v184, vcc
	v_bfi_b32 v184, s14, v184, v180
	v_add_f32_e32 v184, 1.0, v184
	v_mul_f32_e32 v95, 0.5, v95
	v_mul_f32_e32 v75, v75, v79
	v_mul_f32_e32 v95, v95, v184
	v_mul_f32_e32 v95, v75, v95
	global_store_dword v160, v94, s[12:13]
	global_store_dword v160, v95, s[12:13] offset:256
	s_add_u32 s12, s12, s18
	s_addc_u32 s13, s13, 0
	s_lshl_b32 s17, s92, 6
	s_add_u32 s69, s69, s17
	s_cmpk_lt_u32 s69, 0x8000
	s_cbranch_scc1 .Lgu0_chunk
	s_branch .LBB0_578

.Lgv0_start:
	s_mov_b64 exec, -1
	v_and_b32_e32 v210, 63, v205
	v_lshrrev_b32_e32 v209, 6, v205
	v_lshlrev_b32_e32 v196, 2, v210
	v_readfirstlane_b32 s18, v209
	v_and_b32_e32 v209, 7, v210
	v_mul_u32_u24_e32 v199, 24, v209
	v_lshlrev_b32_e32 v200, 7, v209
	s_nop 3
	s_lshl_b32 s15, s18, 14
	s_add_i32 s101, s93, s18
	v_lshrrev_b32_e32 v209, 3, v210
	v_lshl_add_u32 v200, v209, 4, v200
	v_lshl_add_u32 v197, v209, 2, s15
	v_add_u32_e32 v198, 0x2000, v197
	v_add_u32_e32 v206, s15, v196
	v_add_u32_e32 v208, 0x2000, v206
	v_lshlrev_b32_e32 v211, 4, v210
.Lgv0_chunk:
	s_movk_i32 s100, 0xc0
	s_lshl_b32 s16, s92, 14
	s_add_u32 s12, s26, 0xd800000
	s_addc_u32 s13, s27, 0
	s_lshl_b32 s15, s101, 9
	s_add_u32 s12, s12, s15
	s_addc_u32 s13, s13, 0
	s_lshl_b32 s18, s92, 11
	global_load_dword v64, v196, s[12:13]
	global_load_dword v65, v196, s[12:13] offset:256
	s_add_u32 s12, s12, s18
	s_addc_u32 s13, s13, 0
	global_load_dword v66, v196, s[12:13]
	global_load_dword v67, v196, s[12:13] offset:256
	s_add_u32 s12, s12, s18
	s_addc_u32 s13, s13, 0
	global_load_dword v68, v196, s[12:13]
	global_load_dword v69, v196, s[12:13] offset:256
	s_add_u32 s12, s12, s18
	s_addc_u32 s13, s13, 0
	global_load_dword v70, v196, s[12:13]
	global_load_dword v71, v196, s[12:13] offset:256
	s_add_u32 s12, s12, s18
	s_addc_u32 s13, s13, 0
	global_load_dword v72, v196, s[12:13]
	global_load_dword v73, v196, s[12:13] offset:256
	s_add_u32 s12, s12, s18
	s_addc_u32 s13, s13, 0
	global_load_dword v74, v196, s[12:13]
	global_load_dword v75, v196, s[12:13] offset:256
	s_add_u32 s12, s12, s18
	s_addc_u32 s13, s13, 0
	global_load_dword v76, v196, s[12:13]
	global_load_dword v77, v196, s[12:13] offset:256
	s_add_u32 s12, s12, s18
	s_addc_u32 s13, s13, 0
	global_load_dword v78, v196, s[12:13]
	global_load_dword v79, v196, s[12:13] offset:256
	s_add_u32 s12, s12, s18
	s_addc_u32 s13, s13, 0
	global_load_dword v80, v196, s[12:13]
	global_load_dword v81, v196, s[12:13] offset:256
	s_add_u32 s12, s12, s18
	s_addc_u32 s13, s13, 0
	global_load_dword v82, v196, s[12:13]
	global_load_dword v83, v196, s[12:13] offset:256
	s_add_u32 s12, s12, s18
	s_addc_u32 s13, s13, 0
	global_load_dword v84, v196, s[12:13]
	global_load_dword v85, v196, s[12:13] offset:256
	s_add_u32 s12, s12, s18
	s_addc_u32 s13, s13, 0
	global_load_dword v86, v196, s[12:13]
	global_load_dword v87, v196, s[12:13] offset:256
	s_add_u32 s12, s12, s18
	s_addc_u32 s13, s13, 0
	global_load_dword v88, v196, s[12:13]
	global_load_dword v89, v196, s[12:13] offset:256
	s_add_u32 s12, s12, s18
	s_addc_u32 s13, s13, 0
	global_load_dword v90, v196, s[12:13]
	global_load_dword v91, v196, s[12:13] offset:256
	s_add_u32 s12, s12, s18
	s_addc_u32 s13, s13, 0
	global_load_dword v92, v196, s[12:13]
	global_load_dword v93, v196, s[12:13] offset:256
	s_add_u32 s12, s12, s18
	s_addc_u32 s13, s13, 0
	global_load_dword v94, v196, s[12:13]
	global_load_dword v95, v196, s[12:13] offset:256
	s_add_u32 s12, s12, s18
	s_addc_u32 s13, s13, 0
	s_waitcnt vmcnt(0)
	ds_write2st64_b32 v206, v64, v65 offset0:0 offset1:1
	ds_write2st64_b32 v206, v66, v67 offset0:2 offset1:3
	ds_write2st64_b32 v206, v68, v69 offset0:4 offset1:5
	ds_write2st64_b32 v206, v70, v71 offset0:6 offset1:7
	ds_write2st64_b32 v206, v72, v73 offset0:8 offset1:9
	ds_write2st64_b32 v206, v74, v75 offset0:10 offset1:11
	ds_write2st64_b32 v206, v76, v77 offset0:12 offset1:13
	ds_write2st64_b32 v206, v78, v79 offset0:14 offset1:15
	ds_write2st64_b32 v206, v80, v81 offset0:16 offset1:17
	ds_write2st64_b32 v206, v82, v83 offset0:18 offset1:19
	ds_write2st64_b32 v206, v84, v85 offset0:20 offset1:21
	ds_write2st64_b32 v206, v86, v87 offset0:22 offset1:23
	ds_write2st64_b32 v206, v88, v89 offset0:24 offset1:25
	ds_write2st64_b32 v206, v90, v91 offset0:26 offset1:27
	ds_write2st64_b32 v206, v92, v93 offset0:28 offset1:29
	ds_write2st64_b32 v206, v94, v95 offset0:30 offset1:31
	s_add_u32 s12, s26, 0xf800000
	s_addc_u32 s13, s27, 0
	s_lshl_b32 s15, s101, 9
	s_add_u32 s12, s12, s15
	s_addc_u32 s13, s13, 0
	s_lshl_b32 s18, s92, 11
	global_load_dword v64, v196, s[12:13]
	global_load_dword v65, v196, s[12:13] offset:256
	s_add_u32 s12, s12, s18
	s_addc_u32 s13, s13, 0
	global_load_dword v66, v196, s[12:13]
	global_load_dword v67, v196, s[12:13] offset:256
	s_add_u32 s12, s12, s18
	s_addc_u32 s13, s13, 0
	global_load_dword v68, v196, s[12:13]
	global_load_dword v69, v196, s[12:13] offset:256
	s_add_u32 s12, s12, s18
	s_addc_u32 s13, s13, 0
	global_load_dword v70, v196, s[12:13]
	global_load_dword v71, v196, s[12:13] offset:256
	s_add_u32 s12, s12, s18
	s_addc_u32 s13, s13, 0
	global_load_dword v72, v196, s[12:13]
	global_load_dword v73, v196, s[12:13] offset:256
	s_add_u32 s12, s12, s18
	s_addc_u32 s13, s13, 0
	global_load_dword v74, v196, s[12:13]
	global_load_dword v75, v196, s[12:13] offset:256
	s_add_u32 s12, s12, s18
	s_addc_u32 s13, s13, 0
	global_load_dword v76, v196, s[12:13]
	global_load_dword v77, v196, s[12:13] offset:256
	s_add_u32 s12, s12, s18
	s_addc_u32 s13, s13, 0
	global_load_dword v78, v196, s[12:13]
	global_load_dword v79, v196, s[12:13] offset:256
	s_add_u32 s12, s12, s18
	s_addc_u32 s13, s13, 0
	global_load_dword v80, v196, s[12:13]
	global_load_dword v81, v196, s[12:13] offset:256
	s_add_u32 s12, s12, s18
	s_addc_u32 s13, s13, 0
	global_load_dword v82, v196, s[12:13]
	global_load_dword v83, v196, s[12:13] offset:256
	s_add_u32 s12, s12, s18
	s_addc_u32 s13, s13, 0
	global_load_dword v84, v196, s[12:13]
	global_load_dword v85, v196, s[12:13] offset:256
	s_add_u32 s12, s12, s18
	s_addc_u32 s13, s13, 0
	global_load_dword v86, v196, s[12:13]
	global_load_dword v87, v196, s[12:13] offset:256
	s_add_u32 s12, s12, s18
	s_addc_u32 s13, s13, 0
	global_load_dword v88, v196, s[12:13]
	global_load_dword v89, v196, s[12:13] offset:256
	s_add_u32 s12, s12, s18
	s_addc_u32 s13, s13, 0
	global_load_dword v90, v196, s[12:13]
	global_load_dword v91, v196, s[12:13] offset:256
	s_add_u32 s12, s12, s18
	s_addc_u32 s13, s13, 0
	global_load_dword v92, v196, s[12:13]
	global_load_dword v93, v196, s[12:13] offset:256
	s_add_u32 s12, s12, s18
	s_addc_u32 s13, s13, 0
	global_load_dword v94, v196, s[12:13]
	global_load_dword v95, v196, s[12:13] offset:256
	s_add_u32 s12, s12, s18
	s_addc_u32 s13, s13, 0
	s_waitcnt vmcnt(0)
	ds_write2st64_b32 v208, v64, v65 offset0:0 offset1:1
	ds_write2st64_b32 v208, v66, v67 offset0:2 offset1:3
	ds_write2st64_b32 v208, v68, v69 offset0:4 offset1:5
	ds_write2st64_b32 v208, v70, v71 offset0:6 offset1:7
	ds_write2st64_b32 v208, v72, v73 offset0:8 offset1:9
	ds_write2st64_b32 v208, v74, v75 offset0:10 offset1:11
	ds_write2st64_b32 v208, v76, v77 offset0:12 offset1:13
	ds_write2st64_b32 v208, v78, v79 offset0:14 offset1:15
	ds_write2st64_b32 v208, v80, v81 offset0:16 offset1:17
	ds_write2st64_b32 v208, v82, v83 offset0:18 offset1:19
	ds_write2st64_b32 v208, v84, v85 offset0:20 offset1:21
	ds_write2st64_b32 v208, v86, v87 offset0:22 offset1:23
	ds_write2st64_b32 v208, v88, v89 offset0:24 offset1:25
	ds_write2st64_b32 v208, v90, v91 offset0:26 offset1:27
	ds_write2st64_b32 v208, v92, v93 offset0:28 offset1:29
	ds_write2st64_b32 v208, v94, v95 offset0:30 offset1:31
	s_waitcnt lgkmcnt(0)
	s_mov_b32 s14, 0
	s_and_b32 s19, s14, 15
	s_lshr_b32 s98, s14, 4
	s_lshl_b32 s99, s19, 9
	s_mul_i32 s15, s19, s16
	s_lshl_b32 s18, s98, 10
	s_add_u32 s15, s15, s18
	s_lshl_b32 s18, s101, 12
	s_add_u32 s15, s15, s18
	s_add_u32 s8, s24, s15
	s_addc_u32 s9, s25, 0
	s_mul_i32 s15, s98, 0x300000
	s_add_u32 s4, s26, 0x3800000
	s_addc_u32 s5, s27, 0
	s_add_u32 s4, s4, s15
	s_addc_u32 s5, s5, 0
	v_add_u32_e32 v201, s99, v197
	v_add_u32_e32 v203, s99, v198
	ds_read2_b32 v[160:161], v201 offset0:0 offset1:8
	ds_read2_b32 v[162:163], v201 offset0:16 offset1:24
	ds_read2_b32 v[164:165], v201 offset0:32 offset1:40
	ds_read2_b32 v[166:167], v201 offset0:48 offset1:56
	s_waitcnt lgkmcnt(0)
	s_waitcnt lgkmcnt(4)
	v_mad_u32_u24 v160, v160, s100, v199
	v_mad_u32_u24 v161, v161, s100, v199
	v_mad_u32_u24 v162, v162, s100, v199
	v_mad_u32_u24 v163, v163, s100, v199
	v_mad_u32_u24 v164, v164, s100, v199
	v_mad_u32_u24 v165, v165, s100, v199
	v_mad_u32_u24 v166, v166, s100, v199
	v_mad_u32_u24 v167, v167, s100, v199
	global_load_dwordx4 v[64:67], v160, s[4:5]
	global_load_dwordx2 v[68:69], v160, s[4:5] offset:16
	global_load_dwordx4 v[70:73], v161, s[4:5]
	global_load_dwordx2 v[74:75], v161, s[4:5] offset:16
	global_load_dwordx4 v[76:79], v162, s[4:5]
	global_load_dwordx2 v[80:81], v162, s[4:5] offset:16
	global_load_dwordx4 v[82:85], v163, s[4:5]
	global_load_dwordx2 v[86:87], v163, s[4:5] offset:16
	global_load_dwordx4 v[88:91], v164, s[4:5]
	global_load_dwordx2 v[92:93], v164, s[4:5] offset:16
	global_load_dwordx4 v[94:97], v165, s[4:5]
	global_load_dwordx2 v[98:99], v165, s[4:5] offset:16
	global_load_dwordx4 v[100:103], v166, s[4:5]
	global_load_dwordx2 v[104:105], v166, s[4:5] offset:16
	global_load_dwordx4 v[106:109], v167, s[4:5]
	global_load_dwordx2 v[110:111], v167, s[4:5] offset:16
	global_load_dword v209, v200, s[8:9]
	ds_read2_b32 v[168:169], v201 offset0:64 offset1:72
	ds_read2_b32 v[170:171], v201 offset0:80 offset1:88
	ds_read2_b32 v[172:173], v201 offset0:96 offset1:104
	ds_read2_b32 v[174:175], v201 offset0:112 offset1:120
	ds_read2_b32 v[176:177], v203 offset0:0 offset1:8
	ds_read2_b32 v[178:179], v203 offset0:16 offset1:24
	ds_read2_b32 v[180:181], v203 offset0:32 offset1:40
	ds_read2_b32 v[182:183], v203 offset0:48 offset1:56
.Lgv0_loop:
	global_load_dwordx4 v[192:195], v200, s[8:9]
	s_waitcnt lgkmcnt(4)
	v_mad_u32_u24 v168, v168, s100, v199
	v_mad_u32_u24 v169, v169, s100, v199
	v_mad_u32_u24 v170, v170, s100, v199
	v_mad_u32_u24 v171, v171, s100, v199
	v_mad_u32_u24 v172, v172, s100, v199
	v_mad_u32_u24 v173, v173, s100, v199
	v_mad_u32_u24 v174, v174, s100, v199
	v_mad_u32_u24 v175, v175, s100, v199
	global_load_dwordx4 v[112:115], v168, s[4:5]
	global_load_dwordx2 v[116:117], v168, s[4:5] offset:16
	global_load_dwordx4 v[118:121], v169, s[4:5]
	global_load_dwordx2 v[122:123], v169, s[4:5] offset:16
	global_load_dwordx4 v[124:127], v170, s[4:5]
	global_load_dwordx2 v[128:129], v170, s[4:5] offset:16
	global_load_dwordx4 v[130:133], v171, s[4:5]
	global_load_dwordx2 v[134:135], v171, s[4:5] offset:16
	global_load_dwordx4 v[136:139], v172, s[4:5]
	global_load_dwordx2 v[140:141], v172, s[4:5] offset:16
	global_load_dwordx4 v[142:145], v173, s[4:5]
	global_load_dwordx2 v[146:147], v173, s[4:5] offset:16
	global_load_dwordx4 v[148:151], v174, s[4:5]
	global_load_dwordx2 v[152:153], v174, s[4:5] offset:16
	global_load_dwordx4 v[154:157], v175, s[4:5]
	global_load_dwordx2 v[158:159], v175, s[4:5] offset:16
	s_add_u32 s14, s14, 1
	s_and_b32 s19, s14, 15
	s_lshr_b32 s98, s14, 4
	s_lshl_b32 s99, s19, 9
	s_mul_i32 s15, s19, s16
	s_lshl_b32 s18, s98, 10
	s_add_u32 s15, s15, s18
	s_lshl_b32 s18, s101, 12
	s_add_u32 s15, s15, s18
	s_add_u32 s10, s24, s15
	s_addc_u32 s11, s25, 0
	s_mul_i32 s15, s98, 0x300000
	s_add_u32 s4, s26, 0x3800000
	s_addc_u32 s5, s27, 0
	s_add_u32 s4, s4, s15
	s_addc_u32 s5, s5, 0
	v_add_u32_e32 v202, s99, v197
	v_add_u32_e32 v204, s99, v198
	ds_read2_b32 v[160:161], v202 offset0:0 offset1:8
	ds_read2_b32 v[162:163], v202 offset0:16 offset1:24
	ds_read2_b32 v[164:165], v202 offset0:32 offset1:40
	ds_read2_b32 v[166:167], v202 offset0:48 offset1:56
	ds_read2_b32 v[184:185], v203 offset0:64 offset1:72
	ds_read2_b32 v[186:187], v203 offset0:80 offset1:88
	ds_read2_b32 v[188:189], v203 offset0:96 offset1:104
	ds_read2_b32 v[190:191], v203 offset0:112 offset1:120
	s_waitcnt lgkmcnt(8)
	s_waitcnt vmcnt(32)
	v_cvt_scalef32_pk32_f32_fp6 v[32:63], v[64:69], 1.0
	v_pk_mul_f32 v[0:1], v[176:177], v[32:33] op_sel_hi:[0,1]
	v_pk_mul_f32 v[2:3], v[176:177], v[34:35] op_sel_hi:[0,1]
	v_pk_mul_f32 v[4:5], v[176:177], v[36:37] op_sel_hi:[0,1]
	v_pk_mul_f32 v[6:7], v[176:177], v[38:39] op_sel_hi:[0,1]
	v_pk_mul_f32 v[8:9], v[176:177], v[40:41] op_sel_hi:[0,1]
	v_pk_mul_f32 v[10:11], v[176:177], v[42:43] op_sel_hi:[0,1]
	v_pk_mul_f32 v[12:13], v[176:177], v[44:45] op_sel_hi:[0,1]
	v_pk_mul_f32 v[14:15], v[176:177], v[46:47] op_sel_hi:[0,1]
	v_pk_mul_f32 v[16:17], v[176:177], v[48:49] op_sel_hi:[0,1]
	v_pk_mul_f32 v[18:19], v[176:177], v[50:51] op_sel_hi:[0,1]
	v_pk_mul_f32 v[20:21], v[176:177], v[52:53] op_sel_hi:[0,1]
	v_pk_mul_f32 v[22:23], v[176:177], v[54:55] op_sel_hi:[0,1]
	v_pk_mul_f32 v[24:25], v[176:177], v[56:57] op_sel_hi:[0,1]
	v_pk_mul_f32 v[26:27], v[176:177], v[58:59] op_sel_hi:[0,1]
	v_pk_mul_f32 v[28:29], v[176:177], v[60:61] op_sel_hi:[0,1]
	v_pk_mul_f32 v[30:31], v[176:177], v[62:63] op_sel_hi:[0,1]
	s_waitcnt vmcnt(30)
	v_cvt_scalef32_pk32_f32_fp6 v[32:63], v[70:75], 1.0
	v_pk_fma_f32 v[0:1], v[176:177], v[32:33], v[0:1] op_sel:[1,0,0] op_sel_hi:[1,1,1]
	v_pk_fma_f32 v[2:3], v[176:177], v[34:35], v[2:3] op_sel:[1,0,0] op_sel_hi:[1,1,1]
	v_pk_fma_f32 v[4:5], v[176:177], v[36:37], v[4:5] op_sel:[1,0,0] op_sel_hi:[1,1,1]
	v_pk_fma_f32 v[6:7], v[176:177], v[38:39], v[6:7] op_sel:[1,0,0] op_sel_hi:[1,1,1]
	v_pk_fma_f32 v[8:9], v[176:177], v[40:41], v[8:9] op_sel:[1,0,0] op_sel_hi:[1,1,1]
	v_pk_fma_f32 v[10:11], v[176:177], v[42:43], v[10:11] op_sel:[1,0,0] op_sel_hi:[1,1,1]
	v_pk_fma_f32 v[12:13], v[176:177], v[44:45], v[12:13] op_sel:[1,0,0] op_sel_hi:[1,1,1]
	v_pk_fma_f32 v[14:15], v[176:177], v[46:47], v[14:15] op_sel:[1,0,0] op_sel_hi:[1,1,1]
	v_pk_fma_f32 v[16:17], v[176:177], v[48:49], v[16:17] op_sel:[1,0,0] op_sel_hi:[1,1,1]
	v_pk_fma_f32 v[18:19], v[176:177], v[50:51], v[18:19] op_sel:[1,0,0] op_sel_hi:[1,1,1]
	v_pk_fma_f32 v[20:21], v[176:177], v[52:53], v[20:21] op_sel:[1,0,0] op_sel_hi:[1,1,1]
	v_pk_fma_f32 v[22:23], v[176:177], v[54:55], v[22:23] op_sel:[1,0,0] op_sel_hi:[1,1,1]
	v_pk_fma_f32 v[24:25], v[176:177], v[56:57], v[24:25] op_sel:[1,0,0] op_sel_hi:[1,1,1]
	v_pk_fma_f32 v[26:27], v[176:177], v[58:59], v[26:27] op_sel:[1,0,0] op_sel_hi:[1,1,1]
	v_pk_fma_f32 v[28:29], v[176:177], v[60:61], v[28:29] op_sel:[1,0,0] op_sel_hi:[1,1,1]
	v_pk_fma_f32 v[30:31], v[176:177], v[62:63], v[30:31] op_sel:[1,0,0] op_sel_hi:[1,1,1]
	s_waitcnt vmcnt(28)
	v_cvt_scalef32_pk32_f32_fp6 v[32:63], v[76:81], 1.0
	v_pk_fma_f32 v[0:1], v[178:179], v[32:33], v[0:1] op_sel_hi:[0,1,1]
	v_pk_fma_f32 v[2:3], v[178:179], v[34:35], v[2:3] op_sel_hi:[0,1,1]
	v_pk_fma_f32 v[4:5], v[178:179], v[36:37], v[4:5] op_sel_hi:[0,1,1]
	v_pk_fma_f32 v[6:7], v[178:179], v[38:39], v[6:7] op_sel_hi:[0,1,1]
	v_pk_fma_f32 v[8:9], v[178:179], v[40:41], v[8:9] op_sel_hi:[0,1,1]
	v_pk_fma_f32 v[10:11], v[178:179], v[42:43], v[10:11] op_sel_hi:[0,1,1]
	v_pk_fma_f32 v[12:13], v[178:179], v[44:45], v[12:13] op_sel_hi:[0,1,1]
	v_pk_fma_f32 v[14:15], v[178:179], v[46:47], v[14:15] op_sel_hi:[0,1,1]
	v_pk_fma_f32 v[16:17], v[178:179], v[48:49], v[16:17] op_sel_hi:[0,1,1]
	v_pk_fma_f32 v[18:19], v[178:179], v[50:51], v[18:19] op_sel_hi:[0,1,1]
	v_pk_fma_f32 v[20:21], v[178:179], v[52:53], v[20:21] op_sel_hi:[0,1,1]
	v_pk_fma_f32 v[22:23], v[178:179], v[54:55], v[22:23] op_sel_hi:[0,1,1]
	v_pk_fma_f32 v[24:25], v[178:179], v[56:57], v[24:25] op_sel_hi:[0,1,1]
	v_pk_fma_f32 v[26:27], v[178:179], v[58:59], v[26:27] op_sel_hi:[0,1,1]
	v_pk_fma_f32 v[28:29], v[178:179], v[60:61], v[28:29] op_sel_hi:[0,1,1]
	v_pk_fma_f32 v[30:31], v[178:179], v[62:63], v[30:31] op_sel_hi:[0,1,1]
	s_waitcnt vmcnt(26)
	v_cvt_scalef32_pk32_f32_fp6 v[32:63], v[82:87], 1.0
	v_pk_fma_f32 v[0:1], v[178:179], v[32:33], v[0:1] op_sel:[1,0,0] op_sel_hi:[1,1,1]
	v_pk_fma_f32 v[2:3], v[178:179], v[34:35], v[2:3] op_sel:[1,0,0] op_sel_hi:[1,1,1]
	v_pk_fma_f32 v[4:5], v[178:179], v[36:37], v[4:5] op_sel:[1,0,0] op_sel_hi:[1,1,1]
	v_pk_fma_f32 v[6:7], v[178:179], v[38:39], v[6:7] op_sel:[1,0,0] op_sel_hi:[1,1,1]
	v_pk_fma_f32 v[8:9], v[178:179], v[40:41], v[8:9] op_sel:[1,0,0] op_sel_hi:[1,1,1]
	v_pk_fma_f32 v[10:11], v[178:179], v[42:43], v[10:11] op_sel:[1,0,0] op_sel_hi:[1,1,1]
	v_pk_fma_f32 v[12:13], v[178:179], v[44:45], v[12:13] op_sel:[1,0,0] op_sel_hi:[1,1,1]
	v_pk_fma_f32 v[14:15], v[178:179], v[46:47], v[14:15] op_sel:[1,0,0] op_sel_hi:[1,1,1]
	v_pk_fma_f32 v[16:17], v[178:179], v[48:49], v[16:17] op_sel:[1,0,0] op_sel_hi:[1,1,1]
	v_pk_fma_f32 v[18:19], v[178:179], v[50:51], v[18:19] op_sel:[1,0,0] op_sel_hi:[1,1,1]
	v_pk_fma_f32 v[20:21], v[178:179], v[52:53], v[20:21] op_sel:[1,0,0] op_sel_hi:[1,1,1]
	v_pk_fma_f32 v[22:23], v[178:179], v[54:55], v[22:23] op_sel:[1,0,0] op_sel_hi:[1,1,1]
	v_pk_fma_f32 v[24:25], v[178:179], v[56:57], v[24:25] op_sel:[1,0,0] op_sel_hi:[1,1,1]
	v_pk_fma_f32 v[26:27], v[178:179], v[58:59], v[26:27] op_sel:[1,0,0] op_sel_hi:[1,1,1]
	v_pk_fma_f32 v[28:29], v[178:179], v[60:61], v[28:29] op_sel:[1,0,0] op_sel_hi:[1,1,1]
	v_pk_fma_f32 v[30:31], v[178:179], v[62:63], v[30:31] op_sel:[1,0,0] op_sel_hi:[1,1,1]
	s_waitcnt vmcnt(24)
	v_cvt_scalef32_pk32_f32_fp6 v[32:63], v[88:93], 1.0
	v_pk_fma_f32 v[0:1], v[180:181], v[32:33], v[0:1] op_sel_hi:[0,1,1]
	v_pk_fma_f32 v[2:3], v[180:181], v[34:35], v[2:3] op_sel_hi:[0,1,1]
	v_pk_fma_f32 v[4:5], v[180:181], v[36:37], v[4:5] op_sel_hi:[0,1,1]
	v_pk_fma_f32 v[6:7], v[180:181], v[38:39], v[6:7] op_sel_hi:[0,1,1]
	v_pk_fma_f32 v[8:9], v[180:181], v[40:41], v[8:9] op_sel_hi:[0,1,1]
	v_pk_fma_f32 v[10:11], v[180:181], v[42:43], v[10:11] op_sel_hi:[0,1,1]
	v_pk_fma_f32 v[12:13], v[180:181], v[44:45], v[12:13] op_sel_hi:[0,1,1]
	v_pk_fma_f32 v[14:15], v[180:181], v[46:47], v[14:15] op_sel_hi:[0,1,1]
	v_pk_fma_f32 v[16:17], v[180:181], v[48:49], v[16:17] op_sel_hi:[0,1,1]
	v_pk_fma_f32 v[18:19], v[180:181], v[50:51], v[18:19] op_sel_hi:[0,1,1]
	v_pk_fma_f32 v[20:21], v[180:181], v[52:53], v[20:21] op_sel_hi:[0,1,1]
	v_pk_fma_f32 v[22:23], v[180:181], v[54:55], v[22:23] op_sel_hi:[0,1,1]
	v_pk_fma_f32 v[24:25], v[180:181], v[56:57], v[24:25] op_sel_hi:[0,1,1]
	v_pk_fma_f32 v[26:27], v[180:181], v[58:59], v[26:27] op_sel_hi:[0,1,1]
	v_pk_fma_f32 v[28:29], v[180:181], v[60:61], v[28:29] op_sel_hi:[0,1,1]
	v_pk_fma_f32 v[30:31], v[180:181], v[62:63], v[30:31] op_sel_hi:[0,1,1]
	s_waitcnt vmcnt(22)
	v_cvt_scalef32_pk32_f32_fp6 v[32:63], v[94:99], 1.0
	v_pk_fma_f32 v[0:1], v[180:181], v[32:33], v[0:1] op_sel:[1,0,0] op_sel_hi:[1,1,1]
	v_pk_fma_f32 v[2:3], v[180:181], v[34:35], v[2:3] op_sel:[1,0,0] op_sel_hi:[1,1,1]
	v_pk_fma_f32 v[4:5], v[180:181], v[36:37], v[4:5] op_sel:[1,0,0] op_sel_hi:[1,1,1]
	v_pk_fma_f32 v[6:7], v[180:181], v[38:39], v[6:7] op_sel:[1,0,0] op_sel_hi:[1,1,1]
	v_pk_fma_f32 v[8:9], v[180:181], v[40:41], v[8:9] op_sel:[1,0,0] op_sel_hi:[1,1,1]
	v_pk_fma_f32 v[10:11], v[180:181], v[42:43], v[10:11] op_sel:[1,0,0] op_sel_hi:[1,1,1]
	v_pk_fma_f32 v[12:13], v[180:181], v[44:45], v[12:13] op_sel:[1,0,0] op_sel_hi:[1,1,1]
	v_pk_fma_f32 v[14:15], v[180:181], v[46:47], v[14:15] op_sel:[1,0,0] op_sel_hi:[1,1,1]
	v_pk_fma_f32 v[16:17], v[180:181], v[48:49], v[16:17] op_sel:[1,0,0] op_sel_hi:[1,1,1]
	v_pk_fma_f32 v[18:19], v[180:181], v[50:51], v[18:19] op_sel:[1,0,0] op_sel_hi:[1,1,1]
	v_pk_fma_f32 v[20:21], v[180:181], v[52:53], v[20:21] op_sel:[1,0,0] op_sel_hi:[1,1,1]
	v_pk_fma_f32 v[22:23], v[180:181], v[54:55], v[22:23] op_sel:[1,0,0] op_sel_hi:[1,1,1]
	v_pk_fma_f32 v[24:25], v[180:181], v[56:57], v[24:25] op_sel:[1,0,0] op_sel_hi:[1,1,1]
	v_pk_fma_f32 v[26:27], v[180:181], v[58:59], v[26:27] op_sel:[1,0,0] op_sel_hi:[1,1,1]
	v_pk_fma_f32 v[28:29], v[180:181], v[60:61], v[28:29] op_sel:[1,0,0] op_sel_hi:[1,1,1]
	v_pk_fma_f32 v[30:31], v[180:181], v[62:63], v[30:31] op_sel:[1,0,0] op_sel_hi:[1,1,1]
	s_waitcnt vmcnt(20)
	v_cvt_scalef32_pk32_f32_fp6 v[32:63], v[100:105], 1.0
	v_pk_fma_f32 v[0:1], v[182:183], v[32:33], v[0:1] op_sel_hi:[0,1,1]
	v_pk_fma_f32 v[2:3], v[182:183], v[34:35], v[2:3] op_sel_hi:[0,1,1]
	v_pk_fma_f32 v[4:5], v[182:183], v[36:37], v[4:5] op_sel_hi:[0,1,1]
	v_pk_fma_f32 v[6:7], v[182:183], v[38:39], v[6:7] op_sel_hi:[0,1,1]
	v_pk_fma_f32 v[8:9], v[182:183], v[40:41], v[8:9] op_sel_hi:[0,1,1]
	v_pk_fma_f32 v[10:11], v[182:183], v[42:43], v[10:11] op_sel_hi:[0,1,1]
	v_pk_fma_f32 v[12:13], v[182:183], v[44:45], v[12:13] op_sel_hi:[0,1,1]
	v_pk_fma_f32 v[14:15], v[182:183], v[46:47], v[14:15] op_sel_hi:[0,1,1]
	v_pk_fma_f32 v[16:17], v[182:183], v[48:49], v[16:17] op_sel_hi:[0,1,1]
	v_pk_fma_f32 v[18:19], v[182:183], v[50:51], v[18:19] op_sel_hi:[0,1,1]
	v_pk_fma_f32 v[20:21], v[182:183], v[52:53], v[20:21] op_sel_hi:[0,1,1]
	v_pk_fma_f32 v[22:23], v[182:183], v[54:55], v[22:23] op_sel_hi:[0,1,1]
	v_pk_fma_f32 v[24:25], v[182:183], v[56:57], v[24:25] op_sel_hi:[0,1,1]
	v_pk_fma_f32 v[26:27], v[182:183], v[58:59], v[26:27] op_sel_hi:[0,1,1]
	v_pk_fma_f32 v[28:29], v[182:183], v[60:61], v[28:29] op_sel_hi:[0,1,1]
	v_pk_fma_f32 v[30:31], v[182:183], v[62:63], v[30:31] op_sel_hi:[0,1,1]
	s_waitcnt vmcnt(18)
	v_cvt_scalef32_pk32_f32_fp6 v[32:63], v[106:111], 1.0
	v_pk_fma_f32 v[0:1], v[182:183], v[32:33], v[0:1] op_sel:[1,0,0] op_sel_hi:[1,1,1]
	v_pk_fma_f32 v[2:3], v[182:183], v[34:35], v[2:3] op_sel:[1,0,0] op_sel_hi:[1,1,1]
	v_pk_fma_f32 v[4:5], v[182:183], v[36:37], v[4:5] op_sel:[1,0,0] op_sel_hi:[1,1,1]
	v_pk_fma_f32 v[6:7], v[182:183], v[38:39], v[6:7] op_sel:[1,0,0] op_sel_hi:[1,1,1]
	v_pk_fma_f32 v[8:9], v[182:183], v[40:41], v[8:9] op_sel:[1,0,0] op_sel_hi:[1,1,1]
	v_pk_fma_f32 v[10:11], v[182:183], v[42:43], v[10:11] op_sel:[1,0,0] op_sel_hi:[1,1,1]
	v_pk_fma_f32 v[12:13], v[182:183], v[44:45], v[12:13] op_sel:[1,0,0] op_sel_hi:[1,1,1]
	v_pk_fma_f32 v[14:15], v[182:183], v[46:47], v[14:15] op_sel:[1,0,0] op_sel_hi:[1,1,1]
	v_pk_fma_f32 v[16:17], v[182:183], v[48:49], v[16:17] op_sel:[1,0,0] op_sel_hi:[1,1,1]
	v_pk_fma_f32 v[18:19], v[182:183], v[50:51], v[18:19] op_sel:[1,0,0] op_sel_hi:[1,1,1]
	v_pk_fma_f32 v[20:21], v[182:183], v[52:53], v[20:21] op_sel:[1,0,0] op_sel_hi:[1,1,1]
	v_pk_fma_f32 v[22:23], v[182:183], v[54:55], v[22:23] op_sel:[1,0,0] op_sel_hi:[1,1,1]
	v_pk_fma_f32 v[24:25], v[182:183], v[56:57], v[24:25] op_sel:[1,0,0] op_sel_hi:[1,1,1]
	v_pk_fma_f32 v[26:27], v[182:183], v[58:59], v[26:27] op_sel:[1,0,0] op_sel_hi:[1,1,1]
	v_pk_fma_f32 v[28:29], v[182:183], v[60:61], v[28:29] op_sel:[1,0,0] op_sel_hi:[1,1,1]
	v_pk_fma_f32 v[30:31], v[182:183], v[62:63], v[30:31] op_sel:[1,0,0] op_sel_hi:[1,1,1]
	s_waitcnt lgkmcnt(4)
	v_mad_u32_u24 v160, v160, s100, v199
	v_mad_u32_u24 v161, v161, s100, v199
	v_mad_u32_u24 v162, v162, s100, v199
	v_mad_u32_u24 v163, v163, s100, v199
	v_mad_u32_u24 v164, v164, s100, v199
	v_mad_u32_u24 v165, v165, s100, v199
	v_mad_u32_u24 v166, v166, s100, v199
	v_mad_u32_u24 v167, v167, s100, v199
	global_load_dwordx4 v[64:67], v160, s[4:5]
	global_load_dwordx2 v[68:69], v160, s[4:5] offset:16
	global_load_dwordx4 v[70:73], v161, s[4:5]
	global_load_dwordx2 v[74:75], v161, s[4:5] offset:16
	global_load_dwordx4 v[76:79], v162, s[4:5]
	global_load_dwordx2 v[80:81], v162, s[4:5] offset:16
	global_load_dwordx4 v[82:85], v163, s[4:5]
	global_load_dwordx2 v[86:87], v163, s[4:5] offset:16
	global_load_dwordx4 v[88:91], v164, s[4:5]
	global_load_dwordx2 v[92:93], v164, s[4:5] offset:16
	global_load_dwordx4 v[94:97], v165, s[4:5]
	global_load_dwordx2 v[98:99], v165, s[4:5] offset:16
	global_load_dwordx4 v[100:103], v166, s[4:5]
	global_load_dwordx2 v[104:105], v166, s[4:5] offset:16
	global_load_dwordx4 v[106:109], v167, s[4:5]
	global_load_dwordx2 v[110:111], v167, s[4:5] offset:16
	ds_read2_b32 v[168:169], v202 offset0:64 offset1:72
	ds_read2_b32 v[170:171], v202 offset0:80 offset1:88
	ds_read2_b32 v[172:173], v202 offset0:96 offset1:104
	ds_read2_b32 v[174:175], v202 offset0:112 offset1:120
	ds_read2_b32 v[176:177], v204 offset0:0 offset1:8
	ds_read2_b32 v[178:179], v204 offset0:16 offset1:24
	ds_read2_b32 v[180:181], v204 offset0:32 offset1:40
	ds_read2_b32 v[182:183], v204 offset0:48 offset1:56
	s_waitcnt lgkmcnt(8)
	s_waitcnt vmcnt(30)
	v_cvt_scalef32_pk32_f32_fp6 v[32:63], v[112:117], 1.0
	v_pk_fma_f32 v[0:1], v[184:185], v[32:33], v[0:1] op_sel_hi:[0,1,1]
	v_pk_fma_f32 v[2:3], v[184:185], v[34:35], v[2:3] op_sel_hi:[0,1,1]
	v_pk_fma_f32 v[4:5], v[184:185], v[36:37], v[4:5] op_sel_hi:[0,1,1]
	v_pk_fma_f32 v[6:7], v[184:185], v[38:39], v[6:7] op_sel_hi:[0,1,1]
	v_pk_fma_f32 v[8:9], v[184:185], v[40:41], v[8:9] op_sel_hi:[0,1,1]
	v_pk_fma_f32 v[10:11], v[184:185], v[42:43], v[10:11] op_sel_hi:[0,1,1]
	v_pk_fma_f32 v[12:13], v[184:185], v[44:45], v[12:13] op_sel_hi:[0,1,1]
	v_pk_fma_f32 v[14:15], v[184:185], v[46:47], v[14:15] op_sel_hi:[0,1,1]
	v_pk_fma_f32 v[16:17], v[184:185], v[48:49], v[16:17] op_sel_hi:[0,1,1]
	v_pk_fma_f32 v[18:19], v[184:185], v[50:51], v[18:19] op_sel_hi:[0,1,1]
	v_pk_fma_f32 v[20:21], v[184:185], v[52:53], v[20:21] op_sel_hi:[0,1,1]
	v_pk_fma_f32 v[22:23], v[184:185], v[54:55], v[22:23] op_sel_hi:[0,1,1]
	v_pk_fma_f32 v[24:25], v[184:185], v[56:57], v[24:25] op_sel_hi:[0,1,1]
	v_pk_fma_f32 v[26:27], v[184:185], v[58:59], v[26:27] op_sel_hi:[0,1,1]
	v_pk_fma_f32 v[28:29], v[184:185], v[60:61], v[28:29] op_sel_hi:[0,1,1]
	v_pk_fma_f32 v[30:31], v[184:185], v[62:63], v[30:31] op_sel_hi:[0,1,1]
	s_waitcnt vmcnt(28)
	v_cvt_scalef32_pk32_f32_fp6 v[32:63], v[118:123], 1.0
	v_pk_fma_f32 v[0:1], v[184:185], v[32:33], v[0:1] op_sel:[1,0,0] op_sel_hi:[1,1,1]
	v_pk_fma_f32 v[2:3], v[184:185], v[34:35], v[2:3] op_sel:[1,0,0] op_sel_hi:[1,1,1]
	v_pk_fma_f32 v[4:5], v[184:185], v[36:37], v[4:5] op_sel:[1,0,0] op_sel_hi:[1,1,1]
	v_pk_fma_f32 v[6:7], v[184:185], v[38:39], v[6:7] op_sel:[1,0,0] op_sel_hi:[1,1,1]
	v_pk_fma_f32 v[8:9], v[184:185], v[40:41], v[8:9] op_sel:[1,0,0] op_sel_hi:[1,1,1]
	v_pk_fma_f32 v[10:11], v[184:185], v[42:43], v[10:11] op_sel:[1,0,0] op_sel_hi:[1,1,1]
	v_pk_fma_f32 v[12:13], v[184:185], v[44:45], v[12:13] op_sel:[1,0,0] op_sel_hi:[1,1,1]
	v_pk_fma_f32 v[14:15], v[184:185], v[46:47], v[14:15] op_sel:[1,0,0] op_sel_hi:[1,1,1]
	v_pk_fma_f32 v[16:17], v[184:185], v[48:49], v[16:17] op_sel:[1,0,0] op_sel_hi:[1,1,1]
	v_pk_fma_f32 v[18:19], v[184:185], v[50:51], v[18:19] op_sel:[1,0,0] op_sel_hi:[1,1,1]
	v_pk_fma_f32 v[20:21], v[184:185], v[52:53], v[20:21] op_sel:[1,0,0] op_sel_hi:[1,1,1]
	v_pk_fma_f32 v[22:23], v[184:185], v[54:55], v[22:23] op_sel:[1,0,0] op_sel_hi:[1,1,1]
	v_pk_fma_f32 v[24:25], v[184:185], v[56:57], v[24:25] op_sel:[1,0,0] op_sel_hi:[1,1,1]
	v_pk_fma_f32 v[26:27], v[184:185], v[58:59], v[26:27] op_sel:[1,0,0] op_sel_hi:[1,1,1]
	v_pk_fma_f32 v[28:29], v[184:185], v[60:61], v[28:29] op_sel:[1,0,0] op_sel_hi:[1,1,1]
	v_pk_fma_f32 v[30:31], v[184:185], v[62:63], v[30:31] op_sel:[1,0,0] op_sel_hi:[1,1,1]
	s_waitcnt vmcnt(26)
	v_cvt_scalef32_pk32_f32_fp6 v[32:63], v[124:129], 1.0
	v_pk_fma_f32 v[0:1], v[186:187], v[32:33], v[0:1] op_sel_hi:[0,1,1]
	v_pk_fma_f32 v[2:3], v[186:187], v[34:35], v[2:3] op_sel_hi:[0,1,1]
	v_pk_fma_f32 v[4:5], v[186:187], v[36:37], v[4:5] op_sel_hi:[0,1,1]
	v_pk_fma_f32 v[6:7], v[186:187], v[38:39], v[6:7] op_sel_hi:[0,1,1]
	v_pk_fma_f32 v[8:9], v[186:187], v[40:41], v[8:9] op_sel_hi:[0,1,1]
	v_pk_fma_f32 v[10:11], v[186:187], v[42:43], v[10:11] op_sel_hi:[0,1,1]
	v_pk_fma_f32 v[12:13], v[186:187], v[44:45], v[12:13] op_sel_hi:[0,1,1]
	v_pk_fma_f32 v[14:15], v[186:187], v[46:47], v[14:15] op_sel_hi:[0,1,1]
	v_pk_fma_f32 v[16:17], v[186:187], v[48:49], v[16:17] op_sel_hi:[0,1,1]
	v_pk_fma_f32 v[18:19], v[186:187], v[50:51], v[18:19] op_sel_hi:[0,1,1]
	v_pk_fma_f32 v[20:21], v[186:187], v[52:53], v[20:21] op_sel_hi:[0,1,1]
	v_pk_fma_f32 v[22:23], v[186:187], v[54:55], v[22:23] op_sel_hi:[0,1,1]
	v_pk_fma_f32 v[24:25], v[186:187], v[56:57], v[24:25] op_sel_hi:[0,1,1]
	v_pk_fma_f32 v[26:27], v[186:187], v[58:59], v[26:27] op_sel_hi:[0,1,1]
	v_pk_fma_f32 v[28:29], v[186:187], v[60:61], v[28:29] op_sel_hi:[0,1,1]
	v_pk_fma_f32 v[30:31], v[186:187], v[62:63], v[30:31] op_sel_hi:[0,1,1]
	s_waitcnt vmcnt(24)
	v_cvt_scalef32_pk32_f32_fp6 v[32:63], v[130:135], 1.0
	v_pk_fma_f32 v[0:1], v[186:187], v[32:33], v[0:1] op_sel:[1,0,0] op_sel_hi:[1,1,1]
	v_pk_fma_f32 v[2:3], v[186:187], v[34:35], v[2:3] op_sel:[1,0,0] op_sel_hi:[1,1,1]
	v_pk_fma_f32 v[4:5], v[186:187], v[36:37], v[4:5] op_sel:[1,0,0] op_sel_hi:[1,1,1]
	v_pk_fma_f32 v[6:7], v[186:187], v[38:39], v[6:7] op_sel:[1,0,0] op_sel_hi:[1,1,1]
	v_pk_fma_f32 v[8:9], v[186:187], v[40:41], v[8:9] op_sel:[1,0,0] op_sel_hi:[1,1,1]
	v_pk_fma_f32 v[10:11], v[186:187], v[42:43], v[10:11] op_sel:[1,0,0] op_sel_hi:[1,1,1]
	v_pk_fma_f32 v[12:13], v[186:187], v[44:45], v[12:13] op_sel:[1,0,0] op_sel_hi:[1,1,1]
	v_pk_fma_f32 v[14:15], v[186:187], v[46:47], v[14:15] op_sel:[1,0,0] op_sel_hi:[1,1,1]
	v_pk_fma_f32 v[16:17], v[186:187], v[48:49], v[16:17] op_sel:[1,0,0] op_sel_hi:[1,1,1]
	v_pk_fma_f32 v[18:19], v[186:187], v[50:51], v[18:19] op_sel:[1,0,0] op_sel_hi:[1,1,1]
	v_pk_fma_f32 v[20:21], v[186:187], v[52:53], v[20:21] op_sel:[1,0,0] op_sel_hi:[1,1,1]
	v_pk_fma_f32 v[22:23], v[186:187], v[54:55], v[22:23] op_sel:[1,0,0] op_sel_hi:[1,1,1]
	v_pk_fma_f32 v[24:25], v[186:187], v[56:57], v[24:25] op_sel:[1,0,0] op_sel_hi:[1,1,1]
	v_pk_fma_f32 v[26:27], v[186:187], v[58:59], v[26:27] op_sel:[1,0,0] op_sel_hi:[1,1,1]
	v_pk_fma_f32 v[28:29], v[186:187], v[60:61], v[28:29] op_sel:[1,0,0] op_sel_hi:[1,1,1]
	v_pk_fma_f32 v[30:31], v[186:187], v[62:63], v[30:31] op_sel:[1,0,0] op_sel_hi:[1,1,1]
	s_waitcnt vmcnt(22)
	v_cvt_scalef32_pk32_f32_fp6 v[32:63], v[136:141], 1.0
	v_pk_fma_f32 v[0:1], v[188:189], v[32:33], v[0:1] op_sel_hi:[0,1,1]
	v_pk_fma_f32 v[2:3], v[188:189], v[34:35], v[2:3] op_sel_hi:[0,1,1]
	v_pk_fma_f32 v[4:5], v[188:189], v[36:37], v[4:5] op_sel_hi:[0,1,1]
	v_pk_fma_f32 v[6:7], v[188:189], v[38:39], v[6:7] op_sel_hi:[0,1,1]
	v_pk_fma_f32 v[8:9], v[188:189], v[40:41], v[8:9] op_sel_hi:[0,1,1]
	v_pk_fma_f32 v[10:11], v[188:189], v[42:43], v[10:11] op_sel_hi:[0,1,1]
	v_pk_fma_f32 v[12:13], v[188:189], v[44:45], v[12:13] op_sel_hi:[0,1,1]
	v_pk_fma_f32 v[14:15], v[188:189], v[46:47], v[14:15] op_sel_hi:[0,1,1]
	v_pk_fma_f32 v[16:17], v[188:189], v[48:49], v[16:17] op_sel_hi:[0,1,1]
	v_pk_fma_f32 v[18:19], v[188:189], v[50:51], v[18:19] op_sel_hi:[0,1,1]
	v_pk_fma_f32 v[20:21], v[188:189], v[52:53], v[20:21] op_sel_hi:[0,1,1]
	v_pk_fma_f32 v[22:23], v[188:189], v[54:55], v[22:23] op_sel_hi:[0,1,1]
	v_pk_fma_f32 v[24:25], v[188:189], v[56:57], v[24:25] op_sel_hi:[0,1,1]
	v_pk_fma_f32 v[26:27], v[188:189], v[58:59], v[26:27] op_sel_hi:[0,1,1]
	v_pk_fma_f32 v[28:29], v[188:189], v[60:61], v[28:29] op_sel_hi:[0,1,1]
	v_pk_fma_f32 v[30:31], v[188:189], v[62:63], v[30:31] op_sel_hi:[0,1,1]
	s_waitcnt vmcnt(20)
	v_cvt_scalef32_pk32_f32_fp6 v[32:63], v[142:147], 1.0
	v_pk_fma_f32 v[0:1], v[188:189], v[32:33], v[0:1] op_sel:[1,0,0] op_sel_hi:[1,1,1]
	v_pk_fma_f32 v[2:3], v[188:189], v[34:35], v[2:3] op_sel:[1,0,0] op_sel_hi:[1,1,1]
	v_pk_fma_f32 v[4:5], v[188:189], v[36:37], v[4:5] op_sel:[1,0,0] op_sel_hi:[1,1,1]
	v_pk_fma_f32 v[6:7], v[188:189], v[38:39], v[6:7] op_sel:[1,0,0] op_sel_hi:[1,1,1]
	v_pk_fma_f32 v[8:9], v[188:189], v[40:41], v[8:9] op_sel:[1,0,0] op_sel_hi:[1,1,1]
	v_pk_fma_f32 v[10:11], v[188:189], v[42:43], v[10:11] op_sel:[1,0,0] op_sel_hi:[1,1,1]
	v_pk_fma_f32 v[12:13], v[188:189], v[44:45], v[12:13] op_sel:[1,0,0] op_sel_hi:[1,1,1]
	v_pk_fma_f32 v[14:15], v[188:189], v[46:47], v[14:15] op_sel:[1,0,0] op_sel_hi:[1,1,1]
	v_pk_fma_f32 v[16:17], v[188:189], v[48:49], v[16:17] op_sel:[1,0,0] op_sel_hi:[1,1,1]
	v_pk_fma_f32 v[18:19], v[188:189], v[50:51], v[18:19] op_sel:[1,0,0] op_sel_hi:[1,1,1]
	v_pk_fma_f32 v[20:21], v[188:189], v[52:53], v[20:21] op_sel:[1,0,0] op_sel_hi:[1,1,1]
	v_pk_fma_f32 v[22:23], v[188:189], v[54:55], v[22:23] op_sel:[1,0,0] op_sel_hi:[1,1,1]
	v_pk_fma_f32 v[24:25], v[188:189], v[56:57], v[24:25] op_sel:[1,0,0] op_sel_hi:[1,1,1]
	v_pk_fma_f32 v[26:27], v[188:189], v[58:59], v[26:27] op_sel:[1,0,0] op_sel_hi:[1,1,1]
	v_pk_fma_f32 v[28:29], v[188:189], v[60:61], v[28:29] op_sel:[1,0,0] op_sel_hi:[1,1,1]
	v_pk_fma_f32 v[30:31], v[188:189], v[62:63], v[30:31] op_sel:[1,0,0] op_sel_hi:[1,1,1]
	s_waitcnt vmcnt(18)
	v_cvt_scalef32_pk32_f32_fp6 v[32:63], v[148:153], 1.0
	v_pk_fma_f32 v[0:1], v[190:191], v[32:33], v[0:1] op_sel_hi:[0,1,1]
	v_pk_fma_f32 v[2:3], v[190:191], v[34:35], v[2:3] op_sel_hi:[0,1,1]
	v_pk_fma_f32 v[4:5], v[190:191], v[36:37], v[4:5] op_sel_hi:[0,1,1]
	v_pk_fma_f32 v[6:7], v[190:191], v[38:39], v[6:7] op_sel_hi:[0,1,1]
	v_pk_fma_f32 v[8:9], v[190:191], v[40:41], v[8:9] op_sel_hi:[0,1,1]
	v_pk_fma_f32 v[10:11], v[190:191], v[42:43], v[10:11] op_sel_hi:[0,1,1]
	v_pk_fma_f32 v[12:13], v[190:191], v[44:45], v[12:13] op_sel_hi:[0,1,1]
	v_pk_fma_f32 v[14:15], v[190:191], v[46:47], v[14:15] op_sel_hi:[0,1,1]
	v_pk_fma_f32 v[16:17], v[190:191], v[48:49], v[16:17] op_sel_hi:[0,1,1]
	v_pk_fma_f32 v[18:19], v[190:191], v[50:51], v[18:19] op_sel_hi:[0,1,1]
	v_pk_fma_f32 v[20:21], v[190:191], v[52:53], v[20:21] op_sel_hi:[0,1,1]
	v_pk_fma_f32 v[22:23], v[190:191], v[54:55], v[22:23] op_sel_hi:[0,1,1]
	v_pk_fma_f32 v[24:25], v[190:191], v[56:57], v[24:25] op_sel_hi:[0,1,1]
	v_pk_fma_f32 v[26:27], v[190:191], v[58:59], v[26:27] op_sel_hi:[0,1,1]
	v_pk_fma_f32 v[28:29], v[190:191], v[60:61], v[28:29] op_sel_hi:[0,1,1]
	v_pk_fma_f32 v[30:31], v[190:191], v[62:63], v[30:31] op_sel_hi:[0,1,1]
	s_waitcnt vmcnt(16)
	v_cvt_scalef32_pk32_f32_fp6 v[32:63], v[154:159], 1.0
	v_pk_fma_f32 v[0:1], v[190:191], v[32:33], v[0:1] op_sel:[1,0,0] op_sel_hi:[1,1,1]
	v_pk_fma_f32 v[2:3], v[190:191], v[34:35], v[2:3] op_sel:[1,0,0] op_sel_hi:[1,1,1]
	v_pk_fma_f32 v[4:5], v[190:191], v[36:37], v[4:5] op_sel:[1,0,0] op_sel_hi:[1,1,1]
	v_pk_fma_f32 v[6:7], v[190:191], v[38:39], v[6:7] op_sel:[1,0,0] op_sel_hi:[1,1,1]
	v_pk_fma_f32 v[8:9], v[190:191], v[40:41], v[8:9] op_sel:[1,0,0] op_sel_hi:[1,1,1]
	v_pk_fma_f32 v[10:11], v[190:191], v[42:43], v[10:11] op_sel:[1,0,0] op_sel_hi:[1,1,1]
	v_pk_fma_f32 v[12:13], v[190:191], v[44:45], v[12:13] op_sel:[1,0,0] op_sel_hi:[1,1,1]
	v_pk_fma_f32 v[14:15], v[190:191], v[46:47], v[14:15] op_sel:[1,0,0] op_sel_hi:[1,1,1]
	v_pk_fma_f32 v[16:17], v[190:191], v[48:49], v[16:17] op_sel:[1,0,0] op_sel_hi:[1,1,1]
	v_pk_fma_f32 v[18:19], v[190:191], v[50:51], v[18:19] op_sel:[1,0,0] op_sel_hi:[1,1,1]
	v_pk_fma_f32 v[20:21], v[190:191], v[52:53], v[20:21] op_sel:[1,0,0] op_sel_hi:[1,1,1]
	v_pk_fma_f32 v[22:23], v[190:191], v[54:55], v[22:23] op_sel:[1,0,0] op_sel_hi:[1,1,1]
	v_pk_fma_f32 v[24:25], v[190:191], v[56:57], v[24:25] op_sel:[1,0,0] op_sel_hi:[1,1,1]
	v_pk_fma_f32 v[26:27], v[190:191], v[58:59], v[26:27] op_sel:[1,0,0] op_sel_hi:[1,1,1]
	v_pk_fma_f32 v[28:29], v[190:191], v[60:61], v[28:29] op_sel:[1,0,0] op_sel_hi:[1,1,1]
	v_pk_fma_f32 v[30:31], v[190:191], v[62:63], v[30:31] op_sel:[1,0,0] op_sel_hi:[1,1,1]
	s_nop 1
	v_permlane32_swap_b32_e32 v0, v16
	v_permlane32_swap_b32_e32 v1, v17
	v_permlane32_swap_b32_e32 v2, v18
	v_permlane32_swap_b32_e32 v3, v19
	v_permlane32_swap_b32_e32 v4, v20
	v_permlane32_swap_b32_e32 v5, v21
	v_permlane32_swap_b32_e32 v6, v22
	v_permlane32_swap_b32_e32 v7, v23
	v_permlane32_swap_b32_e32 v8, v24
	v_permlane32_swap_b32_e32 v9, v25
	v_permlane32_swap_b32_e32 v10, v26
	v_permlane32_swap_b32_e32 v11, v27
	v_permlane32_swap_b32_e32 v12, v28
	v_permlane32_swap_b32_e32 v13, v29
	v_permlane32_swap_b32_e32 v14, v30
	v_permlane32_swap_b32_e32 v15, v31
	v_pk_add_f32 v[0:1], v[0:1], v[16:17]
	v_pk_add_f32 v[2:3], v[2:3], v[18:19]
	v_pk_add_f32 v[4:5], v[4:5], v[20:21]
	v_pk_add_f32 v[6:7], v[6:7], v[22:23]
	v_pk_add_f32 v[8:9], v[8:9], v[24:25]
	v_pk_add_f32 v[10:11], v[10:11], v[26:27]
	v_pk_add_f32 v[12:13], v[12:13], v[28:29]
	v_pk_add_f32 v[14:15], v[14:15], v[30:31]
	s_nop 1
	v_permlane16_swap_b32_e32 v0, v8
	v_permlane16_swap_b32_e32 v1, v9
	v_permlane16_swap_b32_e32 v2, v10
	v_permlane16_swap_b32_e32 v3, v11
	v_permlane16_swap_b32_e32 v4, v12
	v_permlane16_swap_b32_e32 v5, v13
	v_permlane16_swap_b32_e32 v6, v14
	v_permlane16_swap_b32_e32 v7, v15
	v_pk_add_f32 v[0:1], v[0:1], v[8:9]
	v_pk_add_f32 v[2:3], v[2:3], v[10:11]
	v_pk_add_f32 v[4:5], v[4:5], v[12:13]
	v_pk_add_f32 v[6:7], v[6:7], v[14:15]
	s_nop 1
	v_add_f32_dpp v0, v0, v0 row_ror:8 row_mask:0xf bank_mask:0x3
	v_add_f32_dpp v1, v1, v1 row_ror:8 row_mask:0xf bank_mask:0x3
	v_add_f32_dpp v2, v2, v2 row_ror:8 row_mask:0xf bank_mask:0x3
	v_add_f32_dpp v3, v3, v3 row_ror:8 row_mask:0xf bank_mask:0x3
	v_add_f32_dpp v0, v4, v4 row_ror:8 row_mask:0xf bank_mask:0xc
	v_add_f32_dpp v1, v5, v5 row_ror:8 row_mask:0xf bank_mask:0xc
	v_add_f32_dpp v2, v6, v6 row_ror:8 row_mask:0xf bank_mask:0xc
	v_add_f32_dpp v3, v7, v7 row_ror:8 row_mask:0xf bank_mask:0xc
	s_waitcnt vmcnt(16)
	v_pk_add_f32 v[192:193], v[192:193], v[0:1]
	v_pk_add_f32 v[194:195], v[194:195], v[2:3]
	global_store_dwordx4 v200, v[192:195], s[8:9]
	global_load_dwordx4 v[192:195], v200, s[10:11]
	s_waitcnt lgkmcnt(4)
	v_mad_u32_u24 v168, v168, s100, v199
	v_mad_u32_u24 v169, v169, s100, v199
	v_mad_u32_u24 v170, v170, s100, v199
	v_mad_u32_u24 v171, v171, s100, v199
	v_mad_u32_u24 v172, v172, s100, v199
	v_mad_u32_u24 v173, v173, s100, v199
	v_mad_u32_u24 v174, v174, s100, v199
	v_mad_u32_u24 v175, v175, s100, v199
	global_load_dwordx4 v[112:115], v168, s[4:5]
	global_load_dwordx2 v[116:117], v168, s[4:5] offset:16
	global_load_dwordx4 v[118:121], v169, s[4:5]
	global_load_dwordx2 v[122:123], v169, s[4:5] offset:16
	global_load_dwordx4 v[124:127], v170, s[4:5]
	global_load_dwordx2 v[128:129], v170, s[4:5] offset:16
	global_load_dwordx4 v[130:133], v171, s[4:5]
	global_load_dwordx2 v[134:135], v171, s[4:5] offset:16
	global_load_dwordx4 v[136:139], v172, s[4:5]
	global_load_dwordx2 v[140:141], v172, s[4:5] offset:16
	global_load_dwordx4 v[142:145], v173, s[4:5]
	global_load_dwordx2 v[146:147], v173, s[4:5] offset:16
	global_load_dwordx4 v[148:151], v174, s[4:5]
	global_load_dwordx2 v[152:153], v174, s[4:5] offset:16
	global_load_dwordx4 v[154:157], v175, s[4:5]
	global_load_dwordx2 v[158:159], v175, s[4:5] offset:16
	s_add_u32 s14, s14, 1
	s_and_b32 s14, s14, 63
	s_and_b32 s19, s14, 15
	s_lshr_b32 s98, s14, 4
	s_lshl_b32 s99, s19, 9
	s_mul_i32 s15, s19, s16
	s_lshl_b32 s18, s98, 10
	s_add_u32 s15, s15, s18
	s_lshl_b32 s18, s101, 12
	s_add_u32 s15, s15, s18
	s_add_u32 s8, s24, s15
	s_addc_u32 s9, s25, 0
	s_mul_i32 s15, s98, 0x300000
	s_add_u32 s4, s26, 0x3800000
	s_addc_u32 s5, s27, 0
	s_add_u32 s4, s4, s15
	s_addc_u32 s5, s5, 0
	v_add_u32_e32 v201, s99, v197
	v_add_u32_e32 v203, s99, v198
	ds_read2_b32 v[160:161], v201 offset0:0 offset1:8
	ds_read2_b32 v[162:163], v201 offset0:16 offset1:24
	ds_read2_b32 v[164:165], v201 offset0:32 offset1:40
	ds_read2_b32 v[166:167], v201 offset0:48 offset1:56
	ds_read2_b32 v[184:185], v204 offset0:64 offset1:72
	ds_read2_b32 v[186:187], v204 offset0:80 offset1:88
	ds_read2_b32 v[188:189], v204 offset0:96 offset1:104
	ds_read2_b32 v[190:191], v204 offset0:112 offset1:120
	s_waitcnt lgkmcnt(8)
	s_waitcnt vmcnt(32)
	v_cvt_scalef32_pk32_f32_fp6 v[32:63], v[64:69], 1.0
	v_pk_mul_f32 v[0:1], v[176:177], v[32:33] op_sel_hi:[0,1]
	v_pk_mul_f32 v[2:3], v[176:177], v[34:35] op_sel_hi:[0,1]
	v_pk_mul_f32 v[4:5], v[176:177], v[36:37] op_sel_hi:[0,1]
	v_pk_mul_f32 v[6:7], v[176:177], v[38:39] op_sel_hi:[0,1]
	v_pk_mul_f32 v[8:9], v[176:177], v[40:41] op_sel_hi:[0,1]
	v_pk_mul_f32 v[10:11], v[176:177], v[42:43] op_sel_hi:[0,1]
	v_pk_mul_f32 v[12:13], v[176:177], v[44:45] op_sel_hi:[0,1]
	v_pk_mul_f32 v[14:15], v[176:177], v[46:47] op_sel_hi:[0,1]
	v_pk_mul_f32 v[16:17], v[176:177], v[48:49] op_sel_hi:[0,1]
	v_pk_mul_f32 v[18:19], v[176:177], v[50:51] op_sel_hi:[0,1]
	v_pk_mul_f32 v[20:21], v[176:177], v[52:53] op_sel_hi:[0,1]
	v_pk_mul_f32 v[22:23], v[176:177], v[54:55] op_sel_hi:[0,1]
	v_pk_mul_f32 v[24:25], v[176:177], v[56:57] op_sel_hi:[0,1]
	v_pk_mul_f32 v[26:27], v[176:177], v[58:59] op_sel_hi:[0,1]
	v_pk_mul_f32 v[28:29], v[176:177], v[60:61] op_sel_hi:[0,1]
	v_pk_mul_f32 v[30:31], v[176:177], v[62:63] op_sel_hi:[0,1]
	s_waitcnt vmcnt(30)
	v_cvt_scalef32_pk32_f32_fp6 v[32:63], v[70:75], 1.0
	v_pk_fma_f32 v[0:1], v[176:177], v[32:33], v[0:1] op_sel:[1,0,0] op_sel_hi:[1,1,1]
	v_pk_fma_f32 v[2:3], v[176:177], v[34:35], v[2:3] op_sel:[1,0,0] op_sel_hi:[1,1,1]
	v_pk_fma_f32 v[4:5], v[176:177], v[36:37], v[4:5] op_sel:[1,0,0] op_sel_hi:[1,1,1]
	v_pk_fma_f32 v[6:7], v[176:177], v[38:39], v[6:7] op_sel:[1,0,0] op_sel_hi:[1,1,1]
	v_pk_fma_f32 v[8:9], v[176:177], v[40:41], v[8:9] op_sel:[1,0,0] op_sel_hi:[1,1,1]
	v_pk_fma_f32 v[10:11], v[176:177], v[42:43], v[10:11] op_sel:[1,0,0] op_sel_hi:[1,1,1]
	v_pk_fma_f32 v[12:13], v[176:177], v[44:45], v[12:13] op_sel:[1,0,0] op_sel_hi:[1,1,1]
	v_pk_fma_f32 v[14:15], v[176:177], v[46:47], v[14:15] op_sel:[1,0,0] op_sel_hi:[1,1,1]
	v_pk_fma_f32 v[16:17], v[176:177], v[48:49], v[16:17] op_sel:[1,0,0] op_sel_hi:[1,1,1]
	v_pk_fma_f32 v[18:19], v[176:177], v[50:51], v[18:19] op_sel:[1,0,0] op_sel_hi:[1,1,1]
	v_pk_fma_f32 v[20:21], v[176:177], v[52:53], v[20:21] op_sel:[1,0,0] op_sel_hi:[1,1,1]
	v_pk_fma_f32 v[22:23], v[176:177], v[54:55], v[22:23] op_sel:[1,0,0] op_sel_hi:[1,1,1]
	v_pk_fma_f32 v[24:25], v[176:177], v[56:57], v[24:25] op_sel:[1,0,0] op_sel_hi:[1,1,1]
	v_pk_fma_f32 v[26:27], v[176:177], v[58:59], v[26:27] op_sel:[1,0,0] op_sel_hi:[1,1,1]
	v_pk_fma_f32 v[28:29], v[176:177], v[60:61], v[28:29] op_sel:[1,0,0] op_sel_hi:[1,1,1]
	v_pk_fma_f32 v[30:31], v[176:177], v[62:63], v[30:31] op_sel:[1,0,0] op_sel_hi:[1,1,1]
	s_waitcnt vmcnt(28)
	v_cvt_scalef32_pk32_f32_fp6 v[32:63], v[76:81], 1.0
	v_pk_fma_f32 v[0:1], v[178:179], v[32:33], v[0:1] op_sel_hi:[0,1,1]
	v_pk_fma_f32 v[2:3], v[178:179], v[34:35], v[2:3] op_sel_hi:[0,1,1]
	v_pk_fma_f32 v[4:5], v[178:179], v[36:37], v[4:5] op_sel_hi:[0,1,1]
	v_pk_fma_f32 v[6:7], v[178:179], v[38:39], v[6:7] op_sel_hi:[0,1,1]
	v_pk_fma_f32 v[8:9], v[178:179], v[40:41], v[8:9] op_sel_hi:[0,1,1]
	v_pk_fma_f32 v[10:11], v[178:179], v[42:43], v[10:11] op_sel_hi:[0,1,1]
	v_pk_fma_f32 v[12:13], v[178:179], v[44:45], v[12:13] op_sel_hi:[0,1,1]
	v_pk_fma_f32 v[14:15], v[178:179], v[46:47], v[14:15] op_sel_hi:[0,1,1]
	v_pk_fma_f32 v[16:17], v[178:179], v[48:49], v[16:17] op_sel_hi:[0,1,1]
	v_pk_fma_f32 v[18:19], v[178:179], v[50:51], v[18:19] op_sel_hi:[0,1,1]
	v_pk_fma_f32 v[20:21], v[178:179], v[52:53], v[20:21] op_sel_hi:[0,1,1]
	v_pk_fma_f32 v[22:23], v[178:179], v[54:55], v[22:23] op_sel_hi:[0,1,1]
	v_pk_fma_f32 v[24:25], v[178:179], v[56:57], v[24:25] op_sel_hi:[0,1,1]
	v_pk_fma_f32 v[26:27], v[178:179], v[58:59], v[26:27] op_sel_hi:[0,1,1]
	v_pk_fma_f32 v[28:29], v[178:179], v[60:61], v[28:29] op_sel_hi:[0,1,1]
	v_pk_fma_f32 v[30:31], v[178:179], v[62:63], v[30:31] op_sel_hi:[0,1,1]
	s_waitcnt vmcnt(26)
	v_cvt_scalef32_pk32_f32_fp6 v[32:63], v[82:87], 1.0
	v_pk_fma_f32 v[0:1], v[178:179], v[32:33], v[0:1] op_sel:[1,0,0] op_sel_hi:[1,1,1]
	v_pk_fma_f32 v[2:3], v[178:179], v[34:35], v[2:3] op_sel:[1,0,0] op_sel_hi:[1,1,1]
	v_pk_fma_f32 v[4:5], v[178:179], v[36:37], v[4:5] op_sel:[1,0,0] op_sel_hi:[1,1,1]
	v_pk_fma_f32 v[6:7], v[178:179], v[38:39], v[6:7] op_sel:[1,0,0] op_sel_hi:[1,1,1]
	v_pk_fma_f32 v[8:9], v[178:179], v[40:41], v[8:9] op_sel:[1,0,0] op_sel_hi:[1,1,1]
	v_pk_fma_f32 v[10:11], v[178:179], v[42:43], v[10:11] op_sel:[1,0,0] op_sel_hi:[1,1,1]
	v_pk_fma_f32 v[12:13], v[178:179], v[44:45], v[12:13] op_sel:[1,0,0] op_sel_hi:[1,1,1]
	v_pk_fma_f32 v[14:15], v[178:179], v[46:47], v[14:15] op_sel:[1,0,0] op_sel_hi:[1,1,1]
	v_pk_fma_f32 v[16:17], v[178:179], v[48:49], v[16:17] op_sel:[1,0,0] op_sel_hi:[1,1,1]
	v_pk_fma_f32 v[18:19], v[178:179], v[50:51], v[18:19] op_sel:[1,0,0] op_sel_hi:[1,1,1]
	v_pk_fma_f32 v[20:21], v[178:179], v[52:53], v[20:21] op_sel:[1,0,0] op_sel_hi:[1,1,1]
	v_pk_fma_f32 v[22:23], v[178:179], v[54:55], v[22:23] op_sel:[1,0,0] op_sel_hi:[1,1,1]
	v_pk_fma_f32 v[24:25], v[178:179], v[56:57], v[24:25] op_sel:[1,0,0] op_sel_hi:[1,1,1]
	v_pk_fma_f32 v[26:27], v[178:179], v[58:59], v[26:27] op_sel:[1,0,0] op_sel_hi:[1,1,1]
	v_pk_fma_f32 v[28:29], v[178:179], v[60:61], v[28:29] op_sel:[1,0,0] op_sel_hi:[1,1,1]
	v_pk_fma_f32 v[30:31], v[178:179], v[62:63], v[30:31] op_sel:[1,0,0] op_sel_hi:[1,1,1]
	s_waitcnt vmcnt(24)
	v_cvt_scalef32_pk32_f32_fp6 v[32:63], v[88:93], 1.0
	v_pk_fma_f32 v[0:1], v[180:181], v[32:33], v[0:1] op_sel_hi:[0,1,1]
	v_pk_fma_f32 v[2:3], v[180:181], v[34:35], v[2:3] op_sel_hi:[0,1,1]
	v_pk_fma_f32 v[4:5], v[180:181], v[36:37], v[4:5] op_sel_hi:[0,1,1]
	v_pk_fma_f32 v[6:7], v[180:181], v[38:39], v[6:7] op_sel_hi:[0,1,1]
	v_pk_fma_f32 v[8:9], v[180:181], v[40:41], v[8:9] op_sel_hi:[0,1,1]
	v_pk_fma_f32 v[10:11], v[180:181], v[42:43], v[10:11] op_sel_hi:[0,1,1]
	v_pk_fma_f32 v[12:13], v[180:181], v[44:45], v[12:13] op_sel_hi:[0,1,1]
	v_pk_fma_f32 v[14:15], v[180:181], v[46:47], v[14:15] op_sel_hi:[0,1,1]
	v_pk_fma_f32 v[16:17], v[180:181], v[48:49], v[16:17] op_sel_hi:[0,1,1]
	v_pk_fma_f32 v[18:19], v[180:181], v[50:51], v[18:19] op_sel_hi:[0,1,1]
	v_pk_fma_f32 v[20:21], v[180:181], v[52:53], v[20:21] op_sel_hi:[0,1,1]
	v_pk_fma_f32 v[22:23], v[180:181], v[54:55], v[22:23] op_sel_hi:[0,1,1]
	v_pk_fma_f32 v[24:25], v[180:181], v[56:57], v[24:25] op_sel_hi:[0,1,1]
	v_pk_fma_f32 v[26:27], v[180:181], v[58:59], v[26:27] op_sel_hi:[0,1,1]
	v_pk_fma_f32 v[28:29], v[180:181], v[60:61], v[28:29] op_sel_hi:[0,1,1]
	v_pk_fma_f32 v[30:31], v[180:181], v[62:63], v[30:31] op_sel_hi:[0,1,1]
	s_waitcnt vmcnt(22)
	v_cvt_scalef32_pk32_f32_fp6 v[32:63], v[94:99], 1.0
	v_pk_fma_f32 v[0:1], v[180:181], v[32:33], v[0:1] op_sel:[1,0,0] op_sel_hi:[1,1,1]
	v_pk_fma_f32 v[2:3], v[180:181], v[34:35], v[2:3] op_sel:[1,0,0] op_sel_hi:[1,1,1]
	v_pk_fma_f32 v[4:5], v[180:181], v[36:37], v[4:5] op_sel:[1,0,0] op_sel_hi:[1,1,1]
	v_pk_fma_f32 v[6:7], v[180:181], v[38:39], v[6:7] op_sel:[1,0,0] op_sel_hi:[1,1,1]
	v_pk_fma_f32 v[8:9], v[180:181], v[40:41], v[8:9] op_sel:[1,0,0] op_sel_hi:[1,1,1]
	v_pk_fma_f32 v[10:11], v[180:181], v[42:43], v[10:11] op_sel:[1,0,0] op_sel_hi:[1,1,1]
	v_pk_fma_f32 v[12:13], v[180:181], v[44:45], v[12:13] op_sel:[1,0,0] op_sel_hi:[1,1,1]
	v_pk_fma_f32 v[14:15], v[180:181], v[46:47], v[14:15] op_sel:[1,0,0] op_sel_hi:[1,1,1]
	v_pk_fma_f32 v[16:17], v[180:181], v[48:49], v[16:17] op_sel:[1,0,0] op_sel_hi:[1,1,1]
	v_pk_fma_f32 v[18:19], v[180:181], v[50:51], v[18:19] op_sel:[1,0,0] op_sel_hi:[1,1,1]
	v_pk_fma_f32 v[20:21], v[180:181], v[52:53], v[20:21] op_sel:[1,0,0] op_sel_hi:[1,1,1]
	v_pk_fma_f32 v[22:23], v[180:181], v[54:55], v[22:23] op_sel:[1,0,0] op_sel_hi:[1,1,1]
	v_pk_fma_f32 v[24:25], v[180:181], v[56:57], v[24:25] op_sel:[1,0,0] op_sel_hi:[1,1,1]
	v_pk_fma_f32 v[26:27], v[180:181], v[58:59], v[26:27] op_sel:[1,0,0] op_sel_hi:[1,1,1]
	v_pk_fma_f32 v[28:29], v[180:181], v[60:61], v[28:29] op_sel:[1,0,0] op_sel_hi:[1,1,1]
	v_pk_fma_f32 v[30:31], v[180:181], v[62:63], v[30:31] op_sel:[1,0,0] op_sel_hi:[1,1,1]
	s_waitcnt vmcnt(20)
	v_cvt_scalef32_pk32_f32_fp6 v[32:63], v[100:105], 1.0
	v_pk_fma_f32 v[0:1], v[182:183], v[32:33], v[0:1] op_sel_hi:[0,1,1]
	v_pk_fma_f32 v[2:3], v[182:183], v[34:35], v[2:3] op_sel_hi:[0,1,1]
	v_pk_fma_f32 v[4:5], v[182:183], v[36:37], v[4:5] op_sel_hi:[0,1,1]
	v_pk_fma_f32 v[6:7], v[182:183], v[38:39], v[6:7] op_sel_hi:[0,1,1]
	v_pk_fma_f32 v[8:9], v[182:183], v[40:41], v[8:9] op_sel_hi:[0,1,1]
	v_pk_fma_f32 v[10:11], v[182:183], v[42:43], v[10:11] op_sel_hi:[0,1,1]
	v_pk_fma_f32 v[12:13], v[182:183], v[44:45], v[12:13] op_sel_hi:[0,1,1]
	v_pk_fma_f32 v[14:15], v[182:183], v[46:47], v[14:15] op_sel_hi:[0,1,1]
	v_pk_fma_f32 v[16:17], v[182:183], v[48:49], v[16:17] op_sel_hi:[0,1,1]
	v_pk_fma_f32 v[18:19], v[182:183], v[50:51], v[18:19] op_sel_hi:[0,1,1]
	v_pk_fma_f32 v[20:21], v[182:183], v[52:53], v[20:21] op_sel_hi:[0,1,1]
	v_pk_fma_f32 v[22:23], v[182:183], v[54:55], v[22:23] op_sel_hi:[0,1,1]
	v_pk_fma_f32 v[24:25], v[182:183], v[56:57], v[24:25] op_sel_hi:[0,1,1]
	v_pk_fma_f32 v[26:27], v[182:183], v[58:59], v[26:27] op_sel_hi:[0,1,1]
	v_pk_fma_f32 v[28:29], v[182:183], v[60:61], v[28:29] op_sel_hi:[0,1,1]
	v_pk_fma_f32 v[30:31], v[182:183], v[62:63], v[30:31] op_sel_hi:[0,1,1]
	s_waitcnt vmcnt(18)
	v_cvt_scalef32_pk32_f32_fp6 v[32:63], v[106:111], 1.0
	v_pk_fma_f32 v[0:1], v[182:183], v[32:33], v[0:1] op_sel:[1,0,0] op_sel_hi:[1,1,1]
	v_pk_fma_f32 v[2:3], v[182:183], v[34:35], v[2:3] op_sel:[1,0,0] op_sel_hi:[1,1,1]
	v_pk_fma_f32 v[4:5], v[182:183], v[36:37], v[4:5] op_sel:[1,0,0] op_sel_hi:[1,1,1]
	v_pk_fma_f32 v[6:7], v[182:183], v[38:39], v[6:7] op_sel:[1,0,0] op_sel_hi:[1,1,1]
	v_pk_fma_f32 v[8:9], v[182:183], v[40:41], v[8:9] op_sel:[1,0,0] op_sel_hi:[1,1,1]
	v_pk_fma_f32 v[10:11], v[182:183], v[42:43], v[10:11] op_sel:[1,0,0] op_sel_hi:[1,1,1]
	v_pk_fma_f32 v[12:13], v[182:183], v[44:45], v[12:13] op_sel:[1,0,0] op_sel_hi:[1,1,1]
	v_pk_fma_f32 v[14:15], v[182:183], v[46:47], v[14:15] op_sel:[1,0,0] op_sel_hi:[1,1,1]
	v_pk_fma_f32 v[16:17], v[182:183], v[48:49], v[16:17] op_sel:[1,0,0] op_sel_hi:[1,1,1]
	v_pk_fma_f32 v[18:19], v[182:183], v[50:51], v[18:19] op_sel:[1,0,0] op_sel_hi:[1,1,1]
	v_pk_fma_f32 v[20:21], v[182:183], v[52:53], v[20:21] op_sel:[1,0,0] op_sel_hi:[1,1,1]
	v_pk_fma_f32 v[22:23], v[182:183], v[54:55], v[22:23] op_sel:[1,0,0] op_sel_hi:[1,1,1]
	v_pk_fma_f32 v[24:25], v[182:183], v[56:57], v[24:25] op_sel:[1,0,0] op_sel_hi:[1,1,1]
	v_pk_fma_f32 v[26:27], v[182:183], v[58:59], v[26:27] op_sel:[1,0,0] op_sel_hi:[1,1,1]
	v_pk_fma_f32 v[28:29], v[182:183], v[60:61], v[28:29] op_sel:[1,0,0] op_sel_hi:[1,1,1]
	v_pk_fma_f32 v[30:31], v[182:183], v[62:63], v[30:31] op_sel:[1,0,0] op_sel_hi:[1,1,1]
	s_waitcnt lgkmcnt(4)
	v_mad_u32_u24 v160, v160, s100, v199
	v_mad_u32_u24 v161, v161, s100, v199
	v_mad_u32_u24 v162, v162, s100, v199
	v_mad_u32_u24 v163, v163, s100, v199
	v_mad_u32_u24 v164, v164, s100, v199
	v_mad_u32_u24 v165, v165, s100, v199
	v_mad_u32_u24 v166, v166, s100, v199
	v_mad_u32_u24 v167, v167, s100, v199
	global_load_dwordx4 v[64:67], v160, s[4:5]
	global_load_dwordx2 v[68:69], v160, s[4:5] offset:16
	global_load_dwordx4 v[70:73], v161, s[4:5]
	global_load_dwordx2 v[74:75], v161, s[4:5] offset:16
	global_load_dwordx4 v[76:79], v162, s[4:5]
	global_load_dwordx2 v[80:81], v162, s[4:5] offset:16
	global_load_dwordx4 v[82:85], v163, s[4:5]
	global_load_dwordx2 v[86:87], v163, s[4:5] offset:16
	global_load_dwordx4 v[88:91], v164, s[4:5]
	global_load_dwordx2 v[92:93], v164, s[4:5] offset:16
	global_load_dwordx4 v[94:97], v165, s[4:5]
	global_load_dwordx2 v[98:99], v165, s[4:5] offset:16
	global_load_dwordx4 v[100:103], v166, s[4:5]
	global_load_dwordx2 v[104:105], v166, s[4:5] offset:16
	global_load_dwordx4 v[106:109], v167, s[4:5]
	global_load_dwordx2 v[110:111], v167, s[4:5] offset:16
	ds_read2_b32 v[168:169], v201 offset0:64 offset1:72
	ds_read2_b32 v[170:171], v201 offset0:80 offset1:88
	ds_read2_b32 v[172:173], v201 offset0:96 offset1:104
	ds_read2_b32 v[174:175], v201 offset0:112 offset1:120
	ds_read2_b32 v[176:177], v203 offset0:0 offset1:8
	ds_read2_b32 v[178:179], v203 offset0:16 offset1:24
	ds_read2_b32 v[180:181], v203 offset0:32 offset1:40
	ds_read2_b32 v[182:183], v203 offset0:48 offset1:56
	s_waitcnt lgkmcnt(8)
	s_waitcnt vmcnt(30)
	v_cvt_scalef32_pk32_f32_fp6 v[32:63], v[112:117], 1.0
	v_pk_fma_f32 v[0:1], v[184:185], v[32:33], v[0:1] op_sel_hi:[0,1,1]
	v_pk_fma_f32 v[2:3], v[184:185], v[34:35], v[2:3] op_sel_hi:[0,1,1]
	v_pk_fma_f32 v[4:5], v[184:185], v[36:37], v[4:5] op_sel_hi:[0,1,1]
	v_pk_fma_f32 v[6:7], v[184:185], v[38:39], v[6:7] op_sel_hi:[0,1,1]
	v_pk_fma_f32 v[8:9], v[184:185], v[40:41], v[8:9] op_sel_hi:[0,1,1]
	v_pk_fma_f32 v[10:11], v[184:185], v[42:43], v[10:11] op_sel_hi:[0,1,1]
	v_pk_fma_f32 v[12:13], v[184:185], v[44:45], v[12:13] op_sel_hi:[0,1,1]
	v_pk_fma_f32 v[14:15], v[184:185], v[46:47], v[14:15] op_sel_hi:[0,1,1]
	v_pk_fma_f32 v[16:17], v[184:185], v[48:49], v[16:17] op_sel_hi:[0,1,1]
	v_pk_fma_f32 v[18:19], v[184:185], v[50:51], v[18:19] op_sel_hi:[0,1,1]
	v_pk_fma_f32 v[20:21], v[184:185], v[52:53], v[20:21] op_sel_hi:[0,1,1]
	v_pk_fma_f32 v[22:23], v[184:185], v[54:55], v[22:23] op_sel_hi:[0,1,1]
	v_pk_fma_f32 v[24:25], v[184:185], v[56:57], v[24:25] op_sel_hi:[0,1,1]
	v_pk_fma_f32 v[26:27], v[184:185], v[58:59], v[26:27] op_sel_hi:[0,1,1]
	v_pk_fma_f32 v[28:29], v[184:185], v[60:61], v[28:29] op_sel_hi:[0,1,1]
	v_pk_fma_f32 v[30:31], v[184:185], v[62:63], v[30:31] op_sel_hi:[0,1,1]
	s_waitcnt vmcnt(28)
	v_cvt_scalef32_pk32_f32_fp6 v[32:63], v[118:123], 1.0
	v_pk_fma_f32 v[0:1], v[184:185], v[32:33], v[0:1] op_sel:[1,0,0] op_sel_hi:[1,1,1]
	v_pk_fma_f32 v[2:3], v[184:185], v[34:35], v[2:3] op_sel:[1,0,0] op_sel_hi:[1,1,1]
	v_pk_fma_f32 v[4:5], v[184:185], v[36:37], v[4:5] op_sel:[1,0,0] op_sel_hi:[1,1,1]
	v_pk_fma_f32 v[6:7], v[184:185], v[38:39], v[6:7] op_sel:[1,0,0] op_sel_hi:[1,1,1]
	v_pk_fma_f32 v[8:9], v[184:185], v[40:41], v[8:9] op_sel:[1,0,0] op_sel_hi:[1,1,1]
	v_pk_fma_f32 v[10:11], v[184:185], v[42:43], v[10:11] op_sel:[1,0,0] op_sel_hi:[1,1,1]
	v_pk_fma_f32 v[12:13], v[184:185], v[44:45], v[12:13] op_sel:[1,0,0] op_sel_hi:[1,1,1]
	v_pk_fma_f32 v[14:15], v[184:185], v[46:47], v[14:15] op_sel:[1,0,0] op_sel_hi:[1,1,1]
	v_pk_fma_f32 v[16:17], v[184:185], v[48:49], v[16:17] op_sel:[1,0,0] op_sel_hi:[1,1,1]
	v_pk_fma_f32 v[18:19], v[184:185], v[50:51], v[18:19] op_sel:[1,0,0] op_sel_hi:[1,1,1]
	v_pk_fma_f32 v[20:21], v[184:185], v[52:53], v[20:21] op_sel:[1,0,0] op_sel_hi:[1,1,1]
	v_pk_fma_f32 v[22:23], v[184:185], v[54:55], v[22:23] op_sel:[1,0,0] op_sel_hi:[1,1,1]
	v_pk_fma_f32 v[24:25], v[184:185], v[56:57], v[24:25] op_sel:[1,0,0] op_sel_hi:[1,1,1]
	v_pk_fma_f32 v[26:27], v[184:185], v[58:59], v[26:27] op_sel:[1,0,0] op_sel_hi:[1,1,1]
	v_pk_fma_f32 v[28:29], v[184:185], v[60:61], v[28:29] op_sel:[1,0,0] op_sel_hi:[1,1,1]
	v_pk_fma_f32 v[30:31], v[184:185], v[62:63], v[30:31] op_sel:[1,0,0] op_sel_hi:[1,1,1]
	s_waitcnt vmcnt(26)
	v_cvt_scalef32_pk32_f32_fp6 v[32:63], v[124:129], 1.0
	v_pk_fma_f32 v[0:1], v[186:187], v[32:33], v[0:1] op_sel_hi:[0,1,1]
	v_pk_fma_f32 v[2:3], v[186:187], v[34:35], v[2:3] op_sel_hi:[0,1,1]
	v_pk_fma_f32 v[4:5], v[186:187], v[36:37], v[4:5] op_sel_hi:[0,1,1]
	v_pk_fma_f32 v[6:7], v[186:187], v[38:39], v[6:7] op_sel_hi:[0,1,1]
	v_pk_fma_f32 v[8:9], v[186:187], v[40:41], v[8:9] op_sel_hi:[0,1,1]
	v_pk_fma_f32 v[10:11], v[186:187], v[42:43], v[10:11] op_sel_hi:[0,1,1]
	v_pk_fma_f32 v[12:13], v[186:187], v[44:45], v[12:13] op_sel_hi:[0,1,1]
	v_pk_fma_f32 v[14:15], v[186:187], v[46:47], v[14:15] op_sel_hi:[0,1,1]
	v_pk_fma_f32 v[16:17], v[186:187], v[48:49], v[16:17] op_sel_hi:[0,1,1]
	v_pk_fma_f32 v[18:19], v[186:187], v[50:51], v[18:19] op_sel_hi:[0,1,1]
	v_pk_fma_f32 v[20:21], v[186:187], v[52:53], v[20:21] op_sel_hi:[0,1,1]
	v_pk_fma_f32 v[22:23], v[186:187], v[54:55], v[22:23] op_sel_hi:[0,1,1]
	v_pk_fma_f32 v[24:25], v[186:187], v[56:57], v[24:25] op_sel_hi:[0,1,1]
	v_pk_fma_f32 v[26:27], v[186:187], v[58:59], v[26:27] op_sel_hi:[0,1,1]
	v_pk_fma_f32 v[28:29], v[186:187], v[60:61], v[28:29] op_sel_hi:[0,1,1]
	v_pk_fma_f32 v[30:31], v[186:187], v[62:63], v[30:31] op_sel_hi:[0,1,1]
	s_waitcnt vmcnt(24)
	v_cvt_scalef32_pk32_f32_fp6 v[32:63], v[130:135], 1.0
	v_pk_fma_f32 v[0:1], v[186:187], v[32:33], v[0:1] op_sel:[1,0,0] op_sel_hi:[1,1,1]
	v_pk_fma_f32 v[2:3], v[186:187], v[34:35], v[2:3] op_sel:[1,0,0] op_sel_hi:[1,1,1]
	v_pk_fma_f32 v[4:5], v[186:187], v[36:37], v[4:5] op_sel:[1,0,0] op_sel_hi:[1,1,1]
	v_pk_fma_f32 v[6:7], v[186:187], v[38:39], v[6:7] op_sel:[1,0,0] op_sel_hi:[1,1,1]
	v_pk_fma_f32 v[8:9], v[186:187], v[40:41], v[8:9] op_sel:[1,0,0] op_sel_hi:[1,1,1]
	v_pk_fma_f32 v[10:11], v[186:187], v[42:43], v[10:11] op_sel:[1,0,0] op_sel_hi:[1,1,1]
	v_pk_fma_f32 v[12:13], v[186:187], v[44:45], v[12:13] op_sel:[1,0,0] op_sel_hi:[1,1,1]
	v_pk_fma_f32 v[14:15], v[186:187], v[46:47], v[14:15] op_sel:[1,0,0] op_sel_hi:[1,1,1]
	v_pk_fma_f32 v[16:17], v[186:187], v[48:49], v[16:17] op_sel:[1,0,0] op_sel_hi:[1,1,1]
	v_pk_fma_f32 v[18:19], v[186:187], v[50:51], v[18:19] op_sel:[1,0,0] op_sel_hi:[1,1,1]
	v_pk_fma_f32 v[20:21], v[186:187], v[52:53], v[20:21] op_sel:[1,0,0] op_sel_hi:[1,1,1]
	v_pk_fma_f32 v[22:23], v[186:187], v[54:55], v[22:23] op_sel:[1,0,0] op_sel_hi:[1,1,1]
	v_pk_fma_f32 v[24:25], v[186:187], v[56:57], v[24:25] op_sel:[1,0,0] op_sel_hi:[1,1,1]
	v_pk_fma_f32 v[26:27], v[186:187], v[58:59], v[26:27] op_sel:[1,0,0] op_sel_hi:[1,1,1]
	v_pk_fma_f32 v[28:29], v[186:187], v[60:61], v[28:29] op_sel:[1,0,0] op_sel_hi:[1,1,1]
	v_pk_fma_f32 v[30:31], v[186:187], v[62:63], v[30:31] op_sel:[1,0,0] op_sel_hi:[1,1,1]
	s_waitcnt vmcnt(22)
	v_cvt_scalef32_pk32_f32_fp6 v[32:63], v[136:141], 1.0
	v_pk_fma_f32 v[0:1], v[188:189], v[32:33], v[0:1] op_sel_hi:[0,1,1]
	v_pk_fma_f32 v[2:3], v[188:189], v[34:35], v[2:3] op_sel_hi:[0,1,1]
	v_pk_fma_f32 v[4:5], v[188:189], v[36:37], v[4:5] op_sel_hi:[0,1,1]
	v_pk_fma_f32 v[6:7], v[188:189], v[38:39], v[6:7] op_sel_hi:[0,1,1]
	v_pk_fma_f32 v[8:9], v[188:189], v[40:41], v[8:9] op_sel_hi:[0,1,1]
	v_pk_fma_f32 v[10:11], v[188:189], v[42:43], v[10:11] op_sel_hi:[0,1,1]
	v_pk_fma_f32 v[12:13], v[188:189], v[44:45], v[12:13] op_sel_hi:[0,1,1]
	v_pk_fma_f32 v[14:15], v[188:189], v[46:47], v[14:15] op_sel_hi:[0,1,1]
	v_pk_fma_f32 v[16:17], v[188:189], v[48:49], v[16:17] op_sel_hi:[0,1,1]
	v_pk_fma_f32 v[18:19], v[188:189], v[50:51], v[18:19] op_sel_hi:[0,1,1]
	v_pk_fma_f32 v[20:21], v[188:189], v[52:53], v[20:21] op_sel_hi:[0,1,1]
	v_pk_fma_f32 v[22:23], v[188:189], v[54:55], v[22:23] op_sel_hi:[0,1,1]
	v_pk_fma_f32 v[24:25], v[188:189], v[56:57], v[24:25] op_sel_hi:[0,1,1]
	v_pk_fma_f32 v[26:27], v[188:189], v[58:59], v[26:27] op_sel_hi:[0,1,1]
	v_pk_fma_f32 v[28:29], v[188:189], v[60:61], v[28:29] op_sel_hi:[0,1,1]
	v_pk_fma_f32 v[30:31], v[188:189], v[62:63], v[30:31] op_sel_hi:[0,1,1]
	s_waitcnt vmcnt(20)
	v_cvt_scalef32_pk32_f32_fp6 v[32:63], v[142:147], 1.0
	v_pk_fma_f32 v[0:1], v[188:189], v[32:33], v[0:1] op_sel:[1,0,0] op_sel_hi:[1,1,1]
	v_pk_fma_f32 v[2:3], v[188:189], v[34:35], v[2:3] op_sel:[1,0,0] op_sel_hi:[1,1,1]
	v_pk_fma_f32 v[4:5], v[188:189], v[36:37], v[4:5] op_sel:[1,0,0] op_sel_hi:[1,1,1]
	v_pk_fma_f32 v[6:7], v[188:189], v[38:39], v[6:7] op_sel:[1,0,0] op_sel_hi:[1,1,1]
	v_pk_fma_f32 v[8:9], v[188:189], v[40:41], v[8:9] op_sel:[1,0,0] op_sel_hi:[1,1,1]
	v_pk_fma_f32 v[10:11], v[188:189], v[42:43], v[10:11] op_sel:[1,0,0] op_sel_hi:[1,1,1]
	v_pk_fma_f32 v[12:13], v[188:189], v[44:45], v[12:13] op_sel:[1,0,0] op_sel_hi:[1,1,1]
	v_pk_fma_f32 v[14:15], v[188:189], v[46:47], v[14:15] op_sel:[1,0,0] op_sel_hi:[1,1,1]
	v_pk_fma_f32 v[16:17], v[188:189], v[48:49], v[16:17] op_sel:[1,0,0] op_sel_hi:[1,1,1]
	v_pk_fma_f32 v[18:19], v[188:189], v[50:51], v[18:19] op_sel:[1,0,0] op_sel_hi:[1,1,1]
	v_pk_fma_f32 v[20:21], v[188:189], v[52:53], v[20:21] op_sel:[1,0,0] op_sel_hi:[1,1,1]
	v_pk_fma_f32 v[22:23], v[188:189], v[54:55], v[22:23] op_sel:[1,0,0] op_sel_hi:[1,1,1]
	v_pk_fma_f32 v[24:25], v[188:189], v[56:57], v[24:25] op_sel:[1,0,0] op_sel_hi:[1,1,1]
	v_pk_fma_f32 v[26:27], v[188:189], v[58:59], v[26:27] op_sel:[1,0,0] op_sel_hi:[1,1,1]
	v_pk_fma_f32 v[28:29], v[188:189], v[60:61], v[28:29] op_sel:[1,0,0] op_sel_hi:[1,1,1]
	v_pk_fma_f32 v[30:31], v[188:189], v[62:63], v[30:31] op_sel:[1,0,0] op_sel_hi:[1,1,1]
	s_waitcnt vmcnt(18)
	v_cvt_scalef32_pk32_f32_fp6 v[32:63], v[148:153], 1.0
	v_pk_fma_f32 v[0:1], v[190:191], v[32:33], v[0:1] op_sel_hi:[0,1,1]
	v_pk_fma_f32 v[2:3], v[190:191], v[34:35], v[2:3] op_sel_hi:[0,1,1]
	v_pk_fma_f32 v[4:5], v[190:191], v[36:37], v[4:5] op_sel_hi:[0,1,1]
	v_pk_fma_f32 v[6:7], v[190:191], v[38:39], v[6:7] op_sel_hi:[0,1,1]
	v_pk_fma_f32 v[8:9], v[190:191], v[40:41], v[8:9] op_sel_hi:[0,1,1]
	v_pk_fma_f32 v[10:11], v[190:191], v[42:43], v[10:11] op_sel_hi:[0,1,1]
	v_pk_fma_f32 v[12:13], v[190:191], v[44:45], v[12:13] op_sel_hi:[0,1,1]
	v_pk_fma_f32 v[14:15], v[190:191], v[46:47], v[14:15] op_sel_hi:[0,1,1]
	v_pk_fma_f32 v[16:17], v[190:191], v[48:49], v[16:17] op_sel_hi:[0,1,1]
	v_pk_fma_f32 v[18:19], v[190:191], v[50:51], v[18:19] op_sel_hi:[0,1,1]
	v_pk_fma_f32 v[20:21], v[190:191], v[52:53], v[20:21] op_sel_hi:[0,1,1]
	v_pk_fma_f32 v[22:23], v[190:191], v[54:55], v[22:23] op_sel_hi:[0,1,1]
	v_pk_fma_f32 v[24:25], v[190:191], v[56:57], v[24:25] op_sel_hi:[0,1,1]
	v_pk_fma_f32 v[26:27], v[190:191], v[58:59], v[26:27] op_sel_hi:[0,1,1]
	v_pk_fma_f32 v[28:29], v[190:191], v[60:61], v[28:29] op_sel_hi:[0,1,1]
	v_pk_fma_f32 v[30:31], v[190:191], v[62:63], v[30:31] op_sel_hi:[0,1,1]
	s_waitcnt vmcnt(16)
	v_cvt_scalef32_pk32_f32_fp6 v[32:63], v[154:159], 1.0
	v_pk_fma_f32 v[0:1], v[190:191], v[32:33], v[0:1] op_sel:[1,0,0] op_sel_hi:[1,1,1]
	v_pk_fma_f32 v[2:3], v[190:191], v[34:35], v[2:3] op_sel:[1,0,0] op_sel_hi:[1,1,1]
	v_pk_fma_f32 v[4:5], v[190:191], v[36:37], v[4:5] op_sel:[1,0,0] op_sel_hi:[1,1,1]
	v_pk_fma_f32 v[6:7], v[190:191], v[38:39], v[6:7] op_sel:[1,0,0] op_sel_hi:[1,1,1]
	v_pk_fma_f32 v[8:9], v[190:191], v[40:41], v[8:9] op_sel:[1,0,0] op_sel_hi:[1,1,1]
	v_pk_fma_f32 v[10:11], v[190:191], v[42:43], v[10:11] op_sel:[1,0,0] op_sel_hi:[1,1,1]
	v_pk_fma_f32 v[12:13], v[190:191], v[44:45], v[12:13] op_sel:[1,0,0] op_sel_hi:[1,1,1]
	v_pk_fma_f32 v[14:15], v[190:191], v[46:47], v[14:15] op_sel:[1,0,0] op_sel_hi:[1,1,1]
	v_pk_fma_f32 v[16:17], v[190:191], v[48:49], v[16:17] op_sel:[1,0,0] op_sel_hi:[1,1,1]
	v_pk_fma_f32 v[18:19], v[190:191], v[50:51], v[18:19] op_sel:[1,0,0] op_sel_hi:[1,1,1]
	v_pk_fma_f32 v[20:21], v[190:191], v[52:53], v[20:21] op_sel:[1,0,0] op_sel_hi:[1,1,1]
	v_pk_fma_f32 v[22:23], v[190:191], v[54:55], v[22:23] op_sel:[1,0,0] op_sel_hi:[1,1,1]
	v_pk_fma_f32 v[24:25], v[190:191], v[56:57], v[24:25] op_sel:[1,0,0] op_sel_hi:[1,1,1]
	v_pk_fma_f32 v[26:27], v[190:191], v[58:59], v[26:27] op_sel:[1,0,0] op_sel_hi:[1,1,1]
	v_pk_fma_f32 v[28:29], v[190:191], v[60:61], v[28:29] op_sel:[1,0,0] op_sel_hi:[1,1,1]
	v_pk_fma_f32 v[30:31], v[190:191], v[62:63], v[30:31] op_sel:[1,0,0] op_sel_hi:[1,1,1]
	s_nop 1
	v_permlane32_swap_b32_e32 v0, v16
	v_permlane32_swap_b32_e32 v1, v17
	v_permlane32_swap_b32_e32 v2, v18
	v_permlane32_swap_b32_e32 v3, v19
	v_permlane32_swap_b32_e32 v4, v20
	v_permlane32_swap_b32_e32 v5, v21
	v_permlane32_swap_b32_e32 v6, v22
	v_permlane32_swap_b32_e32 v7, v23
	v_permlane32_swap_b32_e32 v8, v24
	v_permlane32_swap_b32_e32 v9, v25
	v_permlane32_swap_b32_e32 v10, v26
	v_permlane32_swap_b32_e32 v11, v27
	v_permlane32_swap_b32_e32 v12, v28
	v_permlane32_swap_b32_e32 v13, v29
	v_permlane32_swap_b32_e32 v14, v30
	v_permlane32_swap_b32_e32 v15, v31
	v_pk_add_f32 v[0:1], v[0:1], v[16:17]
	v_pk_add_f32 v[2:3], v[2:3], v[18:19]
	v_pk_add_f32 v[4:5], v[4:5], v[20:21]
	v_pk_add_f32 v[6:7], v[6:7], v[22:23]
	v_pk_add_f32 v[8:9], v[8:9], v[24:25]
	v_pk_add_f32 v[10:11], v[10:11], v[26:27]
	v_pk_add_f32 v[12:13], v[12:13], v[28:29]
	v_pk_add_f32 v[14:15], v[14:15], v[30:31]
	s_nop 1
	v_permlane16_swap_b32_e32 v0, v8
	v_permlane16_swap_b32_e32 v1, v9
	v_permlane16_swap_b32_e32 v2, v10
	v_permlane16_swap_b32_e32 v3, v11
	v_permlane16_swap_b32_e32 v4, v12
	v_permlane16_swap_b32_e32 v5, v13
	v_permlane16_swap_b32_e32 v6, v14
	v_permlane16_swap_b32_e32 v7, v15
	v_pk_add_f32 v[0:1], v[0:1], v[8:9]
	v_pk_add_f32 v[2:3], v[2:3], v[10:11]
	v_pk_add_f32 v[4:5], v[4:5], v[12:13]
	v_pk_add_f32 v[6:7], v[6:7], v[14:15]
	s_nop 1
	v_add_f32_dpp v0, v0, v0 row_ror:8 row_mask:0xf bank_mask:0x3
	v_add_f32_dpp v1, v1, v1 row_ror:8 row_mask:0xf bank_mask:0x3
	v_add_f32_dpp v2, v2, v2 row_ror:8 row_mask:0xf bank_mask:0x3
	v_add_f32_dpp v3, v3, v3 row_ror:8 row_mask:0xf bank_mask:0x3
	v_add_f32_dpp v0, v4, v4 row_ror:8 row_mask:0xf bank_mask:0xc
	v_add_f32_dpp v1, v5, v5 row_ror:8 row_mask:0xf bank_mask:0xc
	v_add_f32_dpp v2, v6, v6 row_ror:8 row_mask:0xf bank_mask:0xc
	v_add_f32_dpp v3, v7, v7 row_ror:8 row_mask:0xf bank_mask:0xc
	s_waitcnt vmcnt(16)
	v_pk_add_f32 v[192:193], v[192:193], v[0:1]
	v_pk_add_f32 v[194:195], v[194:195], v[2:3]
	global_store_dwordx4 v200, v[192:195], s[10:11]
	s_cmp_lg_u32 s14, 0
	s_cbranch_scc1 .Lgv0_loop
	s_waitcnt vmcnt(0) lgkmcnt(0)
	s_add_u32 s4, s40, 0x1000
	s_addc_u32 s5, s41, 0
	global_load_dwordx4 v[64:67], v211, s[4:5] offset:0
	global_load_dwordx4 v[68:71], v211, s[4:5] offset:1024
	global_load_dwordx4 v[72:75], v211, s[4:5] offset:2048
	global_load_dwordx4 v[76:79], v211, s[4:5] offset:3072
	s_lshl_b32 s15, s101, 12
	s_add_u32 s8, s24, s15
	s_addc_u32 s9, s25, 0
	s_lshl_b32 s15, s101, 11
	s_add_u32 s10, s34, s15
	s_addc_u32 s11, s35, 0
	s_lshl_b32 s18, s92, 13
	v_lshlrev_b32_e32 v146, 3, v210
	v_mov_b32_e32 v147, 0x358637bd
	s_mov_b32 s19, 0x800000
	v_mov_b32_e32 v148, v146
	global_load_dwordx4 v[80:83], v211, s[8:9] offset:0
	global_load_dwordx4 v[84:87], v211, s[8:9] offset:1024
	global_load_dwordx4 v[88:91], v211, s[8:9] offset:2048
	global_load_dwordx4 v[92:95], v211, s[8:9] offset:3072
	s_add_u32 s8, s8, s16
	s_addc_u32 s9, s9, 0
	global_load_dwordx4 v[96:99], v211, s[8:9] offset:0
	global_load_dwordx4 v[100:103], v211, s[8:9] offset:1024
	global_load_dwordx4 v[104:107], v211, s[8:9] offset:2048
	global_load_dwordx4 v[108:111], v211, s[8:9] offset:3072
	s_add_u32 s8, s8, s16
	s_addc_u32 s9, s9, 0
	global_load_dwordx4 v[112:115], v211, s[8:9] offset:0
	global_load_dwordx4 v[116:119], v211, s[8:9] offset:1024
	global_load_dwordx4 v[120:123], v211, s[8:9] offset:2048
	global_load_dwordx4 v[124:127], v211, s[8:9] offset:3072
	s_add_u32 s8, s8, s16
	s_addc_u32 s9, s9, 0
	global_load_dwordx4 v[128:131], v211, s[8:9] offset:0
	global_load_dwordx4 v[132:135], v211, s[8:9] offset:1024
	global_load_dwordx4 v[136:139], v211, s[8:9] offset:2048
	global_load_dwordx4 v[140:143], v211, s[8:9] offset:3072
	s_add_u32 s8, s8, s16
	s_addc_u32 s9, s9, 0
	s_waitcnt vmcnt(0)
	v_mul_f32_e32 v144, v80, v80
	v_fmac_f32_e32 v144, v81, v81
	v_fmac_f32_e32 v144, v82, v82
	v_fmac_f32_e32 v144, v83, v83
	v_fmac_f32_e32 v144, v84, v84
	v_fmac_f32_e32 v144, v85, v85
	v_fmac_f32_e32 v144, v86, v86
	v_fmac_f32_e32 v144, v87, v87
	v_fmac_f32_e32 v144, v88, v88
	v_fmac_f32_e32 v144, v89, v89
	v_fmac_f32_e32 v144, v90, v90
	v_fmac_f32_e32 v144, v91, v91
	v_fmac_f32_e32 v144, v92, v92
	v_fmac_f32_e32 v144, v93, v93
	v_fmac_f32_e32 v144, v94, v94
	v_fmac_f32_e32 v144, v95, v95
	s_nop 1
	v_add_f32_dpp v144, v144, v144 quad_perm:[1,0,3,2] row_mask:0xf bank_mask:0xf
	s_nop 1
	v_add_f32_dpp v144, v144, v144 quad_perm:[2,3,0,1] row_mask:0xf bank_mask:0xf
	s_nop 1
	v_add_f32_dpp v144, v144, v144 row_half_mirror row_mask:0xf bank_mask:0xf
	s_nop 1
	v_add_f32_dpp v144, v144, v144 row_mirror row_mask:0xf bank_mask:0xf
	v_mov_b32_e32 v145, v144
	s_nop 1
	v_permlane16_swap_b32_e32 v144, v145
	v_add_f32_e32 v144, v144, v145
	v_mov_b32_e32 v145, v144
	s_nop 1
	v_permlane32_swap_b32_e32 v144, v145
	v_add_f32_e32 v144, v144, v145
	v_fmamk_f32 v144, v144, 0x3a800000, v147
	v_mul_f32_e32 v145, 0x4b800000, v144
	v_cmp_gt_f32_e32 vcc, s19, v144
	s_nop 1
	v_cndmask_b32_e32 v144, v144, v145, vcc
	v_rsq_f32_e32 v144, v144
	s_nop 0
	v_mul_f32_e32 v145, 0x45800000, v144
	v_cndmask_b32_e32 v144, v144, v145, vcc
	v_mul_f32_e32 v80, v80, v144
	v_mul_f32_e32 v80, v64, v80
	v_mul_f32_e32 v81, v81, v144
	v_mul_f32_e32 v81, v65, v81
	v_mul_f32_e32 v82, v82, v144
	v_mul_f32_e32 v82, v66, v82
	v_mul_f32_e32 v83, v83, v144
	v_mul_f32_e32 v83, v67, v83
	v_cvt_pk_bf16_f32 v80, v80, v81
	v_cvt_pk_bf16_f32 v81, v82, v83
	global_store_dwordx2 v148, v[80:81], s[10:11] offset:0
	v_mul_f32_e32 v84, v84, v144
	v_mul_f32_e32 v84, v68, v84
	v_mul_f32_e32 v85, v85, v144
	v_mul_f32_e32 v85, v69, v85
	v_mul_f32_e32 v86, v86, v144
	v_mul_f32_e32 v86, v70, v86
	v_mul_f32_e32 v87, v87, v144
	v_mul_f32_e32 v87, v71, v87
	v_cvt_pk_bf16_f32 v84, v84, v85
	v_cvt_pk_bf16_f32 v85, v86, v87
	global_store_dwordx2 v148, v[84:85], s[10:11] offset:512
	v_mul_f32_e32 v88, v88, v144
	v_mul_f32_e32 v88, v72, v88
	v_mul_f32_e32 v89, v89, v144
	v_mul_f32_e32 v89, v73, v89
	v_mul_f32_e32 v90, v90, v144
	v_mul_f32_e32 v90, v74, v90
	v_mul_f32_e32 v91, v91, v144
	v_mul_f32_e32 v91, v75, v91
	v_cvt_pk_bf16_f32 v88, v88, v89
	v_cvt_pk_bf16_f32 v89, v90, v91
	global_store_dwordx2 v148, v[88:89], s[10:11] offset:1024
	v_mul_f32_e32 v92, v92, v144
	v_mul_f32_e32 v92, v76, v92
	v_mul_f32_e32 v93, v93, v144
	v_mul_f32_e32 v93, v77, v93
	v_mul_f32_e32 v94, v94, v144
	v_mul_f32_e32 v94, v78, v94
	v_mul_f32_e32 v95, v95, v144
	v_mul_f32_e32 v95, v79, v95
	v_cvt_pk_bf16_f32 v92, v92, v93
	v_cvt_pk_bf16_f32 v93, v94, v95
	global_store_dwordx2 v148, v[92:93], s[10:11] offset:1536
	s_add_u32 s10, s10, s18
	s_addc_u32 s11, s11, 0
	v_mul_f32_e32 v144, v96, v96
	v_fmac_f32_e32 v144, v97, v97
	v_fmac_f32_e32 v144, v98, v98
	v_fmac_f32_e32 v144, v99, v99
	v_fmac_f32_e32 v144, v100, v100
	v_fmac_f32_e32 v144, v101, v101
	v_fmac_f32_e32 v144, v102, v102
	v_fmac_f32_e32 v144, v103, v103
	v_fmac_f32_e32 v144, v104, v104
	v_fmac_f32_e32 v144, v105, v105
	v_fmac_f32_e32 v144, v106, v106
	v_fmac_f32_e32 v144, v107, v107
	v_fmac_f32_e32 v144, v108, v108
	v_fmac_f32_e32 v144, v109, v109
	v_fmac_f32_e32 v144, v110, v110
	v_fmac_f32_e32 v144, v111, v111
	s_nop 1
	v_add_f32_dpp v144, v144, v144 quad_perm:[1,0,3,2] row_mask:0xf bank_mask:0xf
	s_nop 1
	v_add_f32_dpp v144, v144, v144 quad_perm:[2,3,0,1] row_mask:0xf bank_mask:0xf
	s_nop 1
	v_add_f32_dpp v144, v144, v144 row_half_mirror row_mask:0xf bank_mask:0xf
	s_nop 1
	v_add_f32_dpp v144, v144, v144 row_mirror row_mask:0xf bank_mask:0xf
	v_mov_b32_e32 v145, v144
	s_nop 1
	v_permlane16_swap_b32_e32 v144, v145
	v_add_f32_e32 v144, v144, v145
	v_mov_b32_e32 v145, v144
	s_nop 1
	v_permlane32_swap_b32_e32 v144, v145
	v_add_f32_e32 v144, v144, v145
	v_fmamk_f32 v144, v144, 0x3a800000, v147
	v_mul_f32_e32 v145, 0x4b800000, v144
	v_cmp_gt_f32_e32 vcc, s19, v144
	s_nop 1
	v_cndmask_b32_e32 v144, v144, v145, vcc
	v_rsq_f32_e32 v144, v144
	s_nop 0
	v_mul_f32_e32 v145, 0x45800000, v144
	v_cndmask_b32_e32 v144, v144, v145, vcc
	v_mul_f32_e32 v96, v96, v144
	v_mul_f32_e32 v96, v64, v96
	v_mul_f32_e32 v97, v97, v144
	v_mul_f32_e32 v97, v65, v97
	v_mul_f32_e32 v98, v98, v144
	v_mul_f32_e32 v98, v66, v98
	v_mul_f32_e32 v99, v99, v144
	v_mul_f32_e32 v99, v67, v99
	v_cvt_pk_bf16_f32 v96, v96, v97
	v_cvt_pk_bf16_f32 v97, v98, v99
	global_store_dwordx2 v148, v[96:97], s[10:11] offset:0
	v_mul_f32_e32 v100, v100, v144
	v_mul_f32_e32 v100, v68, v100
	v_mul_f32_e32 v101, v101, v144
	v_mul_f32_e32 v101, v69, v101
	v_mul_f32_e32 v102, v102, v144
	v_mul_f32_e32 v102, v70, v102
	v_mul_f32_e32 v103, v103, v144
	v_mul_f32_e32 v103, v71, v103
	v_cvt_pk_bf16_f32 v100, v100, v101
	v_cvt_pk_bf16_f32 v101, v102, v103
	global_store_dwordx2 v148, v[100:101], s[10:11] offset:512
	v_mul_f32_e32 v104, v104, v144
	v_mul_f32_e32 v104, v72, v104
	v_mul_f32_e32 v105, v105, v144
	v_mul_f32_e32 v105, v73, v105
	v_mul_f32_e32 v106, v106, v144
	v_mul_f32_e32 v106, v74, v106
	v_mul_f32_e32 v107, v107, v144
	v_mul_f32_e32 v107, v75, v107
	v_cvt_pk_bf16_f32 v104, v104, v105
	v_cvt_pk_bf16_f32 v105, v106, v107
	global_store_dwordx2 v148, v[104:105], s[10:11] offset:1024
	v_mul_f32_e32 v108, v108, v144
	v_mul_f32_e32 v108, v76, v108
	v_mul_f32_e32 v109, v109, v144
	v_mul_f32_e32 v109, v77, v109
	v_mul_f32_e32 v110, v110, v144
	v_mul_f32_e32 v110, v78, v110
	v_mul_f32_e32 v111, v111, v144
	v_mul_f32_e32 v111, v79, v111
	v_cvt_pk_bf16_f32 v108, v108, v109
	v_cvt_pk_bf16_f32 v109, v110, v111
	global_store_dwordx2 v148, v[108:109], s[10:11] offset:1536
	s_add_u32 s10, s10, s18
	s_addc_u32 s11, s11, 0
	v_mul_f32_e32 v144, v112, v112
	v_fmac_f32_e32 v144, v113, v113
	v_fmac_f32_e32 v144, v114, v114
	v_fmac_f32_e32 v144, v115, v115
	v_fmac_f32_e32 v144, v116, v116
	v_fmac_f32_e32 v144, v117, v117
	v_fmac_f32_e32 v144, v118, v118
	v_fmac_f32_e32 v144, v119, v119
	v_fmac_f32_e32 v144, v120, v120
	v_fmac_f32_e32 v144, v121, v121
	v_fmac_f32_e32 v144, v122, v122
	v_fmac_f32_e32 v144, v123, v123
	v_fmac_f32_e32 v144, v124, v124
	v_fmac_f32_e32 v144, v125, v125
	v_fmac_f32_e32 v144, v126, v126
	v_fmac_f32_e32 v144, v127, v127
	s_nop 1
	v_add_f32_dpp v144, v144, v144 quad_perm:[1,0,3,2] row_mask:0xf bank_mask:0xf
	s_nop 1
	v_add_f32_dpp v144, v144, v144 quad_perm:[2,3,0,1] row_mask:0xf bank_mask:0xf
	s_nop 1
	v_add_f32_dpp v144, v144, v144 row_half_mirror row_mask:0xf bank_mask:0xf
	s_nop 1
	v_add_f32_dpp v144, v144, v144 row_mirror row_mask:0xf bank_mask:0xf
	v_mov_b32_e32 v145, v144
	s_nop 1
	v_permlane16_swap_b32_e32 v144, v145
	v_add_f32_e32 v144, v144, v145
	v_mov_b32_e32 v145, v144
	s_nop 1
	v_permlane32_swap_b32_e32 v144, v145
	v_add_f32_e32 v144, v144, v145
	v_fmamk_f32 v144, v144, 0x3a800000, v147
	v_mul_f32_e32 v145, 0x4b800000, v144
	v_cmp_gt_f32_e32 vcc, s19, v144
	s_nop 1
	v_cndmask_b32_e32 v144, v144, v145, vcc
	v_rsq_f32_e32 v144, v144
	s_nop 0
	v_mul_f32_e32 v145, 0x45800000, v144
	v_cndmask_b32_e32 v144, v144, v145, vcc
	v_mul_f32_e32 v112, v112, v144
	v_mul_f32_e32 v112, v64, v112
	v_mul_f32_e32 v113, v113, v144
	v_mul_f32_e32 v113, v65, v113
	v_mul_f32_e32 v114, v114, v144
	v_mul_f32_e32 v114, v66, v114
	v_mul_f32_e32 v115, v115, v144
	v_mul_f32_e32 v115, v67, v115
	v_cvt_pk_bf16_f32 v112, v112, v113
	v_cvt_pk_bf16_f32 v113, v114, v115
	global_store_dwordx2 v148, v[112:113], s[10:11] offset:0
	v_mul_f32_e32 v116, v116, v144
	v_mul_f32_e32 v116, v68, v116
	v_mul_f32_e32 v117, v117, v144
	v_mul_f32_e32 v117, v69, v117
	v_mul_f32_e32 v118, v118, v144
	v_mul_f32_e32 v118, v70, v118
	v_mul_f32_e32 v119, v119, v144
	v_mul_f32_e32 v119, v71, v119
	v_cvt_pk_bf16_f32 v116, v116, v117
	v_cvt_pk_bf16_f32 v117, v118, v119
	global_store_dwordx2 v148, v[116:117], s[10:11] offset:512
	v_mul_f32_e32 v120, v120, v144
	v_mul_f32_e32 v120, v72, v120
	v_mul_f32_e32 v121, v121, v144
	v_mul_f32_e32 v121, v73, v121
	v_mul_f32_e32 v122, v122, v144
	v_mul_f32_e32 v122, v74, v122
	v_mul_f32_e32 v123, v123, v144
	v_mul_f32_e32 v123, v75, v123
	v_cvt_pk_bf16_f32 v120, v120, v121
	v_cvt_pk_bf16_f32 v121, v122, v123
	global_store_dwordx2 v148, v[120:121], s[10:11] offset:1024
	v_mul_f32_e32 v124, v124, v144
	v_mul_f32_e32 v124, v76, v124
	v_mul_f32_e32 v125, v125, v144
	v_mul_f32_e32 v125, v77, v125
	v_mul_f32_e32 v126, v126, v144
	v_mul_f32_e32 v126, v78, v126
	v_mul_f32_e32 v127, v127, v144
	v_mul_f32_e32 v127, v79, v127
	v_cvt_pk_bf16_f32 v124, v124, v125
	v_cvt_pk_bf16_f32 v125, v126, v127
	global_store_dwordx2 v148, v[124:125], s[10:11] offset:1536
	s_add_u32 s10, s10, s18
	s_addc_u32 s11, s11, 0
	v_mul_f32_e32 v144, v128, v128
	v_fmac_f32_e32 v144, v129, v129
	v_fmac_f32_e32 v144, v130, v130
	v_fmac_f32_e32 v144, v131, v131
	v_fmac_f32_e32 v144, v132, v132
	v_fmac_f32_e32 v144, v133, v133
	v_fmac_f32_e32 v144, v134, v134
	v_fmac_f32_e32 v144, v135, v135
	v_fmac_f32_e32 v144, v136, v136
	v_fmac_f32_e32 v144, v137, v137
	v_fmac_f32_e32 v144, v138, v138
	v_fmac_f32_e32 v144, v139, v139
	v_fmac_f32_e32 v144, v140, v140
	v_fmac_f32_e32 v144, v141, v141
	v_fmac_f32_e32 v144, v142, v142
	v_fmac_f32_e32 v144, v143, v143
	s_nop 1
	v_add_f32_dpp v144, v144, v144 quad_perm:[1,0,3,2] row_mask:0xf bank_mask:0xf
	s_nop 1
	v_add_f32_dpp v144, v144, v144 quad_perm:[2,3,0,1] row_mask:0xf bank_mask:0xf
	s_nop 1
	v_add_f32_dpp v144, v144, v144 row_half_mirror row_mask:0xf bank_mask:0xf
	s_nop 1
	v_add_f32_dpp v144, v144, v144 row_mirror row_mask:0xf bank_mask:0xf
	v_mov_b32_e32 v145, v144
	s_nop 1
	v_permlane16_swap_b32_e32 v144, v145
	v_add_f32_e32 v144, v144, v145
	v_mov_b32_e32 v145, v144
	s_nop 1
	v_permlane32_swap_b32_e32 v144, v145
	v_add_f32_e32 v144, v144, v145
	v_fmamk_f32 v144, v144, 0x3a800000, v147
	v_mul_f32_e32 v145, 0x4b800000, v144
	v_cmp_gt_f32_e32 vcc, s19, v144
	s_nop 1
	v_cndmask_b32_e32 v144, v144, v145, vcc
	v_rsq_f32_e32 v144, v144
	s_nop 0
	v_mul_f32_e32 v145, 0x45800000, v144
	v_cndmask_b32_e32 v144, v144, v145, vcc
	v_mul_f32_e32 v128, v128, v144
	v_mul_f32_e32 v128, v64, v128
	v_mul_f32_e32 v129, v129, v144
	v_mul_f32_e32 v129, v65, v129
	v_mul_f32_e32 v130, v130, v144
	v_mul_f32_e32 v130, v66, v130
	v_mul_f32_e32 v131, v131, v144
	v_mul_f32_e32 v131, v67, v131
	v_cvt_pk_bf16_f32 v128, v128, v129
	v_cvt_pk_bf16_f32 v129, v130, v131
	global_store_dwordx2 v148, v[128:129], s[10:11] offset:0
	v_mul_f32_e32 v132, v132, v144
	v_mul_f32_e32 v132, v68, v132
	v_mul_f32_e32 v133, v133, v144
	v_mul_f32_e32 v133, v69, v133
	v_mul_f32_e32 v134, v134, v144
	v_mul_f32_e32 v134, v70, v134
	v_mul_f32_e32 v135, v135, v144
	v_mul_f32_e32 v135, v71, v135
	v_cvt_pk_bf16_f32 v132, v132, v133
	v_cvt_pk_bf16_f32 v133, v134, v135
	global_store_dwordx2 v148, v[132:133], s[10:11] offset:512
	v_mul_f32_e32 v136, v136, v144
	v_mul_f32_e32 v136, v72, v136
	v_mul_f32_e32 v137, v137, v144
	v_mul_f32_e32 v137, v73, v137
	v_mul_f32_e32 v138, v138, v144
	v_mul_f32_e32 v138, v74, v138
	v_mul_f32_e32 v139, v139, v144
	v_mul_f32_e32 v139, v75, v139
	v_cvt_pk_bf16_f32 v136, v136, v137
	v_cvt_pk_bf16_f32 v137, v138, v139
	global_store_dwordx2 v148, v[136:137], s[10:11] offset:1024
	v_mul_f32_e32 v140, v140, v144
	v_mul_f32_e32 v140, v76, v140
	v_mul_f32_e32 v141, v141, v144
	v_mul_f32_e32 v141, v77, v141
	v_mul_f32_e32 v142, v142, v144
	v_mul_f32_e32 v142, v78, v142
	v_mul_f32_e32 v143, v143, v144
	v_mul_f32_e32 v143, v79, v143
	v_cvt_pk_bf16_f32 v140, v140, v141
	v_cvt_pk_bf16_f32 v141, v142, v143
	global_store_dwordx2 v148, v[140:141], s[10:11] offset:1536
	s_add_u32 s10, s10, s18
	s_addc_u32 s11, s11, 0
	global_load_dwordx4 v[80:83], v211, s[8:9] offset:0
	global_load_dwordx4 v[84:87], v211, s[8:9] offset:1024
	global_load_dwordx4 v[88:91], v211, s[8:9] offset:2048
	global_load_dwordx4 v[92:95], v211, s[8:9] offset:3072
	s_add_u32 s8, s8, s16
	s_addc_u32 s9, s9, 0
	global_load_dwordx4 v[96:99], v211, s[8:9] offset:0
	global_load_dwordx4 v[100:103], v211, s[8:9] offset:1024
	global_load_dwordx4 v[104:107], v211, s[8:9] offset:2048
	global_load_dwordx4 v[108:111], v211, s[8:9] offset:3072
	s_add_u32 s8, s8, s16
	s_addc_u32 s9, s9, 0
	global_load_dwordx4 v[112:115], v211, s[8:9] offset:0
	global_load_dwordx4 v[116:119], v211, s[8:9] offset:1024
	global_load_dwordx4 v[120:123], v211, s[8:9] offset:2048
	global_load_dwordx4 v[124:127], v211, s[8:9] offset:3072
	s_add_u32 s8, s8, s16
	s_addc_u32 s9, s9, 0
	global_load_dwordx4 v[128:131], v211, s[8:9] offset:0
	global_load_dwordx4 v[132:135], v211, s[8:9] offset:1024
	global_load_dwordx4 v[136:139], v211, s[8:9] offset:2048
	global_load_dwordx4 v[140:143], v211, s[8:9] offset:3072
	s_add_u32 s8, s8, s16
	s_addc_u32 s9, s9, 0
	s_waitcnt vmcnt(0)
	v_mul_f32_e32 v144, v80, v80
	v_fmac_f32_e32 v144, v81, v81
	v_fmac_f32_e32 v144, v82, v82
	v_fmac_f32_e32 v144, v83, v83
	v_fmac_f32_e32 v144, v84, v84
	v_fmac_f32_e32 v144, v85, v85
	v_fmac_f32_e32 v144, v86, v86
	v_fmac_f32_e32 v144, v87, v87
	v_fmac_f32_e32 v144, v88, v88
	v_fmac_f32_e32 v144, v89, v89
	v_fmac_f32_e32 v144, v90, v90
	v_fmac_f32_e32 v144, v91, v91
	v_fmac_f32_e32 v144, v92, v92
	v_fmac_f32_e32 v144, v93, v93
	v_fmac_f32_e32 v144, v94, v94
	v_fmac_f32_e32 v144, v95, v95
	s_nop 1
	v_add_f32_dpp v144, v144, v144 quad_perm:[1,0,3,2] row_mask:0xf bank_mask:0xf
	s_nop 1
	v_add_f32_dpp v144, v144, v144 quad_perm:[2,3,0,1] row_mask:0xf bank_mask:0xf
	s_nop 1
	v_add_f32_dpp v144, v144, v144 row_half_mirror row_mask:0xf bank_mask:0xf
	s_nop 1
	v_add_f32_dpp v144, v144, v144 row_mirror row_mask:0xf bank_mask:0xf
	v_mov_b32_e32 v145, v144
	s_nop 1
	v_permlane16_swap_b32_e32 v144, v145
	v_add_f32_e32 v144, v144, v145
	v_mov_b32_e32 v145, v144
	s_nop 1
	v_permlane32_swap_b32_e32 v144, v145
	v_add_f32_e32 v144, v144, v145
	v_fmamk_f32 v144, v144, 0x3a800000, v147
	v_mul_f32_e32 v145, 0x4b800000, v144
	v_cmp_gt_f32_e32 vcc, s19, v144
	s_nop 1
	v_cndmask_b32_e32 v144, v144, v145, vcc
	v_rsq_f32_e32 v144, v144
	s_nop 0
	v_mul_f32_e32 v145, 0x45800000, v144
	v_cndmask_b32_e32 v144, v144, v145, vcc
	v_mul_f32_e32 v80, v80, v144
	v_mul_f32_e32 v80, v64, v80
	v_mul_f32_e32 v81, v81, v144
	v_mul_f32_e32 v81, v65, v81
	v_mul_f32_e32 v82, v82, v144
	v_mul_f32_e32 v82, v66, v82
	v_mul_f32_e32 v83, v83, v144
	v_mul_f32_e32 v83, v67, v83
	v_cvt_pk_bf16_f32 v80, v80, v81
	v_cvt_pk_bf16_f32 v81, v82, v83
	global_store_dwordx2 v148, v[80:81], s[10:11] offset:0
	v_mul_f32_e32 v84, v84, v144
	v_mul_f32_e32 v84, v68, v84
	v_mul_f32_e32 v85, v85, v144
	v_mul_f32_e32 v85, v69, v85
	v_mul_f32_e32 v86, v86, v144
	v_mul_f32_e32 v86, v70, v86
	v_mul_f32_e32 v87, v87, v144
	v_mul_f32_e32 v87, v71, v87
	v_cvt_pk_bf16_f32 v84, v84, v85
	v_cvt_pk_bf16_f32 v85, v86, v87
	global_store_dwordx2 v148, v[84:85], s[10:11] offset:512
	v_mul_f32_e32 v88, v88, v144
	v_mul_f32_e32 v88, v72, v88
	v_mul_f32_e32 v89, v89, v144
	v_mul_f32_e32 v89, v73, v89
	v_mul_f32_e32 v90, v90, v144
	v_mul_f32_e32 v90, v74, v90
	v_mul_f32_e32 v91, v91, v144
	v_mul_f32_e32 v91, v75, v91
	v_cvt_pk_bf16_f32 v88, v88, v89
	v_cvt_pk_bf16_f32 v89, v90, v91
	global_store_dwordx2 v148, v[88:89], s[10:11] offset:1024
	v_mul_f32_e32 v92, v92, v144
	v_mul_f32_e32 v92, v76, v92
	v_mul_f32_e32 v93, v93, v144
	v_mul_f32_e32 v93, v77, v93
	v_mul_f32_e32 v94, v94, v144
	v_mul_f32_e32 v94, v78, v94
	v_mul_f32_e32 v95, v95, v144
	v_mul_f32_e32 v95, v79, v95
	v_cvt_pk_bf16_f32 v92, v92, v93
	v_cvt_pk_bf16_f32 v93, v94, v95
	global_store_dwordx2 v148, v[92:93], s[10:11] offset:1536
	s_add_u32 s10, s10, s18
	s_addc_u32 s11, s11, 0
	v_mul_f32_e32 v144, v96, v96
	v_fmac_f32_e32 v144, v97, v97
	v_fmac_f32_e32 v144, v98, v98
	v_fmac_f32_e32 v144, v99, v99
	v_fmac_f32_e32 v144, v100, v100
	v_fmac_f32_e32 v144, v101, v101
	v_fmac_f32_e32 v144, v102, v102
	v_fmac_f32_e32 v144, v103, v103
	v_fmac_f32_e32 v144, v104, v104
	v_fmac_f32_e32 v144, v105, v105
	v_fmac_f32_e32 v144, v106, v106
	v_fmac_f32_e32 v144, v107, v107
	v_fmac_f32_e32 v144, v108, v108
	v_fmac_f32_e32 v144, v109, v109
	v_fmac_f32_e32 v144, v110, v110
	v_fmac_f32_e32 v144, v111, v111
	s_nop 1
	v_add_f32_dpp v144, v144, v144 quad_perm:[1,0,3,2] row_mask:0xf bank_mask:0xf
	s_nop 1
	v_add_f32_dpp v144, v144, v144 quad_perm:[2,3,0,1] row_mask:0xf bank_mask:0xf
	s_nop 1
	v_add_f32_dpp v144, v144, v144 row_half_mirror row_mask:0xf bank_mask:0xf
	s_nop 1
	v_add_f32_dpp v144, v144, v144 row_mirror row_mask:0xf bank_mask:0xf
	v_mov_b32_e32 v145, v144
	s_nop 1
	v_permlane16_swap_b32_e32 v144, v145
	v_add_f32_e32 v144, v144, v145
	v_mov_b32_e32 v145, v144
	s_nop 1
	v_permlane32_swap_b32_e32 v144, v145
	v_add_f32_e32 v144, v144, v145
	v_fmamk_f32 v144, v144, 0x3a800000, v147
	v_mul_f32_e32 v145, 0x4b800000, v144
	v_cmp_gt_f32_e32 vcc, s19, v144
	s_nop 1
	v_cndmask_b32_e32 v144, v144, v145, vcc
	v_rsq_f32_e32 v144, v144
	s_nop 0
	v_mul_f32_e32 v145, 0x45800000, v144
	v_cndmask_b32_e32 v144, v144, v145, vcc
	v_mul_f32_e32 v96, v96, v144
	v_mul_f32_e32 v96, v64, v96
	v_mul_f32_e32 v97, v97, v144
	v_mul_f32_e32 v97, v65, v97
	v_mul_f32_e32 v98, v98, v144
	v_mul_f32_e32 v98, v66, v98
	v_mul_f32_e32 v99, v99, v144
	v_mul_f32_e32 v99, v67, v99
	v_cvt_pk_bf16_f32 v96, v96, v97
	v_cvt_pk_bf16_f32 v97, v98, v99
	global_store_dwordx2 v148, v[96:97], s[10:11] offset:0
	v_mul_f32_e32 v100, v100, v144
	v_mul_f32_e32 v100, v68, v100
	v_mul_f32_e32 v101, v101, v144
	v_mul_f32_e32 v101, v69, v101
	v_mul_f32_e32 v102, v102, v144
	v_mul_f32_e32 v102, v70, v102
	v_mul_f32_e32 v103, v103, v144
	v_mul_f32_e32 v103, v71, v103
	v_cvt_pk_bf16_f32 v100, v100, v101
	v_cvt_pk_bf16_f32 v101, v102, v103
	global_store_dwordx2 v148, v[100:101], s[10:11] offset:512
	v_mul_f32_e32 v104, v104, v144
	v_mul_f32_e32 v104, v72, v104
	v_mul_f32_e32 v105, v105, v144
	v_mul_f32_e32 v105, v73, v105
	v_mul_f32_e32 v106, v106, v144
	v_mul_f32_e32 v106, v74, v106
	v_mul_f32_e32 v107, v107, v144
	v_mul_f32_e32 v107, v75, v107
	v_cvt_pk_bf16_f32 v104, v104, v105
	v_cvt_pk_bf16_f32 v105, v106, v107
	global_store_dwordx2 v148, v[104:105], s[10:11] offset:1024
	v_mul_f32_e32 v108, v108, v144
	v_mul_f32_e32 v108, v76, v108
	v_mul_f32_e32 v109, v109, v144
	v_mul_f32_e32 v109, v77, v109
	v_mul_f32_e32 v110, v110, v144
	v_mul_f32_e32 v110, v78, v110
	v_mul_f32_e32 v111, v111, v144
	v_mul_f32_e32 v111, v79, v111
	v_cvt_pk_bf16_f32 v108, v108, v109
	v_cvt_pk_bf16_f32 v109, v110, v111
	global_store_dwordx2 v148, v[108:109], s[10:11] offset:1536
	s_add_u32 s10, s10, s18
	s_addc_u32 s11, s11, 0
	v_mul_f32_e32 v144, v112, v112
	v_fmac_f32_e32 v144, v113, v113
	v_fmac_f32_e32 v144, v114, v114
	v_fmac_f32_e32 v144, v115, v115
	v_fmac_f32_e32 v144, v116, v116
	v_fmac_f32_e32 v144, v117, v117
	v_fmac_f32_e32 v144, v118, v118
	v_fmac_f32_e32 v144, v119, v119
	v_fmac_f32_e32 v144, v120, v120
	v_fmac_f32_e32 v144, v121, v121
	v_fmac_f32_e32 v144, v122, v122
	v_fmac_f32_e32 v144, v123, v123
	v_fmac_f32_e32 v144, v124, v124
	v_fmac_f32_e32 v144, v125, v125
	v_fmac_f32_e32 v144, v126, v126
	v_fmac_f32_e32 v144, v127, v127
	s_nop 1
	v_add_f32_dpp v144, v144, v144 quad_perm:[1,0,3,2] row_mask:0xf bank_mask:0xf
	s_nop 1
	v_add_f32_dpp v144, v144, v144 quad_perm:[2,3,0,1] row_mask:0xf bank_mask:0xf
	s_nop 1
	v_add_f32_dpp v144, v144, v144 row_half_mirror row_mask:0xf bank_mask:0xf
	s_nop 1
	v_add_f32_dpp v144, v144, v144 row_mirror row_mask:0xf bank_mask:0xf
	v_mov_b32_e32 v145, v144
	s_nop 1
	v_permlane16_swap_b32_e32 v144, v145
	v_add_f32_e32 v144, v144, v145
	v_mov_b32_e32 v145, v144
	s_nop 1
	v_permlane32_swap_b32_e32 v144, v145
	v_add_f32_e32 v144, v144, v145
	v_fmamk_f32 v144, v144, 0x3a800000, v147
	v_mul_f32_e32 v145, 0x4b800000, v144
	v_cmp_gt_f32_e32 vcc, s19, v144
	s_nop 1
	v_cndmask_b32_e32 v144, v144, v145, vcc
	v_rsq_f32_e32 v144, v144
	s_nop 0
	v_mul_f32_e32 v145, 0x45800000, v144
	v_cndmask_b32_e32 v144, v144, v145, vcc
	v_mul_f32_e32 v112, v112, v144
	v_mul_f32_e32 v112, v64, v112
	v_mul_f32_e32 v113, v113, v144
	v_mul_f32_e32 v113, v65, v113
	v_mul_f32_e32 v114, v114, v144
	v_mul_f32_e32 v114, v66, v114
	v_mul_f32_e32 v115, v115, v144
	v_mul_f32_e32 v115, v67, v115
	v_cvt_pk_bf16_f32 v112, v112, v113
	v_cvt_pk_bf16_f32 v113, v114, v115
	global_store_dwordx2 v148, v[112:113], s[10:11] offset:0
	v_mul_f32_e32 v116, v116, v144
	v_mul_f32_e32 v116, v68, v116
	v_mul_f32_e32 v117, v117, v144
	v_mul_f32_e32 v117, v69, v117
	v_mul_f32_e32 v118, v118, v144
	v_mul_f32_e32 v118, v70, v118
	v_mul_f32_e32 v119, v119, v144
	v_mul_f32_e32 v119, v71, v119
	v_cvt_pk_bf16_f32 v116, v116, v117
	v_cvt_pk_bf16_f32 v117, v118, v119
	global_store_dwordx2 v148, v[116:117], s[10:11] offset:512
	v_mul_f32_e32 v120, v120, v144
	v_mul_f32_e32 v120, v72, v120
	v_mul_f32_e32 v121, v121, v144
	v_mul_f32_e32 v121, v73, v121
	v_mul_f32_e32 v122, v122, v144
	v_mul_f32_e32 v122, v74, v122
	v_mul_f32_e32 v123, v123, v144
	v_mul_f32_e32 v123, v75, v123
	v_cvt_pk_bf16_f32 v120, v120, v121
	v_cvt_pk_bf16_f32 v121, v122, v123
	global_store_dwordx2 v148, v[120:121], s[10:11] offset:1024
	v_mul_f32_e32 v124, v124, v144
	v_mul_f32_e32 v124, v76, v124
	v_mul_f32_e32 v125, v125, v144
	v_mul_f32_e32 v125, v77, v125
	v_mul_f32_e32 v126, v126, v144
	v_mul_f32_e32 v126, v78, v126
	v_mul_f32_e32 v127, v127, v144
	v_mul_f32_e32 v127, v79, v127
	v_cvt_pk_bf16_f32 v124, v124, v125
	v_cvt_pk_bf16_f32 v125, v126, v127
	global_store_dwordx2 v148, v[124:125], s[10:11] offset:1536
	s_add_u32 s10, s10, s18
	s_addc_u32 s11, s11, 0
	v_mul_f32_e32 v144, v128, v128
	v_fmac_f32_e32 v144, v129, v129
	v_fmac_f32_e32 v144, v130, v130
	v_fmac_f32_e32 v144, v131, v131
	v_fmac_f32_e32 v144, v132, v132
	v_fmac_f32_e32 v144, v133, v133
	v_fmac_f32_e32 v144, v134, v134
	v_fmac_f32_e32 v144, v135, v135
	v_fmac_f32_e32 v144, v136, v136
	v_fmac_f32_e32 v144, v137, v137
	v_fmac_f32_e32 v144, v138, v138
	v_fmac_f32_e32 v144, v139, v139
	v_fmac_f32_e32 v144, v140, v140
	v_fmac_f32_e32 v144, v141, v141
	v_fmac_f32_e32 v144, v142, v142
	v_fmac_f32_e32 v144, v143, v143
	s_nop 1
	v_add_f32_dpp v144, v144, v144 quad_perm:[1,0,3,2] row_mask:0xf bank_mask:0xf
	s_nop 1
	v_add_f32_dpp v144, v144, v144 quad_perm:[2,3,0,1] row_mask:0xf bank_mask:0xf
	s_nop 1
	v_add_f32_dpp v144, v144, v144 row_half_mirror row_mask:0xf bank_mask:0xf
	s_nop 1
	v_add_f32_dpp v144, v144, v144 row_mirror row_mask:0xf bank_mask:0xf
	v_mov_b32_e32 v145, v144
	s_nop 1
	v_permlane16_swap_b32_e32 v144, v145
	v_add_f32_e32 v144, v144, v145
	v_mov_b32_e32 v145, v144
	s_nop 1
	v_permlane32_swap_b32_e32 v144, v145
	v_add_f32_e32 v144, v144, v145
	v_fmamk_f32 v144, v144, 0x3a800000, v147
	v_mul_f32_e32 v145, 0x4b800000, v144
	v_cmp_gt_f32_e32 vcc, s19, v144
	s_nop 1
	v_cndmask_b32_e32 v144, v144, v145, vcc
	v_rsq_f32_e32 v144, v144
	s_nop 0
	v_mul_f32_e32 v145, 0x45800000, v144
	v_cndmask_b32_e32 v144, v144, v145, vcc
	v_mul_f32_e32 v128, v128, v144
	v_mul_f32_e32 v128, v64, v128
	v_mul_f32_e32 v129, v129, v144
	v_mul_f32_e32 v129, v65, v129
	v_mul_f32_e32 v130, v130, v144
	v_mul_f32_e32 v130, v66, v130
	v_mul_f32_e32 v131, v131, v144
	v_mul_f32_e32 v131, v67, v131
	v_cvt_pk_bf16_f32 v128, v128, v129
	v_cvt_pk_bf16_f32 v129, v130, v131
	global_store_dwordx2 v148, v[128:129], s[10:11] offset:0
	v_mul_f32_e32 v132, v132, v144
	v_mul_f32_e32 v132, v68, v132
	v_mul_f32_e32 v133, v133, v144
	v_mul_f32_e32 v133, v69, v133
	v_mul_f32_e32 v134, v134, v144
	v_mul_f32_e32 v134, v70, v134
	v_mul_f32_e32 v135, v135, v144
	v_mul_f32_e32 v135, v71, v135
	v_cvt_pk_bf16_f32 v132, v132, v133
	v_cvt_pk_bf16_f32 v133, v134, v135
	global_store_dwordx2 v148, v[132:133], s[10:11] offset:512
	v_mul_f32_e32 v136, v136, v144
	v_mul_f32_e32 v136, v72, v136
	v_mul_f32_e32 v137, v137, v144
	v_mul_f32_e32 v137, v73, v137
	v_mul_f32_e32 v138, v138, v144
	v_mul_f32_e32 v138, v74, v138
	v_mul_f32_e32 v139, v139, v144
	v_mul_f32_e32 v139, v75, v139
	v_cvt_pk_bf16_f32 v136, v136, v137
	v_cvt_pk_bf16_f32 v137, v138, v139
	global_store_dwordx2 v148, v[136:137], s[10:11] offset:1024
	v_mul_f32_e32 v140, v140, v144
	v_mul_f32_e32 v140, v76, v140
	v_mul_f32_e32 v141, v141, v144
	v_mul_f32_e32 v141, v77, v141
	v_mul_f32_e32 v142, v142, v144
	v_mul_f32_e32 v142, v78, v142
	v_mul_f32_e32 v143, v143, v144
	v_mul_f32_e32 v143, v79, v143
	v_cvt_pk_bf16_f32 v140, v140, v141
	v_cvt_pk_bf16_f32 v141, v142, v143
	global_store_dwordx2 v148, v[140:141], s[10:11] offset:1536
	s_add_u32 s10, s10, s18
	s_addc_u32 s11, s11, 0
	global_load_dwordx4 v[80:83], v211, s[8:9] offset:0
	global_load_dwordx4 v[84:87], v211, s[8:9] offset:1024
	global_load_dwordx4 v[88:91], v211, s[8:9] offset:2048
	global_load_dwordx4 v[92:95], v211, s[8:9] offset:3072
	s_add_u32 s8, s8, s16
	s_addc_u32 s9, s9, 0
	global_load_dwordx4 v[96:99], v211, s[8:9] offset:0
	global_load_dwordx4 v[100:103], v211, s[8:9] offset:1024
	global_load_dwordx4 v[104:107], v211, s[8:9] offset:2048
	global_load_dwordx4 v[108:111], v211, s[8:9] offset:3072
	s_add_u32 s8, s8, s16
	s_addc_u32 s9, s9, 0
	global_load_dwordx4 v[112:115], v211, s[8:9] offset:0
	global_load_dwordx4 v[116:119], v211, s[8:9] offset:1024
	global_load_dwordx4 v[120:123], v211, s[8:9] offset:2048
	global_load_dwordx4 v[124:127], v211, s[8:9] offset:3072
	s_add_u32 s8, s8, s16
	s_addc_u32 s9, s9, 0
	global_load_dwordx4 v[128:131], v211, s[8:9] offset:0
	global_load_dwordx4 v[132:135], v211, s[8:9] offset:1024
	global_load_dwordx4 v[136:139], v211, s[8:9] offset:2048
	global_load_dwordx4 v[140:143], v211, s[8:9] offset:3072
	s_add_u32 s8, s8, s16
	s_addc_u32 s9, s9, 0
	s_waitcnt vmcnt(0)
	v_mul_f32_e32 v144, v80, v80
	v_fmac_f32_e32 v144, v81, v81
	v_fmac_f32_e32 v144, v82, v82
	v_fmac_f32_e32 v144, v83, v83
	v_fmac_f32_e32 v144, v84, v84
	v_fmac_f32_e32 v144, v85, v85
	v_fmac_f32_e32 v144, v86, v86
	v_fmac_f32_e32 v144, v87, v87
	v_fmac_f32_e32 v144, v88, v88
	v_fmac_f32_e32 v144, v89, v89
	v_fmac_f32_e32 v144, v90, v90
	v_fmac_f32_e32 v144, v91, v91
	v_fmac_f32_e32 v144, v92, v92
	v_fmac_f32_e32 v144, v93, v93
	v_fmac_f32_e32 v144, v94, v94
	v_fmac_f32_e32 v144, v95, v95
	s_nop 1
	v_add_f32_dpp v144, v144, v144 quad_perm:[1,0,3,2] row_mask:0xf bank_mask:0xf
	s_nop 1
	v_add_f32_dpp v144, v144, v144 quad_perm:[2,3,0,1] row_mask:0xf bank_mask:0xf
	s_nop 1
	v_add_f32_dpp v144, v144, v144 row_half_mirror row_mask:0xf bank_mask:0xf
	s_nop 1
	v_add_f32_dpp v144, v144, v144 row_mirror row_mask:0xf bank_mask:0xf
	v_mov_b32_e32 v145, v144
	s_nop 1
	v_permlane16_swap_b32_e32 v144, v145
	v_add_f32_e32 v144, v144, v145
	v_mov_b32_e32 v145, v144
	s_nop 1
	v_permlane32_swap_b32_e32 v144, v145
	v_add_f32_e32 v144, v144, v145
	v_fmamk_f32 v144, v144, 0x3a800000, v147
	v_mul_f32_e32 v145, 0x4b800000, v144
	v_cmp_gt_f32_e32 vcc, s19, v144
	s_nop 1
	v_cndmask_b32_e32 v144, v144, v145, vcc
	v_rsq_f32_e32 v144, v144
	s_nop 0
	v_mul_f32_e32 v145, 0x45800000, v144
	v_cndmask_b32_e32 v144, v144, v145, vcc
	v_mul_f32_e32 v80, v80, v144
	v_mul_f32_e32 v80, v64, v80
	v_mul_f32_e32 v81, v81, v144
	v_mul_f32_e32 v81, v65, v81
	v_mul_f32_e32 v82, v82, v144
	v_mul_f32_e32 v82, v66, v82
	v_mul_f32_e32 v83, v83, v144
	v_mul_f32_e32 v83, v67, v83
	v_cvt_pk_bf16_f32 v80, v80, v81
	v_cvt_pk_bf16_f32 v81, v82, v83
	global_store_dwordx2 v148, v[80:81], s[10:11] offset:0
	v_mul_f32_e32 v84, v84, v144
	v_mul_f32_e32 v84, v68, v84
	v_mul_f32_e32 v85, v85, v144
	v_mul_f32_e32 v85, v69, v85
	v_mul_f32_e32 v86, v86, v144
	v_mul_f32_e32 v86, v70, v86
	v_mul_f32_e32 v87, v87, v144
	v_mul_f32_e32 v87, v71, v87
	v_cvt_pk_bf16_f32 v84, v84, v85
	v_cvt_pk_bf16_f32 v85, v86, v87
	global_store_dwordx2 v148, v[84:85], s[10:11] offset:512
	v_mul_f32_e32 v88, v88, v144
	v_mul_f32_e32 v88, v72, v88
	v_mul_f32_e32 v89, v89, v144
	v_mul_f32_e32 v89, v73, v89
	v_mul_f32_e32 v90, v90, v144
	v_mul_f32_e32 v90, v74, v90
	v_mul_f32_e32 v91, v91, v144
	v_mul_f32_e32 v91, v75, v91
	v_cvt_pk_bf16_f32 v88, v88, v89
	v_cvt_pk_bf16_f32 v89, v90, v91
	global_store_dwordx2 v148, v[88:89], s[10:11] offset:1024
	v_mul_f32_e32 v92, v92, v144
	v_mul_f32_e32 v92, v76, v92
	v_mul_f32_e32 v93, v93, v144
	v_mul_f32_e32 v93, v77, v93
	v_mul_f32_e32 v94, v94, v144
	v_mul_f32_e32 v94, v78, v94
	v_mul_f32_e32 v95, v95, v144
	v_mul_f32_e32 v95, v79, v95
	v_cvt_pk_bf16_f32 v92, v92, v93
	v_cvt_pk_bf16_f32 v93, v94, v95
	global_store_dwordx2 v148, v[92:93], s[10:11] offset:1536
	s_add_u32 s10, s10, s18
	s_addc_u32 s11, s11, 0
	v_mul_f32_e32 v144, v96, v96
	v_fmac_f32_e32 v144, v97, v97
	v_fmac_f32_e32 v144, v98, v98
	v_fmac_f32_e32 v144, v99, v99
	v_fmac_f32_e32 v144, v100, v100
	v_fmac_f32_e32 v144, v101, v101
	v_fmac_f32_e32 v144, v102, v102
	v_fmac_f32_e32 v144, v103, v103
	v_fmac_f32_e32 v144, v104, v104
	v_fmac_f32_e32 v144, v105, v105
	v_fmac_f32_e32 v144, v106, v106
	v_fmac_f32_e32 v144, v107, v107
	v_fmac_f32_e32 v144, v108, v108
	v_fmac_f32_e32 v144, v109, v109
	v_fmac_f32_e32 v144, v110, v110
	v_fmac_f32_e32 v144, v111, v111
	s_nop 1
	v_add_f32_dpp v144, v144, v144 quad_perm:[1,0,3,2] row_mask:0xf bank_mask:0xf
	s_nop 1
	v_add_f32_dpp v144, v144, v144 quad_perm:[2,3,0,1] row_mask:0xf bank_mask:0xf
	s_nop 1
	v_add_f32_dpp v144, v144, v144 row_half_mirror row_mask:0xf bank_mask:0xf
	s_nop 1
	v_add_f32_dpp v144, v144, v144 row_mirror row_mask:0xf bank_mask:0xf
	v_mov_b32_e32 v145, v144
	s_nop 1
	v_permlane16_swap_b32_e32 v144, v145
	v_add_f32_e32 v144, v144, v145
	v_mov_b32_e32 v145, v144
	s_nop 1
	v_permlane32_swap_b32_e32 v144, v145
	v_add_f32_e32 v144, v144, v145
	v_fmamk_f32 v144, v144, 0x3a800000, v147
	v_mul_f32_e32 v145, 0x4b800000, v144
	v_cmp_gt_f32_e32 vcc, s19, v144
	s_nop 1
	v_cndmask_b32_e32 v144, v144, v145, vcc
	v_rsq_f32_e32 v144, v144
	s_nop 0
	v_mul_f32_e32 v145, 0x45800000, v144
	v_cndmask_b32_e32 v144, v144, v145, vcc
	v_mul_f32_e32 v96, v96, v144
	v_mul_f32_e32 v96, v64, v96
	v_mul_f32_e32 v97, v97, v144
	v_mul_f32_e32 v97, v65, v97
	v_mul_f32_e32 v98, v98, v144
	v_mul_f32_e32 v98, v66, v98
	v_mul_f32_e32 v99, v99, v144
	v_mul_f32_e32 v99, v67, v99
	v_cvt_pk_bf16_f32 v96, v96, v97
	v_cvt_pk_bf16_f32 v97, v98, v99
	global_store_dwordx2 v148, v[96:97], s[10:11] offset:0
	v_mul_f32_e32 v100, v100, v144
	v_mul_f32_e32 v100, v68, v100
	v_mul_f32_e32 v101, v101, v144
	v_mul_f32_e32 v101, v69, v101
	v_mul_f32_e32 v102, v102, v144
	v_mul_f32_e32 v102, v70, v102
	v_mul_f32_e32 v103, v103, v144
	v_mul_f32_e32 v103, v71, v103
	v_cvt_pk_bf16_f32 v100, v100, v101
	v_cvt_pk_bf16_f32 v101, v102, v103
	global_store_dwordx2 v148, v[100:101], s[10:11] offset:512
	v_mul_f32_e32 v104, v104, v144
	v_mul_f32_e32 v104, v72, v104
	v_mul_f32_e32 v105, v105, v144
	v_mul_f32_e32 v105, v73, v105
	v_mul_f32_e32 v106, v106, v144
	v_mul_f32_e32 v106, v74, v106
	v_mul_f32_e32 v107, v107, v144
	v_mul_f32_e32 v107, v75, v107
	v_cvt_pk_bf16_f32 v104, v104, v105
	v_cvt_pk_bf16_f32 v105, v106, v107
	global_store_dwordx2 v148, v[104:105], s[10:11] offset:1024
	v_mul_f32_e32 v108, v108, v144
	v_mul_f32_e32 v108, v76, v108
	v_mul_f32_e32 v109, v109, v144
	v_mul_f32_e32 v109, v77, v109
	v_mul_f32_e32 v110, v110, v144
	v_mul_f32_e32 v110, v78, v110
	v_mul_f32_e32 v111, v111, v144
	v_mul_f32_e32 v111, v79, v111
	v_cvt_pk_bf16_f32 v108, v108, v109
	v_cvt_pk_bf16_f32 v109, v110, v111
	global_store_dwordx2 v148, v[108:109], s[10:11] offset:1536
	s_add_u32 s10, s10, s18
	s_addc_u32 s11, s11, 0
	v_mul_f32_e32 v144, v112, v112
	v_fmac_f32_e32 v144, v113, v113
	v_fmac_f32_e32 v144, v114, v114
	v_fmac_f32_e32 v144, v115, v115
	v_fmac_f32_e32 v144, v116, v116
	v_fmac_f32_e32 v144, v117, v117
	v_fmac_f32_e32 v144, v118, v118
	v_fmac_f32_e32 v144, v119, v119
	v_fmac_f32_e32 v144, v120, v120
	v_fmac_f32_e32 v144, v121, v121
	v_fmac_f32_e32 v144, v122, v122
	v_fmac_f32_e32 v144, v123, v123
	v_fmac_f32_e32 v144, v124, v124
	v_fmac_f32_e32 v144, v125, v125
	v_fmac_f32_e32 v144, v126, v126
	v_fmac_f32_e32 v144, v127, v127
	s_nop 1
	v_add_f32_dpp v144, v144, v144 quad_perm:[1,0,3,2] row_mask:0xf bank_mask:0xf
	s_nop 1
	v_add_f32_dpp v144, v144, v144 quad_perm:[2,3,0,1] row_mask:0xf bank_mask:0xf
	s_nop 1
	v_add_f32_dpp v144, v144, v144 row_half_mirror row_mask:0xf bank_mask:0xf
	s_nop 1
	v_add_f32_dpp v144, v144, v144 row_mirror row_mask:0xf bank_mask:0xf
	v_mov_b32_e32 v145, v144
	s_nop 1
	v_permlane16_swap_b32_e32 v144, v145
	v_add_f32_e32 v144, v144, v145
	v_mov_b32_e32 v145, v144
	s_nop 1
	v_permlane32_swap_b32_e32 v144, v145
	v_add_f32_e32 v144, v144, v145
	v_fmamk_f32 v144, v144, 0x3a800000, v147
	v_mul_f32_e32 v145, 0x4b800000, v144
	v_cmp_gt_f32_e32 vcc, s19, v144
	s_nop 1
	v_cndmask_b32_e32 v144, v144, v145, vcc
	v_rsq_f32_e32 v144, v144
	s_nop 0
	v_mul_f32_e32 v145, 0x45800000, v144
	v_cndmask_b32_e32 v144, v144, v145, vcc
	v_mul_f32_e32 v112, v112, v144
	v_mul_f32_e32 v112, v64, v112
	v_mul_f32_e32 v113, v113, v144
	v_mul_f32_e32 v113, v65, v113
	v_mul_f32_e32 v114, v114, v144
	v_mul_f32_e32 v114, v66, v114
	v_mul_f32_e32 v115, v115, v144
	v_mul_f32_e32 v115, v67, v115
	v_cvt_pk_bf16_f32 v112, v112, v113
	v_cvt_pk_bf16_f32 v113, v114, v115
	global_store_dwordx2 v148, v[112:113], s[10:11] offset:0
	v_mul_f32_e32 v116, v116, v144
	v_mul_f32_e32 v116, v68, v116
	v_mul_f32_e32 v117, v117, v144
	v_mul_f32_e32 v117, v69, v117
	v_mul_f32_e32 v118, v118, v144
	v_mul_f32_e32 v118, v70, v118
	v_mul_f32_e32 v119, v119, v144
	v_mul_f32_e32 v119, v71, v119
	v_cvt_pk_bf16_f32 v116, v116, v117
	v_cvt_pk_bf16_f32 v117, v118, v119
	global_store_dwordx2 v148, v[116:117], s[10:11] offset:512
	v_mul_f32_e32 v120, v120, v144
	v_mul_f32_e32 v120, v72, v120
	v_mul_f32_e32 v121, v121, v144
	v_mul_f32_e32 v121, v73, v121
	v_mul_f32_e32 v122, v122, v144
	v_mul_f32_e32 v122, v74, v122
	v_mul_f32_e32 v123, v123, v144
	v_mul_f32_e32 v123, v75, v123
	v_cvt_pk_bf16_f32 v120, v120, v121
	v_cvt_pk_bf16_f32 v121, v122, v123
	global_store_dwordx2 v148, v[120:121], s[10:11] offset:1024
	v_mul_f32_e32 v124, v124, v144
	v_mul_f32_e32 v124, v76, v124
	v_mul_f32_e32 v125, v125, v144
	v_mul_f32_e32 v125, v77, v125
	v_mul_f32_e32 v126, v126, v144
	v_mul_f32_e32 v126, v78, v126
	v_mul_f32_e32 v127, v127, v144
	v_mul_f32_e32 v127, v79, v127
	v_cvt_pk_bf16_f32 v124, v124, v125
	v_cvt_pk_bf16_f32 v125, v126, v127
	global_store_dwordx2 v148, v[124:125], s[10:11] offset:1536
	s_add_u32 s10, s10, s18
	s_addc_u32 s11, s11, 0
	v_mul_f32_e32 v144, v128, v128
	v_fmac_f32_e32 v144, v129, v129
	v_fmac_f32_e32 v144, v130, v130
	v_fmac_f32_e32 v144, v131, v131
	v_fmac_f32_e32 v144, v132, v132
	v_fmac_f32_e32 v144, v133, v133
	v_fmac_f32_e32 v144, v134, v134
	v_fmac_f32_e32 v144, v135, v135
	v_fmac_f32_e32 v144, v136, v136
	v_fmac_f32_e32 v144, v137, v137
	v_fmac_f32_e32 v144, v138, v138
	v_fmac_f32_e32 v144, v139, v139
	v_fmac_f32_e32 v144, v140, v140
	v_fmac_f32_e32 v144, v141, v141
	v_fmac_f32_e32 v144, v142, v142
	v_fmac_f32_e32 v144, v143, v143
	s_nop 1
	v_add_f32_dpp v144, v144, v144 quad_perm:[1,0,3,2] row_mask:0xf bank_mask:0xf
	s_nop 1
	v_add_f32_dpp v144, v144, v144 quad_perm:[2,3,0,1] row_mask:0xf bank_mask:0xf
	s_nop 1
	v_add_f32_dpp v144, v144, v144 row_half_mirror row_mask:0xf bank_mask:0xf
	s_nop 1
	v_add_f32_dpp v144, v144, v144 row_mirror row_mask:0xf bank_mask:0xf
	v_mov_b32_e32 v145, v144
	s_nop 1
	v_permlane16_swap_b32_e32 v144, v145
	v_add_f32_e32 v144, v144, v145
	v_mov_b32_e32 v145, v144
	s_nop 1
	v_permlane32_swap_b32_e32 v144, v145
	v_add_f32_e32 v144, v144, v145
	v_fmamk_f32 v144, v144, 0x3a800000, v147
	v_mul_f32_e32 v145, 0x4b800000, v144
	v_cmp_gt_f32_e32 vcc, s19, v144
	s_nop 1
	v_cndmask_b32_e32 v144, v144, v145, vcc
	v_rsq_f32_e32 v144, v144
	s_nop 0
	v_mul_f32_e32 v145, 0x45800000, v144
	v_cndmask_b32_e32 v144, v144, v145, vcc
	v_mul_f32_e32 v128, v128, v144
	v_mul_f32_e32 v128, v64, v128
	v_mul_f32_e32 v129, v129, v144
	v_mul_f32_e32 v129, v65, v129
	v_mul_f32_e32 v130, v130, v144
	v_mul_f32_e32 v130, v66, v130
	v_mul_f32_e32 v131, v131, v144
	v_mul_f32_e32 v131, v67, v131
	v_cvt_pk_bf16_f32 v128, v128, v129
	v_cvt_pk_bf16_f32 v129, v130, v131
	global_store_dwordx2 v148, v[128:129], s[10:11] offset:0
	v_mul_f32_e32 v132, v132, v144
	v_mul_f32_e32 v132, v68, v132
	v_mul_f32_e32 v133, v133, v144
	v_mul_f32_e32 v133, v69, v133
	v_mul_f32_e32 v134, v134, v144
	v_mul_f32_e32 v134, v70, v134
	v_mul_f32_e32 v135, v135, v144
	v_mul_f32_e32 v135, v71, v135
	v_cvt_pk_bf16_f32 v132, v132, v133
	v_cvt_pk_bf16_f32 v133, v134, v135
	global_store_dwordx2 v148, v[132:133], s[10:11] offset:512
	v_mul_f32_e32 v136, v136, v144
	v_mul_f32_e32 v136, v72, v136
	v_mul_f32_e32 v137, v137, v144
	v_mul_f32_e32 v137, v73, v137
	v_mul_f32_e32 v138, v138, v144
	v_mul_f32_e32 v138, v74, v138
	v_mul_f32_e32 v139, v139, v144
	v_mul_f32_e32 v139, v75, v139
	v_cvt_pk_bf16_f32 v136, v136, v137
	v_cvt_pk_bf16_f32 v137, v138, v139
	global_store_dwordx2 v148, v[136:137], s[10:11] offset:1024
	v_mul_f32_e32 v140, v140, v144
	v_mul_f32_e32 v140, v76, v140
	v_mul_f32_e32 v141, v141, v144
	v_mul_f32_e32 v141, v77, v141
	v_mul_f32_e32 v142, v142, v144
	v_mul_f32_e32 v142, v78, v142
	v_mul_f32_e32 v143, v143, v144
	v_mul_f32_e32 v143, v79, v143
	v_cvt_pk_bf16_f32 v140, v140, v141
	v_cvt_pk_bf16_f32 v141, v142, v143
	global_store_dwordx2 v148, v[140:141], s[10:11] offset:1536
	s_add_u32 s10, s10, s18
	s_addc_u32 s11, s11, 0
	global_load_dwordx4 v[80:83], v211, s[8:9] offset:0
	global_load_dwordx4 v[84:87], v211, s[8:9] offset:1024
	global_load_dwordx4 v[88:91], v211, s[8:9] offset:2048
	global_load_dwordx4 v[92:95], v211, s[8:9] offset:3072
	s_add_u32 s8, s8, s16
	s_addc_u32 s9, s9, 0
	global_load_dwordx4 v[96:99], v211, s[8:9] offset:0
	global_load_dwordx4 v[100:103], v211, s[8:9] offset:1024
	global_load_dwordx4 v[104:107], v211, s[8:9] offset:2048
	global_load_dwordx4 v[108:111], v211, s[8:9] offset:3072
	s_add_u32 s8, s8, s16
	s_addc_u32 s9, s9, 0
	global_load_dwordx4 v[112:115], v211, s[8:9] offset:0
	global_load_dwordx4 v[116:119], v211, s[8:9] offset:1024
	global_load_dwordx4 v[120:123], v211, s[8:9] offset:2048
	global_load_dwordx4 v[124:127], v211, s[8:9] offset:3072
	s_add_u32 s8, s8, s16
	s_addc_u32 s9, s9, 0
	global_load_dwordx4 v[128:131], v211, s[8:9] offset:0
	global_load_dwordx4 v[132:135], v211, s[8:9] offset:1024
	global_load_dwordx4 v[136:139], v211, s[8:9] offset:2048
	global_load_dwordx4 v[140:143], v211, s[8:9] offset:3072
	s_add_u32 s8, s8, s16
	s_addc_u32 s9, s9, 0
	s_waitcnt vmcnt(0)
	v_mul_f32_e32 v144, v80, v80
	v_fmac_f32_e32 v144, v81, v81
	v_fmac_f32_e32 v144, v82, v82
	v_fmac_f32_e32 v144, v83, v83
	v_fmac_f32_e32 v144, v84, v84
	v_fmac_f32_e32 v144, v85, v85
	v_fmac_f32_e32 v144, v86, v86
	v_fmac_f32_e32 v144, v87, v87
	v_fmac_f32_e32 v144, v88, v88
	v_fmac_f32_e32 v144, v89, v89
	v_fmac_f32_e32 v144, v90, v90
	v_fmac_f32_e32 v144, v91, v91
	v_fmac_f32_e32 v144, v92, v92
	v_fmac_f32_e32 v144, v93, v93
	v_fmac_f32_e32 v144, v94, v94
	v_fmac_f32_e32 v144, v95, v95
	s_nop 1
	v_add_f32_dpp v144, v144, v144 quad_perm:[1,0,3,2] row_mask:0xf bank_mask:0xf
	s_nop 1
	v_add_f32_dpp v144, v144, v144 quad_perm:[2,3,0,1] row_mask:0xf bank_mask:0xf
	s_nop 1
	v_add_f32_dpp v144, v144, v144 row_half_mirror row_mask:0xf bank_mask:0xf
	s_nop 1
	v_add_f32_dpp v144, v144, v144 row_mirror row_mask:0xf bank_mask:0xf
	v_mov_b32_e32 v145, v144
	s_nop 1
	v_permlane16_swap_b32_e32 v144, v145
	v_add_f32_e32 v144, v144, v145
	v_mov_b32_e32 v145, v144
	s_nop 1
	v_permlane32_swap_b32_e32 v144, v145
	v_add_f32_e32 v144, v144, v145
	v_fmamk_f32 v144, v144, 0x3a800000, v147
	v_mul_f32_e32 v145, 0x4b800000, v144
	v_cmp_gt_f32_e32 vcc, s19, v144
	s_nop 1
	v_cndmask_b32_e32 v144, v144, v145, vcc
	v_rsq_f32_e32 v144, v144
	s_nop 0
	v_mul_f32_e32 v145, 0x45800000, v144
	v_cndmask_b32_e32 v144, v144, v145, vcc
	v_mul_f32_e32 v80, v80, v144
	v_mul_f32_e32 v80, v64, v80
	v_mul_f32_e32 v81, v81, v144
	v_mul_f32_e32 v81, v65, v81
	v_mul_f32_e32 v82, v82, v144
	v_mul_f32_e32 v82, v66, v82
	v_mul_f32_e32 v83, v83, v144
	v_mul_f32_e32 v83, v67, v83
	v_cvt_pk_bf16_f32 v80, v80, v81
	v_cvt_pk_bf16_f32 v81, v82, v83
	global_store_dwordx2 v148, v[80:81], s[10:11] offset:0
	v_mul_f32_e32 v84, v84, v144
	v_mul_f32_e32 v84, v68, v84
	v_mul_f32_e32 v85, v85, v144
	v_mul_f32_e32 v85, v69, v85
	v_mul_f32_e32 v86, v86, v144
	v_mul_f32_e32 v86, v70, v86
	v_mul_f32_e32 v87, v87, v144
	v_mul_f32_e32 v87, v71, v87
	v_cvt_pk_bf16_f32 v84, v84, v85
	v_cvt_pk_bf16_f32 v85, v86, v87
	global_store_dwordx2 v148, v[84:85], s[10:11] offset:512
	v_mul_f32_e32 v88, v88, v144
	v_mul_f32_e32 v88, v72, v88
	v_mul_f32_e32 v89, v89, v144
	v_mul_f32_e32 v89, v73, v89
	v_mul_f32_e32 v90, v90, v144
	v_mul_f32_e32 v90, v74, v90
	v_mul_f32_e32 v91, v91, v144
	v_mul_f32_e32 v91, v75, v91
	v_cvt_pk_bf16_f32 v88, v88, v89
	v_cvt_pk_bf16_f32 v89, v90, v91
	global_store_dwordx2 v148, v[88:89], s[10:11] offset:1024
	v_mul_f32_e32 v92, v92, v144
	v_mul_f32_e32 v92, v76, v92
	v_mul_f32_e32 v93, v93, v144
	v_mul_f32_e32 v93, v77, v93
	v_mul_f32_e32 v94, v94, v144
	v_mul_f32_e32 v94, v78, v94
	v_mul_f32_e32 v95, v95, v144
	v_mul_f32_e32 v95, v79, v95
	v_cvt_pk_bf16_f32 v92, v92, v93
	v_cvt_pk_bf16_f32 v93, v94, v95
	global_store_dwordx2 v148, v[92:93], s[10:11] offset:1536
	s_add_u32 s10, s10, s18
	s_addc_u32 s11, s11, 0
	v_mul_f32_e32 v144, v96, v96
	v_fmac_f32_e32 v144, v97, v97
	v_fmac_f32_e32 v144, v98, v98
	v_fmac_f32_e32 v144, v99, v99
	v_fmac_f32_e32 v144, v100, v100
	v_fmac_f32_e32 v144, v101, v101
	v_fmac_f32_e32 v144, v102, v102
	v_fmac_f32_e32 v144, v103, v103
	v_fmac_f32_e32 v144, v104, v104
	v_fmac_f32_e32 v144, v105, v105
	v_fmac_f32_e32 v144, v106, v106
	v_fmac_f32_e32 v144, v107, v107
	v_fmac_f32_e32 v144, v108, v108
	v_fmac_f32_e32 v144, v109, v109
	v_fmac_f32_e32 v144, v110, v110
	v_fmac_f32_e32 v144, v111, v111
	s_nop 1
	v_add_f32_dpp v144, v144, v144 quad_perm:[1,0,3,2] row_mask:0xf bank_mask:0xf
	s_nop 1
	v_add_f32_dpp v144, v144, v144 quad_perm:[2,3,0,1] row_mask:0xf bank_mask:0xf
	s_nop 1
	v_add_f32_dpp v144, v144, v144 row_half_mirror row_mask:0xf bank_mask:0xf
	s_nop 1
	v_add_f32_dpp v144, v144, v144 row_mirror row_mask:0xf bank_mask:0xf
	v_mov_b32_e32 v145, v144
	s_nop 1
	v_permlane16_swap_b32_e32 v144, v145
	v_add_f32_e32 v144, v144, v145
	v_mov_b32_e32 v145, v144
	s_nop 1
	v_permlane32_swap_b32_e32 v144, v145
	v_add_f32_e32 v144, v144, v145
	v_fmamk_f32 v144, v144, 0x3a800000, v147
	v_mul_f32_e32 v145, 0x4b800000, v144
	v_cmp_gt_f32_e32 vcc, s19, v144
	s_nop 1
	v_cndmask_b32_e32 v144, v144, v145, vcc
	v_rsq_f32_e32 v144, v144
	s_nop 0
	v_mul_f32_e32 v145, 0x45800000, v144
	v_cndmask_b32_e32 v144, v144, v145, vcc
	v_mul_f32_e32 v96, v96, v144
	v_mul_f32_e32 v96, v64, v96
	v_mul_f32_e32 v97, v97, v144
	v_mul_f32_e32 v97, v65, v97
	v_mul_f32_e32 v98, v98, v144
	v_mul_f32_e32 v98, v66, v98
	v_mul_f32_e32 v99, v99, v144
	v_mul_f32_e32 v99, v67, v99
	v_cvt_pk_bf16_f32 v96, v96, v97
	v_cvt_pk_bf16_f32 v97, v98, v99
	global_store_dwordx2 v148, v[96:97], s[10:11] offset:0
	v_mul_f32_e32 v100, v100, v144
	v_mul_f32_e32 v100, v68, v100
	v_mul_f32_e32 v101, v101, v144
	v_mul_f32_e32 v101, v69, v101
	v_mul_f32_e32 v102, v102, v144
	v_mul_f32_e32 v102, v70, v102
	v_mul_f32_e32 v103, v103, v144
	v_mul_f32_e32 v103, v71, v103
	v_cvt_pk_bf16_f32 v100, v100, v101
	v_cvt_pk_bf16_f32 v101, v102, v103
	global_store_dwordx2 v148, v[100:101], s[10:11] offset:512
	v_mul_f32_e32 v104, v104, v144
	v_mul_f32_e32 v104, v72, v104
	v_mul_f32_e32 v105, v105, v144
	v_mul_f32_e32 v105, v73, v105
	v_mul_f32_e32 v106, v106, v144
	v_mul_f32_e32 v106, v74, v106
	v_mul_f32_e32 v107, v107, v144
	v_mul_f32_e32 v107, v75, v107
	v_cvt_pk_bf16_f32 v104, v104, v105
	v_cvt_pk_bf16_f32 v105, v106, v107
	global_store_dwordx2 v148, v[104:105], s[10:11] offset:1024
	v_mul_f32_e32 v108, v108, v144
	v_mul_f32_e32 v108, v76, v108
	v_mul_f32_e32 v109, v109, v144
	v_mul_f32_e32 v109, v77, v109
	v_mul_f32_e32 v110, v110, v144
	v_mul_f32_e32 v110, v78, v110
	v_mul_f32_e32 v111, v111, v144
	v_mul_f32_e32 v111, v79, v111
	v_cvt_pk_bf16_f32 v108, v108, v109
	v_cvt_pk_bf16_f32 v109, v110, v111
	global_store_dwordx2 v148, v[108:109], s[10:11] offset:1536
	s_add_u32 s10, s10, s18
	s_addc_u32 s11, s11, 0
	v_mul_f32_e32 v144, v112, v112
	v_fmac_f32_e32 v144, v113, v113
	v_fmac_f32_e32 v144, v114, v114
	v_fmac_f32_e32 v144, v115, v115
	v_fmac_f32_e32 v144, v116, v116
	v_fmac_f32_e32 v144, v117, v117
	v_fmac_f32_e32 v144, v118, v118
	v_fmac_f32_e32 v144, v119, v119
	v_fmac_f32_e32 v144, v120, v120
	v_fmac_f32_e32 v144, v121, v121
	v_fmac_f32_e32 v144, v122, v122
	v_fmac_f32_e32 v144, v123, v123
	v_fmac_f32_e32 v144, v124, v124
	v_fmac_f32_e32 v144, v125, v125
	v_fmac_f32_e32 v144, v126, v126
	v_fmac_f32_e32 v144, v127, v127
	s_nop 1
	v_add_f32_dpp v144, v144, v144 quad_perm:[1,0,3,2] row_mask:0xf bank_mask:0xf
	s_nop 1
	v_add_f32_dpp v144, v144, v144 quad_perm:[2,3,0,1] row_mask:0xf bank_mask:0xf
	s_nop 1
	v_add_f32_dpp v144, v144, v144 row_half_mirror row_mask:0xf bank_mask:0xf
	s_nop 1
	v_add_f32_dpp v144, v144, v144 row_mirror row_mask:0xf bank_mask:0xf
	v_mov_b32_e32 v145, v144
	s_nop 1
	v_permlane16_swap_b32_e32 v144, v145
	v_add_f32_e32 v144, v144, v145
	v_mov_b32_e32 v145, v144
	s_nop 1
	v_permlane32_swap_b32_e32 v144, v145
	v_add_f32_e32 v144, v144, v145
	v_fmamk_f32 v144, v144, 0x3a800000, v147
	v_mul_f32_e32 v145, 0x4b800000, v144
	v_cmp_gt_f32_e32 vcc, s19, v144
	s_nop 1
	v_cndmask_b32_e32 v144, v144, v145, vcc
	v_rsq_f32_e32 v144, v144
	s_nop 0
	v_mul_f32_e32 v145, 0x45800000, v144
	v_cndmask_b32_e32 v144, v144, v145, vcc
	v_mul_f32_e32 v112, v112, v144
	v_mul_f32_e32 v112, v64, v112
	v_mul_f32_e32 v113, v113, v144
	v_mul_f32_e32 v113, v65, v113
	v_mul_f32_e32 v114, v114, v144
	v_mul_f32_e32 v114, v66, v114
	v_mul_f32_e32 v115, v115, v144
	v_mul_f32_e32 v115, v67, v115
	v_cvt_pk_bf16_f32 v112, v112, v113
	v_cvt_pk_bf16_f32 v113, v114, v115
	global_store_dwordx2 v148, v[112:113], s[10:11] offset:0
	v_mul_f32_e32 v116, v116, v144
	v_mul_f32_e32 v116, v68, v116
	v_mul_f32_e32 v117, v117, v144
	v_mul_f32_e32 v117, v69, v117
	v_mul_f32_e32 v118, v118, v144
	v_mul_f32_e32 v118, v70, v118
	v_mul_f32_e32 v119, v119, v144
	v_mul_f32_e32 v119, v71, v119
	v_cvt_pk_bf16_f32 v116, v116, v117
	v_cvt_pk_bf16_f32 v117, v118, v119
	global_store_dwordx2 v148, v[116:117], s[10:11] offset:512
	v_mul_f32_e32 v120, v120, v144
	v_mul_f32_e32 v120, v72, v120
	v_mul_f32_e32 v121, v121, v144
	v_mul_f32_e32 v121, v73, v121
	v_mul_f32_e32 v122, v122, v144
	v_mul_f32_e32 v122, v74, v122
	v_mul_f32_e32 v123, v123, v144
	v_mul_f32_e32 v123, v75, v123
	v_cvt_pk_bf16_f32 v120, v120, v121
	v_cvt_pk_bf16_f32 v121, v122, v123
	global_store_dwordx2 v148, v[120:121], s[10:11] offset:1024
	v_mul_f32_e32 v124, v124, v144
	v_mul_f32_e32 v124, v76, v124
	v_mul_f32_e32 v125, v125, v144
	v_mul_f32_e32 v125, v77, v125
	v_mul_f32_e32 v126, v126, v144
	v_mul_f32_e32 v126, v78, v126
	v_mul_f32_e32 v127, v127, v144
	v_mul_f32_e32 v127, v79, v127
	v_cvt_pk_bf16_f32 v124, v124, v125
	v_cvt_pk_bf16_f32 v125, v126, v127
	global_store_dwordx2 v148, v[124:125], s[10:11] offset:1536
	s_add_u32 s10, s10, s18
	s_addc_u32 s11, s11, 0
	v_mul_f32_e32 v144, v128, v128
	v_fmac_f32_e32 v144, v129, v129
	v_fmac_f32_e32 v144, v130, v130
	v_fmac_f32_e32 v144, v131, v131
	v_fmac_f32_e32 v144, v132, v132
	v_fmac_f32_e32 v144, v133, v133
	v_fmac_f32_e32 v144, v134, v134
	v_fmac_f32_e32 v144, v135, v135
	v_fmac_f32_e32 v144, v136, v136
	v_fmac_f32_e32 v144, v137, v137
	v_fmac_f32_e32 v144, v138, v138
	v_fmac_f32_e32 v144, v139, v139
	v_fmac_f32_e32 v144, v140, v140
	v_fmac_f32_e32 v144, v141, v141
	v_fmac_f32_e32 v144, v142, v142
	v_fmac_f32_e32 v144, v143, v143
	s_nop 1
	v_add_f32_dpp v144, v144, v144 quad_perm:[1,0,3,2] row_mask:0xf bank_mask:0xf
	s_nop 1
	v_add_f32_dpp v144, v144, v144 quad_perm:[2,3,0,1] row_mask:0xf bank_mask:0xf
	s_nop 1
	v_add_f32_dpp v144, v144, v144 row_half_mirror row_mask:0xf bank_mask:0xf
	s_nop 1
	v_add_f32_dpp v144, v144, v144 row_mirror row_mask:0xf bank_mask:0xf
	v_mov_b32_e32 v145, v144
	s_nop 1
	v_permlane16_swap_b32_e32 v144, v145
	v_add_f32_e32 v144, v144, v145
	v_mov_b32_e32 v145, v144
	s_nop 1
	v_permlane32_swap_b32_e32 v144, v145
	v_add_f32_e32 v144, v144, v145
	v_fmamk_f32 v144, v144, 0x3a800000, v147
	v_mul_f32_e32 v145, 0x4b800000, v144
	v_cmp_gt_f32_e32 vcc, s19, v144
	s_nop 1
	v_cndmask_b32_e32 v144, v144, v145, vcc
	v_rsq_f32_e32 v144, v144
	s_nop 0
	v_mul_f32_e32 v145, 0x45800000, v144
	v_cndmask_b32_e32 v144, v144, v145, vcc
	v_mul_f32_e32 v128, v128, v144
	v_mul_f32_e32 v128, v64, v128
	v_mul_f32_e32 v129, v129, v144
	v_mul_f32_e32 v129, v65, v129
	v_mul_f32_e32 v130, v130, v144
	v_mul_f32_e32 v130, v66, v130
	v_mul_f32_e32 v131, v131, v144
	v_mul_f32_e32 v131, v67, v131
	v_cvt_pk_bf16_f32 v128, v128, v129
	v_cvt_pk_bf16_f32 v129, v130, v131
	global_store_dwordx2 v148, v[128:129], s[10:11] offset:0
	v_mul_f32_e32 v132, v132, v144
	v_mul_f32_e32 v132, v68, v132
	v_mul_f32_e32 v133, v133, v144
	v_mul_f32_e32 v133, v69, v133
	v_mul_f32_e32 v134, v134, v144
	v_mul_f32_e32 v134, v70, v134
	v_mul_f32_e32 v135, v135, v144
	v_mul_f32_e32 v135, v71, v135
	v_cvt_pk_bf16_f32 v132, v132, v133
	v_cvt_pk_bf16_f32 v133, v134, v135
	global_store_dwordx2 v148, v[132:133], s[10:11] offset:512
	v_mul_f32_e32 v136, v136, v144
	v_mul_f32_e32 v136, v72, v136
	v_mul_f32_e32 v137, v137, v144
	v_mul_f32_e32 v137, v73, v137
	v_mul_f32_e32 v138, v138, v144
	v_mul_f32_e32 v138, v74, v138
	v_mul_f32_e32 v139, v139, v144
	v_mul_f32_e32 v139, v75, v139
	v_cvt_pk_bf16_f32 v136, v136, v137
	v_cvt_pk_bf16_f32 v137, v138, v139
	global_store_dwordx2 v148, v[136:137], s[10:11] offset:1024
	v_mul_f32_e32 v140, v140, v144
	v_mul_f32_e32 v140, v76, v140
	v_mul_f32_e32 v141, v141, v144
	v_mul_f32_e32 v141, v77, v141
	v_mul_f32_e32 v142, v142, v144
	v_mul_f32_e32 v142, v78, v142
	v_mul_f32_e32 v143, v143, v144
	v_mul_f32_e32 v143, v79, v143
	v_cvt_pk_bf16_f32 v140, v140, v141
	v_cvt_pk_bf16_f32 v141, v142, v143
	global_store_dwordx2 v148, v[140:141], s[10:11] offset:1536
	s_add_u32 s10, s10, s18
	s_addc_u32 s11, s11, 0
	s_waitcnt vmcnt(0)
	s_lshl_b32 s15, s92, 6
	s_add_u32 s101, s101, s15
	s_cmpk_lt_u32 s101, 0x8000
	s_cbranch_scc1 .Lgv0_chunk
	s_branch .LBB0_637

.Lgu1_start:
	s_mov_b64 exec, -1
	v_and_b32_e32 v171, 63, v205
	v_lshrrev_b32_e32 v172, 6, v205
	v_lshlrev_b32_e32 v160, 2, v171
	v_readfirstlane_b32 s34, v172
	v_and_b32_e32 v172, 7, v171
	v_lshlrev_b32_e32 v163, 6, v172
	v_mul_u32_u24_e32 v164, 24, v172
	s_nop 3
	s_lshl_b32 s13, s34, 14
	s_add_i32 s35, s93, s34
	v_lshrrev_b32_e32 v172, 3, v171
	v_lshl_add_u32 v162, v172, 2, s13
	v_add_u32_e32 v161, 0x2000, v162
	v_and_b32_e32 v172, 7, v171
	v_lshl_add_u32 v162, v172, 5, v162
	v_lshl_add_u32 v173, v171, 4, s13
	v_add_u32_e32 v175, s13, v160
	v_add_u32_e32 v174, 0x2000, v175
.Lgu1_chunk:
	s_movk_i32 s18, 0xc0
	s_lshl_b32 s19, s92, 13
	s_mov_b32 s10, 0xaaaaaaaa
	s_mov_b32 s11, 0xaaaaaaaa
	s_mov_b32 s100, 0xcccccccc
	s_mov_b32 s101, 0xcccccccc
	s_add_u32 s6, s26, 0xd800000
	s_addc_u32 s7, s27, 0
	s_lshl_b32 s13, s35, 9
	s_add_u32 s6, s6, s13
	s_addc_u32 s7, s7, 0
	s_lshl_b32 s14, s92, 11
	global_load_dword v16, v160, s[6:7]
	global_load_dword v17, v160, s[6:7] offset:256
	s_add_u32 s6, s6, s14
	s_addc_u32 s7, s7, 0
	global_load_dword v18, v160, s[6:7]
	global_load_dword v19, v160, s[6:7] offset:256
	s_add_u32 s6, s6, s14
	s_addc_u32 s7, s7, 0
	global_load_dword v20, v160, s[6:7]
	global_load_dword v21, v160, s[6:7] offset:256
	s_add_u32 s6, s6, s14
	s_addc_u32 s7, s7, 0
	global_load_dword v22, v160, s[6:7]
	global_load_dword v23, v160, s[6:7] offset:256
	s_add_u32 s6, s6, s14
	s_addc_u32 s7, s7, 0
	global_load_dword v24, v160, s[6:7]
	global_load_dword v25, v160, s[6:7] offset:256
	s_add_u32 s6, s6, s14
	s_addc_u32 s7, s7, 0
	global_load_dword v26, v160, s[6:7]
	global_load_dword v27, v160, s[6:7] offset:256
	s_add_u32 s6, s6, s14
	s_addc_u32 s7, s7, 0
	global_load_dword v28, v160, s[6:7]
	global_load_dword v29, v160, s[6:7] offset:256
	s_add_u32 s6, s6, s14
	s_addc_u32 s7, s7, 0
	global_load_dword v30, v160, s[6:7]
	global_load_dword v31, v160, s[6:7] offset:256
	s_add_u32 s6, s6, s14
	s_addc_u32 s7, s7, 0
	global_load_dword v32, v160, s[6:7]
	global_load_dword v33, v160, s[6:7] offset:256
	s_add_u32 s6, s6, s14
	s_addc_u32 s7, s7, 0
	global_load_dword v34, v160, s[6:7]
	global_load_dword v35, v160, s[6:7] offset:256
	s_add_u32 s6, s6, s14
	s_addc_u32 s7, s7, 0
	global_load_dword v36, v160, s[6:7]
	global_load_dword v37, v160, s[6:7] offset:256
	s_add_u32 s6, s6, s14
	s_addc_u32 s7, s7, 0
	global_load_dword v38, v160, s[6:7]
	global_load_dword v39, v160, s[6:7] offset:256
	s_add_u32 s6, s6, s14
	s_addc_u32 s7, s7, 0
	global_load_dword v40, v160, s[6:7]
	global_load_dword v41, v160, s[6:7] offset:256
	s_add_u32 s6, s6, s14
	s_addc_u32 s7, s7, 0
	global_load_dword v42, v160, s[6:7]
	global_load_dword v43, v160, s[6:7] offset:256
	s_add_u32 s6, s6, s14
	s_addc_u32 s7, s7, 0
	global_load_dword v44, v160, s[6:7]
	global_load_dword v45, v160, s[6:7] offset:256
	s_add_u32 s6, s6, s14
	s_addc_u32 s7, s7, 0
	global_load_dword v46, v160, s[6:7]
	global_load_dword v47, v160, s[6:7] offset:256
	s_add_u32 s6, s6, s14
	s_addc_u32 s7, s7, 0
	v_mov_b32_e32 v0, 0
	v_mov_b32_e32 v1, 0
	v_mov_b32_e32 v2, 0
	v_mov_b32_e32 v3, 0
	ds_write_b128 v173, v[0:3] offset:0
	ds_write_b128 v173, v[0:3] offset:1024
	ds_write_b128 v173, v[0:3] offset:2048
	ds_write_b128 v173, v[0:3] offset:3072
	ds_write_b128 v173, v[0:3] offset:4096
	ds_write_b128 v173, v[0:3] offset:5120
	ds_write_b128 v173, v[0:3] offset:6144
	ds_write_b128 v173, v[0:3] offset:7168
	s_waitcnt vmcnt(0)
	ds_write2st64_b32 v174, v16, v17 offset0:0 offset1:1
	ds_write2st64_b32 v174, v18, v19 offset0:2 offset1:3
	ds_write2st64_b32 v174, v20, v21 offset0:4 offset1:5
	ds_write2st64_b32 v174, v22, v23 offset0:6 offset1:7
	ds_write2st64_b32 v174, v24, v25 offset0:8 offset1:9
	ds_write2st64_b32 v174, v26, v27 offset0:10 offset1:11
	ds_write2st64_b32 v174, v28, v29 offset0:12 offset1:13
	ds_write2st64_b32 v174, v30, v31 offset0:14 offset1:15
	ds_write2st64_b32 v174, v32, v33 offset0:16 offset1:17
	ds_write2st64_b32 v174, v34, v35 offset0:18 offset1:19
	ds_write2st64_b32 v174, v36, v37 offset0:20 offset1:21
	ds_write2st64_b32 v174, v38, v39 offset0:22 offset1:23
	ds_write2st64_b32 v174, v40, v41 offset0:24 offset1:25
	ds_write2st64_b32 v174, v42, v43 offset0:26 offset1:27
	ds_write2st64_b32 v174, v44, v45 offset0:28 offset1:29
	ds_write2st64_b32 v174, v46, v47 offset0:30 offset1:31
	s_waitcnt lgkmcnt(0)
	s_add_u32 s0, s26, 0x2800000
	s_addc_u32 s1, s27, 0
	s_add_u32 s4, s26, 0x5800000
	s_addc_u32 s5, s27, 0
	s_lshl_b32 s13, s35, 11
	s_add_u32 s4, s4, s13
	s_addc_u32 s5, s5, 0
	s_mov_b32 s12, 0
	s_and_b32 s15, s12, 15
	s_lshr_b32 s16, s12, 4
	s_lshl_b32 s17, s15, 9
	s_mul_i32 s13, s15, s19
	s_lshl_b32 s14, s16, 9
	s_add_u32 s13, s13, s14
	s_add_u32 s6, s4, s13
	s_addc_u32 s7, s5, 0
	s_mul_i32 s13, s16, 0x300000
	s_add_u32 s0, s26, 0x2800000
	s_addc_u32 s1, s27, 0
	s_add_u32 s0, s0, s13
	s_addc_u32 s1, s1, 0
	v_mov_b32_e32 v165, v164
	v_add_u32_e32 v167, s17, v161
	v_add_u32_e32 v169, s17, v162
	ds_read2_b32 v[144:145], v167 offset0:0 offset1:8
	ds_read2_b32 v[146:147], v167 offset0:16 offset1:24
	ds_read2_b32 v[148:149], v167 offset0:32 offset1:40
	ds_read2_b32 v[150:151], v167 offset0:48 offset1:56
	global_load_dwordx4 v[112:115], v163, s[6:7]
	global_load_dwordx4 v[116:119], v163, s[6:7] offset:16
	global_load_dwordx4 v[120:123], v163, s[6:7] offset:32
	global_load_dwordx4 v[124:127], v163, s[6:7] offset:48
	s_waitcnt lgkmcnt(0)
	v_mad_u32_u24 v144, v144, s18, v165
	v_mad_u32_u24 v145, v145, s18, v165
	v_mad_u32_u24 v146, v146, s18, v165
	v_mad_u32_u24 v147, v147, s18, v165
	v_mad_u32_u24 v148, v148, s18, v165
	v_mad_u32_u24 v149, v149, s18, v165
	v_mad_u32_u24 v150, v150, s18, v165
	v_mad_u32_u24 v151, v151, s18, v165
	global_load_dwordx4 v[16:19], v144, s[0:1]
	global_load_dwordx2 v[20:21], v144, s[0:1] offset:16
	global_load_dwordx4 v[22:25], v145, s[0:1]
	global_load_dwordx2 v[26:27], v145, s[0:1] offset:16
	global_load_dwordx4 v[28:31], v146, s[0:1]
	global_load_dwordx2 v[32:33], v146, s[0:1] offset:16
	global_load_dwordx4 v[34:37], v147, s[0:1]
	global_load_dwordx2 v[38:39], v147, s[0:1] offset:16
	global_load_dwordx4 v[40:43], v148, s[0:1]
	global_load_dwordx2 v[44:45], v148, s[0:1] offset:16
	global_load_dwordx4 v[46:49], v149, s[0:1]
	global_load_dwordx2 v[50:51], v149, s[0:1] offset:16
	global_load_dwordx4 v[52:55], v150, s[0:1]
	global_load_dwordx2 v[56:57], v150, s[0:1] offset:16
	global_load_dwordx4 v[58:61], v151, s[0:1]
	global_load_dwordx2 v[62:63], v151, s[0:1] offset:16
	ds_read2_b32 v[176:177], v167 offset0:64 offset1:72
	ds_read2_b32 v[178:179], v167 offset0:80 offset1:88
	ds_read2_b32 v[180:181], v167 offset0:96 offset1:104
	ds_read2_b32 v[182:183], v167 offset0:112 offset1:120
.Lgu1_loop:
	s_waitcnt lgkmcnt(0)
	v_mad_u32_u24 v176, v176, s18, v165
	v_mad_u32_u24 v177, v177, s18, v165
	v_mad_u32_u24 v178, v178, s18, v165
	v_mad_u32_u24 v179, v179, s18, v165
	v_mad_u32_u24 v180, v180, s18, v165
	v_mad_u32_u24 v181, v181, s18, v165
	v_mad_u32_u24 v182, v182, s18, v165
	v_mad_u32_u24 v183, v183, s18, v165
	global_load_dwordx4 v[64:67], v176, s[0:1]
	global_load_dwordx2 v[68:69], v176, s[0:1] offset:16
	global_load_dwordx4 v[70:73], v177, s[0:1]
	global_load_dwordx2 v[74:75], v177, s[0:1] offset:16
	global_load_dwordx4 v[76:79], v178, s[0:1]
	global_load_dwordx2 v[80:81], v178, s[0:1] offset:16
	global_load_dwordx4 v[82:85], v179, s[0:1]
	global_load_dwordx2 v[86:87], v179, s[0:1] offset:16
	global_load_dwordx4 v[88:91], v180, s[0:1]
	global_load_dwordx2 v[92:93], v180, s[0:1] offset:16
	global_load_dwordx4 v[94:97], v181, s[0:1]
	global_load_dwordx2 v[98:99], v181, s[0:1] offset:16
	global_load_dwordx4 v[100:103], v182, s[0:1]
	global_load_dwordx2 v[104:105], v182, s[0:1] offset:16
	global_load_dwordx4 v[106:109], v183, s[0:1]
	global_load_dwordx2 v[110:111], v183, s[0:1] offset:16
	s_add_u32 s12, s12, 1
	s_and_b32 s15, s12, 15
	s_lshr_b32 s16, s12, 4
	s_lshl_b32 s17, s15, 9
	s_mul_i32 s13, s15, s19
	s_lshl_b32 s14, s16, 9
	s_add_u32 s13, s13, s14
	s_add_u32 s8, s4, s13
	s_addc_u32 s9, s5, 0
	s_mul_i32 s13, s16, 0x300000
	s_add_u32 s0, s26, 0x2800000
	s_addc_u32 s1, s27, 0
	s_add_u32 s0, s0, s13
	s_addc_u32 s1, s1, 0
	v_mov_b32_e32 v166, v164
	v_add_u32_e32 v168, s17, v161
	v_add_u32_e32 v170, s17, v162
	ds_read2_b32 v[144:145], v168 offset0:0 offset1:8
	ds_read2_b32 v[146:147], v168 offset0:16 offset1:24
	ds_read2_b32 v[148:149], v168 offset0:32 offset1:40
	ds_read2_b32 v[150:151], v168 offset0:48 offset1:56
	s_waitcnt vmcnt(30)
	v_cvt_scalef32_pk32_bf16_fp6 v[0:15], v[16:21], 1.0
	v_dot2_f32_bf16 v152, v0, v112, 0
	v_dot2_f32_bf16 v153, v1, v113, 0
	v_dot2_f32_bf16 v154, v2, v114, 0
	v_dot2_f32_bf16 v155, v3, v115, 0
	v_dot2c_f32_bf16_e32 v152, v4, v116
	v_dot2c_f32_bf16_e32 v153, v5, v117
	v_dot2c_f32_bf16_e32 v154, v6, v118
	v_dot2c_f32_bf16_e32 v155, v7, v119
	v_dot2c_f32_bf16_e32 v152, v8, v120
	v_dot2c_f32_bf16_e32 v153, v9, v121
	v_dot2c_f32_bf16_e32 v154, v10, v122
	v_dot2c_f32_bf16_e32 v155, v11, v123
	v_dot2c_f32_bf16_e32 v152, v12, v124
	v_dot2c_f32_bf16_e32 v153, v13, v125
	v_dot2c_f32_bf16_e32 v154, v14, v126
	v_dot2c_f32_bf16_e32 v155, v15, v127
	s_waitcnt vmcnt(28)
	v_cvt_scalef32_pk32_bf16_fp6 v[0:15], v[22:27], 1.0
	v_dot2_f32_bf16 v192, v0, v112, 0
	v_dot2_f32_bf16 v193, v1, v113, 0
	v_dot2_f32_bf16 v194, v2, v114, 0
	v_dot2_f32_bf16 v195, v3, v115, 0
	v_dot2c_f32_bf16_e32 v192, v4, v116
	v_dot2c_f32_bf16_e32 v193, v5, v117
	v_add_f32_e32 v156, v152, v153
	v_dot2c_f32_bf16_e32 v194, v6, v118
	v_dot2c_f32_bf16_e32 v195, v7, v119
	v_dot2c_f32_bf16_e32 v192, v8, v120
	v_add_f32_e32 v157, v154, v155
	v_dot2c_f32_bf16_e32 v193, v9, v121
	v_dot2c_f32_bf16_e32 v194, v10, v122
	v_dot2c_f32_bf16_e32 v195, v11, v123
	v_add_f32_e32 v184, v156, v157
	v_dot2c_f32_bf16_e32 v192, v12, v124
	v_dot2c_f32_bf16_e32 v193, v13, v125
	v_dot2c_f32_bf16_e32 v194, v14, v126
	v_dot2c_f32_bf16_e32 v195, v15, v127
	s_waitcnt vmcnt(26)
	v_cvt_scalef32_pk32_bf16_fp6 v[0:15], v[28:33], 1.0
	v_dot2_f32_bf16 v152, v0, v112, 0
	v_dot2_f32_bf16 v153, v1, v113, 0
	v_dot2_f32_bf16 v154, v2, v114, 0
	v_dot2_f32_bf16 v155, v3, v115, 0
	v_dot2c_f32_bf16_e32 v152, v4, v116
	v_dot2c_f32_bf16_e32 v153, v5, v117
	v_add_f32_e32 v156, v192, v193
	v_dot2c_f32_bf16_e32 v154, v6, v118
	v_dot2c_f32_bf16_e32 v155, v7, v119
	v_dot2c_f32_bf16_e32 v152, v8, v120
	v_add_f32_e32 v157, v194, v195
	v_dot2c_f32_bf16_e32 v153, v9, v121
	v_dot2c_f32_bf16_e32 v154, v10, v122
	v_dot2c_f32_bf16_e32 v155, v11, v123
	v_add_f32_e32 v185, v156, v157
	v_dot2c_f32_bf16_e32 v152, v12, v124
	v_dot2c_f32_bf16_e32 v153, v13, v125
	v_dot2c_f32_bf16_e32 v154, v14, v126
	v_dot2c_f32_bf16_e32 v155, v15, v127
	s_waitcnt vmcnt(24)
	v_cvt_scalef32_pk32_bf16_fp6 v[0:15], v[34:39], 1.0
	v_dot2_f32_bf16 v192, v0, v112, 0
	v_dot2_f32_bf16 v193, v1, v113, 0
	v_dot2_f32_bf16 v194, v2, v114, 0
	v_dot2_f32_bf16 v195, v3, v115, 0
	v_dot2c_f32_bf16_e32 v192, v4, v116
	v_dot2c_f32_bf16_e32 v193, v5, v117
	v_add_f32_e32 v156, v152, v153
	v_dot2c_f32_bf16_e32 v194, v6, v118
	v_dot2c_f32_bf16_e32 v195, v7, v119
	v_dot2c_f32_bf16_e32 v192, v8, v120
	v_add_f32_e32 v157, v154, v155
	v_dot2c_f32_bf16_e32 v193, v9, v121
	v_dot2c_f32_bf16_e32 v194, v10, v122
	v_dot2c_f32_bf16_e32 v195, v11, v123
	v_add_f32_e32 v186, v156, v157
	v_dot2c_f32_bf16_e32 v192, v12, v124
	v_dot2c_f32_bf16_e32 v193, v13, v125
	v_dot2c_f32_bf16_e32 v194, v14, v126
	v_dot2c_f32_bf16_e32 v195, v15, v127
	s_waitcnt vmcnt(22)
	v_cvt_scalef32_pk32_bf16_fp6 v[0:15], v[40:45], 1.0
	v_dot2_f32_bf16 v152, v0, v112, 0
	v_dot2_f32_bf16 v153, v1, v113, 0
	v_dot2_f32_bf16 v154, v2, v114, 0
	v_dot2_f32_bf16 v155, v3, v115, 0
	v_dot2c_f32_bf16_e32 v152, v4, v116
	v_dot2c_f32_bf16_e32 v153, v5, v117
	v_add_f32_e32 v156, v192, v193
	v_dot2c_f32_bf16_e32 v154, v6, v118
	v_dot2c_f32_bf16_e32 v155, v7, v119
	v_dot2c_f32_bf16_e32 v152, v8, v120
	v_add_f32_e32 v157, v194, v195
	v_dot2c_f32_bf16_e32 v153, v9, v121
	v_dot2c_f32_bf16_e32 v154, v10, v122
	v_dot2c_f32_bf16_e32 v155, v11, v123
	v_add_f32_e32 v187, v156, v157
	v_dot2c_f32_bf16_e32 v152, v12, v124
	v_dot2c_f32_bf16_e32 v153, v13, v125
	v_dot2c_f32_bf16_e32 v154, v14, v126
	v_dot2c_f32_bf16_e32 v155, v15, v127
	s_waitcnt vmcnt(20)
	v_cvt_scalef32_pk32_bf16_fp6 v[0:15], v[46:51], 1.0
	v_dot2_f32_bf16 v192, v0, v112, 0
	v_dot2_f32_bf16 v193, v1, v113, 0
	v_dot2_f32_bf16 v194, v2, v114, 0
	v_dot2_f32_bf16 v195, v3, v115, 0
	v_dot2c_f32_bf16_e32 v192, v4, v116
	v_dot2c_f32_bf16_e32 v193, v5, v117
	v_add_f32_e32 v156, v152, v153
	v_dot2c_f32_bf16_e32 v194, v6, v118
	v_dot2c_f32_bf16_e32 v195, v7, v119
	v_dot2c_f32_bf16_e32 v192, v8, v120
	v_add_f32_e32 v157, v154, v155
	v_dot2c_f32_bf16_e32 v193, v9, v121
	v_dot2c_f32_bf16_e32 v194, v10, v122
	v_dot2c_f32_bf16_e32 v195, v11, v123
	v_add_f32_e32 v188, v156, v157
	v_dot2c_f32_bf16_e32 v192, v12, v124
	v_dot2c_f32_bf16_e32 v193, v13, v125
	v_dot2c_f32_bf16_e32 v194, v14, v126
	v_dot2c_f32_bf16_e32 v195, v15, v127
	s_waitcnt vmcnt(18)
	v_cvt_scalef32_pk32_bf16_fp6 v[0:15], v[52:57], 1.0
	v_dot2_f32_bf16 v152, v0, v112, 0
	v_dot2_f32_bf16 v153, v1, v113, 0
	v_dot2_f32_bf16 v154, v2, v114, 0
	v_dot2_f32_bf16 v155, v3, v115, 0
	v_dot2c_f32_bf16_e32 v152, v4, v116
	v_dot2c_f32_bf16_e32 v153, v5, v117
	v_add_f32_e32 v156, v192, v193
	v_dot2c_f32_bf16_e32 v154, v6, v118
	v_dot2c_f32_bf16_e32 v155, v7, v119
	v_dot2c_f32_bf16_e32 v152, v8, v120
	v_add_f32_e32 v157, v194, v195
	v_dot2c_f32_bf16_e32 v153, v9, v121
	v_dot2c_f32_bf16_e32 v154, v10, v122
	v_dot2c_f32_bf16_e32 v155, v11, v123
	v_add_f32_e32 v189, v156, v157
	v_dot2c_f32_bf16_e32 v152, v12, v124
	v_dot2c_f32_bf16_e32 v153, v13, v125
	v_dot2c_f32_bf16_e32 v154, v14, v126
	v_dot2c_f32_bf16_e32 v155, v15, v127
	s_waitcnt vmcnt(16)
	v_cvt_scalef32_pk32_bf16_fp6 v[0:15], v[58:63], 1.0
	v_dot2_f32_bf16 v192, v0, v112, 0
	v_dot2_f32_bf16 v193, v1, v113, 0
	v_dot2_f32_bf16 v194, v2, v114, 0
	v_dot2_f32_bf16 v195, v3, v115, 0
	v_dot2c_f32_bf16_e32 v192, v4, v116
	v_dot2c_f32_bf16_e32 v193, v5, v117
	v_add_f32_e32 v156, v152, v153
	v_dot2c_f32_bf16_e32 v194, v6, v118
	v_dot2c_f32_bf16_e32 v195, v7, v119
	v_dot2c_f32_bf16_e32 v192, v8, v120
	v_add_f32_e32 v157, v154, v155
	v_dot2c_f32_bf16_e32 v193, v9, v121
	v_dot2c_f32_bf16_e32 v194, v10, v122
	v_dot2c_f32_bf16_e32 v195, v11, v123
	v_add_f32_e32 v190, v156, v157
	v_dot2c_f32_bf16_e32 v192, v12, v124
	v_dot2c_f32_bf16_e32 v193, v13, v125
	v_dot2c_f32_bf16_e32 v194, v14, v126
	v_dot2c_f32_bf16_e32 v195, v15, v127
	s_nop 1
	v_add_f32_e32 v156, v192, v193
	v_add_f32_e32 v157, v194, v195
	v_add_f32_e32 v191, v156, v157
	v_add_f32_dpp v184, v184, v184 row_half_mirror row_mask:0xf bank_mask:0x5
	v_add_f32_dpp v185, v185, v185 row_half_mirror row_mask:0xf bank_mask:0x5
	v_add_f32_dpp v186, v186, v186 row_half_mirror row_mask:0xf bank_mask:0x5
	v_add_f32_dpp v187, v187, v187 row_half_mirror row_mask:0xf bank_mask:0x5
	v_add_f32_dpp v184, v188, v188 row_half_mirror row_mask:0xf bank_mask:0xa
	v_add_f32_dpp v185, v189, v189 row_half_mirror row_mask:0xf bank_mask:0xa
	v_add_f32_dpp v186, v190, v190 row_half_mirror row_mask:0xf bank_mask:0xa
	v_add_f32_dpp v187, v191, v191 row_half_mirror row_mask:0xf bank_mask:0xa
	v_add_f32_dpp v184, v184, v184 quad_perm:[1,0,3,2] row_mask:0xf bank_mask:0xf
	v_add_f32_dpp v185, v185, v185 quad_perm:[1,0,3,2] row_mask:0xf bank_mask:0xf
	v_add_f32_dpp v186, v186, v186 quad_perm:[1,0,3,2] row_mask:0xf bank_mask:0xf
	v_add_f32_dpp v187, v187, v187 quad_perm:[1,0,3,2] row_mask:0xf bank_mask:0xf
	v_add_f32_dpp v184, v184, v184 quad_perm:[2,3,0,1] row_mask:0xf bank_mask:0xf
	v_add_f32_dpp v185, v185, v185 quad_perm:[2,3,0,1] row_mask:0xf bank_mask:0xf
	v_add_f32_dpp v186, v186, v186 quad_perm:[2,3,0,1] row_mask:0xf bank_mask:0xf
	v_add_f32_dpp v187, v187, v187 quad_perm:[2,3,0,1] row_mask:0xf bank_mask:0xf
	v_cndmask_b32_e64 v156, v184, v185, s[10:11]
	v_cndmask_b32_e64 v157, v186, v187, s[10:11]
	v_cndmask_b32_e64 v156, v156, v157, s[100:101]
	ds_add_f32 v169, v156 offset:0
	global_load_dwordx4 v[128:131], v163, s[8:9]
	global_load_dwordx4 v[132:135], v163, s[8:9] offset:16
	global_load_dwordx4 v[136:139], v163, s[8:9] offset:32
	global_load_dwordx4 v[140:143], v163, s[8:9] offset:48
	s_waitcnt lgkmcnt(0)
	v_mad_u32_u24 v144, v144, s18, v166
	v_mad_u32_u24 v145, v145, s18, v166
	v_mad_u32_u24 v146, v146, s18, v166
	v_mad_u32_u24 v147, v147, s18, v166
	v_mad_u32_u24 v148, v148, s18, v166
	v_mad_u32_u24 v149, v149, s18, v166
	v_mad_u32_u24 v150, v150, s18, v166
	v_mad_u32_u24 v151, v151, s18, v166
	global_load_dwordx4 v[16:19], v144, s[0:1]
	global_load_dwordx2 v[20:21], v144, s[0:1] offset:16
	global_load_dwordx4 v[22:25], v145, s[0:1]
	global_load_dwordx2 v[26:27], v145, s[0:1] offset:16
	global_load_dwordx4 v[28:31], v146, s[0:1]
	global_load_dwordx2 v[32:33], v146, s[0:1] offset:16
	global_load_dwordx4 v[34:37], v147, s[0:1]
	global_load_dwordx2 v[38:39], v147, s[0:1] offset:16
	global_load_dwordx4 v[40:43], v148, s[0:1]
	global_load_dwordx2 v[44:45], v148, s[0:1] offset:16
	global_load_dwordx4 v[46:49], v149, s[0:1]
	global_load_dwordx2 v[50:51], v149, s[0:1] offset:16
	global_load_dwordx4 v[52:55], v150, s[0:1]
	global_load_dwordx2 v[56:57], v150, s[0:1] offset:16
	global_load_dwordx4 v[58:61], v151, s[0:1]
	global_load_dwordx2 v[62:63], v151, s[0:1] offset:16
	ds_read2_b32 v[176:177], v168 offset0:64 offset1:72
	ds_read2_b32 v[178:179], v168 offset0:80 offset1:88
	ds_read2_b32 v[180:181], v168 offset0:96 offset1:104
	ds_read2_b32 v[182:183], v168 offset0:112 offset1:120
	s_waitcnt vmcnt(34)
	v_cvt_scalef32_pk32_bf16_fp6 v[0:15], v[64:69], 1.0
	v_dot2_f32_bf16 v152, v0, v112, 0
	v_dot2_f32_bf16 v153, v1, v113, 0
	v_dot2_f32_bf16 v154, v2, v114, 0
	v_dot2_f32_bf16 v155, v3, v115, 0
	v_dot2c_f32_bf16_e32 v152, v4, v116
	v_dot2c_f32_bf16_e32 v153, v5, v117
	v_dot2c_f32_bf16_e32 v154, v6, v118
	v_dot2c_f32_bf16_e32 v155, v7, v119
	v_dot2c_f32_bf16_e32 v152, v8, v120
	v_dot2c_f32_bf16_e32 v153, v9, v121
	v_dot2c_f32_bf16_e32 v154, v10, v122
	v_dot2c_f32_bf16_e32 v155, v11, v123
	v_dot2c_f32_bf16_e32 v152, v12, v124
	v_dot2c_f32_bf16_e32 v153, v13, v125
	v_dot2c_f32_bf16_e32 v154, v14, v126
	v_dot2c_f32_bf16_e32 v155, v15, v127
	s_waitcnt vmcnt(32)
	v_cvt_scalef32_pk32_bf16_fp6 v[0:15], v[70:75], 1.0
	v_dot2_f32_bf16 v192, v0, v112, 0
	v_dot2_f32_bf16 v193, v1, v113, 0
	v_dot2_f32_bf16 v194, v2, v114, 0
	v_dot2_f32_bf16 v195, v3, v115, 0
	v_dot2c_f32_bf16_e32 v192, v4, v116
	v_dot2c_f32_bf16_e32 v193, v5, v117
	v_add_f32_e32 v156, v152, v153
	v_dot2c_f32_bf16_e32 v194, v6, v118
	v_dot2c_f32_bf16_e32 v195, v7, v119
	v_dot2c_f32_bf16_e32 v192, v8, v120
	v_add_f32_e32 v157, v154, v155
	v_dot2c_f32_bf16_e32 v193, v9, v121
	v_dot2c_f32_bf16_e32 v194, v10, v122
	v_dot2c_f32_bf16_e32 v195, v11, v123
	v_add_f32_e32 v184, v156, v157
	v_dot2c_f32_bf16_e32 v192, v12, v124
	v_dot2c_f32_bf16_e32 v193, v13, v125
	v_dot2c_f32_bf16_e32 v194, v14, v126
	v_dot2c_f32_bf16_e32 v195, v15, v127
	s_waitcnt vmcnt(30)
	v_cvt_scalef32_pk32_bf16_fp6 v[0:15], v[76:81], 1.0
	v_dot2_f32_bf16 v152, v0, v112, 0
	v_dot2_f32_bf16 v153, v1, v113, 0
	v_dot2_f32_bf16 v154, v2, v114, 0
	v_dot2_f32_bf16 v155, v3, v115, 0
	v_dot2c_f32_bf16_e32 v152, v4, v116
	v_dot2c_f32_bf16_e32 v153, v5, v117
	v_add_f32_e32 v156, v192, v193
	v_dot2c_f32_bf16_e32 v154, v6, v118
	v_dot2c_f32_bf16_e32 v155, v7, v119
	v_dot2c_f32_bf16_e32 v152, v8, v120
	v_add_f32_e32 v157, v194, v195
	v_dot2c_f32_bf16_e32 v153, v9, v121
	v_dot2c_f32_bf16_e32 v154, v10, v122
	v_dot2c_f32_bf16_e32 v155, v11, v123
	v_add_f32_e32 v185, v156, v157
	v_dot2c_f32_bf16_e32 v152, v12, v124
	v_dot2c_f32_bf16_e32 v153, v13, v125
	v_dot2c_f32_bf16_e32 v154, v14, v126
	v_dot2c_f32_bf16_e32 v155, v15, v127
	s_waitcnt vmcnt(28)
	v_cvt_scalef32_pk32_bf16_fp6 v[0:15], v[82:87], 1.0
	v_dot2_f32_bf16 v192, v0, v112, 0
	v_dot2_f32_bf16 v193, v1, v113, 0
	v_dot2_f32_bf16 v194, v2, v114, 0
	v_dot2_f32_bf16 v195, v3, v115, 0
	v_dot2c_f32_bf16_e32 v192, v4, v116
	v_dot2c_f32_bf16_e32 v193, v5, v117
	v_add_f32_e32 v156, v152, v153
	v_dot2c_f32_bf16_e32 v194, v6, v118
	v_dot2c_f32_bf16_e32 v195, v7, v119
	v_dot2c_f32_bf16_e32 v192, v8, v120
	v_add_f32_e32 v157, v154, v155
	v_dot2c_f32_bf16_e32 v193, v9, v121
	v_dot2c_f32_bf16_e32 v194, v10, v122
	v_dot2c_f32_bf16_e32 v195, v11, v123
	v_add_f32_e32 v186, v156, v157
	v_dot2c_f32_bf16_e32 v192, v12, v124
	v_dot2c_f32_bf16_e32 v193, v13, v125
	v_dot2c_f32_bf16_e32 v194, v14, v126
	v_dot2c_f32_bf16_e32 v195, v15, v127
	s_waitcnt vmcnt(26)
	v_cvt_scalef32_pk32_bf16_fp6 v[0:15], v[88:93], 1.0
	v_dot2_f32_bf16 v152, v0, v112, 0
	v_dot2_f32_bf16 v153, v1, v113, 0
	v_dot2_f32_bf16 v154, v2, v114, 0
	v_dot2_f32_bf16 v155, v3, v115, 0
	v_dot2c_f32_bf16_e32 v152, v4, v116
	v_dot2c_f32_bf16_e32 v153, v5, v117
	v_add_f32_e32 v156, v192, v193
	v_dot2c_f32_bf16_e32 v154, v6, v118
	v_dot2c_f32_bf16_e32 v155, v7, v119
	v_dot2c_f32_bf16_e32 v152, v8, v120
	v_add_f32_e32 v157, v194, v195
	v_dot2c_f32_bf16_e32 v153, v9, v121
	v_dot2c_f32_bf16_e32 v154, v10, v122
	v_dot2c_f32_bf16_e32 v155, v11, v123
	v_add_f32_e32 v187, v156, v157
	v_dot2c_f32_bf16_e32 v152, v12, v124
	v_dot2c_f32_bf16_e32 v153, v13, v125
	v_dot2c_f32_bf16_e32 v154, v14, v126
	v_dot2c_f32_bf16_e32 v155, v15, v127
	s_waitcnt vmcnt(24)
	v_cvt_scalef32_pk32_bf16_fp6 v[0:15], v[94:99], 1.0
	v_dot2_f32_bf16 v192, v0, v112, 0
	v_dot2_f32_bf16 v193, v1, v113, 0
	v_dot2_f32_bf16 v194, v2, v114, 0
	v_dot2_f32_bf16 v195, v3, v115, 0
	v_dot2c_f32_bf16_e32 v192, v4, v116
	v_dot2c_f32_bf16_e32 v193, v5, v117
	v_add_f32_e32 v156, v152, v153
	v_dot2c_f32_bf16_e32 v194, v6, v118
	v_dot2c_f32_bf16_e32 v195, v7, v119
	v_dot2c_f32_bf16_e32 v192, v8, v120
	v_add_f32_e32 v157, v154, v155
	v_dot2c_f32_bf16_e32 v193, v9, v121
	v_dot2c_f32_bf16_e32 v194, v10, v122
	v_dot2c_f32_bf16_e32 v195, v11, v123
	v_add_f32_e32 v188, v156, v157
	v_dot2c_f32_bf16_e32 v192, v12, v124
	v_dot2c_f32_bf16_e32 v193, v13, v125
	v_dot2c_f32_bf16_e32 v194, v14, v126
	v_dot2c_f32_bf16_e32 v195, v15, v127
	s_waitcnt vmcnt(22)
	v_cvt_scalef32_pk32_bf16_fp6 v[0:15], v[100:105], 1.0
	v_dot2_f32_bf16 v152, v0, v112, 0
	v_dot2_f32_bf16 v153, v1, v113, 0
	v_dot2_f32_bf16 v154, v2, v114, 0
	v_dot2_f32_bf16 v155, v3, v115, 0
	v_dot2c_f32_bf16_e32 v152, v4, v116
	v_dot2c_f32_bf16_e32 v153, v5, v117
	v_add_f32_e32 v156, v192, v193
	v_dot2c_f32_bf16_e32 v154, v6, v118
	v_dot2c_f32_bf16_e32 v155, v7, v119
	v_dot2c_f32_bf16_e32 v152, v8, v120
	v_add_f32_e32 v157, v194, v195
	v_dot2c_f32_bf16_e32 v153, v9, v121
	v_dot2c_f32_bf16_e32 v154, v10, v122
	v_dot2c_f32_bf16_e32 v155, v11, v123
	v_add_f32_e32 v189, v156, v157
	v_dot2c_f32_bf16_e32 v152, v12, v124
	v_dot2c_f32_bf16_e32 v153, v13, v125
	v_dot2c_f32_bf16_e32 v154, v14, v126
	v_dot2c_f32_bf16_e32 v155, v15, v127
	s_waitcnt vmcnt(20)
	v_cvt_scalef32_pk32_bf16_fp6 v[0:15], v[106:111], 1.0
	v_dot2_f32_bf16 v192, v0, v112, 0
	v_dot2_f32_bf16 v193, v1, v113, 0
	v_dot2_f32_bf16 v194, v2, v114, 0
	v_dot2_f32_bf16 v195, v3, v115, 0
	v_dot2c_f32_bf16_e32 v192, v4, v116
	v_dot2c_f32_bf16_e32 v193, v5, v117
	v_add_f32_e32 v156, v152, v153
	v_dot2c_f32_bf16_e32 v194, v6, v118
	v_dot2c_f32_bf16_e32 v195, v7, v119
	v_dot2c_f32_bf16_e32 v192, v8, v120
	v_add_f32_e32 v157, v154, v155
	v_dot2c_f32_bf16_e32 v193, v9, v121
	v_dot2c_f32_bf16_e32 v194, v10, v122
	v_dot2c_f32_bf16_e32 v195, v11, v123
	v_add_f32_e32 v190, v156, v157
	v_dot2c_f32_bf16_e32 v192, v12, v124
	v_dot2c_f32_bf16_e32 v193, v13, v125
	v_dot2c_f32_bf16_e32 v194, v14, v126
	v_dot2c_f32_bf16_e32 v195, v15, v127
	s_nop 1
	v_add_f32_e32 v156, v192, v193
	v_add_f32_e32 v157, v194, v195
	v_add_f32_e32 v191, v156, v157
	v_add_f32_dpp v184, v184, v184 row_half_mirror row_mask:0xf bank_mask:0x5
	v_add_f32_dpp v185, v185, v185 row_half_mirror row_mask:0xf bank_mask:0x5
	v_add_f32_dpp v186, v186, v186 row_half_mirror row_mask:0xf bank_mask:0x5
	v_add_f32_dpp v187, v187, v187 row_half_mirror row_mask:0xf bank_mask:0x5
	v_add_f32_dpp v184, v188, v188 row_half_mirror row_mask:0xf bank_mask:0xa
	v_add_f32_dpp v185, v189, v189 row_half_mirror row_mask:0xf bank_mask:0xa
	v_add_f32_dpp v186, v190, v190 row_half_mirror row_mask:0xf bank_mask:0xa
	v_add_f32_dpp v187, v191, v191 row_half_mirror row_mask:0xf bank_mask:0xa
	v_add_f32_dpp v184, v184, v184 quad_perm:[1,0,3,2] row_mask:0xf bank_mask:0xf
	v_add_f32_dpp v185, v185, v185 quad_perm:[1,0,3,2] row_mask:0xf bank_mask:0xf
	v_add_f32_dpp v186, v186, v186 quad_perm:[1,0,3,2] row_mask:0xf bank_mask:0xf
	v_add_f32_dpp v187, v187, v187 quad_perm:[1,0,3,2] row_mask:0xf bank_mask:0xf
	v_add_f32_dpp v184, v184, v184 quad_perm:[2,3,0,1] row_mask:0xf bank_mask:0xf
	v_add_f32_dpp v185, v185, v185 quad_perm:[2,3,0,1] row_mask:0xf bank_mask:0xf
	v_add_f32_dpp v186, v186, v186 quad_perm:[2,3,0,1] row_mask:0xf bank_mask:0xf
	v_add_f32_dpp v187, v187, v187 quad_perm:[2,3,0,1] row_mask:0xf bank_mask:0xf
	v_cndmask_b32_e64 v156, v184, v185, s[10:11]
	v_cndmask_b32_e64 v157, v186, v187, s[10:11]
	v_cndmask_b32_e64 v156, v156, v157, s[100:101]
	ds_add_f32 v169, v156 offset:256
	s_waitcnt lgkmcnt(0)
	v_mad_u32_u24 v176, v176, s18, v166
	v_mad_u32_u24 v177, v177, s18, v166
	v_mad_u32_u24 v178, v178, s18, v166
	v_mad_u32_u24 v179, v179, s18, v166
	v_mad_u32_u24 v180, v180, s18, v166
	v_mad_u32_u24 v181, v181, s18, v166
	v_mad_u32_u24 v182, v182, s18, v166
	v_mad_u32_u24 v183, v183, s18, v166
	global_load_dwordx4 v[64:67], v176, s[0:1]
	global_load_dwordx2 v[68:69], v176, s[0:1] offset:16
	global_load_dwordx4 v[70:73], v177, s[0:1]
	global_load_dwordx2 v[74:75], v177, s[0:1] offset:16
	global_load_dwordx4 v[76:79], v178, s[0:1]
	global_load_dwordx2 v[80:81], v178, s[0:1] offset:16
	global_load_dwordx4 v[82:85], v179, s[0:1]
	global_load_dwordx2 v[86:87], v179, s[0:1] offset:16
	global_load_dwordx4 v[88:91], v180, s[0:1]
	global_load_dwordx2 v[92:93], v180, s[0:1] offset:16
	global_load_dwordx4 v[94:97], v181, s[0:1]
	global_load_dwordx2 v[98:99], v181, s[0:1] offset:16
	global_load_dwordx4 v[100:103], v182, s[0:1]
	global_load_dwordx2 v[104:105], v182, s[0:1] offset:16
	global_load_dwordx4 v[106:109], v183, s[0:1]
	global_load_dwordx2 v[110:111], v183, s[0:1] offset:16
	s_add_u32 s12, s12, 1
	s_and_b32 s12, s12, 63
	s_and_b32 s15, s12, 15
	s_lshr_b32 s16, s12, 4
	s_lshl_b32 s17, s15, 9
	s_mul_i32 s13, s15, s19
	s_lshl_b32 s14, s16, 9
	s_add_u32 s13, s13, s14
	s_add_u32 s6, s4, s13
	s_addc_u32 s7, s5, 0
	s_mul_i32 s13, s16, 0x300000
	s_add_u32 s0, s26, 0x2800000
	s_addc_u32 s1, s27, 0
	s_add_u32 s0, s0, s13
	s_addc_u32 s1, s1, 0
	v_mov_b32_e32 v165, v164
	v_add_u32_e32 v167, s17, v161
	v_add_u32_e32 v169, s17, v162
	ds_read2_b32 v[144:145], v167 offset0:0 offset1:8
	ds_read2_b32 v[146:147], v167 offset0:16 offset1:24
	ds_read2_b32 v[148:149], v167 offset0:32 offset1:40
	ds_read2_b32 v[150:151], v167 offset0:48 offset1:56
	s_waitcnt vmcnt(30)
	v_cvt_scalef32_pk32_bf16_fp6 v[0:15], v[16:21], 1.0
	v_dot2_f32_bf16 v152, v0, v128, 0
	v_dot2_f32_bf16 v153, v1, v129, 0
	v_dot2_f32_bf16 v154, v2, v130, 0
	v_dot2_f32_bf16 v155, v3, v131, 0
	v_dot2c_f32_bf16_e32 v152, v4, v132
	v_dot2c_f32_bf16_e32 v153, v5, v133
	v_dot2c_f32_bf16_e32 v154, v6, v134
	v_dot2c_f32_bf16_e32 v155, v7, v135
	v_dot2c_f32_bf16_e32 v152, v8, v136
	v_dot2c_f32_bf16_e32 v153, v9, v137
	v_dot2c_f32_bf16_e32 v154, v10, v138
	v_dot2c_f32_bf16_e32 v155, v11, v139
	v_dot2c_f32_bf16_e32 v152, v12, v140
	v_dot2c_f32_bf16_e32 v153, v13, v141
	v_dot2c_f32_bf16_e32 v154, v14, v142
	v_dot2c_f32_bf16_e32 v155, v15, v143
	s_waitcnt vmcnt(28)
	v_cvt_scalef32_pk32_bf16_fp6 v[0:15], v[22:27], 1.0
	v_dot2_f32_bf16 v192, v0, v128, 0
	v_dot2_f32_bf16 v193, v1, v129, 0
	v_dot2_f32_bf16 v194, v2, v130, 0
	v_dot2_f32_bf16 v195, v3, v131, 0
	v_dot2c_f32_bf16_e32 v192, v4, v132
	v_dot2c_f32_bf16_e32 v193, v5, v133
	v_add_f32_e32 v156, v152, v153
	v_dot2c_f32_bf16_e32 v194, v6, v134
	v_dot2c_f32_bf16_e32 v195, v7, v135
	v_dot2c_f32_bf16_e32 v192, v8, v136
	v_add_f32_e32 v157, v154, v155
	v_dot2c_f32_bf16_e32 v193, v9, v137
	v_dot2c_f32_bf16_e32 v194, v10, v138
	v_dot2c_f32_bf16_e32 v195, v11, v139
	v_add_f32_e32 v184, v156, v157
	v_dot2c_f32_bf16_e32 v192, v12, v140
	v_dot2c_f32_bf16_e32 v193, v13, v141
	v_dot2c_f32_bf16_e32 v194, v14, v142
	v_dot2c_f32_bf16_e32 v195, v15, v143
	s_waitcnt vmcnt(26)
	v_cvt_scalef32_pk32_bf16_fp6 v[0:15], v[28:33], 1.0
	v_dot2_f32_bf16 v152, v0, v128, 0
	v_dot2_f32_bf16 v153, v1, v129, 0
	v_dot2_f32_bf16 v154, v2, v130, 0
	v_dot2_f32_bf16 v155, v3, v131, 0
	v_dot2c_f32_bf16_e32 v152, v4, v132
	v_dot2c_f32_bf16_e32 v153, v5, v133
	v_add_f32_e32 v156, v192, v193
	v_dot2c_f32_bf16_e32 v154, v6, v134
	v_dot2c_f32_bf16_e32 v155, v7, v135
	v_dot2c_f32_bf16_e32 v152, v8, v136
	v_add_f32_e32 v157, v194, v195
	v_dot2c_f32_bf16_e32 v153, v9, v137
	v_dot2c_f32_bf16_e32 v154, v10, v138
	v_dot2c_f32_bf16_e32 v155, v11, v139
	v_add_f32_e32 v185, v156, v157
	v_dot2c_f32_bf16_e32 v152, v12, v140
	v_dot2c_f32_bf16_e32 v153, v13, v141
	v_dot2c_f32_bf16_e32 v154, v14, v142
	v_dot2c_f32_bf16_e32 v155, v15, v143
	s_waitcnt vmcnt(24)
	v_cvt_scalef32_pk32_bf16_fp6 v[0:15], v[34:39], 1.0
	v_dot2_f32_bf16 v192, v0, v128, 0
	v_dot2_f32_bf16 v193, v1, v129, 0
	v_dot2_f32_bf16 v194, v2, v130, 0
	v_dot2_f32_bf16 v195, v3, v131, 0
	v_dot2c_f32_bf16_e32 v192, v4, v132
	v_dot2c_f32_bf16_e32 v193, v5, v133
	v_add_f32_e32 v156, v152, v153
	v_dot2c_f32_bf16_e32 v194, v6, v134
	v_dot2c_f32_bf16_e32 v195, v7, v135
	v_dot2c_f32_bf16_e32 v192, v8, v136
	v_add_f32_e32 v157, v154, v155
	v_dot2c_f32_bf16_e32 v193, v9, v137
	v_dot2c_f32_bf16_e32 v194, v10, v138
	v_dot2c_f32_bf16_e32 v195, v11, v139
	v_add_f32_e32 v186, v156, v157
	v_dot2c_f32_bf16_e32 v192, v12, v140
	v_dot2c_f32_bf16_e32 v193, v13, v141
	v_dot2c_f32_bf16_e32 v194, v14, v142
	v_dot2c_f32_bf16_e32 v195, v15, v143
	s_waitcnt vmcnt(22)
	v_cvt_scalef32_pk32_bf16_fp6 v[0:15], v[40:45], 1.0
	v_dot2_f32_bf16 v152, v0, v128, 0
	v_dot2_f32_bf16 v153, v1, v129, 0
	v_dot2_f32_bf16 v154, v2, v130, 0
	v_dot2_f32_bf16 v155, v3, v131, 0
	v_dot2c_f32_bf16_e32 v152, v4, v132
	v_dot2c_f32_bf16_e32 v153, v5, v133
	v_add_f32_e32 v156, v192, v193
	v_dot2c_f32_bf16_e32 v154, v6, v134
	v_dot2c_f32_bf16_e32 v155, v7, v135
	v_dot2c_f32_bf16_e32 v152, v8, v136
	v_add_f32_e32 v157, v194, v195
	v_dot2c_f32_bf16_e32 v153, v9, v137
	v_dot2c_f32_bf16_e32 v154, v10, v138
	v_dot2c_f32_bf16_e32 v155, v11, v139
	v_add_f32_e32 v187, v156, v157
	v_dot2c_f32_bf16_e32 v152, v12, v140
	v_dot2c_f32_bf16_e32 v153, v13, v141
	v_dot2c_f32_bf16_e32 v154, v14, v142
	v_dot2c_f32_bf16_e32 v155, v15, v143
	s_waitcnt vmcnt(20)
	v_cvt_scalef32_pk32_bf16_fp6 v[0:15], v[46:51], 1.0
	v_dot2_f32_bf16 v192, v0, v128, 0
	v_dot2_f32_bf16 v193, v1, v129, 0
	v_dot2_f32_bf16 v194, v2, v130, 0
	v_dot2_f32_bf16 v195, v3, v131, 0
	v_dot2c_f32_bf16_e32 v192, v4, v132
	v_dot2c_f32_bf16_e32 v193, v5, v133
	v_add_f32_e32 v156, v152, v153
	v_dot2c_f32_bf16_e32 v194, v6, v134
	v_dot2c_f32_bf16_e32 v195, v7, v135
	v_dot2c_f32_bf16_e32 v192, v8, v136
	v_add_f32_e32 v157, v154, v155
	v_dot2c_f32_bf16_e32 v193, v9, v137
	v_dot2c_f32_bf16_e32 v194, v10, v138
	v_dot2c_f32_bf16_e32 v195, v11, v139
	v_add_f32_e32 v188, v156, v157
	v_dot2c_f32_bf16_e32 v192, v12, v140
	v_dot2c_f32_bf16_e32 v193, v13, v141
	v_dot2c_f32_bf16_e32 v194, v14, v142
	v_dot2c_f32_bf16_e32 v195, v15, v143
	s_waitcnt vmcnt(18)
	v_cvt_scalef32_pk32_bf16_fp6 v[0:15], v[52:57], 1.0
	v_dot2_f32_bf16 v152, v0, v128, 0
	v_dot2_f32_bf16 v153, v1, v129, 0
	v_dot2_f32_bf16 v154, v2, v130, 0
	v_dot2_f32_bf16 v155, v3, v131, 0
	v_dot2c_f32_bf16_e32 v152, v4, v132
	v_dot2c_f32_bf16_e32 v153, v5, v133
	v_add_f32_e32 v156, v192, v193
	v_dot2c_f32_bf16_e32 v154, v6, v134
	v_dot2c_f32_bf16_e32 v155, v7, v135
	v_dot2c_f32_bf16_e32 v152, v8, v136
	v_add_f32_e32 v157, v194, v195
	v_dot2c_f32_bf16_e32 v153, v9, v137
	v_dot2c_f32_bf16_e32 v154, v10, v138
	v_dot2c_f32_bf16_e32 v155, v11, v139
	v_add_f32_e32 v189, v156, v157
	v_dot2c_f32_bf16_e32 v152, v12, v140
	v_dot2c_f32_bf16_e32 v153, v13, v141
	v_dot2c_f32_bf16_e32 v154, v14, v142
	v_dot2c_f32_bf16_e32 v155, v15, v143
	s_waitcnt vmcnt(16)
	v_cvt_scalef32_pk32_bf16_fp6 v[0:15], v[58:63], 1.0
	v_dot2_f32_bf16 v192, v0, v128, 0
	v_dot2_f32_bf16 v193, v1, v129, 0
	v_dot2_f32_bf16 v194, v2, v130, 0
	v_dot2_f32_bf16 v195, v3, v131, 0
	v_dot2c_f32_bf16_e32 v192, v4, v132
	v_dot2c_f32_bf16_e32 v193, v5, v133
	v_add_f32_e32 v156, v152, v153
	v_dot2c_f32_bf16_e32 v194, v6, v134
	v_dot2c_f32_bf16_e32 v195, v7, v135
	v_dot2c_f32_bf16_e32 v192, v8, v136
	v_add_f32_e32 v157, v154, v155
	v_dot2c_f32_bf16_e32 v193, v9, v137
	v_dot2c_f32_bf16_e32 v194, v10, v138
	v_dot2c_f32_bf16_e32 v195, v11, v139
	v_add_f32_e32 v190, v156, v157
	v_dot2c_f32_bf16_e32 v192, v12, v140
	v_dot2c_f32_bf16_e32 v193, v13, v141
	v_dot2c_f32_bf16_e32 v194, v14, v142
	v_dot2c_f32_bf16_e32 v195, v15, v143
	s_nop 1
	v_add_f32_e32 v156, v192, v193
	v_add_f32_e32 v157, v194, v195
	v_add_f32_e32 v191, v156, v157
	v_add_f32_dpp v184, v184, v184 row_half_mirror row_mask:0xf bank_mask:0x5
	v_add_f32_dpp v185, v185, v185 row_half_mirror row_mask:0xf bank_mask:0x5
	v_add_f32_dpp v186, v186, v186 row_half_mirror row_mask:0xf bank_mask:0x5
	v_add_f32_dpp v187, v187, v187 row_half_mirror row_mask:0xf bank_mask:0x5
	v_add_f32_dpp v184, v188, v188 row_half_mirror row_mask:0xf bank_mask:0xa
	v_add_f32_dpp v185, v189, v189 row_half_mirror row_mask:0xf bank_mask:0xa
	v_add_f32_dpp v186, v190, v190 row_half_mirror row_mask:0xf bank_mask:0xa
	v_add_f32_dpp v187, v191, v191 row_half_mirror row_mask:0xf bank_mask:0xa
	v_add_f32_dpp v184, v184, v184 quad_perm:[1,0,3,2] row_mask:0xf bank_mask:0xf
	v_add_f32_dpp v185, v185, v185 quad_perm:[1,0,3,2] row_mask:0xf bank_mask:0xf
	v_add_f32_dpp v186, v186, v186 quad_perm:[1,0,3,2] row_mask:0xf bank_mask:0xf
	v_add_f32_dpp v187, v187, v187 quad_perm:[1,0,3,2] row_mask:0xf bank_mask:0xf
	v_add_f32_dpp v184, v184, v184 quad_perm:[2,3,0,1] row_mask:0xf bank_mask:0xf
	v_add_f32_dpp v185, v185, v185 quad_perm:[2,3,0,1] row_mask:0xf bank_mask:0xf
	v_add_f32_dpp v186, v186, v186 quad_perm:[2,3,0,1] row_mask:0xf bank_mask:0xf
	v_add_f32_dpp v187, v187, v187 quad_perm:[2,3,0,1] row_mask:0xf bank_mask:0xf
	v_cndmask_b32_e64 v156, v184, v185, s[10:11]
	v_cndmask_b32_e64 v157, v186, v187, s[10:11]
	v_cndmask_b32_e64 v156, v156, v157, s[100:101]
	ds_add_f32 v170, v156 offset:0
	global_load_dwordx4 v[112:115], v163, s[6:7]
	global_load_dwordx4 v[116:119], v163, s[6:7] offset:16
	global_load_dwordx4 v[120:123], v163, s[6:7] offset:32
	global_load_dwordx4 v[124:127], v163, s[6:7] offset:48
	s_waitcnt lgkmcnt(0)
	v_mad_u32_u24 v144, v144, s18, v165
	v_mad_u32_u24 v145, v145, s18, v165
	v_mad_u32_u24 v146, v146, s18, v165
	v_mad_u32_u24 v147, v147, s18, v165
	v_mad_u32_u24 v148, v148, s18, v165
	v_mad_u32_u24 v149, v149, s18, v165
	v_mad_u32_u24 v150, v150, s18, v165
	v_mad_u32_u24 v151, v151, s18, v165
	global_load_dwordx4 v[16:19], v144, s[0:1]
	global_load_dwordx2 v[20:21], v144, s[0:1] offset:16
	global_load_dwordx4 v[22:25], v145, s[0:1]
	global_load_dwordx2 v[26:27], v145, s[0:1] offset:16
	global_load_dwordx4 v[28:31], v146, s[0:1]
	global_load_dwordx2 v[32:33], v146, s[0:1] offset:16
	global_load_dwordx4 v[34:37], v147, s[0:1]
	global_load_dwordx2 v[38:39], v147, s[0:1] offset:16
	global_load_dwordx4 v[40:43], v148, s[0:1]
	global_load_dwordx2 v[44:45], v148, s[0:1] offset:16
	global_load_dwordx4 v[46:49], v149, s[0:1]
	global_load_dwordx2 v[50:51], v149, s[0:1] offset:16
	global_load_dwordx4 v[52:55], v150, s[0:1]
	global_load_dwordx2 v[56:57], v150, s[0:1] offset:16
	global_load_dwordx4 v[58:61], v151, s[0:1]
	global_load_dwordx2 v[62:63], v151, s[0:1] offset:16
	ds_read2_b32 v[176:177], v167 offset0:64 offset1:72
	ds_read2_b32 v[178:179], v167 offset0:80 offset1:88
	ds_read2_b32 v[180:181], v167 offset0:96 offset1:104
	ds_read2_b32 v[182:183], v167 offset0:112 offset1:120
	s_waitcnt vmcnt(34)
	v_cvt_scalef32_pk32_bf16_fp6 v[0:15], v[64:69], 1.0
	v_dot2_f32_bf16 v152, v0, v128, 0
	v_dot2_f32_bf16 v153, v1, v129, 0
	v_dot2_f32_bf16 v154, v2, v130, 0
	v_dot2_f32_bf16 v155, v3, v131, 0
	v_dot2c_f32_bf16_e32 v152, v4, v132
	v_dot2c_f32_bf16_e32 v153, v5, v133
	v_dot2c_f32_bf16_e32 v154, v6, v134
	v_dot2c_f32_bf16_e32 v155, v7, v135
	v_dot2c_f32_bf16_e32 v152, v8, v136
	v_dot2c_f32_bf16_e32 v153, v9, v137
	v_dot2c_f32_bf16_e32 v154, v10, v138
	v_dot2c_f32_bf16_e32 v155, v11, v139
	v_dot2c_f32_bf16_e32 v152, v12, v140
	v_dot2c_f32_bf16_e32 v153, v13, v141
	v_dot2c_f32_bf16_e32 v154, v14, v142
	v_dot2c_f32_bf16_e32 v155, v15, v143
	s_waitcnt vmcnt(32)
	v_cvt_scalef32_pk32_bf16_fp6 v[0:15], v[70:75], 1.0
	v_dot2_f32_bf16 v192, v0, v128, 0
	v_dot2_f32_bf16 v193, v1, v129, 0
	v_dot2_f32_bf16 v194, v2, v130, 0
	v_dot2_f32_bf16 v195, v3, v131, 0
	v_dot2c_f32_bf16_e32 v192, v4, v132
	v_dot2c_f32_bf16_e32 v193, v5, v133
	v_add_f32_e32 v156, v152, v153
	v_dot2c_f32_bf16_e32 v194, v6, v134
	v_dot2c_f32_bf16_e32 v195, v7, v135
	v_dot2c_f32_bf16_e32 v192, v8, v136
	v_add_f32_e32 v157, v154, v155
	v_dot2c_f32_bf16_e32 v193, v9, v137
	v_dot2c_f32_bf16_e32 v194, v10, v138
	v_dot2c_f32_bf16_e32 v195, v11, v139
	v_add_f32_e32 v184, v156, v157
	v_dot2c_f32_bf16_e32 v192, v12, v140
	v_dot2c_f32_bf16_e32 v193, v13, v141
	v_dot2c_f32_bf16_e32 v194, v14, v142
	v_dot2c_f32_bf16_e32 v195, v15, v143
	s_waitcnt vmcnt(30)
	v_cvt_scalef32_pk32_bf16_fp6 v[0:15], v[76:81], 1.0
	v_dot2_f32_bf16 v152, v0, v128, 0
	v_dot2_f32_bf16 v153, v1, v129, 0
	v_dot2_f32_bf16 v154, v2, v130, 0
	v_dot2_f32_bf16 v155, v3, v131, 0
	v_dot2c_f32_bf16_e32 v152, v4, v132
	v_dot2c_f32_bf16_e32 v153, v5, v133
	v_add_f32_e32 v156, v192, v193
	v_dot2c_f32_bf16_e32 v154, v6, v134
	v_dot2c_f32_bf16_e32 v155, v7, v135
	v_dot2c_f32_bf16_e32 v152, v8, v136
	v_add_f32_e32 v157, v194, v195
	v_dot2c_f32_bf16_e32 v153, v9, v137
	v_dot2c_f32_bf16_e32 v154, v10, v138
	v_dot2c_f32_bf16_e32 v155, v11, v139
	v_add_f32_e32 v185, v156, v157
	v_dot2c_f32_bf16_e32 v152, v12, v140
	v_dot2c_f32_bf16_e32 v153, v13, v141
	v_dot2c_f32_bf16_e32 v154, v14, v142
	v_dot2c_f32_bf16_e32 v155, v15, v143
	s_waitcnt vmcnt(28)
	v_cvt_scalef32_pk32_bf16_fp6 v[0:15], v[82:87], 1.0
	v_dot2_f32_bf16 v192, v0, v128, 0
	v_dot2_f32_bf16 v193, v1, v129, 0
	v_dot2_f32_bf16 v194, v2, v130, 0
	v_dot2_f32_bf16 v195, v3, v131, 0
	v_dot2c_f32_bf16_e32 v192, v4, v132
	v_dot2c_f32_bf16_e32 v193, v5, v133
	v_add_f32_e32 v156, v152, v153
	v_dot2c_f32_bf16_e32 v194, v6, v134
	v_dot2c_f32_bf16_e32 v195, v7, v135
	v_dot2c_f32_bf16_e32 v192, v8, v136
	v_add_f32_e32 v157, v154, v155
	v_dot2c_f32_bf16_e32 v193, v9, v137
	v_dot2c_f32_bf16_e32 v194, v10, v138
	v_dot2c_f32_bf16_e32 v195, v11, v139
	v_add_f32_e32 v186, v156, v157
	v_dot2c_f32_bf16_e32 v192, v12, v140
	v_dot2c_f32_bf16_e32 v193, v13, v141
	v_dot2c_f32_bf16_e32 v194, v14, v142
	v_dot2c_f32_bf16_e32 v195, v15, v143
	s_waitcnt vmcnt(26)
	v_cvt_scalef32_pk32_bf16_fp6 v[0:15], v[88:93], 1.0
	v_dot2_f32_bf16 v152, v0, v128, 0
	v_dot2_f32_bf16 v153, v1, v129, 0
	v_dot2_f32_bf16 v154, v2, v130, 0
	v_dot2_f32_bf16 v155, v3, v131, 0
	v_dot2c_f32_bf16_e32 v152, v4, v132
	v_dot2c_f32_bf16_e32 v153, v5, v133
	v_add_f32_e32 v156, v192, v193
	v_dot2c_f32_bf16_e32 v154, v6, v134
	v_dot2c_f32_bf16_e32 v155, v7, v135
	v_dot2c_f32_bf16_e32 v152, v8, v136
	v_add_f32_e32 v157, v194, v195
	v_dot2c_f32_bf16_e32 v153, v9, v137
	v_dot2c_f32_bf16_e32 v154, v10, v138
	v_dot2c_f32_bf16_e32 v155, v11, v139
	v_add_f32_e32 v187, v156, v157
	v_dot2c_f32_bf16_e32 v152, v12, v140
	v_dot2c_f32_bf16_e32 v153, v13, v141
	v_dot2c_f32_bf16_e32 v154, v14, v142
	v_dot2c_f32_bf16_e32 v155, v15, v143
	s_waitcnt vmcnt(24)
	v_cvt_scalef32_pk32_bf16_fp6 v[0:15], v[94:99], 1.0
	v_dot2_f32_bf16 v192, v0, v128, 0
	v_dot2_f32_bf16 v193, v1, v129, 0
	v_dot2_f32_bf16 v194, v2, v130, 0
	v_dot2_f32_bf16 v195, v3, v131, 0
	v_dot2c_f32_bf16_e32 v192, v4, v132
	v_dot2c_f32_bf16_e32 v193, v5, v133
	v_add_f32_e32 v156, v152, v153
	v_dot2c_f32_bf16_e32 v194, v6, v134
	v_dot2c_f32_bf16_e32 v195, v7, v135
	v_dot2c_f32_bf16_e32 v192, v8, v136
	v_add_f32_e32 v157, v154, v155
	v_dot2c_f32_bf16_e32 v193, v9, v137
	v_dot2c_f32_bf16_e32 v194, v10, v138
	v_dot2c_f32_bf16_e32 v195, v11, v139
	v_add_f32_e32 v188, v156, v157
	v_dot2c_f32_bf16_e32 v192, v12, v140
	v_dot2c_f32_bf16_e32 v193, v13, v141
	v_dot2c_f32_bf16_e32 v194, v14, v142
	v_dot2c_f32_bf16_e32 v195, v15, v143
	s_waitcnt vmcnt(22)
	v_cvt_scalef32_pk32_bf16_fp6 v[0:15], v[100:105], 1.0
	v_dot2_f32_bf16 v152, v0, v128, 0
	v_dot2_f32_bf16 v153, v1, v129, 0
	v_dot2_f32_bf16 v154, v2, v130, 0
	v_dot2_f32_bf16 v155, v3, v131, 0
	v_dot2c_f32_bf16_e32 v152, v4, v132
	v_dot2c_f32_bf16_e32 v153, v5, v133
	v_add_f32_e32 v156, v192, v193
	v_dot2c_f32_bf16_e32 v154, v6, v134
	v_dot2c_f32_bf16_e32 v155, v7, v135
	v_dot2c_f32_bf16_e32 v152, v8, v136
	v_add_f32_e32 v157, v194, v195
	v_dot2c_f32_bf16_e32 v153, v9, v137
	v_dot2c_f32_bf16_e32 v154, v10, v138
	v_dot2c_f32_bf16_e32 v155, v11, v139
	v_add_f32_e32 v189, v156, v157
	v_dot2c_f32_bf16_e32 v152, v12, v140
	v_dot2c_f32_bf16_e32 v153, v13, v141
	v_dot2c_f32_bf16_e32 v154, v14, v142
	v_dot2c_f32_bf16_e32 v155, v15, v143
	s_waitcnt vmcnt(20)
	v_cvt_scalef32_pk32_bf16_fp6 v[0:15], v[106:111], 1.0
	v_dot2_f32_bf16 v192, v0, v128, 0
	v_dot2_f32_bf16 v193, v1, v129, 0
	v_dot2_f32_bf16 v194, v2, v130, 0
	v_dot2_f32_bf16 v195, v3, v131, 0
	v_dot2c_f32_bf16_e32 v192, v4, v132
	v_dot2c_f32_bf16_e32 v193, v5, v133
	v_add_f32_e32 v156, v152, v153
	v_dot2c_f32_bf16_e32 v194, v6, v134
	v_dot2c_f32_bf16_e32 v195, v7, v135
	v_dot2c_f32_bf16_e32 v192, v8, v136
	v_add_f32_e32 v157, v154, v155
	v_dot2c_f32_bf16_e32 v193, v9, v137
	v_dot2c_f32_bf16_e32 v194, v10, v138
	v_dot2c_f32_bf16_e32 v195, v11, v139
	v_add_f32_e32 v190, v156, v157
	v_dot2c_f32_bf16_e32 v192, v12, v140
	v_dot2c_f32_bf16_e32 v193, v13, v141
	v_dot2c_f32_bf16_e32 v194, v14, v142
	v_dot2c_f32_bf16_e32 v195, v15, v143
	s_nop 1
	v_add_f32_e32 v156, v192, v193
	v_add_f32_e32 v157, v194, v195
	v_add_f32_e32 v191, v156, v157
	v_add_f32_dpp v184, v184, v184 row_half_mirror row_mask:0xf bank_mask:0x5
	v_add_f32_dpp v185, v185, v185 row_half_mirror row_mask:0xf bank_mask:0x5
	v_add_f32_dpp v186, v186, v186 row_half_mirror row_mask:0xf bank_mask:0x5
	v_add_f32_dpp v187, v187, v187 row_half_mirror row_mask:0xf bank_mask:0x5
	v_add_f32_dpp v184, v188, v188 row_half_mirror row_mask:0xf bank_mask:0xa
	v_add_f32_dpp v185, v189, v189 row_half_mirror row_mask:0xf bank_mask:0xa
	v_add_f32_dpp v186, v190, v190 row_half_mirror row_mask:0xf bank_mask:0xa
	v_add_f32_dpp v187, v191, v191 row_half_mirror row_mask:0xf bank_mask:0xa
	v_add_f32_dpp v184, v184, v184 quad_perm:[1,0,3,2] row_mask:0xf bank_mask:0xf
	v_add_f32_dpp v185, v185, v185 quad_perm:[1,0,3,2] row_mask:0xf bank_mask:0xf
	v_add_f32_dpp v186, v186, v186 quad_perm:[1,0,3,2] row_mask:0xf bank_mask:0xf
	v_add_f32_dpp v187, v187, v187 quad_perm:[1,0,3,2] row_mask:0xf bank_mask:0xf
	v_add_f32_dpp v184, v184, v184 quad_perm:[2,3,0,1] row_mask:0xf bank_mask:0xf
	v_add_f32_dpp v185, v185, v185 quad_perm:[2,3,0,1] row_mask:0xf bank_mask:0xf
	v_add_f32_dpp v186, v186, v186 quad_perm:[2,3,0,1] row_mask:0xf bank_mask:0xf
	v_add_f32_dpp v187, v187, v187 quad_perm:[2,3,0,1] row_mask:0xf bank_mask:0xf
	v_cndmask_b32_e64 v156, v184, v185, s[10:11]
	v_cndmask_b32_e64 v157, v186, v187, s[10:11]
	v_cndmask_b32_e64 v156, v156, v157, s[100:101]
	ds_add_f32 v170, v156 offset:256
	s_cmp_lg_u32 s12, 0
	s_cbranch_scc1 .Lgu1_loop
	s_waitcnt vmcnt(0) lgkmcnt(0)
	s_add_u32 s0, s26, 0x1420000
	s_addc_u32 s1, s27, 0
	s_add_u32 s4, s26, 0x1430000
	s_addc_u32 s5, s27, 0
	s_lshl_b32 s13, s35, 9
	s_add_u32 s6, s26, 0xe800000
	s_addc_u32 s7, s27, 0
	s_add_u32 s6, s6, s13
	s_addc_u32 s7, s7, 0
	s_add_u32 s8, s26, 0xf800000
	s_addc_u32 s9, s27, 0
	s_add_u32 s8, s8, s13
	s_addc_u32 s9, s9, 0
	s_lshl_b32 s14, s92, 11
	s_mov_b32 s12, 0x378e98ab
	s_mov_b32 s15, 0x3b7cd369
	s_mov_b32 s16, 0xbcc618b2
	s_mov_b32 s17, 0x3dda74e4
	s_mov_b32 s18, 0x3f228afd
	s_mov_b32 s19, 0x3e03c728
	s_mov_b32 s98, 0xbfb8aa3b
	s_mov_b32 s38, 0x42ce8ed0
	s_mov_b32 s39, 0xc2b17218
	s_mov_b32 s10, 0x7fffffff
	v_mov_b32_e32 v176, 0x3ba10414
	v_mov_b32_e32 v177, 0xb9c68948
	v_mov_b32_e32 v178, 0x7f800000
	ds_read2st64_b32 v[16:17], v174 offset0:0 offset1:1
	ds_read2st64_b32 v[80:81], v175 offset0:0 offset1:1
	ds_read2st64_b32 v[18:19], v174 offset0:2 offset1:3
	ds_read2st64_b32 v[82:83], v175 offset0:2 offset1:3
	ds_read2st64_b32 v[20:21], v174 offset0:4 offset1:5
	ds_read2st64_b32 v[84:85], v175 offset0:4 offset1:5
	ds_read2st64_b32 v[22:23], v174 offset0:6 offset1:7
	ds_read2st64_b32 v[86:87], v175 offset0:6 offset1:7
	ds_read2st64_b32 v[24:25], v174 offset0:8 offset1:9
	ds_read2st64_b32 v[88:89], v175 offset0:8 offset1:9
	ds_read2st64_b32 v[26:27], v174 offset0:10 offset1:11
	ds_read2st64_b32 v[90:91], v175 offset0:10 offset1:11
	ds_read2st64_b32 v[28:29], v174 offset0:12 offset1:13
	ds_read2st64_b32 v[92:93], v175 offset0:12 offset1:13
	ds_read2st64_b32 v[30:31], v174 offset0:14 offset1:15
	ds_read2st64_b32 v[94:95], v175 offset0:14 offset1:15
	s_waitcnt lgkmcnt(0)
	v_lshlrev_b32_e32 v16, 2, v16
	v_lshlrev_b32_e32 v17, 2, v17
	v_lshlrev_b32_e32 v18, 2, v18
	v_lshlrev_b32_e32 v19, 2, v19
	v_lshlrev_b32_e32 v20, 2, v20
	v_lshlrev_b32_e32 v21, 2, v21
	v_lshlrev_b32_e32 v22, 2, v22
	v_lshlrev_b32_e32 v23, 2, v23
	v_lshlrev_b32_e32 v24, 2, v24
	v_lshlrev_b32_e32 v25, 2, v25
	v_lshlrev_b32_e32 v26, 2, v26
	v_lshlrev_b32_e32 v27, 2, v27
	v_lshlrev_b32_e32 v28, 2, v28
	v_lshlrev_b32_e32 v29, 2, v29
	v_lshlrev_b32_e32 v30, 2, v30
	v_lshlrev_b32_e32 v31, 2, v31
	global_load_dword v32, v160, s[6:7]
	global_load_dword v33, v160, s[6:7] offset:256
	global_load_dword v34, v16, s[0:1]
	global_load_dword v35, v17, s[0:1]
	global_load_dword v36, v16, s[4:5]
	global_load_dword v37, v17, s[4:5]
	s_add_u32 s6, s6, s14
	s_addc_u32 s7, s7, 0
	global_load_dword v38, v160, s[6:7]
	global_load_dword v39, v160, s[6:7] offset:256
	global_load_dword v40, v18, s[0:1]
	global_load_dword v41, v19, s[0:1]
	global_load_dword v42, v18, s[4:5]
	global_load_dword v43, v19, s[4:5]
	s_add_u32 s6, s6, s14
	s_addc_u32 s7, s7, 0
	global_load_dword v44, v160, s[6:7]
	global_load_dword v45, v160, s[6:7] offset:256
	global_load_dword v46, v20, s[0:1]
	global_load_dword v47, v21, s[0:1]
	global_load_dword v48, v20, s[4:5]
	global_load_dword v49, v21, s[4:5]
	s_add_u32 s6, s6, s14
	s_addc_u32 s7, s7, 0
	global_load_dword v50, v160, s[6:7]
	global_load_dword v51, v160, s[6:7] offset:256
	global_load_dword v52, v22, s[0:1]
	global_load_dword v53, v23, s[0:1]
	global_load_dword v54, v22, s[4:5]
	global_load_dword v55, v23, s[4:5]
	s_add_u32 s6, s6, s14
	s_addc_u32 s7, s7, 0
	global_load_dword v56, v160, s[6:7]
	global_load_dword v57, v160, s[6:7] offset:256
	global_load_dword v58, v24, s[0:1]
	global_load_dword v59, v25, s[0:1]
	global_load_dword v60, v24, s[4:5]
	global_load_dword v61, v25, s[4:5]
	s_add_u32 s6, s6, s14
	s_addc_u32 s7, s7, 0
	global_load_dword v62, v160, s[6:7]
	global_load_dword v63, v160, s[6:7] offset:256
	global_load_dword v64, v26, s[0:1]
	global_load_dword v65, v27, s[0:1]
	global_load_dword v66, v26, s[4:5]
	global_load_dword v67, v27, s[4:5]
	s_add_u32 s6, s6, s14
	s_addc_u32 s7, s7, 0
	global_load_dword v68, v160, s[6:7]
	global_load_dword v69, v160, s[6:7] offset:256
	global_load_dword v70, v28, s[0:1]
	global_load_dword v71, v29, s[0:1]
	global_load_dword v72, v28, s[4:5]
	global_load_dword v73, v29, s[4:5]
	s_add_u32 s6, s6, s14
	s_addc_u32 s7, s7, 0
	global_load_dword v74, v160, s[6:7]
	global_load_dword v75, v160, s[6:7] offset:256
	global_load_dword v76, v30, s[0:1]
	global_load_dword v77, v31, s[0:1]
	global_load_dword v78, v30, s[4:5]
	global_load_dword v79, v31, s[4:5]
	s_add_u32 s6, s6, s14
	s_addc_u32 s7, s7, 0
	s_waitcnt vmcnt(0)
	v_mul_f32_e32 v80, v34, v80
	v_mul_f32_e32 v180, 0x3f3504f3, v80
	v_fma_f32 v182, |v180|, s12, v177
	v_fma_f32 v182, |v180|, v182, s15
	v_fma_f32 v182, |v180|, v182, s16
	v_fma_f32 v182, |v180|, v182, s17
	v_fma_f32 v182, |v180|, v182, s18
	v_fma_f32 v182, |v180|, v182, s19
	v_fma_f32 v182, |v180|, v182, |v180|
	v_mul_f32_e32 v184, 0xbfb8aa3b, v182
	v_fma_f32 v185, v182, s98, -v184
	v_rndne_f32_e32 v186, v184
	v_fmac_f32_e32 v185, 0xb2a5705f, v182
	v_sub_f32_e32 v184, v184, v186
	v_add_f32_e32 v184, v184, v185
	v_cvt_i32_f32_e32 v185, v186
	v_exp_f32_e32 v184, v184
	v_cmp_nlt_f32_e32 vcc, s38, v182
	v_ldexp_f32 v184, v184, v185
	s_nop 0
	v_cndmask_b32_e32 v184, 0, v184, vcc
	v_cmp_ngt_f32_e32 vcc, s39, v182
	s_nop 1
	v_cndmask_b32_e32 v184, v178, v184, vcc
	v_sub_f32_e32 v184, 1.0, v184
	v_mul_f32_e32 v183, v180, v180
	v_fmamk_f32 v185, v183, 0xba1345e1, v176
	v_fmaak_f32 v185, v183, v185, 0xbcdac9b8
	v_fmaak_f32 v185, v183, v185, 0x3de703be
	v_fmaak_f32 v185, v183, v185, 0xbec09330
	v_fmaak_f32 v183, v183, v185, 0x3e0375d0
	v_fma_f32 v183, |v180|, v183, |v180|
	v_cmp_nlt_f32_e64 vcc, |v180|, 1.0
	s_nop 1
	v_cndmask_b32_e32 v184, v183, v184, vcc
	v_bfi_b32 v184, s10, v184, v180
	v_add_f32_e32 v184, 1.0, v184
	v_mul_f32_e32 v80, 0.5, v80
	v_mul_f32_e32 v32, v32, v36
	v_mul_f32_e32 v80, v80, v184
	v_mul_f32_e32 v80, v32, v80
	v_mul_f32_e32 v81, v35, v81
	v_mul_f32_e32 v180, 0x3f3504f3, v81
	v_fma_f32 v182, |v180|, s12, v177
	v_fma_f32 v182, |v180|, v182, s15
	v_fma_f32 v182, |v180|, v182, s16
	v_fma_f32 v182, |v180|, v182, s17
	v_fma_f32 v182, |v180|, v182, s18
	v_fma_f32 v182, |v180|, v182, s19
	v_fma_f32 v182, |v180|, v182, |v180|
	v_mul_f32_e32 v184, 0xbfb8aa3b, v182
	v_fma_f32 v185, v182, s98, -v184
	v_rndne_f32_e32 v186, v184
	v_fmac_f32_e32 v185, 0xb2a5705f, v182
	v_sub_f32_e32 v184, v184, v186
	v_add_f32_e32 v184, v184, v185
	v_cvt_i32_f32_e32 v185, v186
	v_exp_f32_e32 v184, v184
	v_cmp_nlt_f32_e32 vcc, s38, v182
	v_ldexp_f32 v184, v184, v185
	s_nop 0
	v_cndmask_b32_e32 v184, 0, v184, vcc
	v_cmp_ngt_f32_e32 vcc, s39, v182
	s_nop 1
	v_cndmask_b32_e32 v184, v178, v184, vcc
	v_sub_f32_e32 v184, 1.0, v184
	v_mul_f32_e32 v183, v180, v180
	v_fmamk_f32 v185, v183, 0xba1345e1, v176
	v_fmaak_f32 v185, v183, v185, 0xbcdac9b8
	v_fmaak_f32 v185, v183, v185, 0x3de703be
	v_fmaak_f32 v185, v183, v185, 0xbec09330
	v_fmaak_f32 v183, v183, v185, 0x3e0375d0
	v_fma_f32 v183, |v180|, v183, |v180|
	v_cmp_nlt_f32_e64 vcc, |v180|, 1.0
	s_nop 1
	v_cndmask_b32_e32 v184, v183, v184, vcc
	v_bfi_b32 v184, s10, v184, v180
	v_add_f32_e32 v184, 1.0, v184
	v_mul_f32_e32 v81, 0.5, v81
	v_mul_f32_e32 v33, v33, v37
	v_mul_f32_e32 v81, v81, v184
	v_mul_f32_e32 v81, v33, v81
	global_store_dword v160, v80, s[8:9]
	global_store_dword v160, v81, s[8:9] offset:256
	s_add_u32 s8, s8, s14
	s_addc_u32 s9, s9, 0
	v_mul_f32_e32 v82, v40, v82
	v_mul_f32_e32 v180, 0x3f3504f3, v82
	v_fma_f32 v182, |v180|, s12, v177
	v_fma_f32 v182, |v180|, v182, s15
	v_fma_f32 v182, |v180|, v182, s16
	v_fma_f32 v182, |v180|, v182, s17
	v_fma_f32 v182, |v180|, v182, s18
	v_fma_f32 v182, |v180|, v182, s19
	v_fma_f32 v182, |v180|, v182, |v180|
	v_mul_f32_e32 v184, 0xbfb8aa3b, v182
	v_fma_f32 v185, v182, s98, -v184
	v_rndne_f32_e32 v186, v184
	v_fmac_f32_e32 v185, 0xb2a5705f, v182
	v_sub_f32_e32 v184, v184, v186
	v_add_f32_e32 v184, v184, v185
	v_cvt_i32_f32_e32 v185, v186
	v_exp_f32_e32 v184, v184
	v_cmp_nlt_f32_e32 vcc, s38, v182
	v_ldexp_f32 v184, v184, v185
	s_nop 0
	v_cndmask_b32_e32 v184, 0, v184, vcc
	v_cmp_ngt_f32_e32 vcc, s39, v182
	s_nop 1
	v_cndmask_b32_e32 v184, v178, v184, vcc
	v_sub_f32_e32 v184, 1.0, v184
	v_mul_f32_e32 v183, v180, v180
	v_fmamk_f32 v185, v183, 0xba1345e1, v176
	v_fmaak_f32 v185, v183, v185, 0xbcdac9b8
	v_fmaak_f32 v185, v183, v185, 0x3de703be
	v_fmaak_f32 v185, v183, v185, 0xbec09330
	v_fmaak_f32 v183, v183, v185, 0x3e0375d0
	v_fma_f32 v183, |v180|, v183, |v180|
	v_cmp_nlt_f32_e64 vcc, |v180|, 1.0
	s_nop 1
	v_cndmask_b32_e32 v184, v183, v184, vcc
	v_bfi_b32 v184, s10, v184, v180
	v_add_f32_e32 v184, 1.0, v184
	v_mul_f32_e32 v82, 0.5, v82
	v_mul_f32_e32 v38, v38, v42
	v_mul_f32_e32 v82, v82, v184
	v_mul_f32_e32 v82, v38, v82
	v_mul_f32_e32 v83, v41, v83
	v_mul_f32_e32 v180, 0x3f3504f3, v83
	v_fma_f32 v182, |v180|, s12, v177
	v_fma_f32 v182, |v180|, v182, s15
	v_fma_f32 v182, |v180|, v182, s16
	v_fma_f32 v182, |v180|, v182, s17
	v_fma_f32 v182, |v180|, v182, s18
	v_fma_f32 v182, |v180|, v182, s19
	v_fma_f32 v182, |v180|, v182, |v180|
	v_mul_f32_e32 v184, 0xbfb8aa3b, v182
	v_fma_f32 v185, v182, s98, -v184
	v_rndne_f32_e32 v186, v184
	v_fmac_f32_e32 v185, 0xb2a5705f, v182
	v_sub_f32_e32 v184, v184, v186
	v_add_f32_e32 v184, v184, v185
	v_cvt_i32_f32_e32 v185, v186
	v_exp_f32_e32 v184, v184
	v_cmp_nlt_f32_e32 vcc, s38, v182
	v_ldexp_f32 v184, v184, v185
	s_nop 0
	v_cndmask_b32_e32 v184, 0, v184, vcc
	v_cmp_ngt_f32_e32 vcc, s39, v182
	s_nop 1
	v_cndmask_b32_e32 v184, v178, v184, vcc
	v_sub_f32_e32 v184, 1.0, v184
	v_mul_f32_e32 v183, v180, v180
	v_fmamk_f32 v185, v183, 0xba1345e1, v176
	v_fmaak_f32 v185, v183, v185, 0xbcdac9b8
	v_fmaak_f32 v185, v183, v185, 0x3de703be
	v_fmaak_f32 v185, v183, v185, 0xbec09330
	v_fmaak_f32 v183, v183, v185, 0x3e0375d0
	v_fma_f32 v183, |v180|, v183, |v180|
	v_cmp_nlt_f32_e64 vcc, |v180|, 1.0
	s_nop 1
	v_cndmask_b32_e32 v184, v183, v184, vcc
	v_bfi_b32 v184, s10, v184, v180
	v_add_f32_e32 v184, 1.0, v184
	v_mul_f32_e32 v83, 0.5, v83
	v_mul_f32_e32 v39, v39, v43
	v_mul_f32_e32 v83, v83, v184
	v_mul_f32_e32 v83, v39, v83
	global_store_dword v160, v82, s[8:9]
	global_store_dword v160, v83, s[8:9] offset:256
	s_add_u32 s8, s8, s14
	s_addc_u32 s9, s9, 0
	v_mul_f32_e32 v84, v46, v84
	v_mul_f32_e32 v180, 0x3f3504f3, v84
	v_fma_f32 v182, |v180|, s12, v177
	v_fma_f32 v182, |v180|, v182, s15
	v_fma_f32 v182, |v180|, v182, s16
	v_fma_f32 v182, |v180|, v182, s17
	v_fma_f32 v182, |v180|, v182, s18
	v_fma_f32 v182, |v180|, v182, s19
	v_fma_f32 v182, |v180|, v182, |v180|
	v_mul_f32_e32 v184, 0xbfb8aa3b, v182
	v_fma_f32 v185, v182, s98, -v184
	v_rndne_f32_e32 v186, v184
	v_fmac_f32_e32 v185, 0xb2a5705f, v182
	v_sub_f32_e32 v184, v184, v186
	v_add_f32_e32 v184, v184, v185
	v_cvt_i32_f32_e32 v185, v186
	v_exp_f32_e32 v184, v184
	v_cmp_nlt_f32_e32 vcc, s38, v182
	v_ldexp_f32 v184, v184, v185
	s_nop 0
	v_cndmask_b32_e32 v184, 0, v184, vcc
	v_cmp_ngt_f32_e32 vcc, s39, v182
	s_nop 1
	v_cndmask_b32_e32 v184, v178, v184, vcc
	v_sub_f32_e32 v184, 1.0, v184
	v_mul_f32_e32 v183, v180, v180
	v_fmamk_f32 v185, v183, 0xba1345e1, v176
	v_fmaak_f32 v185, v183, v185, 0xbcdac9b8
	v_fmaak_f32 v185, v183, v185, 0x3de703be
	v_fmaak_f32 v185, v183, v185, 0xbec09330
	v_fmaak_f32 v183, v183, v185, 0x3e0375d0
	v_fma_f32 v183, |v180|, v183, |v180|
	v_cmp_nlt_f32_e64 vcc, |v180|, 1.0
	s_nop 1
	v_cndmask_b32_e32 v184, v183, v184, vcc
	v_bfi_b32 v184, s10, v184, v180
	v_add_f32_e32 v184, 1.0, v184
	v_mul_f32_e32 v84, 0.5, v84
	v_mul_f32_e32 v44, v44, v48
	v_mul_f32_e32 v84, v84, v184
	v_mul_f32_e32 v84, v44, v84
	v_mul_f32_e32 v85, v47, v85
	v_mul_f32_e32 v180, 0x3f3504f3, v85
	v_fma_f32 v182, |v180|, s12, v177
	v_fma_f32 v182, |v180|, v182, s15
	v_fma_f32 v182, |v180|, v182, s16
	v_fma_f32 v182, |v180|, v182, s17
	v_fma_f32 v182, |v180|, v182, s18
	v_fma_f32 v182, |v180|, v182, s19
	v_fma_f32 v182, |v180|, v182, |v180|
	v_mul_f32_e32 v184, 0xbfb8aa3b, v182
	v_fma_f32 v185, v182, s98, -v184
	v_rndne_f32_e32 v186, v184
	v_fmac_f32_e32 v185, 0xb2a5705f, v182
	v_sub_f32_e32 v184, v184, v186
	v_add_f32_e32 v184, v184, v185
	v_cvt_i32_f32_e32 v185, v186
	v_exp_f32_e32 v184, v184
	v_cmp_nlt_f32_e32 vcc, s38, v182
	v_ldexp_f32 v184, v184, v185
	s_nop 0
	v_cndmask_b32_e32 v184, 0, v184, vcc
	v_cmp_ngt_f32_e32 vcc, s39, v182
	s_nop 1
	v_cndmask_b32_e32 v184, v178, v184, vcc
	v_sub_f32_e32 v184, 1.0, v184
	v_mul_f32_e32 v183, v180, v180
	v_fmamk_f32 v185, v183, 0xba1345e1, v176
	v_fmaak_f32 v185, v183, v185, 0xbcdac9b8
	v_fmaak_f32 v185, v183, v185, 0x3de703be
	v_fmaak_f32 v185, v183, v185, 0xbec09330
	v_fmaak_f32 v183, v183, v185, 0x3e0375d0
	v_fma_f32 v183, |v180|, v183, |v180|
	v_cmp_nlt_f32_e64 vcc, |v180|, 1.0
	s_nop 1
	v_cndmask_b32_e32 v184, v183, v184, vcc
	v_bfi_b32 v184, s10, v184, v180
	v_add_f32_e32 v184, 1.0, v184
	v_mul_f32_e32 v85, 0.5, v85
	v_mul_f32_e32 v45, v45, v49
	v_mul_f32_e32 v85, v85, v184
	v_mul_f32_e32 v85, v45, v85
	global_store_dword v160, v84, s[8:9]
	global_store_dword v160, v85, s[8:9] offset:256
	s_add_u32 s8, s8, s14
	s_addc_u32 s9, s9, 0
	v_mul_f32_e32 v86, v52, v86
	v_mul_f32_e32 v180, 0x3f3504f3, v86
	v_fma_f32 v182, |v180|, s12, v177
	v_fma_f32 v182, |v180|, v182, s15
	v_fma_f32 v182, |v180|, v182, s16
	v_fma_f32 v182, |v180|, v182, s17
	v_fma_f32 v182, |v180|, v182, s18
	v_fma_f32 v182, |v180|, v182, s19
	v_fma_f32 v182, |v180|, v182, |v180|
	v_mul_f32_e32 v184, 0xbfb8aa3b, v182
	v_fma_f32 v185, v182, s98, -v184
	v_rndne_f32_e32 v186, v184
	v_fmac_f32_e32 v185, 0xb2a5705f, v182
	v_sub_f32_e32 v184, v184, v186
	v_add_f32_e32 v184, v184, v185
	v_cvt_i32_f32_e32 v185, v186
	v_exp_f32_e32 v184, v184
	v_cmp_nlt_f32_e32 vcc, s38, v182
	v_ldexp_f32 v184, v184, v185
	s_nop 0
	v_cndmask_b32_e32 v184, 0, v184, vcc
	v_cmp_ngt_f32_e32 vcc, s39, v182
	s_nop 1
	v_cndmask_b32_e32 v184, v178, v184, vcc
	v_sub_f32_e32 v184, 1.0, v184
	v_mul_f32_e32 v183, v180, v180
	v_fmamk_f32 v185, v183, 0xba1345e1, v176
	v_fmaak_f32 v185, v183, v185, 0xbcdac9b8
	v_fmaak_f32 v185, v183, v185, 0x3de703be
	v_fmaak_f32 v185, v183, v185, 0xbec09330
	v_fmaak_f32 v183, v183, v185, 0x3e0375d0
	v_fma_f32 v183, |v180|, v183, |v180|
	v_cmp_nlt_f32_e64 vcc, |v180|, 1.0
	s_nop 1
	v_cndmask_b32_e32 v184, v183, v184, vcc
	v_bfi_b32 v184, s10, v184, v180
	v_add_f32_e32 v184, 1.0, v184
	v_mul_f32_e32 v86, 0.5, v86
	v_mul_f32_e32 v50, v50, v54
	v_mul_f32_e32 v86, v86, v184
	v_mul_f32_e32 v86, v50, v86
	v_mul_f32_e32 v87, v53, v87
	v_mul_f32_e32 v180, 0x3f3504f3, v87
	v_fma_f32 v182, |v180|, s12, v177
	v_fma_f32 v182, |v180|, v182, s15
	v_fma_f32 v182, |v180|, v182, s16
	v_fma_f32 v182, |v180|, v182, s17
	v_fma_f32 v182, |v180|, v182, s18
	v_fma_f32 v182, |v180|, v182, s19
	v_fma_f32 v182, |v180|, v182, |v180|
	v_mul_f32_e32 v184, 0xbfb8aa3b, v182
	v_fma_f32 v185, v182, s98, -v184
	v_rndne_f32_e32 v186, v184
	v_fmac_f32_e32 v185, 0xb2a5705f, v182
	v_sub_f32_e32 v184, v184, v186
	v_add_f32_e32 v184, v184, v185
	v_cvt_i32_f32_e32 v185, v186
	v_exp_f32_e32 v184, v184
	v_cmp_nlt_f32_e32 vcc, s38, v182
	v_ldexp_f32 v184, v184, v185
	s_nop 0
	v_cndmask_b32_e32 v184, 0, v184, vcc
	v_cmp_ngt_f32_e32 vcc, s39, v182
	s_nop 1
	v_cndmask_b32_e32 v184, v178, v184, vcc
	v_sub_f32_e32 v184, 1.0, v184
	v_mul_f32_e32 v183, v180, v180
	v_fmamk_f32 v185, v183, 0xba1345e1, v176
	v_fmaak_f32 v185, v183, v185, 0xbcdac9b8
	v_fmaak_f32 v185, v183, v185, 0x3de703be
	v_fmaak_f32 v185, v183, v185, 0xbec09330
	v_fmaak_f32 v183, v183, v185, 0x3e0375d0
	v_fma_f32 v183, |v180|, v183, |v180|
	v_cmp_nlt_f32_e64 vcc, |v180|, 1.0
	s_nop 1
	v_cndmask_b32_e32 v184, v183, v184, vcc
	v_bfi_b32 v184, s10, v184, v180
	v_add_f32_e32 v184, 1.0, v184
	v_mul_f32_e32 v87, 0.5, v87
	v_mul_f32_e32 v51, v51, v55
	v_mul_f32_e32 v87, v87, v184
	v_mul_f32_e32 v87, v51, v87
	global_store_dword v160, v86, s[8:9]
	global_store_dword v160, v87, s[8:9] offset:256
	s_add_u32 s8, s8, s14
	s_addc_u32 s9, s9, 0
	v_mul_f32_e32 v88, v58, v88
	v_mul_f32_e32 v180, 0x3f3504f3, v88
	v_fma_f32 v182, |v180|, s12, v177
	v_fma_f32 v182, |v180|, v182, s15
	v_fma_f32 v182, |v180|, v182, s16
	v_fma_f32 v182, |v180|, v182, s17
	v_fma_f32 v182, |v180|, v182, s18
	v_fma_f32 v182, |v180|, v182, s19
	v_fma_f32 v182, |v180|, v182, |v180|
	v_mul_f32_e32 v184, 0xbfb8aa3b, v182
	v_fma_f32 v185, v182, s98, -v184
	v_rndne_f32_e32 v186, v184
	v_fmac_f32_e32 v185, 0xb2a5705f, v182
	v_sub_f32_e32 v184, v184, v186
	v_add_f32_e32 v184, v184, v185
	v_cvt_i32_f32_e32 v185, v186
	v_exp_f32_e32 v184, v184
	v_cmp_nlt_f32_e32 vcc, s38, v182
	v_ldexp_f32 v184, v184, v185
	s_nop 0
	v_cndmask_b32_e32 v184, 0, v184, vcc
	v_cmp_ngt_f32_e32 vcc, s39, v182
	s_nop 1
	v_cndmask_b32_e32 v184, v178, v184, vcc
	v_sub_f32_e32 v184, 1.0, v184
	v_mul_f32_e32 v183, v180, v180
	v_fmamk_f32 v185, v183, 0xba1345e1, v176
	v_fmaak_f32 v185, v183, v185, 0xbcdac9b8
	v_fmaak_f32 v185, v183, v185, 0x3de703be
	v_fmaak_f32 v185, v183, v185, 0xbec09330
	v_fmaak_f32 v183, v183, v185, 0x3e0375d0
	v_fma_f32 v183, |v180|, v183, |v180|
	v_cmp_nlt_f32_e64 vcc, |v180|, 1.0
	s_nop 1
	v_cndmask_b32_e32 v184, v183, v184, vcc
	v_bfi_b32 v184, s10, v184, v180
	v_add_f32_e32 v184, 1.0, v184
	v_mul_f32_e32 v88, 0.5, v88
	v_mul_f32_e32 v56, v56, v60
	v_mul_f32_e32 v88, v88, v184
	v_mul_f32_e32 v88, v56, v88
	v_mul_f32_e32 v89, v59, v89
	v_mul_f32_e32 v180, 0x3f3504f3, v89
	v_fma_f32 v182, |v180|, s12, v177
	v_fma_f32 v182, |v180|, v182, s15
	v_fma_f32 v182, |v180|, v182, s16
	v_fma_f32 v182, |v180|, v182, s17
	v_fma_f32 v182, |v180|, v182, s18
	v_fma_f32 v182, |v180|, v182, s19
	v_fma_f32 v182, |v180|, v182, |v180|
	v_mul_f32_e32 v184, 0xbfb8aa3b, v182
	v_fma_f32 v185, v182, s98, -v184
	v_rndne_f32_e32 v186, v184
	v_fmac_f32_e32 v185, 0xb2a5705f, v182
	v_sub_f32_e32 v184, v184, v186
	v_add_f32_e32 v184, v184, v185
	v_cvt_i32_f32_e32 v185, v186
	v_exp_f32_e32 v184, v184
	v_cmp_nlt_f32_e32 vcc, s38, v182
	v_ldexp_f32 v184, v184, v185
	s_nop 0
	v_cndmask_b32_e32 v184, 0, v184, vcc
	v_cmp_ngt_f32_e32 vcc, s39, v182
	s_nop 1
	v_cndmask_b32_e32 v184, v178, v184, vcc
	v_sub_f32_e32 v184, 1.0, v184
	v_mul_f32_e32 v183, v180, v180
	v_fmamk_f32 v185, v183, 0xba1345e1, v176
	v_fmaak_f32 v185, v183, v185, 0xbcdac9b8
	v_fmaak_f32 v185, v183, v185, 0x3de703be
	v_fmaak_f32 v185, v183, v185, 0xbec09330
	v_fmaak_f32 v183, v183, v185, 0x3e0375d0
	v_fma_f32 v183, |v180|, v183, |v180|
	v_cmp_nlt_f32_e64 vcc, |v180|, 1.0
	s_nop 1
	v_cndmask_b32_e32 v184, v183, v184, vcc
	v_bfi_b32 v184, s10, v184, v180
	v_add_f32_e32 v184, 1.0, v184
	v_mul_f32_e32 v89, 0.5, v89
	v_mul_f32_e32 v57, v57, v61
	v_mul_f32_e32 v89, v89, v184
	v_mul_f32_e32 v89, v57, v89
	global_store_dword v160, v88, s[8:9]
	global_store_dword v160, v89, s[8:9] offset:256
	s_add_u32 s8, s8, s14
	s_addc_u32 s9, s9, 0
	v_mul_f32_e32 v90, v64, v90
	v_mul_f32_e32 v180, 0x3f3504f3, v90
	v_fma_f32 v182, |v180|, s12, v177
	v_fma_f32 v182, |v180|, v182, s15
	v_fma_f32 v182, |v180|, v182, s16
	v_fma_f32 v182, |v180|, v182, s17
	v_fma_f32 v182, |v180|, v182, s18
	v_fma_f32 v182, |v180|, v182, s19
	v_fma_f32 v182, |v180|, v182, |v180|
	v_mul_f32_e32 v184, 0xbfb8aa3b, v182
	v_fma_f32 v185, v182, s98, -v184
	v_rndne_f32_e32 v186, v184
	v_fmac_f32_e32 v185, 0xb2a5705f, v182
	v_sub_f32_e32 v184, v184, v186
	v_add_f32_e32 v184, v184, v185
	v_cvt_i32_f32_e32 v185, v186
	v_exp_f32_e32 v184, v184
	v_cmp_nlt_f32_e32 vcc, s38, v182
	v_ldexp_f32 v184, v184, v185
	s_nop 0
	v_cndmask_b32_e32 v184, 0, v184, vcc
	v_cmp_ngt_f32_e32 vcc, s39, v182
	s_nop 1
	v_cndmask_b32_e32 v184, v178, v184, vcc
	v_sub_f32_e32 v184, 1.0, v184
	v_mul_f32_e32 v183, v180, v180
	v_fmamk_f32 v185, v183, 0xba1345e1, v176
	v_fmaak_f32 v185, v183, v185, 0xbcdac9b8
	v_fmaak_f32 v185, v183, v185, 0x3de703be
	v_fmaak_f32 v185, v183, v185, 0xbec09330
	v_fmaak_f32 v183, v183, v185, 0x3e0375d0
	v_fma_f32 v183, |v180|, v183, |v180|
	v_cmp_nlt_f32_e64 vcc, |v180|, 1.0
	s_nop 1
	v_cndmask_b32_e32 v184, v183, v184, vcc
	v_bfi_b32 v184, s10, v184, v180
	v_add_f32_e32 v184, 1.0, v184
	v_mul_f32_e32 v90, 0.5, v90
	v_mul_f32_e32 v62, v62, v66
	v_mul_f32_e32 v90, v90, v184
	v_mul_f32_e32 v90, v62, v90
	v_mul_f32_e32 v91, v65, v91
	v_mul_f32_e32 v180, 0x3f3504f3, v91
	v_fma_f32 v182, |v180|, s12, v177
	v_fma_f32 v182, |v180|, v182, s15
	v_fma_f32 v182, |v180|, v182, s16
	v_fma_f32 v182, |v180|, v182, s17
	v_fma_f32 v182, |v180|, v182, s18
	v_fma_f32 v182, |v180|, v182, s19
	v_fma_f32 v182, |v180|, v182, |v180|
	v_mul_f32_e32 v184, 0xbfb8aa3b, v182
	v_fma_f32 v185, v182, s98, -v184
	v_rndne_f32_e32 v186, v184
	v_fmac_f32_e32 v185, 0xb2a5705f, v182
	v_sub_f32_e32 v184, v184, v186
	v_add_f32_e32 v184, v184, v185
	v_cvt_i32_f32_e32 v185, v186
	v_exp_f32_e32 v184, v184
	v_cmp_nlt_f32_e32 vcc, s38, v182
	v_ldexp_f32 v184, v184, v185
	s_nop 0
	v_cndmask_b32_e32 v184, 0, v184, vcc
	v_cmp_ngt_f32_e32 vcc, s39, v182
	s_nop 1
	v_cndmask_b32_e32 v184, v178, v184, vcc
	v_sub_f32_e32 v184, 1.0, v184
	v_mul_f32_e32 v183, v180, v180
	v_fmamk_f32 v185, v183, 0xba1345e1, v176
	v_fmaak_f32 v185, v183, v185, 0xbcdac9b8
	v_fmaak_f32 v185, v183, v185, 0x3de703be
	v_fmaak_f32 v185, v183, v185, 0xbec09330
	v_fmaak_f32 v183, v183, v185, 0x3e0375d0
	v_fma_f32 v183, |v180|, v183, |v180|
	v_cmp_nlt_f32_e64 vcc, |v180|, 1.0
	s_nop 1
	v_cndmask_b32_e32 v184, v183, v184, vcc
	v_bfi_b32 v184, s10, v184, v180
	v_add_f32_e32 v184, 1.0, v184
	v_mul_f32_e32 v91, 0.5, v91
	v_mul_f32_e32 v63, v63, v67
	v_mul_f32_e32 v91, v91, v184
	v_mul_f32_e32 v91, v63, v91
	global_store_dword v160, v90, s[8:9]
	global_store_dword v160, v91, s[8:9] offset:256
	s_add_u32 s8, s8, s14
	s_addc_u32 s9, s9, 0
	v_mul_f32_e32 v92, v70, v92
	v_mul_f32_e32 v180, 0x3f3504f3, v92
	v_fma_f32 v182, |v180|, s12, v177
	v_fma_f32 v182, |v180|, v182, s15
	v_fma_f32 v182, |v180|, v182, s16
	v_fma_f32 v182, |v180|, v182, s17
	v_fma_f32 v182, |v180|, v182, s18
	v_fma_f32 v182, |v180|, v182, s19
	v_fma_f32 v182, |v180|, v182, |v180|
	v_mul_f32_e32 v184, 0xbfb8aa3b, v182
	v_fma_f32 v185, v182, s98, -v184
	v_rndne_f32_e32 v186, v184
	v_fmac_f32_e32 v185, 0xb2a5705f, v182
	v_sub_f32_e32 v184, v184, v186
	v_add_f32_e32 v184, v184, v185
	v_cvt_i32_f32_e32 v185, v186
	v_exp_f32_e32 v184, v184
	v_cmp_nlt_f32_e32 vcc, s38, v182
	v_ldexp_f32 v184, v184, v185
	s_nop 0
	v_cndmask_b32_e32 v184, 0, v184, vcc
	v_cmp_ngt_f32_e32 vcc, s39, v182
	s_nop 1
	v_cndmask_b32_e32 v184, v178, v184, vcc
	v_sub_f32_e32 v184, 1.0, v184
	v_mul_f32_e32 v183, v180, v180
	v_fmamk_f32 v185, v183, 0xba1345e1, v176
	v_fmaak_f32 v185, v183, v185, 0xbcdac9b8
	v_fmaak_f32 v185, v183, v185, 0x3de703be
	v_fmaak_f32 v185, v183, v185, 0xbec09330
	v_fmaak_f32 v183, v183, v185, 0x3e0375d0
	v_fma_f32 v183, |v180|, v183, |v180|
	v_cmp_nlt_f32_e64 vcc, |v180|, 1.0
	s_nop 1
	v_cndmask_b32_e32 v184, v183, v184, vcc
	v_bfi_b32 v184, s10, v184, v180
	v_add_f32_e32 v184, 1.0, v184
	v_mul_f32_e32 v92, 0.5, v92
	v_mul_f32_e32 v68, v68, v72
	v_mul_f32_e32 v92, v92, v184
	v_mul_f32_e32 v92, v68, v92
	v_mul_f32_e32 v93, v71, v93
	v_mul_f32_e32 v180, 0x3f3504f3, v93
	v_fma_f32 v182, |v180|, s12, v177
	v_fma_f32 v182, |v180|, v182, s15
	v_fma_f32 v182, |v180|, v182, s16
	v_fma_f32 v182, |v180|, v182, s17
	v_fma_f32 v182, |v180|, v182, s18
	v_fma_f32 v182, |v180|, v182, s19
	v_fma_f32 v182, |v180|, v182, |v180|
	v_mul_f32_e32 v184, 0xbfb8aa3b, v182
	v_fma_f32 v185, v182, s98, -v184
	v_rndne_f32_e32 v186, v184
	v_fmac_f32_e32 v185, 0xb2a5705f, v182
	v_sub_f32_e32 v184, v184, v186
	v_add_f32_e32 v184, v184, v185
	v_cvt_i32_f32_e32 v185, v186
	v_exp_f32_e32 v184, v184
	v_cmp_nlt_f32_e32 vcc, s38, v182
	v_ldexp_f32 v184, v184, v185
	s_nop 0
	v_cndmask_b32_e32 v184, 0, v184, vcc
	v_cmp_ngt_f32_e32 vcc, s39, v182
	s_nop 1
	v_cndmask_b32_e32 v184, v178, v184, vcc
	v_sub_f32_e32 v184, 1.0, v184
	v_mul_f32_e32 v183, v180, v180
	v_fmamk_f32 v185, v183, 0xba1345e1, v176
	v_fmaak_f32 v185, v183, v185, 0xbcdac9b8
	v_fmaak_f32 v185, v183, v185, 0x3de703be
	v_fmaak_f32 v185, v183, v185, 0xbec09330
	v_fmaak_f32 v183, v183, v185, 0x3e0375d0
	v_fma_f32 v183, |v180|, v183, |v180|
	v_cmp_nlt_f32_e64 vcc, |v180|, 1.0
	s_nop 1
	v_cndmask_b32_e32 v184, v183, v184, vcc
	v_bfi_b32 v184, s10, v184, v180
	v_add_f32_e32 v184, 1.0, v184
	v_mul_f32_e32 v93, 0.5, v93
	v_mul_f32_e32 v69, v69, v73
	v_mul_f32_e32 v93, v93, v184
	v_mul_f32_e32 v93, v69, v93
	global_store_dword v160, v92, s[8:9]
	global_store_dword v160, v93, s[8:9] offset:256
	s_add_u32 s8, s8, s14
	s_addc_u32 s9, s9, 0
	v_mul_f32_e32 v94, v76, v94
	v_mul_f32_e32 v180, 0x3f3504f3, v94
	v_fma_f32 v182, |v180|, s12, v177
	v_fma_f32 v182, |v180|, v182, s15
	v_fma_f32 v182, |v180|, v182, s16
	v_fma_f32 v182, |v180|, v182, s17
	v_fma_f32 v182, |v180|, v182, s18
	v_fma_f32 v182, |v180|, v182, s19
	v_fma_f32 v182, |v180|, v182, |v180|
	v_mul_f32_e32 v184, 0xbfb8aa3b, v182
	v_fma_f32 v185, v182, s98, -v184
	v_rndne_f32_e32 v186, v184
	v_fmac_f32_e32 v185, 0xb2a5705f, v182
	v_sub_f32_e32 v184, v184, v186
	v_add_f32_e32 v184, v184, v185
	v_cvt_i32_f32_e32 v185, v186
	v_exp_f32_e32 v184, v184
	v_cmp_nlt_f32_e32 vcc, s38, v182
	v_ldexp_f32 v184, v184, v185
	s_nop 0
	v_cndmask_b32_e32 v184, 0, v184, vcc
	v_cmp_ngt_f32_e32 vcc, s39, v182
	s_nop 1
	v_cndmask_b32_e32 v184, v178, v184, vcc
	v_sub_f32_e32 v184, 1.0, v184
	v_mul_f32_e32 v183, v180, v180
	v_fmamk_f32 v185, v183, 0xba1345e1, v176
	v_fmaak_f32 v185, v183, v185, 0xbcdac9b8
	v_fmaak_f32 v185, v183, v185, 0x3de703be
	v_fmaak_f32 v185, v183, v185, 0xbec09330
	v_fmaak_f32 v183, v183, v185, 0x3e0375d0
	v_fma_f32 v183, |v180|, v183, |v180|
	v_cmp_nlt_f32_e64 vcc, |v180|, 1.0
	s_nop 1
	v_cndmask_b32_e32 v184, v183, v184, vcc
	v_bfi_b32 v184, s10, v184, v180
	v_add_f32_e32 v184, 1.0, v184
	v_mul_f32_e32 v94, 0.5, v94
	v_mul_f32_e32 v74, v74, v78
	v_mul_f32_e32 v94, v94, v184
	v_mul_f32_e32 v94, v74, v94
	v_mul_f32_e32 v95, v77, v95
	v_mul_f32_e32 v180, 0x3f3504f3, v95
	v_fma_f32 v182, |v180|, s12, v177
	v_fma_f32 v182, |v180|, v182, s15
	v_fma_f32 v182, |v180|, v182, s16
	v_fma_f32 v182, |v180|, v182, s17
	v_fma_f32 v182, |v180|, v182, s18
	v_fma_f32 v182, |v180|, v182, s19
	v_fma_f32 v182, |v180|, v182, |v180|
	v_mul_f32_e32 v184, 0xbfb8aa3b, v182
	v_fma_f32 v185, v182, s98, -v184
	v_rndne_f32_e32 v186, v184
	v_fmac_f32_e32 v185, 0xb2a5705f, v182
	v_sub_f32_e32 v184, v184, v186
	v_add_f32_e32 v184, v184, v185
	v_cvt_i32_f32_e32 v185, v186
	v_exp_f32_e32 v184, v184
	v_cmp_nlt_f32_e32 vcc, s38, v182
	v_ldexp_f32 v184, v184, v185
	s_nop 0
	v_cndmask_b32_e32 v184, 0, v184, vcc
	v_cmp_ngt_f32_e32 vcc, s39, v182
	s_nop 1
	v_cndmask_b32_e32 v184, v178, v184, vcc
	v_sub_f32_e32 v184, 1.0, v184
	v_mul_f32_e32 v183, v180, v180
	v_fmamk_f32 v185, v183, 0xba1345e1, v176
	v_fmaak_f32 v185, v183, v185, 0xbcdac9b8
	v_fmaak_f32 v185, v183, v185, 0x3de703be
	v_fmaak_f32 v185, v183, v185, 0xbec09330
	v_fmaak_f32 v183, v183, v185, 0x3e0375d0
	v_fma_f32 v183, |v180|, v183, |v180|
	v_cmp_nlt_f32_e64 vcc, |v180|, 1.0
	s_nop 1
	v_cndmask_b32_e32 v184, v183, v184, vcc
	v_bfi_b32 v184, s10, v184, v180
	v_add_f32_e32 v184, 1.0, v184
	v_mul_f32_e32 v95, 0.5, v95
	v_mul_f32_e32 v75, v75, v79
	v_mul_f32_e32 v95, v95, v184
	v_mul_f32_e32 v95, v75, v95
	global_store_dword v160, v94, s[8:9]
	global_store_dword v160, v95, s[8:9] offset:256
	s_add_u32 s8, s8, s14
	s_addc_u32 s9, s9, 0
	ds_read2st64_b32 v[16:17], v174 offset0:16 offset1:17
	ds_read2st64_b32 v[80:81], v175 offset0:16 offset1:17
	ds_read2st64_b32 v[18:19], v174 offset0:18 offset1:19
	ds_read2st64_b32 v[82:83], v175 offset0:18 offset1:19
	ds_read2st64_b32 v[20:21], v174 offset0:20 offset1:21
	ds_read2st64_b32 v[84:85], v175 offset0:20 offset1:21
	ds_read2st64_b32 v[22:23], v174 offset0:22 offset1:23
	ds_read2st64_b32 v[86:87], v175 offset0:22 offset1:23
	ds_read2st64_b32 v[24:25], v174 offset0:24 offset1:25
	ds_read2st64_b32 v[88:89], v175 offset0:24 offset1:25
	ds_read2st64_b32 v[26:27], v174 offset0:26 offset1:27
	ds_read2st64_b32 v[90:91], v175 offset0:26 offset1:27
	ds_read2st64_b32 v[28:29], v174 offset0:28 offset1:29
	ds_read2st64_b32 v[92:93], v175 offset0:28 offset1:29
	ds_read2st64_b32 v[30:31], v174 offset0:30 offset1:31
	ds_read2st64_b32 v[94:95], v175 offset0:30 offset1:31
	s_waitcnt lgkmcnt(0)
	v_lshlrev_b32_e32 v16, 2, v16
	v_lshlrev_b32_e32 v17, 2, v17
	v_lshlrev_b32_e32 v18, 2, v18
	v_lshlrev_b32_e32 v19, 2, v19
	v_lshlrev_b32_e32 v20, 2, v20
	v_lshlrev_b32_e32 v21, 2, v21
	v_lshlrev_b32_e32 v22, 2, v22
	v_lshlrev_b32_e32 v23, 2, v23
	v_lshlrev_b32_e32 v24, 2, v24
	v_lshlrev_b32_e32 v25, 2, v25
	v_lshlrev_b32_e32 v26, 2, v26
	v_lshlrev_b32_e32 v27, 2, v27
	v_lshlrev_b32_e32 v28, 2, v28
	v_lshlrev_b32_e32 v29, 2, v29
	v_lshlrev_b32_e32 v30, 2, v30
	v_lshlrev_b32_e32 v31, 2, v31
	global_load_dword v32, v160, s[6:7]
	global_load_dword v33, v160, s[6:7] offset:256
	global_load_dword v34, v16, s[0:1]
	global_load_dword v35, v17, s[0:1]
	global_load_dword v36, v16, s[4:5]
	global_load_dword v37, v17, s[4:5]
	s_add_u32 s6, s6, s14
	s_addc_u32 s7, s7, 0
	global_load_dword v38, v160, s[6:7]
	global_load_dword v39, v160, s[6:7] offset:256
	global_load_dword v40, v18, s[0:1]
	global_load_dword v41, v19, s[0:1]
	global_load_dword v42, v18, s[4:5]
	global_load_dword v43, v19, s[4:5]
	s_add_u32 s6, s6, s14
	s_addc_u32 s7, s7, 0
	global_load_dword v44, v160, s[6:7]
	global_load_dword v45, v160, s[6:7] offset:256
	global_load_dword v46, v20, s[0:1]
	global_load_dword v47, v21, s[0:1]
	global_load_dword v48, v20, s[4:5]
	global_load_dword v49, v21, s[4:5]
	s_add_u32 s6, s6, s14
	s_addc_u32 s7, s7, 0
	global_load_dword v50, v160, s[6:7]
	global_load_dword v51, v160, s[6:7] offset:256
	global_load_dword v52, v22, s[0:1]
	global_load_dword v53, v23, s[0:1]
	global_load_dword v54, v22, s[4:5]
	global_load_dword v55, v23, s[4:5]
	s_add_u32 s6, s6, s14
	s_addc_u32 s7, s7, 0
	global_load_dword v56, v160, s[6:7]
	global_load_dword v57, v160, s[6:7] offset:256
	global_load_dword v58, v24, s[0:1]
	global_load_dword v59, v25, s[0:1]
	global_load_dword v60, v24, s[4:5]
	global_load_dword v61, v25, s[4:5]
	s_add_u32 s6, s6, s14
	s_addc_u32 s7, s7, 0
	global_load_dword v62, v160, s[6:7]
	global_load_dword v63, v160, s[6:7] offset:256
	global_load_dword v64, v26, s[0:1]
	global_load_dword v65, v27, s[0:1]
	global_load_dword v66, v26, s[4:5]
	global_load_dword v67, v27, s[4:5]
	s_add_u32 s6, s6, s14
	s_addc_u32 s7, s7, 0
	global_load_dword v68, v160, s[6:7]
	global_load_dword v69, v160, s[6:7] offset:256
	global_load_dword v70, v28, s[0:1]
	global_load_dword v71, v29, s[0:1]
	global_load_dword v72, v28, s[4:5]
	global_load_dword v73, v29, s[4:5]
	s_add_u32 s6, s6, s14
	s_addc_u32 s7, s7, 0
	global_load_dword v74, v160, s[6:7]
	global_load_dword v75, v160, s[6:7] offset:256
	global_load_dword v76, v30, s[0:1]
	global_load_dword v77, v31, s[0:1]
	global_load_dword v78, v30, s[4:5]
	global_load_dword v79, v31, s[4:5]
	s_add_u32 s6, s6, s14
	s_addc_u32 s7, s7, 0
	s_waitcnt vmcnt(0)
	v_mul_f32_e32 v80, v34, v80
	v_mul_f32_e32 v180, 0x3f3504f3, v80
	v_fma_f32 v182, |v180|, s12, v177
	v_fma_f32 v182, |v180|, v182, s15
	v_fma_f32 v182, |v180|, v182, s16
	v_fma_f32 v182, |v180|, v182, s17
	v_fma_f32 v182, |v180|, v182, s18
	v_fma_f32 v182, |v180|, v182, s19
	v_fma_f32 v182, |v180|, v182, |v180|
	v_mul_f32_e32 v184, 0xbfb8aa3b, v182
	v_fma_f32 v185, v182, s98, -v184
	v_rndne_f32_e32 v186, v184
	v_fmac_f32_e32 v185, 0xb2a5705f, v182
	v_sub_f32_e32 v184, v184, v186
	v_add_f32_e32 v184, v184, v185
	v_cvt_i32_f32_e32 v185, v186
	v_exp_f32_e32 v184, v184
	v_cmp_nlt_f32_e32 vcc, s38, v182
	v_ldexp_f32 v184, v184, v185
	s_nop 0
	v_cndmask_b32_e32 v184, 0, v184, vcc
	v_cmp_ngt_f32_e32 vcc, s39, v182
	s_nop 1
	v_cndmask_b32_e32 v184, v178, v184, vcc
	v_sub_f32_e32 v184, 1.0, v184
	v_mul_f32_e32 v183, v180, v180
	v_fmamk_f32 v185, v183, 0xba1345e1, v176
	v_fmaak_f32 v185, v183, v185, 0xbcdac9b8
	v_fmaak_f32 v185, v183, v185, 0x3de703be
	v_fmaak_f32 v185, v183, v185, 0xbec09330
	v_fmaak_f32 v183, v183, v185, 0x3e0375d0
	v_fma_f32 v183, |v180|, v183, |v180|
	v_cmp_nlt_f32_e64 vcc, |v180|, 1.0
	s_nop 1
	v_cndmask_b32_e32 v184, v183, v184, vcc
	v_bfi_b32 v184, s10, v184, v180
	v_add_f32_e32 v184, 1.0, v184
	v_mul_f32_e32 v80, 0.5, v80
	v_mul_f32_e32 v32, v32, v36
	v_mul_f32_e32 v80, v80, v184
	v_mul_f32_e32 v80, v32, v80
	v_mul_f32_e32 v81, v35, v81
	v_mul_f32_e32 v180, 0x3f3504f3, v81
	v_fma_f32 v182, |v180|, s12, v177
	v_fma_f32 v182, |v180|, v182, s15
	v_fma_f32 v182, |v180|, v182, s16
	v_fma_f32 v182, |v180|, v182, s17
	v_fma_f32 v182, |v180|, v182, s18
	v_fma_f32 v182, |v180|, v182, s19
	v_fma_f32 v182, |v180|, v182, |v180|
	v_mul_f32_e32 v184, 0xbfb8aa3b, v182
	v_fma_f32 v185, v182, s98, -v184
	v_rndne_f32_e32 v186, v184
	v_fmac_f32_e32 v185, 0xb2a5705f, v182
	v_sub_f32_e32 v184, v184, v186
	v_add_f32_e32 v184, v184, v185
	v_cvt_i32_f32_e32 v185, v186
	v_exp_f32_e32 v184, v184
	v_cmp_nlt_f32_e32 vcc, s38, v182
	v_ldexp_f32 v184, v184, v185
	s_nop 0
	v_cndmask_b32_e32 v184, 0, v184, vcc
	v_cmp_ngt_f32_e32 vcc, s39, v182
	s_nop 1
	v_cndmask_b32_e32 v184, v178, v184, vcc
	v_sub_f32_e32 v184, 1.0, v184
	v_mul_f32_e32 v183, v180, v180
	v_fmamk_f32 v185, v183, 0xba1345e1, v176
	v_fmaak_f32 v185, v183, v185, 0xbcdac9b8
	v_fmaak_f32 v185, v183, v185, 0x3de703be
	v_fmaak_f32 v185, v183, v185, 0xbec09330
	v_fmaak_f32 v183, v183, v185, 0x3e0375d0
	v_fma_f32 v183, |v180|, v183, |v180|
	v_cmp_nlt_f32_e64 vcc, |v180|, 1.0
	s_nop 1
	v_cndmask_b32_e32 v184, v183, v184, vcc
	v_bfi_b32 v184, s10, v184, v180
	v_add_f32_e32 v184, 1.0, v184
	v_mul_f32_e32 v81, 0.5, v81
	v_mul_f32_e32 v33, v33, v37
	v_mul_f32_e32 v81, v81, v184
	v_mul_f32_e32 v81, v33, v81
	global_store_dword v160, v80, s[8:9]
	global_store_dword v160, v81, s[8:9] offset:256
	s_add_u32 s8, s8, s14
	s_addc_u32 s9, s9, 0
	v_mul_f32_e32 v82, v40, v82
	v_mul_f32_e32 v180, 0x3f3504f3, v82
	v_fma_f32 v182, |v180|, s12, v177
	v_fma_f32 v182, |v180|, v182, s15
	v_fma_f32 v182, |v180|, v182, s16
	v_fma_f32 v182, |v180|, v182, s17
	v_fma_f32 v182, |v180|, v182, s18
	v_fma_f32 v182, |v180|, v182, s19
	v_fma_f32 v182, |v180|, v182, |v180|
	v_mul_f32_e32 v184, 0xbfb8aa3b, v182
	v_fma_f32 v185, v182, s98, -v184
	v_rndne_f32_e32 v186, v184
	v_fmac_f32_e32 v185, 0xb2a5705f, v182
	v_sub_f32_e32 v184, v184, v186
	v_add_f32_e32 v184, v184, v185
	v_cvt_i32_f32_e32 v185, v186
	v_exp_f32_e32 v184, v184
	v_cmp_nlt_f32_e32 vcc, s38, v182
	v_ldexp_f32 v184, v184, v185
	s_nop 0
	v_cndmask_b32_e32 v184, 0, v184, vcc
	v_cmp_ngt_f32_e32 vcc, s39, v182
	s_nop 1
	v_cndmask_b32_e32 v184, v178, v184, vcc
	v_sub_f32_e32 v184, 1.0, v184
	v_mul_f32_e32 v183, v180, v180
	v_fmamk_f32 v185, v183, 0xba1345e1, v176
	v_fmaak_f32 v185, v183, v185, 0xbcdac9b8
	v_fmaak_f32 v185, v183, v185, 0x3de703be
	v_fmaak_f32 v185, v183, v185, 0xbec09330
	v_fmaak_f32 v183, v183, v185, 0x3e0375d0
	v_fma_f32 v183, |v180|, v183, |v180|
	v_cmp_nlt_f32_e64 vcc, |v180|, 1.0
	s_nop 1
	v_cndmask_b32_e32 v184, v183, v184, vcc
	v_bfi_b32 v184, s10, v184, v180
	v_add_f32_e32 v184, 1.0, v184
	v_mul_f32_e32 v82, 0.5, v82
	v_mul_f32_e32 v38, v38, v42
	v_mul_f32_e32 v82, v82, v184
	v_mul_f32_e32 v82, v38, v82
	v_mul_f32_e32 v83, v41, v83
	v_mul_f32_e32 v180, 0x3f3504f3, v83
	v_fma_f32 v182, |v180|, s12, v177
	v_fma_f32 v182, |v180|, v182, s15
	v_fma_f32 v182, |v180|, v182, s16
	v_fma_f32 v182, |v180|, v182, s17
	v_fma_f32 v182, |v180|, v182, s18
	v_fma_f32 v182, |v180|, v182, s19
	v_fma_f32 v182, |v180|, v182, |v180|
	v_mul_f32_e32 v184, 0xbfb8aa3b, v182
	v_fma_f32 v185, v182, s98, -v184
	v_rndne_f32_e32 v186, v184
	v_fmac_f32_e32 v185, 0xb2a5705f, v182
	v_sub_f32_e32 v184, v184, v186
	v_add_f32_e32 v184, v184, v185
	v_cvt_i32_f32_e32 v185, v186
	v_exp_f32_e32 v184, v184
	v_cmp_nlt_f32_e32 vcc, s38, v182
	v_ldexp_f32 v184, v184, v185
	s_nop 0
	v_cndmask_b32_e32 v184, 0, v184, vcc
	v_cmp_ngt_f32_e32 vcc, s39, v182
	s_nop 1
	v_cndmask_b32_e32 v184, v178, v184, vcc
	v_sub_f32_e32 v184, 1.0, v184
	v_mul_f32_e32 v183, v180, v180
	v_fmamk_f32 v185, v183, 0xba1345e1, v176
	v_fmaak_f32 v185, v183, v185, 0xbcdac9b8
	v_fmaak_f32 v185, v183, v185, 0x3de703be
	v_fmaak_f32 v185, v183, v185, 0xbec09330
	v_fmaak_f32 v183, v183, v185, 0x3e0375d0
	v_fma_f32 v183, |v180|, v183, |v180|
	v_cmp_nlt_f32_e64 vcc, |v180|, 1.0
	s_nop 1
	v_cndmask_b32_e32 v184, v183, v184, vcc
	v_bfi_b32 v184, s10, v184, v180
	v_add_f32_e32 v184, 1.0, v184
	v_mul_f32_e32 v83, 0.5, v83
	v_mul_f32_e32 v39, v39, v43
	v_mul_f32_e32 v83, v83, v184
	v_mul_f32_e32 v83, v39, v83
	global_store_dword v160, v82, s[8:9]
	global_store_dword v160, v83, s[8:9] offset:256
	s_add_u32 s8, s8, s14
	s_addc_u32 s9, s9, 0
	v_mul_f32_e32 v84, v46, v84
	v_mul_f32_e32 v180, 0x3f3504f3, v84
	v_fma_f32 v182, |v180|, s12, v177
	v_fma_f32 v182, |v180|, v182, s15
	v_fma_f32 v182, |v180|, v182, s16
	v_fma_f32 v182, |v180|, v182, s17
	v_fma_f32 v182, |v180|, v182, s18
	v_fma_f32 v182, |v180|, v182, s19
	v_fma_f32 v182, |v180|, v182, |v180|
	v_mul_f32_e32 v184, 0xbfb8aa3b, v182
	v_fma_f32 v185, v182, s98, -v184
	v_rndne_f32_e32 v186, v184
	v_fmac_f32_e32 v185, 0xb2a5705f, v182
	v_sub_f32_e32 v184, v184, v186
	v_add_f32_e32 v184, v184, v185
	v_cvt_i32_f32_e32 v185, v186
	v_exp_f32_e32 v184, v184
	v_cmp_nlt_f32_e32 vcc, s38, v182
	v_ldexp_f32 v184, v184, v185
	s_nop 0
	v_cndmask_b32_e32 v184, 0, v184, vcc
	v_cmp_ngt_f32_e32 vcc, s39, v182
	s_nop 1
	v_cndmask_b32_e32 v184, v178, v184, vcc
	v_sub_f32_e32 v184, 1.0, v184
	v_mul_f32_e32 v183, v180, v180
	v_fmamk_f32 v185, v183, 0xba1345e1, v176
	v_fmaak_f32 v185, v183, v185, 0xbcdac9b8
	v_fmaak_f32 v185, v183, v185, 0x3de703be
	v_fmaak_f32 v185, v183, v185, 0xbec09330
	v_fmaak_f32 v183, v183, v185, 0x3e0375d0
	v_fma_f32 v183, |v180|, v183, |v180|
	v_cmp_nlt_f32_e64 vcc, |v180|, 1.0
	s_nop 1
	v_cndmask_b32_e32 v184, v183, v184, vcc
	v_bfi_b32 v184, s10, v184, v180
	v_add_f32_e32 v184, 1.0, v184
	v_mul_f32_e32 v84, 0.5, v84
	v_mul_f32_e32 v44, v44, v48
	v_mul_f32_e32 v84, v84, v184
	v_mul_f32_e32 v84, v44, v84
	v_mul_f32_e32 v85, v47, v85
	v_mul_f32_e32 v180, 0x3f3504f3, v85
	v_fma_f32 v182, |v180|, s12, v177
	v_fma_f32 v182, |v180|, v182, s15
	v_fma_f32 v182, |v180|, v182, s16
	v_fma_f32 v182, |v180|, v182, s17
	v_fma_f32 v182, |v180|, v182, s18
	v_fma_f32 v182, |v180|, v182, s19
	v_fma_f32 v182, |v180|, v182, |v180|
	v_mul_f32_e32 v184, 0xbfb8aa3b, v182
	v_fma_f32 v185, v182, s98, -v184
	v_rndne_f32_e32 v186, v184
	v_fmac_f32_e32 v185, 0xb2a5705f, v182
	v_sub_f32_e32 v184, v184, v186
	v_add_f32_e32 v184, v184, v185
	v_cvt_i32_f32_e32 v185, v186
	v_exp_f32_e32 v184, v184
	v_cmp_nlt_f32_e32 vcc, s38, v182
	v_ldexp_f32 v184, v184, v185
	s_nop 0
	v_cndmask_b32_e32 v184, 0, v184, vcc
	v_cmp_ngt_f32_e32 vcc, s39, v182
	s_nop 1
	v_cndmask_b32_e32 v184, v178, v184, vcc
	v_sub_f32_e32 v184, 1.0, v184
	v_mul_f32_e32 v183, v180, v180
	v_fmamk_f32 v185, v183, 0xba1345e1, v176
	v_fmaak_f32 v185, v183, v185, 0xbcdac9b8
	v_fmaak_f32 v185, v183, v185, 0x3de703be
	v_fmaak_f32 v185, v183, v185, 0xbec09330
	v_fmaak_f32 v183, v183, v185, 0x3e0375d0
	v_fma_f32 v183, |v180|, v183, |v180|
	v_cmp_nlt_f32_e64 vcc, |v180|, 1.0
	s_nop 1
	v_cndmask_b32_e32 v184, v183, v184, vcc
	v_bfi_b32 v184, s10, v184, v180
	v_add_f32_e32 v184, 1.0, v184
	v_mul_f32_e32 v85, 0.5, v85
	v_mul_f32_e32 v45, v45, v49
	v_mul_f32_e32 v85, v85, v184
	v_mul_f32_e32 v85, v45, v85
	global_store_dword v160, v84, s[8:9]
	global_store_dword v160, v85, s[8:9] offset:256
	s_add_u32 s8, s8, s14
	s_addc_u32 s9, s9, 0
	v_mul_f32_e32 v86, v52, v86
	v_mul_f32_e32 v180, 0x3f3504f3, v86
	v_fma_f32 v182, |v180|, s12, v177
	v_fma_f32 v182, |v180|, v182, s15
	v_fma_f32 v182, |v180|, v182, s16
	v_fma_f32 v182, |v180|, v182, s17
	v_fma_f32 v182, |v180|, v182, s18
	v_fma_f32 v182, |v180|, v182, s19
	v_fma_f32 v182, |v180|, v182, |v180|
	v_mul_f32_e32 v184, 0xbfb8aa3b, v182
	v_fma_f32 v185, v182, s98, -v184
	v_rndne_f32_e32 v186, v184
	v_fmac_f32_e32 v185, 0xb2a5705f, v182
	v_sub_f32_e32 v184, v184, v186
	v_add_f32_e32 v184, v184, v185
	v_cvt_i32_f32_e32 v185, v186
	v_exp_f32_e32 v184, v184
	v_cmp_nlt_f32_e32 vcc, s38, v182
	v_ldexp_f32 v184, v184, v185
	s_nop 0
	v_cndmask_b32_e32 v184, 0, v184, vcc
	v_cmp_ngt_f32_e32 vcc, s39, v182
	s_nop 1
	v_cndmask_b32_e32 v184, v178, v184, vcc
	v_sub_f32_e32 v184, 1.0, v184
	v_mul_f32_e32 v183, v180, v180
	v_fmamk_f32 v185, v183, 0xba1345e1, v176
	v_fmaak_f32 v185, v183, v185, 0xbcdac9b8
	v_fmaak_f32 v185, v183, v185, 0x3de703be
	v_fmaak_f32 v185, v183, v185, 0xbec09330
	v_fmaak_f32 v183, v183, v185, 0x3e0375d0
	v_fma_f32 v183, |v180|, v183, |v180|
	v_cmp_nlt_f32_e64 vcc, |v180|, 1.0
	s_nop 1
	v_cndmask_b32_e32 v184, v183, v184, vcc
	v_bfi_b32 v184, s10, v184, v180
	v_add_f32_e32 v184, 1.0, v184
	v_mul_f32_e32 v86, 0.5, v86
	v_mul_f32_e32 v50, v50, v54
	v_mul_f32_e32 v86, v86, v184
	v_mul_f32_e32 v86, v50, v86
	v_mul_f32_e32 v87, v53, v87
	v_mul_f32_e32 v180, 0x3f3504f3, v87
	v_fma_f32 v182, |v180|, s12, v177
	v_fma_f32 v182, |v180|, v182, s15
	v_fma_f32 v182, |v180|, v182, s16
	v_fma_f32 v182, |v180|, v182, s17
	v_fma_f32 v182, |v180|, v182, s18
	v_fma_f32 v182, |v180|, v182, s19
	v_fma_f32 v182, |v180|, v182, |v180|
	v_mul_f32_e32 v184, 0xbfb8aa3b, v182
	v_fma_f32 v185, v182, s98, -v184
	v_rndne_f32_e32 v186, v184
	v_fmac_f32_e32 v185, 0xb2a5705f, v182
	v_sub_f32_e32 v184, v184, v186
	v_add_f32_e32 v184, v184, v185
	v_cvt_i32_f32_e32 v185, v186
	v_exp_f32_e32 v184, v184
	v_cmp_nlt_f32_e32 vcc, s38, v182
	v_ldexp_f32 v184, v184, v185
	s_nop 0
	v_cndmask_b32_e32 v184, 0, v184, vcc
	v_cmp_ngt_f32_e32 vcc, s39, v182
	s_nop 1
	v_cndmask_b32_e32 v184, v178, v184, vcc
	v_sub_f32_e32 v184, 1.0, v184
	v_mul_f32_e32 v183, v180, v180
	v_fmamk_f32 v185, v183, 0xba1345e1, v176
	v_fmaak_f32 v185, v183, v185, 0xbcdac9b8
	v_fmaak_f32 v185, v183, v185, 0x3de703be
	v_fmaak_f32 v185, v183, v185, 0xbec09330
	v_fmaak_f32 v183, v183, v185, 0x3e0375d0
	v_fma_f32 v183, |v180|, v183, |v180|
	v_cmp_nlt_f32_e64 vcc, |v180|, 1.0
	s_nop 1
	v_cndmask_b32_e32 v184, v183, v184, vcc
	v_bfi_b32 v184, s10, v184, v180
	v_add_f32_e32 v184, 1.0, v184
	v_mul_f32_e32 v87, 0.5, v87
	v_mul_f32_e32 v51, v51, v55
	v_mul_f32_e32 v87, v87, v184
	v_mul_f32_e32 v87, v51, v87
	global_store_dword v160, v86, s[8:9]
	global_store_dword v160, v87, s[8:9] offset:256
	s_add_u32 s8, s8, s14
	s_addc_u32 s9, s9, 0
	v_mul_f32_e32 v88, v58, v88
	v_mul_f32_e32 v180, 0x3f3504f3, v88
	v_fma_f32 v182, |v180|, s12, v177
	v_fma_f32 v182, |v180|, v182, s15
	v_fma_f32 v182, |v180|, v182, s16
	v_fma_f32 v182, |v180|, v182, s17
	v_fma_f32 v182, |v180|, v182, s18
	v_fma_f32 v182, |v180|, v182, s19
	v_fma_f32 v182, |v180|, v182, |v180|
	v_mul_f32_e32 v184, 0xbfb8aa3b, v182
	v_fma_f32 v185, v182, s98, -v184
	v_rndne_f32_e32 v186, v184
	v_fmac_f32_e32 v185, 0xb2a5705f, v182
	v_sub_f32_e32 v184, v184, v186
	v_add_f32_e32 v184, v184, v185
	v_cvt_i32_f32_e32 v185, v186
	v_exp_f32_e32 v184, v184
	v_cmp_nlt_f32_e32 vcc, s38, v182
	v_ldexp_f32 v184, v184, v185
	s_nop 0
	v_cndmask_b32_e32 v184, 0, v184, vcc
	v_cmp_ngt_f32_e32 vcc, s39, v182
	s_nop 1
	v_cndmask_b32_e32 v184, v178, v184, vcc
	v_sub_f32_e32 v184, 1.0, v184
	v_mul_f32_e32 v183, v180, v180
	v_fmamk_f32 v185, v183, 0xba1345e1, v176
	v_fmaak_f32 v185, v183, v185, 0xbcdac9b8
	v_fmaak_f32 v185, v183, v185, 0x3de703be
	v_fmaak_f32 v185, v183, v185, 0xbec09330
	v_fmaak_f32 v183, v183, v185, 0x3e0375d0
	v_fma_f32 v183, |v180|, v183, |v180|
	v_cmp_nlt_f32_e64 vcc, |v180|, 1.0
	s_nop 1
	v_cndmask_b32_e32 v184, v183, v184, vcc
	v_bfi_b32 v184, s10, v184, v180
	v_add_f32_e32 v184, 1.0, v184
	v_mul_f32_e32 v88, 0.5, v88
	v_mul_f32_e32 v56, v56, v60
	v_mul_f32_e32 v88, v88, v184
	v_mul_f32_e32 v88, v56, v88
	v_mul_f32_e32 v89, v59, v89
	v_mul_f32_e32 v180, 0x3f3504f3, v89
	v_fma_f32 v182, |v180|, s12, v177
	v_fma_f32 v182, |v180|, v182, s15
	v_fma_f32 v182, |v180|, v182, s16
	v_fma_f32 v182, |v180|, v182, s17
	v_fma_f32 v182, |v180|, v182, s18
	v_fma_f32 v182, |v180|, v182, s19
	v_fma_f32 v182, |v180|, v182, |v180|
	v_mul_f32_e32 v184, 0xbfb8aa3b, v182
	v_fma_f32 v185, v182, s98, -v184
	v_rndne_f32_e32 v186, v184
	v_fmac_f32_e32 v185, 0xb2a5705f, v182
	v_sub_f32_e32 v184, v184, v186
	v_add_f32_e32 v184, v184, v185
	v_cvt_i32_f32_e32 v185, v186
	v_exp_f32_e32 v184, v184
	v_cmp_nlt_f32_e32 vcc, s38, v182
	v_ldexp_f32 v184, v184, v185
	s_nop 0
	v_cndmask_b32_e32 v184, 0, v184, vcc
	v_cmp_ngt_f32_e32 vcc, s39, v182
	s_nop 1
	v_cndmask_b32_e32 v184, v178, v184, vcc
	v_sub_f32_e32 v184, 1.0, v184
	v_mul_f32_e32 v183, v180, v180
	v_fmamk_f32 v185, v183, 0xba1345e1, v176
	v_fmaak_f32 v185, v183, v185, 0xbcdac9b8
	v_fmaak_f32 v185, v183, v185, 0x3de703be
	v_fmaak_f32 v185, v183, v185, 0xbec09330
	v_fmaak_f32 v183, v183, v185, 0x3e0375d0
	v_fma_f32 v183, |v180|, v183, |v180|
	v_cmp_nlt_f32_e64 vcc, |v180|, 1.0
	s_nop 1
	v_cndmask_b32_e32 v184, v183, v184, vcc
	v_bfi_b32 v184, s10, v184, v180
	v_add_f32_e32 v184, 1.0, v184
	v_mul_f32_e32 v89, 0.5, v89
	v_mul_f32_e32 v57, v57, v61
	v_mul_f32_e32 v89, v89, v184
	v_mul_f32_e32 v89, v57, v89
	global_store_dword v160, v88, s[8:9]
	global_store_dword v160, v89, s[8:9] offset:256
	s_add_u32 s8, s8, s14
	s_addc_u32 s9, s9, 0
	v_mul_f32_e32 v90, v64, v90
	v_mul_f32_e32 v180, 0x3f3504f3, v90
	v_fma_f32 v182, |v180|, s12, v177
	v_fma_f32 v182, |v180|, v182, s15
	v_fma_f32 v182, |v180|, v182, s16
	v_fma_f32 v182, |v180|, v182, s17
	v_fma_f32 v182, |v180|, v182, s18
	v_fma_f32 v182, |v180|, v182, s19
	v_fma_f32 v182, |v180|, v182, |v180|
	v_mul_f32_e32 v184, 0xbfb8aa3b, v182
	v_fma_f32 v185, v182, s98, -v184
	v_rndne_f32_e32 v186, v184
	v_fmac_f32_e32 v185, 0xb2a5705f, v182
	v_sub_f32_e32 v184, v184, v186
	v_add_f32_e32 v184, v184, v185
	v_cvt_i32_f32_e32 v185, v186
	v_exp_f32_e32 v184, v184
	v_cmp_nlt_f32_e32 vcc, s38, v182
	v_ldexp_f32 v184, v184, v185
	s_nop 0
	v_cndmask_b32_e32 v184, 0, v184, vcc
	v_cmp_ngt_f32_e32 vcc, s39, v182
	s_nop 1
	v_cndmask_b32_e32 v184, v178, v184, vcc
	v_sub_f32_e32 v184, 1.0, v184
	v_mul_f32_e32 v183, v180, v180
	v_fmamk_f32 v185, v183, 0xba1345e1, v176
	v_fmaak_f32 v185, v183, v185, 0xbcdac9b8
	v_fmaak_f32 v185, v183, v185, 0x3de703be
	v_fmaak_f32 v185, v183, v185, 0xbec09330
	v_fmaak_f32 v183, v183, v185, 0x3e0375d0
	v_fma_f32 v183, |v180|, v183, |v180|
	v_cmp_nlt_f32_e64 vcc, |v180|, 1.0
	s_nop 1
	v_cndmask_b32_e32 v184, v183, v184, vcc
	v_bfi_b32 v184, s10, v184, v180
	v_add_f32_e32 v184, 1.0, v184
	v_mul_f32_e32 v90, 0.5, v90
	v_mul_f32_e32 v62, v62, v66
	v_mul_f32_e32 v90, v90, v184
	v_mul_f32_e32 v90, v62, v90
	v_mul_f32_e32 v91, v65, v91
	v_mul_f32_e32 v180, 0x3f3504f3, v91
	v_fma_f32 v182, |v180|, s12, v177
	v_fma_f32 v182, |v180|, v182, s15
	v_fma_f32 v182, |v180|, v182, s16
	v_fma_f32 v182, |v180|, v182, s17
	v_fma_f32 v182, |v180|, v182, s18
	v_fma_f32 v182, |v180|, v182, s19
	v_fma_f32 v182, |v180|, v182, |v180|
	v_mul_f32_e32 v184, 0xbfb8aa3b, v182
	v_fma_f32 v185, v182, s98, -v184
	v_rndne_f32_e32 v186, v184
	v_fmac_f32_e32 v185, 0xb2a5705f, v182
	v_sub_f32_e32 v184, v184, v186
	v_add_f32_e32 v184, v184, v185
	v_cvt_i32_f32_e32 v185, v186
	v_exp_f32_e32 v184, v184
	v_cmp_nlt_f32_e32 vcc, s38, v182
	v_ldexp_f32 v184, v184, v185
	s_nop 0
	v_cndmask_b32_e32 v184, 0, v184, vcc
	v_cmp_ngt_f32_e32 vcc, s39, v182
	s_nop 1
	v_cndmask_b32_e32 v184, v178, v184, vcc
	v_sub_f32_e32 v184, 1.0, v184
	v_mul_f32_e32 v183, v180, v180
	v_fmamk_f32 v185, v183, 0xba1345e1, v176
	v_fmaak_f32 v185, v183, v185, 0xbcdac9b8
	v_fmaak_f32 v185, v183, v185, 0x3de703be
	v_fmaak_f32 v185, v183, v185, 0xbec09330
	v_fmaak_f32 v183, v183, v185, 0x3e0375d0
	v_fma_f32 v183, |v180|, v183, |v180|
	v_cmp_nlt_f32_e64 vcc, |v180|, 1.0
	s_nop 1
	v_cndmask_b32_e32 v184, v183, v184, vcc
	v_bfi_b32 v184, s10, v184, v180
	v_add_f32_e32 v184, 1.0, v184
	v_mul_f32_e32 v91, 0.5, v91
	v_mul_f32_e32 v63, v63, v67
	v_mul_f32_e32 v91, v91, v184
	v_mul_f32_e32 v91, v63, v91
	global_store_dword v160, v90, s[8:9]
	global_store_dword v160, v91, s[8:9] offset:256
	s_add_u32 s8, s8, s14
	s_addc_u32 s9, s9, 0
	v_mul_f32_e32 v92, v70, v92
	v_mul_f32_e32 v180, 0x3f3504f3, v92
	v_fma_f32 v182, |v180|, s12, v177
	v_fma_f32 v182, |v180|, v182, s15
	v_fma_f32 v182, |v180|, v182, s16
	v_fma_f32 v182, |v180|, v182, s17
	v_fma_f32 v182, |v180|, v182, s18
	v_fma_f32 v182, |v180|, v182, s19
	v_fma_f32 v182, |v180|, v182, |v180|
	v_mul_f32_e32 v184, 0xbfb8aa3b, v182
	v_fma_f32 v185, v182, s98, -v184
	v_rndne_f32_e32 v186, v184
	v_fmac_f32_e32 v185, 0xb2a5705f, v182
	v_sub_f32_e32 v184, v184, v186
	v_add_f32_e32 v184, v184, v185
	v_cvt_i32_f32_e32 v185, v186
	v_exp_f32_e32 v184, v184
	v_cmp_nlt_f32_e32 vcc, s38, v182
	v_ldexp_f32 v184, v184, v185
	s_nop 0
	v_cndmask_b32_e32 v184, 0, v184, vcc
	v_cmp_ngt_f32_e32 vcc, s39, v182
	s_nop 1
	v_cndmask_b32_e32 v184, v178, v184, vcc
	v_sub_f32_e32 v184, 1.0, v184
	v_mul_f32_e32 v183, v180, v180
	v_fmamk_f32 v185, v183, 0xba1345e1, v176
	v_fmaak_f32 v185, v183, v185, 0xbcdac9b8
	v_fmaak_f32 v185, v183, v185, 0x3de703be
	v_fmaak_f32 v185, v183, v185, 0xbec09330
	v_fmaak_f32 v183, v183, v185, 0x3e0375d0
	v_fma_f32 v183, |v180|, v183, |v180|
	v_cmp_nlt_f32_e64 vcc, |v180|, 1.0
	s_nop 1
	v_cndmask_b32_e32 v184, v183, v184, vcc
	v_bfi_b32 v184, s10, v184, v180
	v_add_f32_e32 v184, 1.0, v184
	v_mul_f32_e32 v92, 0.5, v92
	v_mul_f32_e32 v68, v68, v72
	v_mul_f32_e32 v92, v92, v184
	v_mul_f32_e32 v92, v68, v92
	v_mul_f32_e32 v93, v71, v93
	v_mul_f32_e32 v180, 0x3f3504f3, v93
	v_fma_f32 v182, |v180|, s12, v177
	v_fma_f32 v182, |v180|, v182, s15
	v_fma_f32 v182, |v180|, v182, s16
	v_fma_f32 v182, |v180|, v182, s17
	v_fma_f32 v182, |v180|, v182, s18
	v_fma_f32 v182, |v180|, v182, s19
	v_fma_f32 v182, |v180|, v182, |v180|
	v_mul_f32_e32 v184, 0xbfb8aa3b, v182
	v_fma_f32 v185, v182, s98, -v184
	v_rndne_f32_e32 v186, v184
	v_fmac_f32_e32 v185, 0xb2a5705f, v182
	v_sub_f32_e32 v184, v184, v186
	v_add_f32_e32 v184, v184, v185
	v_cvt_i32_f32_e32 v185, v186
	v_exp_f32_e32 v184, v184
	v_cmp_nlt_f32_e32 vcc, s38, v182
	v_ldexp_f32 v184, v184, v185
	s_nop 0
	v_cndmask_b32_e32 v184, 0, v184, vcc
	v_cmp_ngt_f32_e32 vcc, s39, v182
	s_nop 1
	v_cndmask_b32_e32 v184, v178, v184, vcc
	v_sub_f32_e32 v184, 1.0, v184
	v_mul_f32_e32 v183, v180, v180
	v_fmamk_f32 v185, v183, 0xba1345e1, v176
	v_fmaak_f32 v185, v183, v185, 0xbcdac9b8
	v_fmaak_f32 v185, v183, v185, 0x3de703be
	v_fmaak_f32 v185, v183, v185, 0xbec09330
	v_fmaak_f32 v183, v183, v185, 0x3e0375d0
	v_fma_f32 v183, |v180|, v183, |v180|
	v_cmp_nlt_f32_e64 vcc, |v180|, 1.0
	s_nop 1
	v_cndmask_b32_e32 v184, v183, v184, vcc
	v_bfi_b32 v184, s10, v184, v180
	v_add_f32_e32 v184, 1.0, v184
	v_mul_f32_e32 v93, 0.5, v93
	v_mul_f32_e32 v69, v69, v73
	v_mul_f32_e32 v93, v93, v184
	v_mul_f32_e32 v93, v69, v93
	global_store_dword v160, v92, s[8:9]
	global_store_dword v160, v93, s[8:9] offset:256
	s_add_u32 s8, s8, s14
	s_addc_u32 s9, s9, 0
	v_mul_f32_e32 v94, v76, v94
	v_mul_f32_e32 v180, 0x3f3504f3, v94
	v_fma_f32 v182, |v180|, s12, v177
	v_fma_f32 v182, |v180|, v182, s15
	v_fma_f32 v182, |v180|, v182, s16
	v_fma_f32 v182, |v180|, v182, s17
	v_fma_f32 v182, |v180|, v182, s18
	v_fma_f32 v182, |v180|, v182, s19
	v_fma_f32 v182, |v180|, v182, |v180|
	v_mul_f32_e32 v184, 0xbfb8aa3b, v182
	v_fma_f32 v185, v182, s98, -v184
	v_rndne_f32_e32 v186, v184
	v_fmac_f32_e32 v185, 0xb2a5705f, v182
	v_sub_f32_e32 v184, v184, v186
	v_add_f32_e32 v184, v184, v185
	v_cvt_i32_f32_e32 v185, v186
	v_exp_f32_e32 v184, v184
	v_cmp_nlt_f32_e32 vcc, s38, v182
	v_ldexp_f32 v184, v184, v185
	s_nop 0
	v_cndmask_b32_e32 v184, 0, v184, vcc
	v_cmp_ngt_f32_e32 vcc, s39, v182
	s_nop 1
	v_cndmask_b32_e32 v184, v178, v184, vcc
	v_sub_f32_e32 v184, 1.0, v184
	v_mul_f32_e32 v183, v180, v180
	v_fmamk_f32 v185, v183, 0xba1345e1, v176
	v_fmaak_f32 v185, v183, v185, 0xbcdac9b8
	v_fmaak_f32 v185, v183, v185, 0x3de703be
	v_fmaak_f32 v185, v183, v185, 0xbec09330
	v_fmaak_f32 v183, v183, v185, 0x3e0375d0
	v_fma_f32 v183, |v180|, v183, |v180|
	v_cmp_nlt_f32_e64 vcc, |v180|, 1.0
	s_nop 1
	v_cndmask_b32_e32 v184, v183, v184, vcc
	v_bfi_b32 v184, s10, v184, v180
	v_add_f32_e32 v184, 1.0, v184
	v_mul_f32_e32 v94, 0.5, v94
	v_mul_f32_e32 v74, v74, v78
	v_mul_f32_e32 v94, v94, v184
	v_mul_f32_e32 v94, v74, v94
	v_mul_f32_e32 v95, v77, v95
	v_mul_f32_e32 v180, 0x3f3504f3, v95
	v_fma_f32 v182, |v180|, s12, v177
	v_fma_f32 v182, |v180|, v182, s15
	v_fma_f32 v182, |v180|, v182, s16
	v_fma_f32 v182, |v180|, v182, s17
	v_fma_f32 v182, |v180|, v182, s18
	v_fma_f32 v182, |v180|, v182, s19
	v_fma_f32 v182, |v180|, v182, |v180|
	v_mul_f32_e32 v184, 0xbfb8aa3b, v182
	v_fma_f32 v185, v182, s98, -v184
	v_rndne_f32_e32 v186, v184
	v_fmac_f32_e32 v185, 0xb2a5705f, v182
	v_sub_f32_e32 v184, v184, v186
	v_add_f32_e32 v184, v184, v185
	v_cvt_i32_f32_e32 v185, v186
	v_exp_f32_e32 v184, v184
	v_cmp_nlt_f32_e32 vcc, s38, v182
	v_ldexp_f32 v184, v184, v185
	s_nop 0
	v_cndmask_b32_e32 v184, 0, v184, vcc
	v_cmp_ngt_f32_e32 vcc, s39, v182
	s_nop 1
	v_cndmask_b32_e32 v184, v178, v184, vcc
	v_sub_f32_e32 v184, 1.0, v184
	v_mul_f32_e32 v183, v180, v180
	v_fmamk_f32 v185, v183, 0xba1345e1, v176
	v_fmaak_f32 v185, v183, v185, 0xbcdac9b8
	v_fmaak_f32 v185, v183, v185, 0x3de703be
	v_fmaak_f32 v185, v183, v185, 0xbec09330
	v_fmaak_f32 v183, v183, v185, 0x3e0375d0
	v_fma_f32 v183, |v180|, v183, |v180|
	v_cmp_nlt_f32_e64 vcc, |v180|, 1.0
	s_nop 1
	v_cndmask_b32_e32 v184, v183, v184, vcc
	v_bfi_b32 v184, s10, v184, v180
	v_add_f32_e32 v184, 1.0, v184
	v_mul_f32_e32 v95, 0.5, v95
	v_mul_f32_e32 v75, v75, v79
	v_mul_f32_e32 v95, v95, v184
	v_mul_f32_e32 v95, v75, v95
	global_store_dword v160, v94, s[8:9]
	global_store_dword v160, v95, s[8:9] offset:256
	s_add_u32 s8, s8, s14
	s_addc_u32 s9, s9, 0
	s_lshl_b32 s13, s92, 6
	s_add_u32 s35, s35, s13
	s_cmpk_lt_u32 s35, 0x8000
	s_cbranch_scc1 .Lgu1_chunk
	s_branch .LBB0_1045

.Lgv1_chunk:
	s_movk_i32 s100, 0xc0
	s_lshl_b32 s16, s92, 14
	s_add_u32 s12, s26, 0xd800000
	s_addc_u32 s13, s27, 0
	s_lshl_b32 s15, s101, 9
	s_add_u32 s12, s12, s15
	s_addc_u32 s13, s13, 0
	s_lshl_b32 s18, s92, 11
	global_load_dword v64, v196, s[12:13]
	global_load_dword v65, v196, s[12:13] offset:256
	s_add_u32 s12, s12, s18
	s_addc_u32 s13, s13, 0
	global_load_dword v66, v196, s[12:13]
	global_load_dword v67, v196, s[12:13] offset:256
	s_add_u32 s12, s12, s18
	s_addc_u32 s13, s13, 0
	global_load_dword v68, v196, s[12:13]
	global_load_dword v69, v196, s[12:13] offset:256
	s_add_u32 s12, s12, s18
	s_addc_u32 s13, s13, 0
	global_load_dword v70, v196, s[12:13]
	global_load_dword v71, v196, s[12:13] offset:256
	s_add_u32 s12, s12, s18
	s_addc_u32 s13, s13, 0
	global_load_dword v72, v196, s[12:13]
	global_load_dword v73, v196, s[12:13] offset:256
	s_add_u32 s12, s12, s18
	s_addc_u32 s13, s13, 0
	global_load_dword v74, v196, s[12:13]
	global_load_dword v75, v196, s[12:13] offset:256
	s_add_u32 s12, s12, s18
	s_addc_u32 s13, s13, 0
	global_load_dword v76, v196, s[12:13]
	global_load_dword v77, v196, s[12:13] offset:256
	s_add_u32 s12, s12, s18
	s_addc_u32 s13, s13, 0
	global_load_dword v78, v196, s[12:13]
	global_load_dword v79, v196, s[12:13] offset:256
	s_add_u32 s12, s12, s18
	s_addc_u32 s13, s13, 0
	global_load_dword v80, v196, s[12:13]
	global_load_dword v81, v196, s[12:13] offset:256
	s_add_u32 s12, s12, s18
	s_addc_u32 s13, s13, 0
	global_load_dword v82, v196, s[12:13]
	global_load_dword v83, v196, s[12:13] offset:256
	s_add_u32 s12, s12, s18
	s_addc_u32 s13, s13, 0
	global_load_dword v84, v196, s[12:13]
	global_load_dword v85, v196, s[12:13] offset:256
	s_add_u32 s12, s12, s18
	s_addc_u32 s13, s13, 0
	global_load_dword v86, v196, s[12:13]
	global_load_dword v87, v196, s[12:13] offset:256
	s_add_u32 s12, s12, s18
	s_addc_u32 s13, s13, 0
	global_load_dword v88, v196, s[12:13]
	global_load_dword v89, v196, s[12:13] offset:256
	s_add_u32 s12, s12, s18
	s_addc_u32 s13, s13, 0
	global_load_dword v90, v196, s[12:13]
	global_load_dword v91, v196, s[12:13] offset:256
	s_add_u32 s12, s12, s18
	s_addc_u32 s13, s13, 0
	global_load_dword v92, v196, s[12:13]
	global_load_dword v93, v196, s[12:13] offset:256
	s_add_u32 s12, s12, s18
	s_addc_u32 s13, s13, 0
	global_load_dword v94, v196, s[12:13]
	global_load_dword v95, v196, s[12:13] offset:256
	s_add_u32 s12, s12, s18
	s_addc_u32 s13, s13, 0
	s_waitcnt vmcnt(0)
	ds_write2st64_b32 v206, v64, v65 offset0:0 offset1:1
	ds_write2st64_b32 v206, v66, v67 offset0:2 offset1:3
	ds_write2st64_b32 v206, v68, v69 offset0:4 offset1:5
	ds_write2st64_b32 v206, v70, v71 offset0:6 offset1:7
	ds_write2st64_b32 v206, v72, v73 offset0:8 offset1:9
	ds_write2st64_b32 v206, v74, v75 offset0:10 offset1:11
	ds_write2st64_b32 v206, v76, v77 offset0:12 offset1:13
	ds_write2st64_b32 v206, v78, v79 offset0:14 offset1:15
	ds_write2st64_b32 v206, v80, v81 offset0:16 offset1:17
	ds_write2st64_b32 v206, v82, v83 offset0:18 offset1:19
	ds_write2st64_b32 v206, v84, v85 offset0:20 offset1:21
	ds_write2st64_b32 v206, v86, v87 offset0:22 offset1:23
	ds_write2st64_b32 v206, v88, v89 offset0:24 offset1:25
	ds_write2st64_b32 v206, v90, v91 offset0:26 offset1:27
	ds_write2st64_b32 v206, v92, v93 offset0:28 offset1:29
	ds_write2st64_b32 v206, v94, v95 offset0:30 offset1:31
	s_add_u32 s12, s26, 0xf800000
	s_addc_u32 s13, s27, 0
	s_lshl_b32 s15, s101, 9
	s_add_u32 s12, s12, s15
	s_addc_u32 s13, s13, 0
	s_lshl_b32 s18, s92, 11
	global_load_dword v64, v196, s[12:13]
	global_load_dword v65, v196, s[12:13] offset:256
	s_add_u32 s12, s12, s18
	s_addc_u32 s13, s13, 0
	global_load_dword v66, v196, s[12:13]
	global_load_dword v67, v196, s[12:13] offset:256
	s_add_u32 s12, s12, s18
	s_addc_u32 s13, s13, 0
	global_load_dword v68, v196, s[12:13]
	global_load_dword v69, v196, s[12:13] offset:256
	s_add_u32 s12, s12, s18
	s_addc_u32 s13, s13, 0
	global_load_dword v70, v196, s[12:13]
	global_load_dword v71, v196, s[12:13] offset:256
	s_add_u32 s12, s12, s18
	s_addc_u32 s13, s13, 0
	global_load_dword v72, v196, s[12:13]
	global_load_dword v73, v196, s[12:13] offset:256
	s_add_u32 s12, s12, s18
	s_addc_u32 s13, s13, 0
	global_load_dword v74, v196, s[12:13]
	global_load_dword v75, v196, s[12:13] offset:256
	s_add_u32 s12, s12, s18
	s_addc_u32 s13, s13, 0
	global_load_dword v76, v196, s[12:13]
	global_load_dword v77, v196, s[12:13] offset:256
	s_add_u32 s12, s12, s18
	s_addc_u32 s13, s13, 0
	global_load_dword v78, v196, s[12:13]
	global_load_dword v79, v196, s[12:13] offset:256
	s_add_u32 s12, s12, s18
	s_addc_u32 s13, s13, 0
	global_load_dword v80, v196, s[12:13]
	global_load_dword v81, v196, s[12:13] offset:256
	s_add_u32 s12, s12, s18
	s_addc_u32 s13, s13, 0
	global_load_dword v82, v196, s[12:13]
	global_load_dword v83, v196, s[12:13] offset:256
	s_add_u32 s12, s12, s18
	s_addc_u32 s13, s13, 0
	global_load_dword v84, v196, s[12:13]
	global_load_dword v85, v196, s[12:13] offset:256
	s_add_u32 s12, s12, s18
	s_addc_u32 s13, s13, 0
	global_load_dword v86, v196, s[12:13]
	global_load_dword v87, v196, s[12:13] offset:256
	s_add_u32 s12, s12, s18
	s_addc_u32 s13, s13, 0
	global_load_dword v88, v196, s[12:13]
	global_load_dword v89, v196, s[12:13] offset:256
	s_add_u32 s12, s12, s18
	s_addc_u32 s13, s13, 0
	global_load_dword v90, v196, s[12:13]
	global_load_dword v91, v196, s[12:13] offset:256
	s_add_u32 s12, s12, s18
	s_addc_u32 s13, s13, 0
	global_load_dword v92, v196, s[12:13]
	global_load_dword v93, v196, s[12:13] offset:256
	s_add_u32 s12, s12, s18
	s_addc_u32 s13, s13, 0
	global_load_dword v94, v196, s[12:13]
	global_load_dword v95, v196, s[12:13] offset:256
	s_add_u32 s12, s12, s18
	s_addc_u32 s13, s13, 0
	s_waitcnt vmcnt(0)
	ds_write2st64_b32 v208, v64, v65 offset0:0 offset1:1
	ds_write2st64_b32 v208, v66, v67 offset0:2 offset1:3
	ds_write2st64_b32 v208, v68, v69 offset0:4 offset1:5
	ds_write2st64_b32 v208, v70, v71 offset0:6 offset1:7
	ds_write2st64_b32 v208, v72, v73 offset0:8 offset1:9
	ds_write2st64_b32 v208, v74, v75 offset0:10 offset1:11
	ds_write2st64_b32 v208, v76, v77 offset0:12 offset1:13
	ds_write2st64_b32 v208, v78, v79 offset0:14 offset1:15
	ds_write2st64_b32 v208, v80, v81 offset0:16 offset1:17
	ds_write2st64_b32 v208, v82, v83 offset0:18 offset1:19
	ds_write2st64_b32 v208, v84, v85 offset0:20 offset1:21
	ds_write2st64_b32 v208, v86, v87 offset0:22 offset1:23
	ds_write2st64_b32 v208, v88, v89 offset0:24 offset1:25
	ds_write2st64_b32 v208, v90, v91 offset0:26 offset1:27
	ds_write2st64_b32 v208, v92, v93 offset0:28 offset1:29
	ds_write2st64_b32 v208, v94, v95 offset0:30 offset1:31
	s_waitcnt lgkmcnt(0)
	s_mov_b32 s14, 0
	s_and_b32 s19, s14, 15
	s_lshr_b32 s98, s14, 4
	s_lshl_b32 s99, s19, 9
	s_mul_i32 s15, s19, s16
	s_lshl_b32 s18, s98, 10
	s_add_u32 s15, s15, s18
	s_lshl_b32 s18, s101, 12
	s_add_u32 s15, s15, s18
	s_add_u32 s8, s24, s15
	s_addc_u32 s9, s25, 0
	s_mul_i32 s15, s98, 0x300000
	s_add_u32 s4, s26, 0x4800000
	s_addc_u32 s5, s27, 0
	s_add_u32 s4, s4, s15
	s_addc_u32 s5, s5, 0
	v_add_u32_e32 v201, s99, v197
	v_add_u32_e32 v203, s99, v198
	ds_read2_b32 v[160:161], v201 offset0:0 offset1:8
	ds_read2_b32 v[162:163], v201 offset0:16 offset1:24
	ds_read2_b32 v[164:165], v201 offset0:32 offset1:40
	ds_read2_b32 v[166:167], v201 offset0:48 offset1:56
	s_waitcnt lgkmcnt(0)
	s_waitcnt lgkmcnt(4)
	v_mad_u32_u24 v160, v160, s100, v199
	v_mad_u32_u24 v161, v161, s100, v199
	v_mad_u32_u24 v162, v162, s100, v199
	v_mad_u32_u24 v163, v163, s100, v199
	v_mad_u32_u24 v164, v164, s100, v199
	v_mad_u32_u24 v165, v165, s100, v199
	v_mad_u32_u24 v166, v166, s100, v199
	v_mad_u32_u24 v167, v167, s100, v199
	global_load_dwordx4 v[64:67], v160, s[4:5]
	global_load_dwordx2 v[68:69], v160, s[4:5] offset:16
	global_load_dwordx4 v[70:73], v161, s[4:5]
	global_load_dwordx2 v[74:75], v161, s[4:5] offset:16
	global_load_dwordx4 v[76:79], v162, s[4:5]
	global_load_dwordx2 v[80:81], v162, s[4:5] offset:16
	global_load_dwordx4 v[82:85], v163, s[4:5]
	global_load_dwordx2 v[86:87], v163, s[4:5] offset:16
	global_load_dwordx4 v[88:91], v164, s[4:5]
	global_load_dwordx2 v[92:93], v164, s[4:5] offset:16
	global_load_dwordx4 v[94:97], v165, s[4:5]
	global_load_dwordx2 v[98:99], v165, s[4:5] offset:16
	global_load_dwordx4 v[100:103], v166, s[4:5]
	global_load_dwordx2 v[104:105], v166, s[4:5] offset:16
	global_load_dwordx4 v[106:109], v167, s[4:5]
	global_load_dwordx2 v[110:111], v167, s[4:5] offset:16
	global_load_dword v209, v200, s[8:9]
	ds_read2_b32 v[168:169], v201 offset0:64 offset1:72
	ds_read2_b32 v[170:171], v201 offset0:80 offset1:88
	ds_read2_b32 v[172:173], v201 offset0:96 offset1:104
	ds_read2_b32 v[174:175], v201 offset0:112 offset1:120
	ds_read2_b32 v[176:177], v203 offset0:0 offset1:8
	ds_read2_b32 v[178:179], v203 offset0:16 offset1:24
	ds_read2_b32 v[180:181], v203 offset0:32 offset1:40
	ds_read2_b32 v[182:183], v203 offset0:48 offset1:56
.Lgv1_loop:
	global_load_dwordx4 v[192:195], v200, s[8:9]
	s_waitcnt lgkmcnt(4)
	v_mad_u32_u24 v168, v168, s100, v199
	v_mad_u32_u24 v169, v169, s100, v199
	v_mad_u32_u24 v170, v170, s100, v199
	v_mad_u32_u24 v171, v171, s100, v199
	v_mad_u32_u24 v172, v172, s100, v199
	v_mad_u32_u24 v173, v173, s100, v199
	v_mad_u32_u24 v174, v174, s100, v199
	v_mad_u32_u24 v175, v175, s100, v199
	global_load_dwordx4 v[112:115], v168, s[4:5]
	global_load_dwordx2 v[116:117], v168, s[4:5] offset:16
	global_load_dwordx4 v[118:121], v169, s[4:5]
	global_load_dwordx2 v[122:123], v169, s[4:5] offset:16
	global_load_dwordx4 v[124:127], v170, s[4:5]
	global_load_dwordx2 v[128:129], v170, s[4:5] offset:16
	global_load_dwordx4 v[130:133], v171, s[4:5]
	global_load_dwordx2 v[134:135], v171, s[4:5] offset:16
	global_load_dwordx4 v[136:139], v172, s[4:5]
	global_load_dwordx2 v[140:141], v172, s[4:5] offset:16
	global_load_dwordx4 v[142:145], v173, s[4:5]
	global_load_dwordx2 v[146:147], v173, s[4:5] offset:16
	global_load_dwordx4 v[148:151], v174, s[4:5]
	global_load_dwordx2 v[152:153], v174, s[4:5] offset:16
	global_load_dwordx4 v[154:157], v175, s[4:5]
	global_load_dwordx2 v[158:159], v175, s[4:5] offset:16
	s_add_u32 s14, s14, 1
	s_and_b32 s19, s14, 15
	s_lshr_b32 s98, s14, 4
	s_lshl_b32 s99, s19, 9
	s_mul_i32 s15, s19, s16
	s_lshl_b32 s18, s98, 10
	s_add_u32 s15, s15, s18
	s_lshl_b32 s18, s101, 12
	s_add_u32 s15, s15, s18
	s_add_u32 s10, s24, s15
	s_addc_u32 s11, s25, 0
	s_mul_i32 s15, s98, 0x300000
	s_add_u32 s4, s26, 0x4800000
	s_addc_u32 s5, s27, 0
	s_add_u32 s4, s4, s15
	s_addc_u32 s5, s5, 0
	v_add_u32_e32 v202, s99, v197
	v_add_u32_e32 v204, s99, v198
	ds_read2_b32 v[160:161], v202 offset0:0 offset1:8
	ds_read2_b32 v[162:163], v202 offset0:16 offset1:24
	ds_read2_b32 v[164:165], v202 offset0:32 offset1:40
	ds_read2_b32 v[166:167], v202 offset0:48 offset1:56
	ds_read2_b32 v[184:185], v203 offset0:64 offset1:72
	ds_read2_b32 v[186:187], v203 offset0:80 offset1:88
	ds_read2_b32 v[188:189], v203 offset0:96 offset1:104
	ds_read2_b32 v[190:191], v203 offset0:112 offset1:120
	s_waitcnt lgkmcnt(8)
	s_waitcnt vmcnt(32)
	v_cvt_scalef32_pk32_f32_fp6 v[32:63], v[64:69], 1.0
	v_pk_mul_f32 v[0:1], v[176:177], v[32:33] op_sel_hi:[0,1]
	v_pk_mul_f32 v[2:3], v[176:177], v[34:35] op_sel_hi:[0,1]
	v_pk_mul_f32 v[4:5], v[176:177], v[36:37] op_sel_hi:[0,1]
	v_pk_mul_f32 v[6:7], v[176:177], v[38:39] op_sel_hi:[0,1]
	v_pk_mul_f32 v[8:9], v[176:177], v[40:41] op_sel_hi:[0,1]
	v_pk_mul_f32 v[10:11], v[176:177], v[42:43] op_sel_hi:[0,1]
	v_pk_mul_f32 v[12:13], v[176:177], v[44:45] op_sel_hi:[0,1]
	v_pk_mul_f32 v[14:15], v[176:177], v[46:47] op_sel_hi:[0,1]
	v_pk_mul_f32 v[16:17], v[176:177], v[48:49] op_sel_hi:[0,1]
	v_pk_mul_f32 v[18:19], v[176:177], v[50:51] op_sel_hi:[0,1]
	v_pk_mul_f32 v[20:21], v[176:177], v[52:53] op_sel_hi:[0,1]
	v_pk_mul_f32 v[22:23], v[176:177], v[54:55] op_sel_hi:[0,1]
	v_pk_mul_f32 v[24:25], v[176:177], v[56:57] op_sel_hi:[0,1]
	v_pk_mul_f32 v[26:27], v[176:177], v[58:59] op_sel_hi:[0,1]
	v_pk_mul_f32 v[28:29], v[176:177], v[60:61] op_sel_hi:[0,1]
	v_pk_mul_f32 v[30:31], v[176:177], v[62:63] op_sel_hi:[0,1]
	s_waitcnt vmcnt(30)
	v_cvt_scalef32_pk32_f32_fp6 v[32:63], v[70:75], 1.0
	v_pk_fma_f32 v[0:1], v[176:177], v[32:33], v[0:1] op_sel:[1,0,0] op_sel_hi:[1,1,1]
	v_pk_fma_f32 v[2:3], v[176:177], v[34:35], v[2:3] op_sel:[1,0,0] op_sel_hi:[1,1,1]
	v_pk_fma_f32 v[4:5], v[176:177], v[36:37], v[4:5] op_sel:[1,0,0] op_sel_hi:[1,1,1]
	v_pk_fma_f32 v[6:7], v[176:177], v[38:39], v[6:7] op_sel:[1,0,0] op_sel_hi:[1,1,1]
	v_pk_fma_f32 v[8:9], v[176:177], v[40:41], v[8:9] op_sel:[1,0,0] op_sel_hi:[1,1,1]
	v_pk_fma_f32 v[10:11], v[176:177], v[42:43], v[10:11] op_sel:[1,0,0] op_sel_hi:[1,1,1]
	v_pk_fma_f32 v[12:13], v[176:177], v[44:45], v[12:13] op_sel:[1,0,0] op_sel_hi:[1,1,1]
	v_pk_fma_f32 v[14:15], v[176:177], v[46:47], v[14:15] op_sel:[1,0,0] op_sel_hi:[1,1,1]
	v_pk_fma_f32 v[16:17], v[176:177], v[48:49], v[16:17] op_sel:[1,0,0] op_sel_hi:[1,1,1]
	v_pk_fma_f32 v[18:19], v[176:177], v[50:51], v[18:19] op_sel:[1,0,0] op_sel_hi:[1,1,1]
	v_pk_fma_f32 v[20:21], v[176:177], v[52:53], v[20:21] op_sel:[1,0,0] op_sel_hi:[1,1,1]
	v_pk_fma_f32 v[22:23], v[176:177], v[54:55], v[22:23] op_sel:[1,0,0] op_sel_hi:[1,1,1]
	v_pk_fma_f32 v[24:25], v[176:177], v[56:57], v[24:25] op_sel:[1,0,0] op_sel_hi:[1,1,1]
	v_pk_fma_f32 v[26:27], v[176:177], v[58:59], v[26:27] op_sel:[1,0,0] op_sel_hi:[1,1,1]
	v_pk_fma_f32 v[28:29], v[176:177], v[60:61], v[28:29] op_sel:[1,0,0] op_sel_hi:[1,1,1]
	v_pk_fma_f32 v[30:31], v[176:177], v[62:63], v[30:31] op_sel:[1,0,0] op_sel_hi:[1,1,1]
	s_waitcnt vmcnt(28)
	v_cvt_scalef32_pk32_f32_fp6 v[32:63], v[76:81], 1.0
	v_pk_fma_f32 v[0:1], v[178:179], v[32:33], v[0:1] op_sel_hi:[0,1,1]
	v_pk_fma_f32 v[2:3], v[178:179], v[34:35], v[2:3] op_sel_hi:[0,1,1]
	v_pk_fma_f32 v[4:5], v[178:179], v[36:37], v[4:5] op_sel_hi:[0,1,1]
	v_pk_fma_f32 v[6:7], v[178:179], v[38:39], v[6:7] op_sel_hi:[0,1,1]
	v_pk_fma_f32 v[8:9], v[178:179], v[40:41], v[8:9] op_sel_hi:[0,1,1]
	v_pk_fma_f32 v[10:11], v[178:179], v[42:43], v[10:11] op_sel_hi:[0,1,1]
	v_pk_fma_f32 v[12:13], v[178:179], v[44:45], v[12:13] op_sel_hi:[0,1,1]
	v_pk_fma_f32 v[14:15], v[178:179], v[46:47], v[14:15] op_sel_hi:[0,1,1]
	v_pk_fma_f32 v[16:17], v[178:179], v[48:49], v[16:17] op_sel_hi:[0,1,1]
	v_pk_fma_f32 v[18:19], v[178:179], v[50:51], v[18:19] op_sel_hi:[0,1,1]
	v_pk_fma_f32 v[20:21], v[178:179], v[52:53], v[20:21] op_sel_hi:[0,1,1]
	v_pk_fma_f32 v[22:23], v[178:179], v[54:55], v[22:23] op_sel_hi:[0,1,1]
	v_pk_fma_f32 v[24:25], v[178:179], v[56:57], v[24:25] op_sel_hi:[0,1,1]
	v_pk_fma_f32 v[26:27], v[178:179], v[58:59], v[26:27] op_sel_hi:[0,1,1]
	v_pk_fma_f32 v[28:29], v[178:179], v[60:61], v[28:29] op_sel_hi:[0,1,1]
	v_pk_fma_f32 v[30:31], v[178:179], v[62:63], v[30:31] op_sel_hi:[0,1,1]
	s_waitcnt vmcnt(26)
	v_cvt_scalef32_pk32_f32_fp6 v[32:63], v[82:87], 1.0
	v_pk_fma_f32 v[0:1], v[178:179], v[32:33], v[0:1] op_sel:[1,0,0] op_sel_hi:[1,1,1]
	v_pk_fma_f32 v[2:3], v[178:179], v[34:35], v[2:3] op_sel:[1,0,0] op_sel_hi:[1,1,1]
	v_pk_fma_f32 v[4:5], v[178:179], v[36:37], v[4:5] op_sel:[1,0,0] op_sel_hi:[1,1,1]
	v_pk_fma_f32 v[6:7], v[178:179], v[38:39], v[6:7] op_sel:[1,0,0] op_sel_hi:[1,1,1]
	v_pk_fma_f32 v[8:9], v[178:179], v[40:41], v[8:9] op_sel:[1,0,0] op_sel_hi:[1,1,1]
	v_pk_fma_f32 v[10:11], v[178:179], v[42:43], v[10:11] op_sel:[1,0,0] op_sel_hi:[1,1,1]
	v_pk_fma_f32 v[12:13], v[178:179], v[44:45], v[12:13] op_sel:[1,0,0] op_sel_hi:[1,1,1]
	v_pk_fma_f32 v[14:15], v[178:179], v[46:47], v[14:15] op_sel:[1,0,0] op_sel_hi:[1,1,1]
	v_pk_fma_f32 v[16:17], v[178:179], v[48:49], v[16:17] op_sel:[1,0,0] op_sel_hi:[1,1,1]
	v_pk_fma_f32 v[18:19], v[178:179], v[50:51], v[18:19] op_sel:[1,0,0] op_sel_hi:[1,1,1]
	v_pk_fma_f32 v[20:21], v[178:179], v[52:53], v[20:21] op_sel:[1,0,0] op_sel_hi:[1,1,1]
	v_pk_fma_f32 v[22:23], v[178:179], v[54:55], v[22:23] op_sel:[1,0,0] op_sel_hi:[1,1,1]
	v_pk_fma_f32 v[24:25], v[178:179], v[56:57], v[24:25] op_sel:[1,0,0] op_sel_hi:[1,1,1]
	v_pk_fma_f32 v[26:27], v[178:179], v[58:59], v[26:27] op_sel:[1,0,0] op_sel_hi:[1,1,1]
	v_pk_fma_f32 v[28:29], v[178:179], v[60:61], v[28:29] op_sel:[1,0,0] op_sel_hi:[1,1,1]
	v_pk_fma_f32 v[30:31], v[178:179], v[62:63], v[30:31] op_sel:[1,0,0] op_sel_hi:[1,1,1]
	s_waitcnt vmcnt(24)
	v_cvt_scalef32_pk32_f32_fp6 v[32:63], v[88:93], 1.0
	v_pk_fma_f32 v[0:1], v[180:181], v[32:33], v[0:1] op_sel_hi:[0,1,1]
	v_pk_fma_f32 v[2:3], v[180:181], v[34:35], v[2:3] op_sel_hi:[0,1,1]
	v_pk_fma_f32 v[4:5], v[180:181], v[36:37], v[4:5] op_sel_hi:[0,1,1]
	v_pk_fma_f32 v[6:7], v[180:181], v[38:39], v[6:7] op_sel_hi:[0,1,1]
	v_pk_fma_f32 v[8:9], v[180:181], v[40:41], v[8:9] op_sel_hi:[0,1,1]
	v_pk_fma_f32 v[10:11], v[180:181], v[42:43], v[10:11] op_sel_hi:[0,1,1]
	v_pk_fma_f32 v[12:13], v[180:181], v[44:45], v[12:13] op_sel_hi:[0,1,1]
	v_pk_fma_f32 v[14:15], v[180:181], v[46:47], v[14:15] op_sel_hi:[0,1,1]
	v_pk_fma_f32 v[16:17], v[180:181], v[48:49], v[16:17] op_sel_hi:[0,1,1]
	v_pk_fma_f32 v[18:19], v[180:181], v[50:51], v[18:19] op_sel_hi:[0,1,1]
	v_pk_fma_f32 v[20:21], v[180:181], v[52:53], v[20:21] op_sel_hi:[0,1,1]
	v_pk_fma_f32 v[22:23], v[180:181], v[54:55], v[22:23] op_sel_hi:[0,1,1]
	v_pk_fma_f32 v[24:25], v[180:181], v[56:57], v[24:25] op_sel_hi:[0,1,1]
	v_pk_fma_f32 v[26:27], v[180:181], v[58:59], v[26:27] op_sel_hi:[0,1,1]
	v_pk_fma_f32 v[28:29], v[180:181], v[60:61], v[28:29] op_sel_hi:[0,1,1]
	v_pk_fma_f32 v[30:31], v[180:181], v[62:63], v[30:31] op_sel_hi:[0,1,1]
	s_waitcnt vmcnt(22)
	v_cvt_scalef32_pk32_f32_fp6 v[32:63], v[94:99], 1.0
	v_pk_fma_f32 v[0:1], v[180:181], v[32:33], v[0:1] op_sel:[1,0,0] op_sel_hi:[1,1,1]
	v_pk_fma_f32 v[2:3], v[180:181], v[34:35], v[2:3] op_sel:[1,0,0] op_sel_hi:[1,1,1]
	v_pk_fma_f32 v[4:5], v[180:181], v[36:37], v[4:5] op_sel:[1,0,0] op_sel_hi:[1,1,1]
	v_pk_fma_f32 v[6:7], v[180:181], v[38:39], v[6:7] op_sel:[1,0,0] op_sel_hi:[1,1,1]
	v_pk_fma_f32 v[8:9], v[180:181], v[40:41], v[8:9] op_sel:[1,0,0] op_sel_hi:[1,1,1]
	v_pk_fma_f32 v[10:11], v[180:181], v[42:43], v[10:11] op_sel:[1,0,0] op_sel_hi:[1,1,1]
	v_pk_fma_f32 v[12:13], v[180:181], v[44:45], v[12:13] op_sel:[1,0,0] op_sel_hi:[1,1,1]
	v_pk_fma_f32 v[14:15], v[180:181], v[46:47], v[14:15] op_sel:[1,0,0] op_sel_hi:[1,1,1]
	v_pk_fma_f32 v[16:17], v[180:181], v[48:49], v[16:17] op_sel:[1,0,0] op_sel_hi:[1,1,1]
	v_pk_fma_f32 v[18:19], v[180:181], v[50:51], v[18:19] op_sel:[1,0,0] op_sel_hi:[1,1,1]
	v_pk_fma_f32 v[20:21], v[180:181], v[52:53], v[20:21] op_sel:[1,0,0] op_sel_hi:[1,1,1]
	v_pk_fma_f32 v[22:23], v[180:181], v[54:55], v[22:23] op_sel:[1,0,0] op_sel_hi:[1,1,1]
	v_pk_fma_f32 v[24:25], v[180:181], v[56:57], v[24:25] op_sel:[1,0,0] op_sel_hi:[1,1,1]
	v_pk_fma_f32 v[26:27], v[180:181], v[58:59], v[26:27] op_sel:[1,0,0] op_sel_hi:[1,1,1]
	v_pk_fma_f32 v[28:29], v[180:181], v[60:61], v[28:29] op_sel:[1,0,0] op_sel_hi:[1,1,1]
	v_pk_fma_f32 v[30:31], v[180:181], v[62:63], v[30:31] op_sel:[1,0,0] op_sel_hi:[1,1,1]
	s_waitcnt vmcnt(20)
	v_cvt_scalef32_pk32_f32_fp6 v[32:63], v[100:105], 1.0
	v_pk_fma_f32 v[0:1], v[182:183], v[32:33], v[0:1] op_sel_hi:[0,1,1]
	v_pk_fma_f32 v[2:3], v[182:183], v[34:35], v[2:3] op_sel_hi:[0,1,1]
	v_pk_fma_f32 v[4:5], v[182:183], v[36:37], v[4:5] op_sel_hi:[0,1,1]
	v_pk_fma_f32 v[6:7], v[182:183], v[38:39], v[6:7] op_sel_hi:[0,1,1]
	v_pk_fma_f32 v[8:9], v[182:183], v[40:41], v[8:9] op_sel_hi:[0,1,1]
	v_pk_fma_f32 v[10:11], v[182:183], v[42:43], v[10:11] op_sel_hi:[0,1,1]
	v_pk_fma_f32 v[12:13], v[182:183], v[44:45], v[12:13] op_sel_hi:[0,1,1]
	v_pk_fma_f32 v[14:15], v[182:183], v[46:47], v[14:15] op_sel_hi:[0,1,1]
	v_pk_fma_f32 v[16:17], v[182:183], v[48:49], v[16:17] op_sel_hi:[0,1,1]
	v_pk_fma_f32 v[18:19], v[182:183], v[50:51], v[18:19] op_sel_hi:[0,1,1]
	v_pk_fma_f32 v[20:21], v[182:183], v[52:53], v[20:21] op_sel_hi:[0,1,1]
	v_pk_fma_f32 v[22:23], v[182:183], v[54:55], v[22:23] op_sel_hi:[0,1,1]
	v_pk_fma_f32 v[24:25], v[182:183], v[56:57], v[24:25] op_sel_hi:[0,1,1]
	v_pk_fma_f32 v[26:27], v[182:183], v[58:59], v[26:27] op_sel_hi:[0,1,1]
	v_pk_fma_f32 v[28:29], v[182:183], v[60:61], v[28:29] op_sel_hi:[0,1,1]
	v_pk_fma_f32 v[30:31], v[182:183], v[62:63], v[30:31] op_sel_hi:[0,1,1]
	s_waitcnt vmcnt(18)
	v_cvt_scalef32_pk32_f32_fp6 v[32:63], v[106:111], 1.0
	v_pk_fma_f32 v[0:1], v[182:183], v[32:33], v[0:1] op_sel:[1,0,0] op_sel_hi:[1,1,1]
	v_pk_fma_f32 v[2:3], v[182:183], v[34:35], v[2:3] op_sel:[1,0,0] op_sel_hi:[1,1,1]
	v_pk_fma_f32 v[4:5], v[182:183], v[36:37], v[4:5] op_sel:[1,0,0] op_sel_hi:[1,1,1]
	v_pk_fma_f32 v[6:7], v[182:183], v[38:39], v[6:7] op_sel:[1,0,0] op_sel_hi:[1,1,1]
	v_pk_fma_f32 v[8:9], v[182:183], v[40:41], v[8:9] op_sel:[1,0,0] op_sel_hi:[1,1,1]
	v_pk_fma_f32 v[10:11], v[182:183], v[42:43], v[10:11] op_sel:[1,0,0] op_sel_hi:[1,1,1]
	v_pk_fma_f32 v[12:13], v[182:183], v[44:45], v[12:13] op_sel:[1,0,0] op_sel_hi:[1,1,1]
	v_pk_fma_f32 v[14:15], v[182:183], v[46:47], v[14:15] op_sel:[1,0,0] op_sel_hi:[1,1,1]
	v_pk_fma_f32 v[16:17], v[182:183], v[48:49], v[16:17] op_sel:[1,0,0] op_sel_hi:[1,1,1]
	v_pk_fma_f32 v[18:19], v[182:183], v[50:51], v[18:19] op_sel:[1,0,0] op_sel_hi:[1,1,1]
	v_pk_fma_f32 v[20:21], v[182:183], v[52:53], v[20:21] op_sel:[1,0,0] op_sel_hi:[1,1,1]
	v_pk_fma_f32 v[22:23], v[182:183], v[54:55], v[22:23] op_sel:[1,0,0] op_sel_hi:[1,1,1]
	v_pk_fma_f32 v[24:25], v[182:183], v[56:57], v[24:25] op_sel:[1,0,0] op_sel_hi:[1,1,1]
	v_pk_fma_f32 v[26:27], v[182:183], v[58:59], v[26:27] op_sel:[1,0,0] op_sel_hi:[1,1,1]
	v_pk_fma_f32 v[28:29], v[182:183], v[60:61], v[28:29] op_sel:[1,0,0] op_sel_hi:[1,1,1]
	v_pk_fma_f32 v[30:31], v[182:183], v[62:63], v[30:31] op_sel:[1,0,0] op_sel_hi:[1,1,1]
	s_waitcnt lgkmcnt(4)
	v_mad_u32_u24 v160, v160, s100, v199
	v_mad_u32_u24 v161, v161, s100, v199
	v_mad_u32_u24 v162, v162, s100, v199
	v_mad_u32_u24 v163, v163, s100, v199
	v_mad_u32_u24 v164, v164, s100, v199
	v_mad_u32_u24 v165, v165, s100, v199
	v_mad_u32_u24 v166, v166, s100, v199
	v_mad_u32_u24 v167, v167, s100, v199
	global_load_dwordx4 v[64:67], v160, s[4:5]
	global_load_dwordx2 v[68:69], v160, s[4:5] offset:16
	global_load_dwordx4 v[70:73], v161, s[4:5]
	global_load_dwordx2 v[74:75], v161, s[4:5] offset:16
	global_load_dwordx4 v[76:79], v162, s[4:5]
	global_load_dwordx2 v[80:81], v162, s[4:5] offset:16
	global_load_dwordx4 v[82:85], v163, s[4:5]
	global_load_dwordx2 v[86:87], v163, s[4:5] offset:16
	global_load_dwordx4 v[88:91], v164, s[4:5]
	global_load_dwordx2 v[92:93], v164, s[4:5] offset:16
	global_load_dwordx4 v[94:97], v165, s[4:5]
	global_load_dwordx2 v[98:99], v165, s[4:5] offset:16
	global_load_dwordx4 v[100:103], v166, s[4:5]
	global_load_dwordx2 v[104:105], v166, s[4:5] offset:16
	global_load_dwordx4 v[106:109], v167, s[4:5]
	global_load_dwordx2 v[110:111], v167, s[4:5] offset:16
	ds_read2_b32 v[168:169], v202 offset0:64 offset1:72
	ds_read2_b32 v[170:171], v202 offset0:80 offset1:88
	ds_read2_b32 v[172:173], v202 offset0:96 offset1:104
	ds_read2_b32 v[174:175], v202 offset0:112 offset1:120
	ds_read2_b32 v[176:177], v204 offset0:0 offset1:8
	ds_read2_b32 v[178:179], v204 offset0:16 offset1:24
	ds_read2_b32 v[180:181], v204 offset0:32 offset1:40
	ds_read2_b32 v[182:183], v204 offset0:48 offset1:56
	s_waitcnt lgkmcnt(8)
	s_waitcnt vmcnt(30)
	v_cvt_scalef32_pk32_f32_fp6 v[32:63], v[112:117], 1.0
	v_pk_fma_f32 v[0:1], v[184:185], v[32:33], v[0:1] op_sel_hi:[0,1,1]
	v_pk_fma_f32 v[2:3], v[184:185], v[34:35], v[2:3] op_sel_hi:[0,1,1]
	v_pk_fma_f32 v[4:5], v[184:185], v[36:37], v[4:5] op_sel_hi:[0,1,1]
	v_pk_fma_f32 v[6:7], v[184:185], v[38:39], v[6:7] op_sel_hi:[0,1,1]
	v_pk_fma_f32 v[8:9], v[184:185], v[40:41], v[8:9] op_sel_hi:[0,1,1]
	v_pk_fma_f32 v[10:11], v[184:185], v[42:43], v[10:11] op_sel_hi:[0,1,1]
	v_pk_fma_f32 v[12:13], v[184:185], v[44:45], v[12:13] op_sel_hi:[0,1,1]
	v_pk_fma_f32 v[14:15], v[184:185], v[46:47], v[14:15] op_sel_hi:[0,1,1]
	v_pk_fma_f32 v[16:17], v[184:185], v[48:49], v[16:17] op_sel_hi:[0,1,1]
	v_pk_fma_f32 v[18:19], v[184:185], v[50:51], v[18:19] op_sel_hi:[0,1,1]
	v_pk_fma_f32 v[20:21], v[184:185], v[52:53], v[20:21] op_sel_hi:[0,1,1]
	v_pk_fma_f32 v[22:23], v[184:185], v[54:55], v[22:23] op_sel_hi:[0,1,1]
	v_pk_fma_f32 v[24:25], v[184:185], v[56:57], v[24:25] op_sel_hi:[0,1,1]
	v_pk_fma_f32 v[26:27], v[184:185], v[58:59], v[26:27] op_sel_hi:[0,1,1]
	v_pk_fma_f32 v[28:29], v[184:185], v[60:61], v[28:29] op_sel_hi:[0,1,1]
	v_pk_fma_f32 v[30:31], v[184:185], v[62:63], v[30:31] op_sel_hi:[0,1,1]
	s_waitcnt vmcnt(28)
	v_cvt_scalef32_pk32_f32_fp6 v[32:63], v[118:123], 1.0
	v_pk_fma_f32 v[0:1], v[184:185], v[32:33], v[0:1] op_sel:[1,0,0] op_sel_hi:[1,1,1]
	v_pk_fma_f32 v[2:3], v[184:185], v[34:35], v[2:3] op_sel:[1,0,0] op_sel_hi:[1,1,1]
	v_pk_fma_f32 v[4:5], v[184:185], v[36:37], v[4:5] op_sel:[1,0,0] op_sel_hi:[1,1,1]
	v_pk_fma_f32 v[6:7], v[184:185], v[38:39], v[6:7] op_sel:[1,0,0] op_sel_hi:[1,1,1]
	v_pk_fma_f32 v[8:9], v[184:185], v[40:41], v[8:9] op_sel:[1,0,0] op_sel_hi:[1,1,1]
	v_pk_fma_f32 v[10:11], v[184:185], v[42:43], v[10:11] op_sel:[1,0,0] op_sel_hi:[1,1,1]
	v_pk_fma_f32 v[12:13], v[184:185], v[44:45], v[12:13] op_sel:[1,0,0] op_sel_hi:[1,1,1]
	v_pk_fma_f32 v[14:15], v[184:185], v[46:47], v[14:15] op_sel:[1,0,0] op_sel_hi:[1,1,1]
	v_pk_fma_f32 v[16:17], v[184:185], v[48:49], v[16:17] op_sel:[1,0,0] op_sel_hi:[1,1,1]
	v_pk_fma_f32 v[18:19], v[184:185], v[50:51], v[18:19] op_sel:[1,0,0] op_sel_hi:[1,1,1]
	v_pk_fma_f32 v[20:21], v[184:185], v[52:53], v[20:21] op_sel:[1,0,0] op_sel_hi:[1,1,1]
	v_pk_fma_f32 v[22:23], v[184:185], v[54:55], v[22:23] op_sel:[1,0,0] op_sel_hi:[1,1,1]
	v_pk_fma_f32 v[24:25], v[184:185], v[56:57], v[24:25] op_sel:[1,0,0] op_sel_hi:[1,1,1]
	v_pk_fma_f32 v[26:27], v[184:185], v[58:59], v[26:27] op_sel:[1,0,0] op_sel_hi:[1,1,1]
	v_pk_fma_f32 v[28:29], v[184:185], v[60:61], v[28:29] op_sel:[1,0,0] op_sel_hi:[1,1,1]
	v_pk_fma_f32 v[30:31], v[184:185], v[62:63], v[30:31] op_sel:[1,0,0] op_sel_hi:[1,1,1]
	s_waitcnt vmcnt(26)
	v_cvt_scalef32_pk32_f32_fp6 v[32:63], v[124:129], 1.0
	v_pk_fma_f32 v[0:1], v[186:187], v[32:33], v[0:1] op_sel_hi:[0,1,1]
	v_pk_fma_f32 v[2:3], v[186:187], v[34:35], v[2:3] op_sel_hi:[0,1,1]
	v_pk_fma_f32 v[4:5], v[186:187], v[36:37], v[4:5] op_sel_hi:[0,1,1]
	v_pk_fma_f32 v[6:7], v[186:187], v[38:39], v[6:7] op_sel_hi:[0,1,1]
	v_pk_fma_f32 v[8:9], v[186:187], v[40:41], v[8:9] op_sel_hi:[0,1,1]
	v_pk_fma_f32 v[10:11], v[186:187], v[42:43], v[10:11] op_sel_hi:[0,1,1]
	v_pk_fma_f32 v[12:13], v[186:187], v[44:45], v[12:13] op_sel_hi:[0,1,1]
	v_pk_fma_f32 v[14:15], v[186:187], v[46:47], v[14:15] op_sel_hi:[0,1,1]
	v_pk_fma_f32 v[16:17], v[186:187], v[48:49], v[16:17] op_sel_hi:[0,1,1]
	v_pk_fma_f32 v[18:19], v[186:187], v[50:51], v[18:19] op_sel_hi:[0,1,1]
	v_pk_fma_f32 v[20:21], v[186:187], v[52:53], v[20:21] op_sel_hi:[0,1,1]
	v_pk_fma_f32 v[22:23], v[186:187], v[54:55], v[22:23] op_sel_hi:[0,1,1]
	v_pk_fma_f32 v[24:25], v[186:187], v[56:57], v[24:25] op_sel_hi:[0,1,1]
	v_pk_fma_f32 v[26:27], v[186:187], v[58:59], v[26:27] op_sel_hi:[0,1,1]
	v_pk_fma_f32 v[28:29], v[186:187], v[60:61], v[28:29] op_sel_hi:[0,1,1]
	v_pk_fma_f32 v[30:31], v[186:187], v[62:63], v[30:31] op_sel_hi:[0,1,1]
	s_waitcnt vmcnt(24)
	v_cvt_scalef32_pk32_f32_fp6 v[32:63], v[130:135], 1.0
	v_pk_fma_f32 v[0:1], v[186:187], v[32:33], v[0:1] op_sel:[1,0,0] op_sel_hi:[1,1,1]
	v_pk_fma_f32 v[2:3], v[186:187], v[34:35], v[2:3] op_sel:[1,0,0] op_sel_hi:[1,1,1]
	v_pk_fma_f32 v[4:5], v[186:187], v[36:37], v[4:5] op_sel:[1,0,0] op_sel_hi:[1,1,1]
	v_pk_fma_f32 v[6:7], v[186:187], v[38:39], v[6:7] op_sel:[1,0,0] op_sel_hi:[1,1,1]
	v_pk_fma_f32 v[8:9], v[186:187], v[40:41], v[8:9] op_sel:[1,0,0] op_sel_hi:[1,1,1]
	v_pk_fma_f32 v[10:11], v[186:187], v[42:43], v[10:11] op_sel:[1,0,0] op_sel_hi:[1,1,1]
	v_pk_fma_f32 v[12:13], v[186:187], v[44:45], v[12:13] op_sel:[1,0,0] op_sel_hi:[1,1,1]
	v_pk_fma_f32 v[14:15], v[186:187], v[46:47], v[14:15] op_sel:[1,0,0] op_sel_hi:[1,1,1]
	v_pk_fma_f32 v[16:17], v[186:187], v[48:49], v[16:17] op_sel:[1,0,0] op_sel_hi:[1,1,1]
	v_pk_fma_f32 v[18:19], v[186:187], v[50:51], v[18:19] op_sel:[1,0,0] op_sel_hi:[1,1,1]
	v_pk_fma_f32 v[20:21], v[186:187], v[52:53], v[20:21] op_sel:[1,0,0] op_sel_hi:[1,1,1]
	v_pk_fma_f32 v[22:23], v[186:187], v[54:55], v[22:23] op_sel:[1,0,0] op_sel_hi:[1,1,1]
	v_pk_fma_f32 v[24:25], v[186:187], v[56:57], v[24:25] op_sel:[1,0,0] op_sel_hi:[1,1,1]
	v_pk_fma_f32 v[26:27], v[186:187], v[58:59], v[26:27] op_sel:[1,0,0] op_sel_hi:[1,1,1]
	v_pk_fma_f32 v[28:29], v[186:187], v[60:61], v[28:29] op_sel:[1,0,0] op_sel_hi:[1,1,1]
	v_pk_fma_f32 v[30:31], v[186:187], v[62:63], v[30:31] op_sel:[1,0,0] op_sel_hi:[1,1,1]
	s_waitcnt vmcnt(22)
	v_cvt_scalef32_pk32_f32_fp6 v[32:63], v[136:141], 1.0
	v_pk_fma_f32 v[0:1], v[188:189], v[32:33], v[0:1] op_sel_hi:[0,1,1]
	v_pk_fma_f32 v[2:3], v[188:189], v[34:35], v[2:3] op_sel_hi:[0,1,1]
	v_pk_fma_f32 v[4:5], v[188:189], v[36:37], v[4:5] op_sel_hi:[0,1,1]
	v_pk_fma_f32 v[6:7], v[188:189], v[38:39], v[6:7] op_sel_hi:[0,1,1]
	v_pk_fma_f32 v[8:9], v[188:189], v[40:41], v[8:9] op_sel_hi:[0,1,1]
	v_pk_fma_f32 v[10:11], v[188:189], v[42:43], v[10:11] op_sel_hi:[0,1,1]
	v_pk_fma_f32 v[12:13], v[188:189], v[44:45], v[12:13] op_sel_hi:[0,1,1]
	v_pk_fma_f32 v[14:15], v[188:189], v[46:47], v[14:15] op_sel_hi:[0,1,1]
	v_pk_fma_f32 v[16:17], v[188:189], v[48:49], v[16:17] op_sel_hi:[0,1,1]
	v_pk_fma_f32 v[18:19], v[188:189], v[50:51], v[18:19] op_sel_hi:[0,1,1]
	v_pk_fma_f32 v[20:21], v[188:189], v[52:53], v[20:21] op_sel_hi:[0,1,1]
	v_pk_fma_f32 v[22:23], v[188:189], v[54:55], v[22:23] op_sel_hi:[0,1,1]
	v_pk_fma_f32 v[24:25], v[188:189], v[56:57], v[24:25] op_sel_hi:[0,1,1]
	v_pk_fma_f32 v[26:27], v[188:189], v[58:59], v[26:27] op_sel_hi:[0,1,1]
	v_pk_fma_f32 v[28:29], v[188:189], v[60:61], v[28:29] op_sel_hi:[0,1,1]
	v_pk_fma_f32 v[30:31], v[188:189], v[62:63], v[30:31] op_sel_hi:[0,1,1]
	s_waitcnt vmcnt(20)
	v_cvt_scalef32_pk32_f32_fp6 v[32:63], v[142:147], 1.0
	v_pk_fma_f32 v[0:1], v[188:189], v[32:33], v[0:1] op_sel:[1,0,0] op_sel_hi:[1,1,1]
	v_pk_fma_f32 v[2:3], v[188:189], v[34:35], v[2:3] op_sel:[1,0,0] op_sel_hi:[1,1,1]
	v_pk_fma_f32 v[4:5], v[188:189], v[36:37], v[4:5] op_sel:[1,0,0] op_sel_hi:[1,1,1]
	v_pk_fma_f32 v[6:7], v[188:189], v[38:39], v[6:7] op_sel:[1,0,0] op_sel_hi:[1,1,1]
	v_pk_fma_f32 v[8:9], v[188:189], v[40:41], v[8:9] op_sel:[1,0,0] op_sel_hi:[1,1,1]
	v_pk_fma_f32 v[10:11], v[188:189], v[42:43], v[10:11] op_sel:[1,0,0] op_sel_hi:[1,1,1]
	v_pk_fma_f32 v[12:13], v[188:189], v[44:45], v[12:13] op_sel:[1,0,0] op_sel_hi:[1,1,1]
	v_pk_fma_f32 v[14:15], v[188:189], v[46:47], v[14:15] op_sel:[1,0,0] op_sel_hi:[1,1,1]
	v_pk_fma_f32 v[16:17], v[188:189], v[48:49], v[16:17] op_sel:[1,0,0] op_sel_hi:[1,1,1]
	v_pk_fma_f32 v[18:19], v[188:189], v[50:51], v[18:19] op_sel:[1,0,0] op_sel_hi:[1,1,1]
	v_pk_fma_f32 v[20:21], v[188:189], v[52:53], v[20:21] op_sel:[1,0,0] op_sel_hi:[1,1,1]
	v_pk_fma_f32 v[22:23], v[188:189], v[54:55], v[22:23] op_sel:[1,0,0] op_sel_hi:[1,1,1]
	v_pk_fma_f32 v[24:25], v[188:189], v[56:57], v[24:25] op_sel:[1,0,0] op_sel_hi:[1,1,1]
	v_pk_fma_f32 v[26:27], v[188:189], v[58:59], v[26:27] op_sel:[1,0,0] op_sel_hi:[1,1,1]
	v_pk_fma_f32 v[28:29], v[188:189], v[60:61], v[28:29] op_sel:[1,0,0] op_sel_hi:[1,1,1]
	v_pk_fma_f32 v[30:31], v[188:189], v[62:63], v[30:31] op_sel:[1,0,0] op_sel_hi:[1,1,1]
	s_waitcnt vmcnt(18)
	v_cvt_scalef32_pk32_f32_fp6 v[32:63], v[148:153], 1.0
	v_pk_fma_f32 v[0:1], v[190:191], v[32:33], v[0:1] op_sel_hi:[0,1,1]
	v_pk_fma_f32 v[2:3], v[190:191], v[34:35], v[2:3] op_sel_hi:[0,1,1]
	v_pk_fma_f32 v[4:5], v[190:191], v[36:37], v[4:5] op_sel_hi:[0,1,1]
	v_pk_fma_f32 v[6:7], v[190:191], v[38:39], v[6:7] op_sel_hi:[0,1,1]
	v_pk_fma_f32 v[8:9], v[190:191], v[40:41], v[8:9] op_sel_hi:[0,1,1]
	v_pk_fma_f32 v[10:11], v[190:191], v[42:43], v[10:11] op_sel_hi:[0,1,1]
	v_pk_fma_f32 v[12:13], v[190:191], v[44:45], v[12:13] op_sel_hi:[0,1,1]
	v_pk_fma_f32 v[14:15], v[190:191], v[46:47], v[14:15] op_sel_hi:[0,1,1]
	v_pk_fma_f32 v[16:17], v[190:191], v[48:49], v[16:17] op_sel_hi:[0,1,1]
	v_pk_fma_f32 v[18:19], v[190:191], v[50:51], v[18:19] op_sel_hi:[0,1,1]
	v_pk_fma_f32 v[20:21], v[190:191], v[52:53], v[20:21] op_sel_hi:[0,1,1]
	v_pk_fma_f32 v[22:23], v[190:191], v[54:55], v[22:23] op_sel_hi:[0,1,1]
	v_pk_fma_f32 v[24:25], v[190:191], v[56:57], v[24:25] op_sel_hi:[0,1,1]
	v_pk_fma_f32 v[26:27], v[190:191], v[58:59], v[26:27] op_sel_hi:[0,1,1]
	v_pk_fma_f32 v[28:29], v[190:191], v[60:61], v[28:29] op_sel_hi:[0,1,1]
	v_pk_fma_f32 v[30:31], v[190:191], v[62:63], v[30:31] op_sel_hi:[0,1,1]
	s_waitcnt vmcnt(16)
	v_cvt_scalef32_pk32_f32_fp6 v[32:63], v[154:159], 1.0
	v_pk_fma_f32 v[0:1], v[190:191], v[32:33], v[0:1] op_sel:[1,0,0] op_sel_hi:[1,1,1]
	v_pk_fma_f32 v[2:3], v[190:191], v[34:35], v[2:3] op_sel:[1,0,0] op_sel_hi:[1,1,1]
	v_pk_fma_f32 v[4:5], v[190:191], v[36:37], v[4:5] op_sel:[1,0,0] op_sel_hi:[1,1,1]
	v_pk_fma_f32 v[6:7], v[190:191], v[38:39], v[6:7] op_sel:[1,0,0] op_sel_hi:[1,1,1]
	v_pk_fma_f32 v[8:9], v[190:191], v[40:41], v[8:9] op_sel:[1,0,0] op_sel_hi:[1,1,1]
	v_pk_fma_f32 v[10:11], v[190:191], v[42:43], v[10:11] op_sel:[1,0,0] op_sel_hi:[1,1,1]
	v_pk_fma_f32 v[12:13], v[190:191], v[44:45], v[12:13] op_sel:[1,0,0] op_sel_hi:[1,1,1]
	v_pk_fma_f32 v[14:15], v[190:191], v[46:47], v[14:15] op_sel:[1,0,0] op_sel_hi:[1,1,1]
	v_pk_fma_f32 v[16:17], v[190:191], v[48:49], v[16:17] op_sel:[1,0,0] op_sel_hi:[1,1,1]
	v_pk_fma_f32 v[18:19], v[190:191], v[50:51], v[18:19] op_sel:[1,0,0] op_sel_hi:[1,1,1]
	v_pk_fma_f32 v[20:21], v[190:191], v[52:53], v[20:21] op_sel:[1,0,0] op_sel_hi:[1,1,1]
	v_pk_fma_f32 v[22:23], v[190:191], v[54:55], v[22:23] op_sel:[1,0,0] op_sel_hi:[1,1,1]
	v_pk_fma_f32 v[24:25], v[190:191], v[56:57], v[24:25] op_sel:[1,0,0] op_sel_hi:[1,1,1]
	v_pk_fma_f32 v[26:27], v[190:191], v[58:59], v[26:27] op_sel:[1,0,0] op_sel_hi:[1,1,1]
	v_pk_fma_f32 v[28:29], v[190:191], v[60:61], v[28:29] op_sel:[1,0,0] op_sel_hi:[1,1,1]
	v_pk_fma_f32 v[30:31], v[190:191], v[62:63], v[30:31] op_sel:[1,0,0] op_sel_hi:[1,1,1]
	s_nop 1
	v_permlane32_swap_b32_e32 v0, v16
	v_permlane32_swap_b32_e32 v1, v17
	v_permlane32_swap_b32_e32 v2, v18
	v_permlane32_swap_b32_e32 v3, v19
	v_permlane32_swap_b32_e32 v4, v20
	v_permlane32_swap_b32_e32 v5, v21
	v_permlane32_swap_b32_e32 v6, v22
	v_permlane32_swap_b32_e32 v7, v23
	v_permlane32_swap_b32_e32 v8, v24
	v_permlane32_swap_b32_e32 v9, v25
	v_permlane32_swap_b32_e32 v10, v26
	v_permlane32_swap_b32_e32 v11, v27
	v_permlane32_swap_b32_e32 v12, v28
	v_permlane32_swap_b32_e32 v13, v29
	v_permlane32_swap_b32_e32 v14, v30
	v_permlane32_swap_b32_e32 v15, v31
	v_pk_add_f32 v[0:1], v[0:1], v[16:17]
	v_pk_add_f32 v[2:3], v[2:3], v[18:19]
	v_pk_add_f32 v[4:5], v[4:5], v[20:21]
	v_pk_add_f32 v[6:7], v[6:7], v[22:23]
	v_pk_add_f32 v[8:9], v[8:9], v[24:25]
	v_pk_add_f32 v[10:11], v[10:11], v[26:27]
	v_pk_add_f32 v[12:13], v[12:13], v[28:29]
	v_pk_add_f32 v[14:15], v[14:15], v[30:31]
	s_nop 1
	v_permlane16_swap_b32_e32 v0, v8
	v_permlane16_swap_b32_e32 v1, v9
	v_permlane16_swap_b32_e32 v2, v10
	v_permlane16_swap_b32_e32 v3, v11
	v_permlane16_swap_b32_e32 v4, v12
	v_permlane16_swap_b32_e32 v5, v13
	v_permlane16_swap_b32_e32 v6, v14
	v_permlane16_swap_b32_e32 v7, v15
	v_pk_add_f32 v[0:1], v[0:1], v[8:9]
	v_pk_add_f32 v[2:3], v[2:3], v[10:11]
	v_pk_add_f32 v[4:5], v[4:5], v[12:13]
	v_pk_add_f32 v[6:7], v[6:7], v[14:15]
	s_nop 1
	v_add_f32_dpp v0, v0, v0 row_ror:8 row_mask:0xf bank_mask:0x3
	v_add_f32_dpp v1, v1, v1 row_ror:8 row_mask:0xf bank_mask:0x3
	v_add_f32_dpp v2, v2, v2 row_ror:8 row_mask:0xf bank_mask:0x3
	v_add_f32_dpp v3, v3, v3 row_ror:8 row_mask:0xf bank_mask:0x3
	v_add_f32_dpp v0, v4, v4 row_ror:8 row_mask:0xf bank_mask:0xc
	v_add_f32_dpp v1, v5, v5 row_ror:8 row_mask:0xf bank_mask:0xc
	v_add_f32_dpp v2, v6, v6 row_ror:8 row_mask:0xf bank_mask:0xc
	v_add_f32_dpp v3, v7, v7 row_ror:8 row_mask:0xf bank_mask:0xc
	s_waitcnt vmcnt(16)
	v_pk_add_f32 v[192:193], v[192:193], v[0:1]
	v_pk_add_f32 v[194:195], v[194:195], v[2:3]
	global_store_dwordx4 v200, v[192:195], s[8:9]
	global_load_dwordx4 v[192:195], v200, s[10:11]
	s_waitcnt lgkmcnt(4)
	v_mad_u32_u24 v168, v168, s100, v199
	v_mad_u32_u24 v169, v169, s100, v199
	v_mad_u32_u24 v170, v170, s100, v199
	v_mad_u32_u24 v171, v171, s100, v199
	v_mad_u32_u24 v172, v172, s100, v199
	v_mad_u32_u24 v173, v173, s100, v199
	v_mad_u32_u24 v174, v174, s100, v199
	v_mad_u32_u24 v175, v175, s100, v199
	global_load_dwordx4 v[112:115], v168, s[4:5]
	global_load_dwordx2 v[116:117], v168, s[4:5] offset:16
	global_load_dwordx4 v[118:121], v169, s[4:5]
	global_load_dwordx2 v[122:123], v169, s[4:5] offset:16
	global_load_dwordx4 v[124:127], v170, s[4:5]
	global_load_dwordx2 v[128:129], v170, s[4:5] offset:16
	global_load_dwordx4 v[130:133], v171, s[4:5]
	global_load_dwordx2 v[134:135], v171, s[4:5] offset:16
	global_load_dwordx4 v[136:139], v172, s[4:5]
	global_load_dwordx2 v[140:141], v172, s[4:5] offset:16
	global_load_dwordx4 v[142:145], v173, s[4:5]
	global_load_dwordx2 v[146:147], v173, s[4:5] offset:16
	global_load_dwordx4 v[148:151], v174, s[4:5]
	global_load_dwordx2 v[152:153], v174, s[4:5] offset:16
	global_load_dwordx4 v[154:157], v175, s[4:5]
	global_load_dwordx2 v[158:159], v175, s[4:5] offset:16
	s_add_u32 s14, s14, 1
	s_and_b32 s14, s14, 63
	s_and_b32 s19, s14, 15
	s_lshr_b32 s98, s14, 4
	s_lshl_b32 s99, s19, 9
	s_mul_i32 s15, s19, s16
	s_lshl_b32 s18, s98, 10
	s_add_u32 s15, s15, s18
	s_lshl_b32 s18, s101, 12
	s_add_u32 s15, s15, s18
	s_add_u32 s8, s24, s15
	s_addc_u32 s9, s25, 0
	s_mul_i32 s15, s98, 0x300000
	s_add_u32 s4, s26, 0x4800000
	s_addc_u32 s5, s27, 0
	s_add_u32 s4, s4, s15
	s_addc_u32 s5, s5, 0
	v_add_u32_e32 v201, s99, v197
	v_add_u32_e32 v203, s99, v198
	ds_read2_b32 v[160:161], v201 offset0:0 offset1:8
	ds_read2_b32 v[162:163], v201 offset0:16 offset1:24
	ds_read2_b32 v[164:165], v201 offset0:32 offset1:40
	ds_read2_b32 v[166:167], v201 offset0:48 offset1:56
	ds_read2_b32 v[184:185], v204 offset0:64 offset1:72
	ds_read2_b32 v[186:187], v204 offset0:80 offset1:88
	ds_read2_b32 v[188:189], v204 offset0:96 offset1:104
	ds_read2_b32 v[190:191], v204 offset0:112 offset1:120
	s_waitcnt lgkmcnt(8)
	s_waitcnt vmcnt(32)
	v_cvt_scalef32_pk32_f32_fp6 v[32:63], v[64:69], 1.0
	v_pk_mul_f32 v[0:1], v[176:177], v[32:33] op_sel_hi:[0,1]
	v_pk_mul_f32 v[2:3], v[176:177], v[34:35] op_sel_hi:[0,1]
	v_pk_mul_f32 v[4:5], v[176:177], v[36:37] op_sel_hi:[0,1]
	v_pk_mul_f32 v[6:7], v[176:177], v[38:39] op_sel_hi:[0,1]
	v_pk_mul_f32 v[8:9], v[176:177], v[40:41] op_sel_hi:[0,1]
	v_pk_mul_f32 v[10:11], v[176:177], v[42:43] op_sel_hi:[0,1]
	v_pk_mul_f32 v[12:13], v[176:177], v[44:45] op_sel_hi:[0,1]
	v_pk_mul_f32 v[14:15], v[176:177], v[46:47] op_sel_hi:[0,1]
	v_pk_mul_f32 v[16:17], v[176:177], v[48:49] op_sel_hi:[0,1]
	v_pk_mul_f32 v[18:19], v[176:177], v[50:51] op_sel_hi:[0,1]
	v_pk_mul_f32 v[20:21], v[176:177], v[52:53] op_sel_hi:[0,1]
	v_pk_mul_f32 v[22:23], v[176:177], v[54:55] op_sel_hi:[0,1]
	v_pk_mul_f32 v[24:25], v[176:177], v[56:57] op_sel_hi:[0,1]
	v_pk_mul_f32 v[26:27], v[176:177], v[58:59] op_sel_hi:[0,1]
	v_pk_mul_f32 v[28:29], v[176:177], v[60:61] op_sel_hi:[0,1]
	v_pk_mul_f32 v[30:31], v[176:177], v[62:63] op_sel_hi:[0,1]
	s_waitcnt vmcnt(30)
	v_cvt_scalef32_pk32_f32_fp6 v[32:63], v[70:75], 1.0
	v_pk_fma_f32 v[0:1], v[176:177], v[32:33], v[0:1] op_sel:[1,0,0] op_sel_hi:[1,1,1]
	v_pk_fma_f32 v[2:3], v[176:177], v[34:35], v[2:3] op_sel:[1,0,0] op_sel_hi:[1,1,1]
	v_pk_fma_f32 v[4:5], v[176:177], v[36:37], v[4:5] op_sel:[1,0,0] op_sel_hi:[1,1,1]
	v_pk_fma_f32 v[6:7], v[176:177], v[38:39], v[6:7] op_sel:[1,0,0] op_sel_hi:[1,1,1]
	v_pk_fma_f32 v[8:9], v[176:177], v[40:41], v[8:9] op_sel:[1,0,0] op_sel_hi:[1,1,1]
	v_pk_fma_f32 v[10:11], v[176:177], v[42:43], v[10:11] op_sel:[1,0,0] op_sel_hi:[1,1,1]
	v_pk_fma_f32 v[12:13], v[176:177], v[44:45], v[12:13] op_sel:[1,0,0] op_sel_hi:[1,1,1]
	v_pk_fma_f32 v[14:15], v[176:177], v[46:47], v[14:15] op_sel:[1,0,0] op_sel_hi:[1,1,1]
	v_pk_fma_f32 v[16:17], v[176:177], v[48:49], v[16:17] op_sel:[1,0,0] op_sel_hi:[1,1,1]
	v_pk_fma_f32 v[18:19], v[176:177], v[50:51], v[18:19] op_sel:[1,0,0] op_sel_hi:[1,1,1]
	v_pk_fma_f32 v[20:21], v[176:177], v[52:53], v[20:21] op_sel:[1,0,0] op_sel_hi:[1,1,1]
	v_pk_fma_f32 v[22:23], v[176:177], v[54:55], v[22:23] op_sel:[1,0,0] op_sel_hi:[1,1,1]
	v_pk_fma_f32 v[24:25], v[176:177], v[56:57], v[24:25] op_sel:[1,0,0] op_sel_hi:[1,1,1]
	v_pk_fma_f32 v[26:27], v[176:177], v[58:59], v[26:27] op_sel:[1,0,0] op_sel_hi:[1,1,1]
	v_pk_fma_f32 v[28:29], v[176:177], v[60:61], v[28:29] op_sel:[1,0,0] op_sel_hi:[1,1,1]
	v_pk_fma_f32 v[30:31], v[176:177], v[62:63], v[30:31] op_sel:[1,0,0] op_sel_hi:[1,1,1]
	s_waitcnt vmcnt(28)
	v_cvt_scalef32_pk32_f32_fp6 v[32:63], v[76:81], 1.0
	v_pk_fma_f32 v[0:1], v[178:179], v[32:33], v[0:1] op_sel_hi:[0,1,1]
	v_pk_fma_f32 v[2:3], v[178:179], v[34:35], v[2:3] op_sel_hi:[0,1,1]
	v_pk_fma_f32 v[4:5], v[178:179], v[36:37], v[4:5] op_sel_hi:[0,1,1]
	v_pk_fma_f32 v[6:7], v[178:179], v[38:39], v[6:7] op_sel_hi:[0,1,1]
	v_pk_fma_f32 v[8:9], v[178:179], v[40:41], v[8:9] op_sel_hi:[0,1,1]
	v_pk_fma_f32 v[10:11], v[178:179], v[42:43], v[10:11] op_sel_hi:[0,1,1]
	v_pk_fma_f32 v[12:13], v[178:179], v[44:45], v[12:13] op_sel_hi:[0,1,1]
	v_pk_fma_f32 v[14:15], v[178:179], v[46:47], v[14:15] op_sel_hi:[0,1,1]
	v_pk_fma_f32 v[16:17], v[178:179], v[48:49], v[16:17] op_sel_hi:[0,1,1]
	v_pk_fma_f32 v[18:19], v[178:179], v[50:51], v[18:19] op_sel_hi:[0,1,1]
	v_pk_fma_f32 v[20:21], v[178:179], v[52:53], v[20:21] op_sel_hi:[0,1,1]
	v_pk_fma_f32 v[22:23], v[178:179], v[54:55], v[22:23] op_sel_hi:[0,1,1]
	v_pk_fma_f32 v[24:25], v[178:179], v[56:57], v[24:25] op_sel_hi:[0,1,1]
	v_pk_fma_f32 v[26:27], v[178:179], v[58:59], v[26:27] op_sel_hi:[0,1,1]
	v_pk_fma_f32 v[28:29], v[178:179], v[60:61], v[28:29] op_sel_hi:[0,1,1]
	v_pk_fma_f32 v[30:31], v[178:179], v[62:63], v[30:31] op_sel_hi:[0,1,1]
	s_waitcnt vmcnt(26)
	v_cvt_scalef32_pk32_f32_fp6 v[32:63], v[82:87], 1.0
	v_pk_fma_f32 v[0:1], v[178:179], v[32:33], v[0:1] op_sel:[1,0,0] op_sel_hi:[1,1,1]
	v_pk_fma_f32 v[2:3], v[178:179], v[34:35], v[2:3] op_sel:[1,0,0] op_sel_hi:[1,1,1]
	v_pk_fma_f32 v[4:5], v[178:179], v[36:37], v[4:5] op_sel:[1,0,0] op_sel_hi:[1,1,1]
	v_pk_fma_f32 v[6:7], v[178:179], v[38:39], v[6:7] op_sel:[1,0,0] op_sel_hi:[1,1,1]
	v_pk_fma_f32 v[8:9], v[178:179], v[40:41], v[8:9] op_sel:[1,0,0] op_sel_hi:[1,1,1]
	v_pk_fma_f32 v[10:11], v[178:179], v[42:43], v[10:11] op_sel:[1,0,0] op_sel_hi:[1,1,1]
	v_pk_fma_f32 v[12:13], v[178:179], v[44:45], v[12:13] op_sel:[1,0,0] op_sel_hi:[1,1,1]
	v_pk_fma_f32 v[14:15], v[178:179], v[46:47], v[14:15] op_sel:[1,0,0] op_sel_hi:[1,1,1]
	v_pk_fma_f32 v[16:17], v[178:179], v[48:49], v[16:17] op_sel:[1,0,0] op_sel_hi:[1,1,1]
	v_pk_fma_f32 v[18:19], v[178:179], v[50:51], v[18:19] op_sel:[1,0,0] op_sel_hi:[1,1,1]
	v_pk_fma_f32 v[20:21], v[178:179], v[52:53], v[20:21] op_sel:[1,0,0] op_sel_hi:[1,1,1]
	v_pk_fma_f32 v[22:23], v[178:179], v[54:55], v[22:23] op_sel:[1,0,0] op_sel_hi:[1,1,1]
	v_pk_fma_f32 v[24:25], v[178:179], v[56:57], v[24:25] op_sel:[1,0,0] op_sel_hi:[1,1,1]
	v_pk_fma_f32 v[26:27], v[178:179], v[58:59], v[26:27] op_sel:[1,0,0] op_sel_hi:[1,1,1]
	v_pk_fma_f32 v[28:29], v[178:179], v[60:61], v[28:29] op_sel:[1,0,0] op_sel_hi:[1,1,1]
	v_pk_fma_f32 v[30:31], v[178:179], v[62:63], v[30:31] op_sel:[1,0,0] op_sel_hi:[1,1,1]
	s_waitcnt vmcnt(24)
	v_cvt_scalef32_pk32_f32_fp6 v[32:63], v[88:93], 1.0
	v_pk_fma_f32 v[0:1], v[180:181], v[32:33], v[0:1] op_sel_hi:[0,1,1]
	v_pk_fma_f32 v[2:3], v[180:181], v[34:35], v[2:3] op_sel_hi:[0,1,1]
	v_pk_fma_f32 v[4:5], v[180:181], v[36:37], v[4:5] op_sel_hi:[0,1,1]
	v_pk_fma_f32 v[6:7], v[180:181], v[38:39], v[6:7] op_sel_hi:[0,1,1]
	v_pk_fma_f32 v[8:9], v[180:181], v[40:41], v[8:9] op_sel_hi:[0,1,1]
	v_pk_fma_f32 v[10:11], v[180:181], v[42:43], v[10:11] op_sel_hi:[0,1,1]
	v_pk_fma_f32 v[12:13], v[180:181], v[44:45], v[12:13] op_sel_hi:[0,1,1]
	v_pk_fma_f32 v[14:15], v[180:181], v[46:47], v[14:15] op_sel_hi:[0,1,1]
	v_pk_fma_f32 v[16:17], v[180:181], v[48:49], v[16:17] op_sel_hi:[0,1,1]
	v_pk_fma_f32 v[18:19], v[180:181], v[50:51], v[18:19] op_sel_hi:[0,1,1]
	v_pk_fma_f32 v[20:21], v[180:181], v[52:53], v[20:21] op_sel_hi:[0,1,1]
	v_pk_fma_f32 v[22:23], v[180:181], v[54:55], v[22:23] op_sel_hi:[0,1,1]
	v_pk_fma_f32 v[24:25], v[180:181], v[56:57], v[24:25] op_sel_hi:[0,1,1]
	v_pk_fma_f32 v[26:27], v[180:181], v[58:59], v[26:27] op_sel_hi:[0,1,1]
	v_pk_fma_f32 v[28:29], v[180:181], v[60:61], v[28:29] op_sel_hi:[0,1,1]
	v_pk_fma_f32 v[30:31], v[180:181], v[62:63], v[30:31] op_sel_hi:[0,1,1]
	s_waitcnt vmcnt(22)
	v_cvt_scalef32_pk32_f32_fp6 v[32:63], v[94:99], 1.0
	v_pk_fma_f32 v[0:1], v[180:181], v[32:33], v[0:1] op_sel:[1,0,0] op_sel_hi:[1,1,1]
	v_pk_fma_f32 v[2:3], v[180:181], v[34:35], v[2:3] op_sel:[1,0,0] op_sel_hi:[1,1,1]
	v_pk_fma_f32 v[4:5], v[180:181], v[36:37], v[4:5] op_sel:[1,0,0] op_sel_hi:[1,1,1]
	v_pk_fma_f32 v[6:7], v[180:181], v[38:39], v[6:7] op_sel:[1,0,0] op_sel_hi:[1,1,1]
	v_pk_fma_f32 v[8:9], v[180:181], v[40:41], v[8:9] op_sel:[1,0,0] op_sel_hi:[1,1,1]
	v_pk_fma_f32 v[10:11], v[180:181], v[42:43], v[10:11] op_sel:[1,0,0] op_sel_hi:[1,1,1]
	v_pk_fma_f32 v[12:13], v[180:181], v[44:45], v[12:13] op_sel:[1,0,0] op_sel_hi:[1,1,1]
	v_pk_fma_f32 v[14:15], v[180:181], v[46:47], v[14:15] op_sel:[1,0,0] op_sel_hi:[1,1,1]
	v_pk_fma_f32 v[16:17], v[180:181], v[48:49], v[16:17] op_sel:[1,0,0] op_sel_hi:[1,1,1]
	v_pk_fma_f32 v[18:19], v[180:181], v[50:51], v[18:19] op_sel:[1,0,0] op_sel_hi:[1,1,1]
	v_pk_fma_f32 v[20:21], v[180:181], v[52:53], v[20:21] op_sel:[1,0,0] op_sel_hi:[1,1,1]
	v_pk_fma_f32 v[22:23], v[180:181], v[54:55], v[22:23] op_sel:[1,0,0] op_sel_hi:[1,1,1]
	v_pk_fma_f32 v[24:25], v[180:181], v[56:57], v[24:25] op_sel:[1,0,0] op_sel_hi:[1,1,1]
	v_pk_fma_f32 v[26:27], v[180:181], v[58:59], v[26:27] op_sel:[1,0,0] op_sel_hi:[1,1,1]
	v_pk_fma_f32 v[28:29], v[180:181], v[60:61], v[28:29] op_sel:[1,0,0] op_sel_hi:[1,1,1]
	v_pk_fma_f32 v[30:31], v[180:181], v[62:63], v[30:31] op_sel:[1,0,0] op_sel_hi:[1,1,1]
	s_waitcnt vmcnt(20)
	v_cvt_scalef32_pk32_f32_fp6 v[32:63], v[100:105], 1.0
	v_pk_fma_f32 v[0:1], v[182:183], v[32:33], v[0:1] op_sel_hi:[0,1,1]
	v_pk_fma_f32 v[2:3], v[182:183], v[34:35], v[2:3] op_sel_hi:[0,1,1]
	v_pk_fma_f32 v[4:5], v[182:183], v[36:37], v[4:5] op_sel_hi:[0,1,1]
	v_pk_fma_f32 v[6:7], v[182:183], v[38:39], v[6:7] op_sel_hi:[0,1,1]
	v_pk_fma_f32 v[8:9], v[182:183], v[40:41], v[8:9] op_sel_hi:[0,1,1]
	v_pk_fma_f32 v[10:11], v[182:183], v[42:43], v[10:11] op_sel_hi:[0,1,1]
	v_pk_fma_f32 v[12:13], v[182:183], v[44:45], v[12:13] op_sel_hi:[0,1,1]
	v_pk_fma_f32 v[14:15], v[182:183], v[46:47], v[14:15] op_sel_hi:[0,1,1]
	v_pk_fma_f32 v[16:17], v[182:183], v[48:49], v[16:17] op_sel_hi:[0,1,1]
	v_pk_fma_f32 v[18:19], v[182:183], v[50:51], v[18:19] op_sel_hi:[0,1,1]
	v_pk_fma_f32 v[20:21], v[182:183], v[52:53], v[20:21] op_sel_hi:[0,1,1]
	v_pk_fma_f32 v[22:23], v[182:183], v[54:55], v[22:23] op_sel_hi:[0,1,1]
	v_pk_fma_f32 v[24:25], v[182:183], v[56:57], v[24:25] op_sel_hi:[0,1,1]
	v_pk_fma_f32 v[26:27], v[182:183], v[58:59], v[26:27] op_sel_hi:[0,1,1]
	v_pk_fma_f32 v[28:29], v[182:183], v[60:61], v[28:29] op_sel_hi:[0,1,1]
	v_pk_fma_f32 v[30:31], v[182:183], v[62:63], v[30:31] op_sel_hi:[0,1,1]
	s_waitcnt vmcnt(18)
	v_cvt_scalef32_pk32_f32_fp6 v[32:63], v[106:111], 1.0
	v_pk_fma_f32 v[0:1], v[182:183], v[32:33], v[0:1] op_sel:[1,0,0] op_sel_hi:[1,1,1]
	v_pk_fma_f32 v[2:3], v[182:183], v[34:35], v[2:3] op_sel:[1,0,0] op_sel_hi:[1,1,1]
	v_pk_fma_f32 v[4:5], v[182:183], v[36:37], v[4:5] op_sel:[1,0,0] op_sel_hi:[1,1,1]
	v_pk_fma_f32 v[6:7], v[182:183], v[38:39], v[6:7] op_sel:[1,0,0] op_sel_hi:[1,1,1]
	v_pk_fma_f32 v[8:9], v[182:183], v[40:41], v[8:9] op_sel:[1,0,0] op_sel_hi:[1,1,1]
	v_pk_fma_f32 v[10:11], v[182:183], v[42:43], v[10:11] op_sel:[1,0,0] op_sel_hi:[1,1,1]
	v_pk_fma_f32 v[12:13], v[182:183], v[44:45], v[12:13] op_sel:[1,0,0] op_sel_hi:[1,1,1]
	v_pk_fma_f32 v[14:15], v[182:183], v[46:47], v[14:15] op_sel:[1,0,0] op_sel_hi:[1,1,1]
	v_pk_fma_f32 v[16:17], v[182:183], v[48:49], v[16:17] op_sel:[1,0,0] op_sel_hi:[1,1,1]
	v_pk_fma_f32 v[18:19], v[182:183], v[50:51], v[18:19] op_sel:[1,0,0] op_sel_hi:[1,1,1]
	v_pk_fma_f32 v[20:21], v[182:183], v[52:53], v[20:21] op_sel:[1,0,0] op_sel_hi:[1,1,1]
	v_pk_fma_f32 v[22:23], v[182:183], v[54:55], v[22:23] op_sel:[1,0,0] op_sel_hi:[1,1,1]
	v_pk_fma_f32 v[24:25], v[182:183], v[56:57], v[24:25] op_sel:[1,0,0] op_sel_hi:[1,1,1]
	v_pk_fma_f32 v[26:27], v[182:183], v[58:59], v[26:27] op_sel:[1,0,0] op_sel_hi:[1,1,1]
	v_pk_fma_f32 v[28:29], v[182:183], v[60:61], v[28:29] op_sel:[1,0,0] op_sel_hi:[1,1,1]
	v_pk_fma_f32 v[30:31], v[182:183], v[62:63], v[30:31] op_sel:[1,0,0] op_sel_hi:[1,1,1]
	s_waitcnt lgkmcnt(4)
	v_mad_u32_u24 v160, v160, s100, v199
	v_mad_u32_u24 v161, v161, s100, v199
	v_mad_u32_u24 v162, v162, s100, v199
	v_mad_u32_u24 v163, v163, s100, v199
	v_mad_u32_u24 v164, v164, s100, v199
	v_mad_u32_u24 v165, v165, s100, v199
	v_mad_u32_u24 v166, v166, s100, v199
	v_mad_u32_u24 v167, v167, s100, v199
	global_load_dwordx4 v[64:67], v160, s[4:5]
	global_load_dwordx2 v[68:69], v160, s[4:5] offset:16
	global_load_dwordx4 v[70:73], v161, s[4:5]
	global_load_dwordx2 v[74:75], v161, s[4:5] offset:16
	global_load_dwordx4 v[76:79], v162, s[4:5]
	global_load_dwordx2 v[80:81], v162, s[4:5] offset:16
	global_load_dwordx4 v[82:85], v163, s[4:5]
	global_load_dwordx2 v[86:87], v163, s[4:5] offset:16
	global_load_dwordx4 v[88:91], v164, s[4:5]
	global_load_dwordx2 v[92:93], v164, s[4:5] offset:16
	global_load_dwordx4 v[94:97], v165, s[4:5]
	global_load_dwordx2 v[98:99], v165, s[4:5] offset:16
	global_load_dwordx4 v[100:103], v166, s[4:5]
	global_load_dwordx2 v[104:105], v166, s[4:5] offset:16
	global_load_dwordx4 v[106:109], v167, s[4:5]
	global_load_dwordx2 v[110:111], v167, s[4:5] offset:16
	ds_read2_b32 v[168:169], v201 offset0:64 offset1:72
	ds_read2_b32 v[170:171], v201 offset0:80 offset1:88
	ds_read2_b32 v[172:173], v201 offset0:96 offset1:104
	ds_read2_b32 v[174:175], v201 offset0:112 offset1:120
	ds_read2_b32 v[176:177], v203 offset0:0 offset1:8
	ds_read2_b32 v[178:179], v203 offset0:16 offset1:24
	ds_read2_b32 v[180:181], v203 offset0:32 offset1:40
	ds_read2_b32 v[182:183], v203 offset0:48 offset1:56
	s_waitcnt lgkmcnt(8)
	s_waitcnt vmcnt(30)
	v_cvt_scalef32_pk32_f32_fp6 v[32:63], v[112:117], 1.0
	v_pk_fma_f32 v[0:1], v[184:185], v[32:33], v[0:1] op_sel_hi:[0,1,1]
	v_pk_fma_f32 v[2:3], v[184:185], v[34:35], v[2:3] op_sel_hi:[0,1,1]
	v_pk_fma_f32 v[4:5], v[184:185], v[36:37], v[4:5] op_sel_hi:[0,1,1]
	v_pk_fma_f32 v[6:7], v[184:185], v[38:39], v[6:7] op_sel_hi:[0,1,1]
	v_pk_fma_f32 v[8:9], v[184:185], v[40:41], v[8:9] op_sel_hi:[0,1,1]
	v_pk_fma_f32 v[10:11], v[184:185], v[42:43], v[10:11] op_sel_hi:[0,1,1]
	v_pk_fma_f32 v[12:13], v[184:185], v[44:45], v[12:13] op_sel_hi:[0,1,1]
	v_pk_fma_f32 v[14:15], v[184:185], v[46:47], v[14:15] op_sel_hi:[0,1,1]
	v_pk_fma_f32 v[16:17], v[184:185], v[48:49], v[16:17] op_sel_hi:[0,1,1]
	v_pk_fma_f32 v[18:19], v[184:185], v[50:51], v[18:19] op_sel_hi:[0,1,1]
	v_pk_fma_f32 v[20:21], v[184:185], v[52:53], v[20:21] op_sel_hi:[0,1,1]
	v_pk_fma_f32 v[22:23], v[184:185], v[54:55], v[22:23] op_sel_hi:[0,1,1]
	v_pk_fma_f32 v[24:25], v[184:185], v[56:57], v[24:25] op_sel_hi:[0,1,1]
	v_pk_fma_f32 v[26:27], v[184:185], v[58:59], v[26:27] op_sel_hi:[0,1,1]
	v_pk_fma_f32 v[28:29], v[184:185], v[60:61], v[28:29] op_sel_hi:[0,1,1]
	v_pk_fma_f32 v[30:31], v[184:185], v[62:63], v[30:31] op_sel_hi:[0,1,1]
	s_waitcnt vmcnt(28)
	v_cvt_scalef32_pk32_f32_fp6 v[32:63], v[118:123], 1.0
	v_pk_fma_f32 v[0:1], v[184:185], v[32:33], v[0:1] op_sel:[1,0,0] op_sel_hi:[1,1,1]
	v_pk_fma_f32 v[2:3], v[184:185], v[34:35], v[2:3] op_sel:[1,0,0] op_sel_hi:[1,1,1]
	v_pk_fma_f32 v[4:5], v[184:185], v[36:37], v[4:5] op_sel:[1,0,0] op_sel_hi:[1,1,1]
	v_pk_fma_f32 v[6:7], v[184:185], v[38:39], v[6:7] op_sel:[1,0,0] op_sel_hi:[1,1,1]
	v_pk_fma_f32 v[8:9], v[184:185], v[40:41], v[8:9] op_sel:[1,0,0] op_sel_hi:[1,1,1]
	v_pk_fma_f32 v[10:11], v[184:185], v[42:43], v[10:11] op_sel:[1,0,0] op_sel_hi:[1,1,1]
	v_pk_fma_f32 v[12:13], v[184:185], v[44:45], v[12:13] op_sel:[1,0,0] op_sel_hi:[1,1,1]
	v_pk_fma_f32 v[14:15], v[184:185], v[46:47], v[14:15] op_sel:[1,0,0] op_sel_hi:[1,1,1]
	v_pk_fma_f32 v[16:17], v[184:185], v[48:49], v[16:17] op_sel:[1,0,0] op_sel_hi:[1,1,1]
	v_pk_fma_f32 v[18:19], v[184:185], v[50:51], v[18:19] op_sel:[1,0,0] op_sel_hi:[1,1,1]
	v_pk_fma_f32 v[20:21], v[184:185], v[52:53], v[20:21] op_sel:[1,0,0] op_sel_hi:[1,1,1]
	v_pk_fma_f32 v[22:23], v[184:185], v[54:55], v[22:23] op_sel:[1,0,0] op_sel_hi:[1,1,1]
	v_pk_fma_f32 v[24:25], v[184:185], v[56:57], v[24:25] op_sel:[1,0,0] op_sel_hi:[1,1,1]
	v_pk_fma_f32 v[26:27], v[184:185], v[58:59], v[26:27] op_sel:[1,0,0] op_sel_hi:[1,1,1]
	v_pk_fma_f32 v[28:29], v[184:185], v[60:61], v[28:29] op_sel:[1,0,0] op_sel_hi:[1,1,1]
	v_pk_fma_f32 v[30:31], v[184:185], v[62:63], v[30:31] op_sel:[1,0,0] op_sel_hi:[1,1,1]
	s_waitcnt vmcnt(26)
	v_cvt_scalef32_pk32_f32_fp6 v[32:63], v[124:129], 1.0
	v_pk_fma_f32 v[0:1], v[186:187], v[32:33], v[0:1] op_sel_hi:[0,1,1]
	v_pk_fma_f32 v[2:3], v[186:187], v[34:35], v[2:3] op_sel_hi:[0,1,1]
	v_pk_fma_f32 v[4:5], v[186:187], v[36:37], v[4:5] op_sel_hi:[0,1,1]
	v_pk_fma_f32 v[6:7], v[186:187], v[38:39], v[6:7] op_sel_hi:[0,1,1]
	v_pk_fma_f32 v[8:9], v[186:187], v[40:41], v[8:9] op_sel_hi:[0,1,1]
	v_pk_fma_f32 v[10:11], v[186:187], v[42:43], v[10:11] op_sel_hi:[0,1,1]
	v_pk_fma_f32 v[12:13], v[186:187], v[44:45], v[12:13] op_sel_hi:[0,1,1]
	v_pk_fma_f32 v[14:15], v[186:187], v[46:47], v[14:15] op_sel_hi:[0,1,1]
	v_pk_fma_f32 v[16:17], v[186:187], v[48:49], v[16:17] op_sel_hi:[0,1,1]
	v_pk_fma_f32 v[18:19], v[186:187], v[50:51], v[18:19] op_sel_hi:[0,1,1]
	v_pk_fma_f32 v[20:21], v[186:187], v[52:53], v[20:21] op_sel_hi:[0,1,1]
	v_pk_fma_f32 v[22:23], v[186:187], v[54:55], v[22:23] op_sel_hi:[0,1,1]
	v_pk_fma_f32 v[24:25], v[186:187], v[56:57], v[24:25] op_sel_hi:[0,1,1]
	v_pk_fma_f32 v[26:27], v[186:187], v[58:59], v[26:27] op_sel_hi:[0,1,1]
	v_pk_fma_f32 v[28:29], v[186:187], v[60:61], v[28:29] op_sel_hi:[0,1,1]
	v_pk_fma_f32 v[30:31], v[186:187], v[62:63], v[30:31] op_sel_hi:[0,1,1]
	s_waitcnt vmcnt(24)
	v_cvt_scalef32_pk32_f32_fp6 v[32:63], v[130:135], 1.0
	v_pk_fma_f32 v[0:1], v[186:187], v[32:33], v[0:1] op_sel:[1,0,0] op_sel_hi:[1,1,1]
	v_pk_fma_f32 v[2:3], v[186:187], v[34:35], v[2:3] op_sel:[1,0,0] op_sel_hi:[1,1,1]
	v_pk_fma_f32 v[4:5], v[186:187], v[36:37], v[4:5] op_sel:[1,0,0] op_sel_hi:[1,1,1]
	v_pk_fma_f32 v[6:7], v[186:187], v[38:39], v[6:7] op_sel:[1,0,0] op_sel_hi:[1,1,1]
	v_pk_fma_f32 v[8:9], v[186:187], v[40:41], v[8:9] op_sel:[1,0,0] op_sel_hi:[1,1,1]
	v_pk_fma_f32 v[10:11], v[186:187], v[42:43], v[10:11] op_sel:[1,0,0] op_sel_hi:[1,1,1]
	v_pk_fma_f32 v[12:13], v[186:187], v[44:45], v[12:13] op_sel:[1,0,0] op_sel_hi:[1,1,1]
	v_pk_fma_f32 v[14:15], v[186:187], v[46:47], v[14:15] op_sel:[1,0,0] op_sel_hi:[1,1,1]
	v_pk_fma_f32 v[16:17], v[186:187], v[48:49], v[16:17] op_sel:[1,0,0] op_sel_hi:[1,1,1]
	v_pk_fma_f32 v[18:19], v[186:187], v[50:51], v[18:19] op_sel:[1,0,0] op_sel_hi:[1,1,1]
	v_pk_fma_f32 v[20:21], v[186:187], v[52:53], v[20:21] op_sel:[1,0,0] op_sel_hi:[1,1,1]
	v_pk_fma_f32 v[22:23], v[186:187], v[54:55], v[22:23] op_sel:[1,0,0] op_sel_hi:[1,1,1]
	v_pk_fma_f32 v[24:25], v[186:187], v[56:57], v[24:25] op_sel:[1,0,0] op_sel_hi:[1,1,1]
	v_pk_fma_f32 v[26:27], v[186:187], v[58:59], v[26:27] op_sel:[1,0,0] op_sel_hi:[1,1,1]
	v_pk_fma_f32 v[28:29], v[186:187], v[60:61], v[28:29] op_sel:[1,0,0] op_sel_hi:[1,1,1]
	v_pk_fma_f32 v[30:31], v[186:187], v[62:63], v[30:31] op_sel:[1,0,0] op_sel_hi:[1,1,1]
	s_waitcnt vmcnt(22)
	v_cvt_scalef32_pk32_f32_fp6 v[32:63], v[136:141], 1.0
	v_pk_fma_f32 v[0:1], v[188:189], v[32:33], v[0:1] op_sel_hi:[0,1,1]
	v_pk_fma_f32 v[2:3], v[188:189], v[34:35], v[2:3] op_sel_hi:[0,1,1]
	v_pk_fma_f32 v[4:5], v[188:189], v[36:37], v[4:5] op_sel_hi:[0,1,1]
	v_pk_fma_f32 v[6:7], v[188:189], v[38:39], v[6:7] op_sel_hi:[0,1,1]
	v_pk_fma_f32 v[8:9], v[188:189], v[40:41], v[8:9] op_sel_hi:[0,1,1]
	v_pk_fma_f32 v[10:11], v[188:189], v[42:43], v[10:11] op_sel_hi:[0,1,1]
	v_pk_fma_f32 v[12:13], v[188:189], v[44:45], v[12:13] op_sel_hi:[0,1,1]
	v_pk_fma_f32 v[14:15], v[188:189], v[46:47], v[14:15] op_sel_hi:[0,1,1]
	v_pk_fma_f32 v[16:17], v[188:189], v[48:49], v[16:17] op_sel_hi:[0,1,1]
	v_pk_fma_f32 v[18:19], v[188:189], v[50:51], v[18:19] op_sel_hi:[0,1,1]
	v_pk_fma_f32 v[20:21], v[188:189], v[52:53], v[20:21] op_sel_hi:[0,1,1]
	v_pk_fma_f32 v[22:23], v[188:189], v[54:55], v[22:23] op_sel_hi:[0,1,1]
	v_pk_fma_f32 v[24:25], v[188:189], v[56:57], v[24:25] op_sel_hi:[0,1,1]
	v_pk_fma_f32 v[26:27], v[188:189], v[58:59], v[26:27] op_sel_hi:[0,1,1]
	v_pk_fma_f32 v[28:29], v[188:189], v[60:61], v[28:29] op_sel_hi:[0,1,1]
	v_pk_fma_f32 v[30:31], v[188:189], v[62:63], v[30:31] op_sel_hi:[0,1,1]
	s_waitcnt vmcnt(20)
	v_cvt_scalef32_pk32_f32_fp6 v[32:63], v[142:147], 1.0
	v_pk_fma_f32 v[0:1], v[188:189], v[32:33], v[0:1] op_sel:[1,0,0] op_sel_hi:[1,1,1]
	v_pk_fma_f32 v[2:3], v[188:189], v[34:35], v[2:3] op_sel:[1,0,0] op_sel_hi:[1,1,1]
	v_pk_fma_f32 v[4:5], v[188:189], v[36:37], v[4:5] op_sel:[1,0,0] op_sel_hi:[1,1,1]
	v_pk_fma_f32 v[6:7], v[188:189], v[38:39], v[6:7] op_sel:[1,0,0] op_sel_hi:[1,1,1]
	v_pk_fma_f32 v[8:9], v[188:189], v[40:41], v[8:9] op_sel:[1,0,0] op_sel_hi:[1,1,1]
	v_pk_fma_f32 v[10:11], v[188:189], v[42:43], v[10:11] op_sel:[1,0,0] op_sel_hi:[1,1,1]
	v_pk_fma_f32 v[12:13], v[188:189], v[44:45], v[12:13] op_sel:[1,0,0] op_sel_hi:[1,1,1]
	v_pk_fma_f32 v[14:15], v[188:189], v[46:47], v[14:15] op_sel:[1,0,0] op_sel_hi:[1,1,1]
	v_pk_fma_f32 v[16:17], v[188:189], v[48:49], v[16:17] op_sel:[1,0,0] op_sel_hi:[1,1,1]
	v_pk_fma_f32 v[18:19], v[188:189], v[50:51], v[18:19] op_sel:[1,0,0] op_sel_hi:[1,1,1]
	v_pk_fma_f32 v[20:21], v[188:189], v[52:53], v[20:21] op_sel:[1,0,0] op_sel_hi:[1,1,1]
	v_pk_fma_f32 v[22:23], v[188:189], v[54:55], v[22:23] op_sel:[1,0,0] op_sel_hi:[1,1,1]
	v_pk_fma_f32 v[24:25], v[188:189], v[56:57], v[24:25] op_sel:[1,0,0] op_sel_hi:[1,1,1]
	v_pk_fma_f32 v[26:27], v[188:189], v[58:59], v[26:27] op_sel:[1,0,0] op_sel_hi:[1,1,1]
	v_pk_fma_f32 v[28:29], v[188:189], v[60:61], v[28:29] op_sel:[1,0,0] op_sel_hi:[1,1,1]
	v_pk_fma_f32 v[30:31], v[188:189], v[62:63], v[30:31] op_sel:[1,0,0] op_sel_hi:[1,1,1]
	s_waitcnt vmcnt(18)
	v_cvt_scalef32_pk32_f32_fp6 v[32:63], v[148:153], 1.0
	v_pk_fma_f32 v[0:1], v[190:191], v[32:33], v[0:1] op_sel_hi:[0,1,1]
	v_pk_fma_f32 v[2:3], v[190:191], v[34:35], v[2:3] op_sel_hi:[0,1,1]
	v_pk_fma_f32 v[4:5], v[190:191], v[36:37], v[4:5] op_sel_hi:[0,1,1]
	v_pk_fma_f32 v[6:7], v[190:191], v[38:39], v[6:7] op_sel_hi:[0,1,1]
	v_pk_fma_f32 v[8:9], v[190:191], v[40:41], v[8:9] op_sel_hi:[0,1,1]
	v_pk_fma_f32 v[10:11], v[190:191], v[42:43], v[10:11] op_sel_hi:[0,1,1]
	v_pk_fma_f32 v[12:13], v[190:191], v[44:45], v[12:13] op_sel_hi:[0,1,1]
	v_pk_fma_f32 v[14:15], v[190:191], v[46:47], v[14:15] op_sel_hi:[0,1,1]
	v_pk_fma_f32 v[16:17], v[190:191], v[48:49], v[16:17] op_sel_hi:[0,1,1]
	v_pk_fma_f32 v[18:19], v[190:191], v[50:51], v[18:19] op_sel_hi:[0,1,1]
	v_pk_fma_f32 v[20:21], v[190:191], v[52:53], v[20:21] op_sel_hi:[0,1,1]
	v_pk_fma_f32 v[22:23], v[190:191], v[54:55], v[22:23] op_sel_hi:[0,1,1]
	v_pk_fma_f32 v[24:25], v[190:191], v[56:57], v[24:25] op_sel_hi:[0,1,1]
	v_pk_fma_f32 v[26:27], v[190:191], v[58:59], v[26:27] op_sel_hi:[0,1,1]
	v_pk_fma_f32 v[28:29], v[190:191], v[60:61], v[28:29] op_sel_hi:[0,1,1]
	v_pk_fma_f32 v[30:31], v[190:191], v[62:63], v[30:31] op_sel_hi:[0,1,1]
	s_waitcnt vmcnt(16)
	v_cvt_scalef32_pk32_f32_fp6 v[32:63], v[154:159], 1.0
	v_pk_fma_f32 v[0:1], v[190:191], v[32:33], v[0:1] op_sel:[1,0,0] op_sel_hi:[1,1,1]
	v_pk_fma_f32 v[2:3], v[190:191], v[34:35], v[2:3] op_sel:[1,0,0] op_sel_hi:[1,1,1]
	v_pk_fma_f32 v[4:5], v[190:191], v[36:37], v[4:5] op_sel:[1,0,0] op_sel_hi:[1,1,1]
	v_pk_fma_f32 v[6:7], v[190:191], v[38:39], v[6:7] op_sel:[1,0,0] op_sel_hi:[1,1,1]
	v_pk_fma_f32 v[8:9], v[190:191], v[40:41], v[8:9] op_sel:[1,0,0] op_sel_hi:[1,1,1]
	v_pk_fma_f32 v[10:11], v[190:191], v[42:43], v[10:11] op_sel:[1,0,0] op_sel_hi:[1,1,1]
	v_pk_fma_f32 v[12:13], v[190:191], v[44:45], v[12:13] op_sel:[1,0,0] op_sel_hi:[1,1,1]
	v_pk_fma_f32 v[14:15], v[190:191], v[46:47], v[14:15] op_sel:[1,0,0] op_sel_hi:[1,1,1]
	v_pk_fma_f32 v[16:17], v[190:191], v[48:49], v[16:17] op_sel:[1,0,0] op_sel_hi:[1,1,1]
	v_pk_fma_f32 v[18:19], v[190:191], v[50:51], v[18:19] op_sel:[1,0,0] op_sel_hi:[1,1,1]
	v_pk_fma_f32 v[20:21], v[190:191], v[52:53], v[20:21] op_sel:[1,0,0] op_sel_hi:[1,1,1]
	v_pk_fma_f32 v[22:23], v[190:191], v[54:55], v[22:23] op_sel:[1,0,0] op_sel_hi:[1,1,1]
	v_pk_fma_f32 v[24:25], v[190:191], v[56:57], v[24:25] op_sel:[1,0,0] op_sel_hi:[1,1,1]
	v_pk_fma_f32 v[26:27], v[190:191], v[58:59], v[26:27] op_sel:[1,0,0] op_sel_hi:[1,1,1]
	v_pk_fma_f32 v[28:29], v[190:191], v[60:61], v[28:29] op_sel:[1,0,0] op_sel_hi:[1,1,1]
	v_pk_fma_f32 v[30:31], v[190:191], v[62:63], v[30:31] op_sel:[1,0,0] op_sel_hi:[1,1,1]
	s_nop 1
	v_permlane32_swap_b32_e32 v0, v16
	v_permlane32_swap_b32_e32 v1, v17
	v_permlane32_swap_b32_e32 v2, v18
	v_permlane32_swap_b32_e32 v3, v19
	v_permlane32_swap_b32_e32 v4, v20
	v_permlane32_swap_b32_e32 v5, v21
	v_permlane32_swap_b32_e32 v6, v22
	v_permlane32_swap_b32_e32 v7, v23
	v_permlane32_swap_b32_e32 v8, v24
	v_permlane32_swap_b32_e32 v9, v25
	v_permlane32_swap_b32_e32 v10, v26
	v_permlane32_swap_b32_e32 v11, v27
	v_permlane32_swap_b32_e32 v12, v28
	v_permlane32_swap_b32_e32 v13, v29
	v_permlane32_swap_b32_e32 v14, v30
	v_permlane32_swap_b32_e32 v15, v31
	v_pk_add_f32 v[0:1], v[0:1], v[16:17]
	v_pk_add_f32 v[2:3], v[2:3], v[18:19]
	v_pk_add_f32 v[4:5], v[4:5], v[20:21]
	v_pk_add_f32 v[6:7], v[6:7], v[22:23]
	v_pk_add_f32 v[8:9], v[8:9], v[24:25]
	v_pk_add_f32 v[10:11], v[10:11], v[26:27]
	v_pk_add_f32 v[12:13], v[12:13], v[28:29]
	v_pk_add_f32 v[14:15], v[14:15], v[30:31]
	s_nop 1
	v_permlane16_swap_b32_e32 v0, v8
	v_permlane16_swap_b32_e32 v1, v9
	v_permlane16_swap_b32_e32 v2, v10
	v_permlane16_swap_b32_e32 v3, v11
	v_permlane16_swap_b32_e32 v4, v12
	v_permlane16_swap_b32_e32 v5, v13
	v_permlane16_swap_b32_e32 v6, v14
	v_permlane16_swap_b32_e32 v7, v15
	v_pk_add_f32 v[0:1], v[0:1], v[8:9]
	v_pk_add_f32 v[2:3], v[2:3], v[10:11]
	v_pk_add_f32 v[4:5], v[4:5], v[12:13]
	v_pk_add_f32 v[6:7], v[6:7], v[14:15]
	s_nop 1
	v_add_f32_dpp v0, v0, v0 row_ror:8 row_mask:0xf bank_mask:0x3
	v_add_f32_dpp v1, v1, v1 row_ror:8 row_mask:0xf bank_mask:0x3
	v_add_f32_dpp v2, v2, v2 row_ror:8 row_mask:0xf bank_mask:0x3
	v_add_f32_dpp v3, v3, v3 row_ror:8 row_mask:0xf bank_mask:0x3
	v_add_f32_dpp v0, v4, v4 row_ror:8 row_mask:0xf bank_mask:0xc
	v_add_f32_dpp v1, v5, v5 row_ror:8 row_mask:0xf bank_mask:0xc
	v_add_f32_dpp v2, v6, v6 row_ror:8 row_mask:0xf bank_mask:0xc
	v_add_f32_dpp v3, v7, v7 row_ror:8 row_mask:0xf bank_mask:0xc
	s_waitcnt vmcnt(16)
	v_pk_add_f32 v[192:193], v[192:193], v[0:1]
	v_pk_add_f32 v[194:195], v[194:195], v[2:3]
	global_store_dwordx4 v200, v[192:195], s[10:11]
	s_cmp_lg_u32 s14, 0
	s_cbranch_scc1 .Lgv1_loop
	s_waitcnt vmcnt(0) lgkmcnt(0)
	s_lshl_b32 s15, s92, 6
	s_add_u32 s101, s101, s15
	s_cmpk_lt_u32 s101, 0x8000
	s_cbranch_scc1 .Lgv1_chunk
	s_branch .LBB0_1104
